# as previous but the 4 shadow A-fragment reads are issued right after the MMA-opening barrier (inside the partner's 2-MFMA tail window)
# baseline (speedup 1.0000x reference)
; #define PG8_STAGE(bufoff, gbase, voff) do { _Pragma("unroll") for (int _i = 0; _i < 2; ++_i) \
;         __builtin_amdgcn_global_load_lds((const unsigned*)((const char*)(gbase) + (voff)[_i]), (LAS unsigned*)(lds + (bufoff) + ldsw + _i * 8192), 16, 0, 0); } while (0)
; #define PG8_LDA(dst, b, h) do { _Pragma("unroll") for (int m = 0; m < 4; ++m) _Pragma("unroll") for (int k = 0; k < 2; ++k) dst[m][k] = *(const LAS bf16x8*)(lds + PG8_SA(b, h) + aoff + m * 2048 + k * 1024); } while (0)
; #define PG8_LDB(dst, b, h) do { _Pragma("unroll") for (int n = 0; n < 2; ++n) _Pragma("unroll") for (int k = 0; k < 2; ++k) dst[n][k] = *(const LAS bf16x8*)(lds + PG8_SB(b, h) + boff + n * 2048 + k * 1024); } while (0)
; #define PG8_MMA(ai, bj, At, Bt) do { __builtin_amdgcn_s_setprio(1); _Pragma("unroll") for (int m = 0; m < 4; ++m) _Pragma("unroll") for (int n = 0; n < 2; ++n) _Pragma("unroll") for (int k = 0; k < 2; ++k) \
;         acc[ai][bj][m][n] = __builtin_amdgcn_mfma_f32_16x16x32_bf16(Bt[n][k], At[m][k], acc[ai][bj][m][n], 0, 0, 0); __builtin_amdgcn_s_setprio(0); } while (0)
; template <class Epi>
; DI void gemm_phase(LAS unsigned char* lds, const Gemm g, const StaticOrder S, const Epi E) {
;     ...
;         for (int t = 0; t < nt; t += 2) {
;             const bool last = (t == nt - 2);
;             const char* a1 = cA + (size_t)(t + 1) * kstep;
;             const char* a2 = last ? nA : cA + (size_t)(t + 2) * kstep; const char* b2 = last ? nB : cB + (size_t)(t + 2) * kstep;
;             const char* a3 = a2 + kstep; const char* b3 = b2 + kstep;
;             PG8_LDB(B0, 0, 0); PG8_SCHED; PG8_LDA(At, 0, 0); PG8_STAGE(PG8_SA(1, 1), a1 + hstep, voffA);
;             PG8_WAIT_L(8); PG8_BAR; PG8_WAIT_L(0); PG8_MMA(0, 0, At, B0); PG8_BAR; PG8_SCHED;
;             PG8_LDB(B1, 0, 1); PG8_STAGE(PG8_SB(0, 0), b2, voffB);
;             PG8_BAR; PG8_WAIT_L(0); PG8_MMA(0, 1, At, B1); PG8_BAR;
;             PG8_LDA(At, 0, 1); PG8_STAGE(PG8_SA(0, 0), a2, voffA);
;             PG8_BAR; PG8_WAIT_L(0); PG8_MMA(1, 0, At, B0); PG8_BAR; PG8_SCHED;
;             PG8_STAGE(PG8_SB(0, 1), b2 + hstep, voffB);
;             PG8_WAIT_V(6); PG8_BAR; PG8_MMA(1, 1, At, B1); PG8_BAR;
;             PG8_LDB(B0, 1, 0); PG8_SCHED; PG8_LDA(At, 1, 0); PG8_STAGE(PG8_SA(0, 1), a2 + hstep, voffA);
;             PG8_WAIT_L(8); PG8_BAR; PG8_WAIT_L(0); PG8_MMA(0, 0, At, B0); PG8_BAR; PG8_SCHED;
.LBB0_107:
	ds_read_b128 v[152:155], v149
	ds_read_b128 v[156:159], v149 offset:1024
	ds_read_b128 v[160:163], v149 offset:2048
	ds_read_b128 v[164:167], v149 offset:3072
	s_add_u32 s14, s76, 0xfffc0080
	s_addc_u32 s15, s77, -1
	s_cmp_eq_u32 s97, 12
	s_cselect_b32 s81, s11, s15
	s_cselect_b32 s80, s93, s14
	s_cselect_b32 s79, s9, s96
	s_cselect_b32 s78, s94, s95
	v_lshl_add_u64 v[144:145], s[76:77], 0, v[136:137]
	s_add_i32 m0, s29, 0xc000
	ds_read_b128 v[168:171], v150
	ds_read_b128 v[176:179], v150 offset:2048
	ds_read_b128 v[184:187], v150 offset:4096
	ds_read_b128 v[192:195], v150 offset:6144
	global_load_lds_dwordx4 v[144:145], off
	v_lshl_add_u64 v[144:145], s[76:77], 0, v[138:139]
	s_add_i32 m0, s29, 0xe000
	s_nop 0
	global_load_lds_dwordx4 v[144:145], off
	s_waitcnt lgkmcnt(4)
	s_setprio 1
	s_barrier
	ds_read_b128 v[172:175], v150 offset:1024
	ds_read_b128 v[180:183], v150 offset:3072
	ds_read_b128 v[188:191], v150 offset:5120
	ds_read_b128 v[196:199], v150 offset:7168
	s_waitcnt lgkmcnt(4)
	v_mfma_f32_16x16x32_bf16 v[124:127], v[152:155], v[168:171], v[124:127]
	v_mfma_f32_16x16x32_bf16 v[116:119], v[160:163], v[168:171], v[116:119]
	v_mfma_f32_16x16x32_bf16 v[108:111], v[152:155], v[176:179], v[108:111]
	v_mfma_f32_16x16x32_bf16 v[100:103], v[160:163], v[176:179], v[100:103]
	v_mfma_f32_16x16x32_bf16 v[92:95], v[152:155], v[184:187], v[92:95]
	v_mfma_f32_16x16x32_bf16 v[84:87], v[160:163], v[184:187], v[84:87]
	v_mfma_f32_16x16x32_bf16 v[76:79], v[152:155], v[192:195], v[76:79]
	v_mfma_f32_16x16x32_bf16 v[68:71], v[160:163], v[192:195], v[68:71]
	s_waitcnt lgkmcnt(3)
	v_mfma_f32_16x16x32_bf16 v[124:127], v[156:159], v[172:175], v[124:127]
	v_mfma_f32_16x16x32_bf16 v[116:119], v[164:167], v[172:175], v[116:119]
	s_waitcnt lgkmcnt(2)
	v_mfma_f32_16x16x32_bf16 v[108:111], v[156:159], v[180:183], v[108:111]
	v_mfma_f32_16x16x32_bf16 v[100:103], v[164:167], v[180:183], v[100:103]
	s_waitcnt lgkmcnt(1)
	v_mfma_f32_16x16x32_bf16 v[92:95], v[156:159], v[188:191], v[92:95]
	v_mfma_f32_16x16x32_bf16 v[84:87], v[164:167], v[188:191], v[84:87]
	s_waitcnt lgkmcnt(0)
	s_setprio 2
	s_barrier
	v_mfma_f32_16x16x32_bf16 v[76:79], v[156:159], v[196:199], v[76:79]
	v_mfma_f32_16x16x32_bf16 v[68:71], v[164:167], v[196:199], v[68:71]
	s_setprio 0
	s_add_i32 s14, s89, s7
	v_lshl_add_u64 v[144:145], s[78:79], 0, v[132:133]
	s_mov_b32 m0, s14
	ds_read_b128 v[200:203], v151
	ds_read_b128 v[204:207], v151 offset:1024
	ds_read_b128 v[208:211], v151 offset:2048
	ds_read_b128 v[212:215], v151 offset:3072
	global_load_lds_dwordx4 v[144:145], off
	v_lshl_add_u64 v[216:217], s[78:79], 0, v[128:129]
	s_add_i32 m0, s14, 0x2000
	s_nop 0
	global_load_lds_dwordx4 v[216:217], off
	s_setprio 1
	s_barrier
	s_waitcnt lgkmcnt(0)
	v_mfma_f32_16x16x32_bf16 v[120:123], v[200:203], v[168:171], v[120:123]
	v_mfma_f32_16x16x32_bf16 v[112:115], v[208:211], v[168:171], v[112:115]
	v_mfma_f32_16x16x32_bf16 v[104:107], v[200:203], v[176:179], v[104:107]
	v_mfma_f32_16x16x32_bf16 v[96:99], v[208:211], v[176:179], v[96:99]
	v_mfma_f32_16x16x32_bf16 v[88:91], v[200:203], v[184:187], v[88:91]
	v_mfma_f32_16x16x32_bf16 v[80:83], v[208:211], v[184:187], v[80:83]
	v_mfma_f32_16x16x32_bf16 v[72:75], v[200:203], v[192:195], v[72:75]
	v_mfma_f32_16x16x32_bf16 v[64:67], v[208:211], v[192:195], v[64:67]
	v_mfma_f32_16x16x32_bf16 v[120:123], v[204:207], v[172:175], v[120:123]
	v_mfma_f32_16x16x32_bf16 v[112:115], v[212:215], v[172:175], v[112:115]
	v_mfma_f32_16x16x32_bf16 v[104:107], v[204:207], v[180:183], v[104:107]
	v_mfma_f32_16x16x32_bf16 v[96:99], v[212:215], v[180:183], v[96:99]
	v_mfma_f32_16x16x32_bf16 v[88:91], v[204:207], v[188:191], v[88:91]
	v_mfma_f32_16x16x32_bf16 v[80:83], v[212:215], v[188:191], v[80:83]
	s_setprio 2
	s_barrier
	v_mfma_f32_16x16x32_bf16 v[72:75], v[204:207], v[196:199], v[72:75]
	v_mfma_f32_16x16x32_bf16 v[64:67], v[212:215], v[196:199], v[64:67]
	s_setprio 0
	s_mov_b32 m0, s29
	v_lshl_add_u64 v[218:219], s[80:81], 0, v[134:135]
	ds_read_b128 v[168:171], v150 offset:16384
	ds_read_b128 v[176:179], v150 offset:18432
	ds_read_b128 v[184:187], v150 offset:20480
	ds_read_b128 v[192:195], v150 offset:22528
	global_load_lds_dwordx4 v[218:219], off
	v_lshl_add_u64 v[220:221], s[80:81], 0, v[130:131]
	s_mov_b32 m0, s59
	s_nop 0
	global_load_lds_dwordx4 v[220:221], off
	s_setprio 1
	s_barrier
	ds_read_b128 v[172:175], v150 offset:17408
	ds_read_b128 v[180:183], v150 offset:19456
	ds_read_b128 v[188:191], v150 offset:21504
	ds_read_b128 v[196:199], v150 offset:23552
	s_waitcnt lgkmcnt(4)
	v_mfma_f32_16x16x32_bf16 v[60:63], v[152:155], v[168:171], v[60:63]
	v_mfma_f32_16x16x32_bf16 v[52:55], v[160:163], v[168:171], v[52:55]
	v_mfma_f32_16x16x32_bf16 v[44:47], v[152:155], v[176:179], v[44:47]
	v_mfma_f32_16x16x32_bf16 v[36:39], v[160:163], v[176:179], v[36:39]
	v_mfma_f32_16x16x32_bf16 v[28:31], v[152:155], v[184:187], v[28:31]
	v_mfma_f32_16x16x32_bf16 v[20:23], v[160:163], v[184:187], v[20:23]
	v_mfma_f32_16x16x32_bf16 v[12:15], v[152:155], v[192:195], v[12:15]
	v_mfma_f32_16x16x32_bf16 v[4:7], v[160:163], v[192:195], v[4:7]
	s_waitcnt lgkmcnt(3)
	v_mfma_f32_16x16x32_bf16 v[60:63], v[156:159], v[172:175], v[60:63]
	v_mfma_f32_16x16x32_bf16 v[52:55], v[164:167], v[172:175], v[52:55]
	s_waitcnt lgkmcnt(2)
	v_mfma_f32_16x16x32_bf16 v[44:47], v[156:159], v[180:183], v[44:47]
	v_mfma_f32_16x16x32_bf16 v[36:39], v[164:167], v[180:183], v[36:39]
	s_waitcnt lgkmcnt(1)
	v_mfma_f32_16x16x32_bf16 v[28:31], v[156:159], v[188:191], v[28:31]
	v_mfma_f32_16x16x32_bf16 v[20:23], v[164:167], v[188:191], v[20:23]
	s_waitcnt lgkmcnt(0)
	s_setprio 2
	s_barrier
; #define PG8_STAGE(bufoff, gbase, voff) do { _Pragma("unroll") for (int _i = 0; _i < 2; ++_i) \
;         __builtin_amdgcn_global_load_lds((const unsigned*)((const char*)(gbase) + (voff)[_i]), (LAS unsigned*)(lds + (bufoff) + ldsw + _i * 8192), 16, 0, 0); } while (0)
; #define PG8_LDA(dst, b, h) do { _Pragma("unroll") for (int m = 0; m < 4; ++m) _Pragma("unroll") for (int k = 0; k < 2; ++k) dst[m][k] = *(const LAS bf16x8*)(lds + PG8_SA(b, h) + aoff + m * 2048 + k * 1024); } while (0)
; #define PG8_LDB(dst, b, h) do { _Pragma("unroll") for (int n = 0; n < 2; ++n) _Pragma("unroll") for (int k = 0; k < 2; ++k) dst[n][k] = *(const LAS bf16x8*)(lds + PG8_SB(b, h) + boff + n * 2048 + k * 1024); } while (0)
; #define PG8_MMA(ai, bj, At, Bt) do { __builtin_amdgcn_s_setprio(1); _Pragma("unroll") for (int m = 0; m < 4; ++m) _Pragma("unroll") for (int n = 0; n < 2; ++n) _Pragma("unroll") for (int k = 0; k < 2; ++k) \
;         acc[ai][bj][m][n] = __builtin_amdgcn_mfma_f32_16x16x32_bf16(Bt[n][k], At[m][k], acc[ai][bj][m][n], 0, 0, 0); __builtin_amdgcn_s_setprio(0); } while (0)
; #define PG8_WAIT_V(n) asm volatile("s_waitcnt vmcnt(" #n ")" ::: "memory")
; #define PG8_WAIT_L(n) asm volatile("s_waitcnt lgkmcnt(" #n ")" ::: "memory")
; #define PG8_BAR __builtin_amdgcn_s_barrier()
; #define PG8_SCHED __builtin_amdgcn_sched_barrier(0)
; #define PG8_WAIT_V(n) asm volatile("s_waitcnt vmcnt(" #n ")" ::: "memory")
; #define PG8_WAIT_L(n) asm volatile("s_waitcnt lgkmcnt(" #n ")" ::: "memory")
; template <class Epi>
; DI void gemm_phase(LAS unsigned char* lds, const Gemm g, const StaticOrder S, const Epi E) {
;     ...
;             PG8_STAGE(PG8_SB(0, 1), b2 + hstep, voffB);
;             PG8_WAIT_V(6); PG8_BAR; PG8_MMA(1, 1, At, B1); PG8_BAR;
;             PG8_LDB(B0, 1, 0); PG8_SCHED; PG8_LDA(At, 1, 0); PG8_STAGE(PG8_SA(0, 1), a2 + hstep, voffA);
;             PG8_WAIT_L(8); PG8_BAR; PG8_WAIT_L(0); PG8_MMA(0, 0, At, B0); PG8_BAR; PG8_SCHED;
;             PG8_LDB(B1, 1, 1); PG8_STAGE(PG8_SB(1, 0), b3, voffB);
;             PG8_BAR; PG8_WAIT_L(0); PG8_MMA(0, 1, At, B1); PG8_BAR;
;             PG8_LDA(At, 1, 1); PG8_STAGE(PG8_SA(1, 0), a3, voffA);
;             PG8_BAR; PG8_WAIT_L(0); PG8_MMA(1, 0, At, B0); PG8_BAR; PG8_SCHED;
;             PG8_STAGE(PG8_SB(1, 1), b3 + hstep, voffB);
;             PG8_WAIT_V(6); PG8_BAR; PG8_MMA(1, 1, At, B1); PG8_BAR;
	v_mfma_f32_16x16x32_bf16 v[12:15], v[156:159], v[196:199], v[12:15]
	v_mfma_f32_16x16x32_bf16 v[4:7], v[164:167], v[196:199], v[4:7]
	s_setprio 0
	s_add_u32 s14, s78, 0x40000
	s_addc_u32 s15, s79, 0
	s_add_i32 s35, s90, s7
	v_lshl_add_u64 v[152:153], s[14:15], 0, v[132:133]
	s_mov_b32 m0, s35
	s_nop 0
	global_load_lds_dwordx4 v[152:153], off
	v_lshl_add_u64 v[152:153], s[14:15], 0, v[128:129]
	s_add_i32 m0, s35, 0x2000
	s_nop 0
	global_load_lds_dwordx4 v[152:153], off
	s_waitcnt vmcnt(6)
	s_setprio 1
	s_barrier
	v_mfma_f32_16x16x32_bf16 v[56:59], v[200:203], v[168:171], v[56:59]
	v_mfma_f32_16x16x32_bf16 v[48:51], v[208:211], v[168:171], v[48:51]
	v_mfma_f32_16x16x32_bf16 v[40:43], v[200:203], v[176:179], v[40:43]
	v_mfma_f32_16x16x32_bf16 v[32:35], v[208:211], v[176:179], v[32:35]
	v_mfma_f32_16x16x32_bf16 v[24:27], v[200:203], v[184:187], v[24:27]
	v_mfma_f32_16x16x32_bf16 v[16:19], v[208:211], v[184:187], v[16:19]
	v_mfma_f32_16x16x32_bf16 v[8:11], v[200:203], v[192:195], v[8:11]
	v_mfma_f32_16x16x32_bf16 v[0:3], v[208:211], v[192:195], v[0:3]
	v_mfma_f32_16x16x32_bf16 v[56:59], v[204:207], v[172:175], v[56:59]
	v_mfma_f32_16x16x32_bf16 v[48:51], v[212:215], v[172:175], v[48:51]
	v_mfma_f32_16x16x32_bf16 v[40:43], v[204:207], v[180:183], v[40:43]
	v_mfma_f32_16x16x32_bf16 v[32:35], v[212:215], v[180:183], v[32:35]
	v_mfma_f32_16x16x32_bf16 v[24:27], v[204:207], v[188:191], v[24:27]
	v_mfma_f32_16x16x32_bf16 v[16:19], v[212:215], v[188:191], v[16:19]
	s_setprio 2
	s_barrier
	v_mfma_f32_16x16x32_bf16 v[8:11], v[204:207], v[196:199], v[8:11]
	v_mfma_f32_16x16x32_bf16 v[0:3], v[212:215], v[196:199], v[0:3]
	s_setprio 0
	s_add_i32 s35, 0, 0x18000
	v_add_u32_e32 v164, s35, v147
	ds_read_b128 v[152:155], v164
	ds_read_b128 v[156:159], v164 offset:1024
	ds_read_b128 v[160:163], v164 offset:2048
	ds_read_b128 v[164:167], v164 offset:3072
	s_add_u32 s14, s80, 0x40000
	s_addc_u32 s15, s81, 0
	s_mov_b32 m0, s82
	v_lshl_add_u64 v[200:201], s[14:15], 0, v[134:135]
	ds_read_b128 v[168:171], v150 offset:32768
	ds_read_b128 v[176:179], v150 offset:34816
	ds_read_b128 v[184:187], v150 offset:36864
	ds_read_b128 v[192:195], v150 offset:38912
	global_load_lds_dwordx4 v[200:201], off
	v_lshl_add_u64 v[200:201], s[14:15], 0, v[130:131]
	s_mov_b32 m0, s83
	s_nop 0
	global_load_lds_dwordx4 v[200:201], off
	s_waitcnt lgkmcnt(4)
	s_setprio 1
	s_barrier
	ds_read_b128 v[172:175], v150 offset:33792
	ds_read_b128 v[180:183], v150 offset:35840
	ds_read_b128 v[188:191], v150 offset:37888
	ds_read_b128 v[196:199], v150 offset:39936
	s_waitcnt lgkmcnt(4)
	v_mfma_f32_16x16x32_bf16 v[124:127], v[152:155], v[168:171], v[124:127]
	v_mfma_f32_16x16x32_bf16 v[116:119], v[160:163], v[168:171], v[116:119]
	v_mfma_f32_16x16x32_bf16 v[108:111], v[152:155], v[176:179], v[108:111]
	v_mfma_f32_16x16x32_bf16 v[100:103], v[160:163], v[176:179], v[100:103]
	v_mfma_f32_16x16x32_bf16 v[92:95], v[152:155], v[184:187], v[92:95]
	v_mfma_f32_16x16x32_bf16 v[84:87], v[160:163], v[184:187], v[84:87]
	v_mfma_f32_16x16x32_bf16 v[76:79], v[152:155], v[192:195], v[76:79]
	v_mfma_f32_16x16x32_bf16 v[68:71], v[160:163], v[192:195], v[68:71]
	s_waitcnt lgkmcnt(3)
	v_mfma_f32_16x16x32_bf16 v[124:127], v[156:159], v[172:175], v[124:127]
	v_mfma_f32_16x16x32_bf16 v[116:119], v[164:167], v[172:175], v[116:119]
	s_waitcnt lgkmcnt(2)
	v_mfma_f32_16x16x32_bf16 v[108:111], v[156:159], v[180:183], v[108:111]
	v_mfma_f32_16x16x32_bf16 v[100:103], v[164:167], v[180:183], v[100:103]
	s_waitcnt lgkmcnt(1)
	v_mfma_f32_16x16x32_bf16 v[92:95], v[156:159], v[188:191], v[92:95]
	v_mfma_f32_16x16x32_bf16 v[84:87], v[164:167], v[188:191], v[84:87]
	s_waitcnt lgkmcnt(0)
	s_setprio 2
	s_barrier
	v_mfma_f32_16x16x32_bf16 v[76:79], v[156:159], v[196:199], v[76:79]
	v_mfma_f32_16x16x32_bf16 v[68:71], v[164:167], v[196:199], v[68:71]
	s_setprio 0
	s_add_i32 s80, 0, 0x1c000
	s_add_i32 s14, s35, s7
	v_add_u32_e32 v212, s80, v147
	v_lshl_add_u64 v[144:145], v[144:145], 0, s[4:5]
	s_mov_b32 m0, s14
	ds_read_b128 v[200:203], v212
	ds_read_b128 v[204:207], v212 offset:1024
	ds_read_b128 v[208:211], v212 offset:2048
	ds_read_b128 v[212:215], v212 offset:3072
	global_load_lds_dwordx4 v[144:145], off
	v_lshl_add_u64 v[144:145], v[216:217], 0, s[4:5]
	s_add_i32 m0, s14, 0x2000
	s_nop 0
	global_load_lds_dwordx4 v[144:145], off
	s_setprio 1
	s_barrier
	s_waitcnt lgkmcnt(0)
	v_mfma_f32_16x16x32_bf16 v[120:123], v[200:203], v[168:171], v[120:123]
	v_mfma_f32_16x16x32_bf16 v[112:115], v[208:211], v[168:171], v[112:115]
	v_mfma_f32_16x16x32_bf16 v[104:107], v[200:203], v[176:179], v[104:107]
	v_mfma_f32_16x16x32_bf16 v[96:99], v[208:211], v[176:179], v[96:99]
	v_mfma_f32_16x16x32_bf16 v[88:91], v[200:203], v[184:187], v[88:91]
	v_mfma_f32_16x16x32_bf16 v[80:83], v[208:211], v[184:187], v[80:83]
	v_mfma_f32_16x16x32_bf16 v[72:75], v[200:203], v[192:195], v[72:75]
	v_mfma_f32_16x16x32_bf16 v[64:67], v[208:211], v[192:195], v[64:67]
	v_mfma_f32_16x16x32_bf16 v[120:123], v[204:207], v[172:175], v[120:123]
	v_mfma_f32_16x16x32_bf16 v[112:115], v[212:215], v[172:175], v[112:115]
	v_mfma_f32_16x16x32_bf16 v[104:107], v[204:207], v[180:183], v[104:107]
	v_mfma_f32_16x16x32_bf16 v[96:99], v[212:215], v[180:183], v[96:99]
	v_mfma_f32_16x16x32_bf16 v[88:91], v[204:207], v[188:191], v[88:91]
	v_mfma_f32_16x16x32_bf16 v[80:83], v[212:215], v[188:191], v[80:83]
	s_setprio 2
	s_barrier
; DI unsigned pk_bf16(float lo, float hi) { f32x2 v = {lo, hi}; return __builtin_bit_cast(unsigned, __builtin_convertvector(v, bf16v2)); }
; DI float fast_silu(float x) { return x * fast_sigmoid(x); }
; #define PG8_STAGE(bufoff, gbase, voff) do { _Pragma("unroll") for (int _i = 0; _i < 2; ++_i) \
;         __builtin_amdgcn_global_load_lds((const unsigned*)((const char*)(gbase) + (voff)[_i]), (LAS unsigned*)(lds + (bufoff) + ldsw + _i * 8192), 16, 0, 0); } while (0)
; #define PG8_LDA(dst, b, h) do { _Pragma("unroll") for (int m = 0; m < 4; ++m) _Pragma("unroll") for (int k = 0; k < 2; ++k) dst[m][k] = *(const LAS bf16x8*)(lds + PG8_SA(b, h) + aoff + m * 2048 + k * 1024); } while (0)
; #define PG8_WAIT_V(n) asm volatile("s_waitcnt vmcnt(" #n ")" ::: "memory")
; #define PG8_WAIT_L(n) asm volatile("s_waitcnt lgkmcnt(" #n ")" ::: "memory")
; #define PG8_BAR __builtin_amdgcn_s_barrier()
; template <class Epi>
; DI void gemm_phase(LAS unsigned char* lds, const Gemm g, const StaticOrder S, const Epi E) {
;     ...
;             PG8_WAIT_L(8); PG8_BAR; PG8_WAIT_L(0); PG8_MMA(0, 0, At, B0); PG8_BAR; PG8_SCHED;
;             PG8_LDB(B1, 1, 1); PG8_STAGE(PG8_SB(1, 0), b3, voffB);
;             PG8_BAR; PG8_WAIT_L(0); PG8_MMA(0, 1, At, B1); PG8_BAR;
;             PG8_LDA(At, 1, 1); PG8_STAGE(PG8_SA(1, 0), a3, voffA);
;             PG8_BAR; PG8_WAIT_L(0); PG8_MMA(1, 0, At, B0); PG8_BAR; PG8_SCHED;
;             PG8_STAGE(PG8_SB(1, 1), b3 + hstep, voffB);
;             PG8_WAIT_V(6); PG8_BAR; PG8_MMA(1, 1, At, B1); PG8_BAR;
;     DI void operator()(AccRef acc, const Unit& u, int wr, int wc, int fr, int fq) const {
;     ...
; #pragma unroll
;         for (int ai = 0; ai < 2; ++ai)
; #pragma unroll
;             for (int m = 0; m < 4; ++m) {
;                 const int row = row0 + ai * 128 + m * 16;
;                 const float r = RS ? rsc.r[ai][m] : 1.0f;
;                 const f32x4 a0 = acc[ai][0][m][0] * r, a1 = acc[ai][0][m][1] * r, b0 = acc[ai][1][m][0] * r, b1 = acc[ai][1][m][1] * r;
;                 u32x4 w;
;                 w.x = pk_bf16(fast_silu(a0[0]) * b0[0], fast_silu(a0[1]) * b0[1]); w.y = pk_bf16(fast_silu(a0[2]) * b0[2], fast_silu(a0[3]) * b0[3]);
;                 w.z = pk_bf16(fast_silu(a1[0]) * b1[0], fast_silu(a1[1]) * b1[1]); w.w = pk_bf16(fast_silu(a1[2]) * b1[2], fast_silu(a1[3]) * b1[3]);
;                 *(u32x4*)(G + (size_t)row * DFF + col) = w;
	v_mfma_f32_16x16x32_bf16 v[72:75], v[204:207], v[196:199], v[72:75]
	v_mfma_f32_16x16x32_bf16 v[64:67], v[212:215], v[196:199], v[64:67]
	s_setprio 0
	s_mov_b32 m0, s85
	v_lshl_add_u64 v[144:145], v[218:219], 0, s[4:5]
	ds_read_b128 v[168:171], v150 offset:49152
	ds_read_b128 v[176:179], v150 offset:51200
	ds_read_b128 v[184:187], v150 offset:53248
	ds_read_b128 v[192:195], v150 offset:55296
	global_load_lds_dwordx4 v[144:145], off
	v_lshl_add_u64 v[144:145], v[220:221], 0, s[4:5]
	s_mov_b32 m0, s86
	s_nop 0
	global_load_lds_dwordx4 v[144:145], off
	s_setprio 1
	s_barrier
	ds_read_b128 v[172:175], v150 offset:50176
	ds_read_b128 v[180:183], v150 offset:52224
	ds_read_b128 v[188:191], v150 offset:54272
	ds_read_b128 v[196:199], v150 offset:56320
	s_waitcnt lgkmcnt(4)
	v_mfma_f32_16x16x32_bf16 v[60:63], v[152:155], v[168:171], v[60:63]
	v_mfma_f32_16x16x32_bf16 v[52:55], v[160:163], v[168:171], v[52:55]
	v_mfma_f32_16x16x32_bf16 v[44:47], v[152:155], v[176:179], v[44:47]
	v_mfma_f32_16x16x32_bf16 v[36:39], v[160:163], v[176:179], v[36:39]
	v_mfma_f32_16x16x32_bf16 v[28:31], v[152:155], v[184:187], v[28:31]
	v_mfma_f32_16x16x32_bf16 v[20:23], v[160:163], v[184:187], v[20:23]
	v_mfma_f32_16x16x32_bf16 v[12:15], v[152:155], v[192:195], v[12:15]
	v_mfma_f32_16x16x32_bf16 v[4:7], v[160:163], v[192:195], v[4:7]
	s_waitcnt lgkmcnt(3)
	v_mfma_f32_16x16x32_bf16 v[60:63], v[156:159], v[172:175], v[60:63]
	v_mfma_f32_16x16x32_bf16 v[52:55], v[164:167], v[172:175], v[52:55]
	s_waitcnt lgkmcnt(2)
	v_mfma_f32_16x16x32_bf16 v[44:47], v[156:159], v[180:183], v[44:47]
	v_mfma_f32_16x16x32_bf16 v[36:39], v[164:167], v[180:183], v[36:39]
	s_waitcnt lgkmcnt(1)
	v_mfma_f32_16x16x32_bf16 v[28:31], v[156:159], v[188:191], v[28:31]
	v_mfma_f32_16x16x32_bf16 v[20:23], v[164:167], v[188:191], v[20:23]
	s_waitcnt lgkmcnt(0)
	s_setprio 2
	s_barrier
	v_mfma_f32_16x16x32_bf16 v[12:15], v[156:159], v[196:199], v[12:15]
	v_mfma_f32_16x16x32_bf16 v[4:7], v[164:167], v[196:199], v[4:7]
	s_setprio 0
	s_add_u32 s14, s78, 0x40080
	s_addc_u32 s15, s79, 0
	s_add_i32 s35, s80, s7
	v_lshl_add_u64 v[144:145], s[14:15], 0, v[132:133]
	s_mov_b32 m0, s35
	s_nop 0
	global_load_lds_dwordx4 v[144:145], off
	v_lshl_add_u64 v[144:145], s[14:15], 0, v[128:129]
	s_add_i32 m0, s35, 0x2000
	s_nop 0
	global_load_lds_dwordx4 v[144:145], off
	s_waitcnt vmcnt(6)
	s_setprio 1
	s_barrier
	v_mfma_f32_16x16x32_bf16 v[56:59], v[200:203], v[168:171], v[56:59]
	v_mfma_f32_16x16x32_bf16 v[48:51], v[208:211], v[168:171], v[48:51]
	v_mfma_f32_16x16x32_bf16 v[40:43], v[200:203], v[176:179], v[40:43]
	v_mfma_f32_16x16x32_bf16 v[32:35], v[208:211], v[176:179], v[32:35]
	v_mfma_f32_16x16x32_bf16 v[24:27], v[200:203], v[184:187], v[24:27]
	v_mfma_f32_16x16x32_bf16 v[16:19], v[208:211], v[184:187], v[16:19]
	v_mfma_f32_16x16x32_bf16 v[8:11], v[200:203], v[192:195], v[8:11]
	v_mfma_f32_16x16x32_bf16 v[0:3], v[208:211], v[192:195], v[0:3]
	v_mfma_f32_16x16x32_bf16 v[56:59], v[204:207], v[172:175], v[56:59]
	v_mfma_f32_16x16x32_bf16 v[48:51], v[212:215], v[172:175], v[48:51]
	v_mfma_f32_16x16x32_bf16 v[40:43], v[204:207], v[180:183], v[40:43]
	v_mfma_f32_16x16x32_bf16 v[32:35], v[212:215], v[180:183], v[32:35]
	v_mfma_f32_16x16x32_bf16 v[24:27], v[204:207], v[188:191], v[24:27]
	v_mfma_f32_16x16x32_bf16 v[16:19], v[212:215], v[188:191], v[16:19]
	s_setprio 2
	s_barrier
	v_mfma_f32_16x16x32_bf16 v[8:11], v[204:207], v[196:199], v[8:11]
	v_mfma_f32_16x16x32_bf16 v[0:3], v[212:215], v[196:199], v[0:3]
	s_setprio 0
	s_add_i32 s97, s97, 2
	s_add_u32 s76, s76, 0x100
	s_addc_u32 s77, s77, 0
	s_add_u32 s95, s95, 0x100
	s_addc_u32 s96, s96, 0
	s_cmp_gt_u32 s97, 13
	s_cbranch_scc0 .LBB0_107
	v_mul_f32_e32 v153, 0xbfb8aa3b, v124
	v_exp_f32_e32 v153, v153
	v_mul_f32_e32 v154, 0xbfb8aa3b, v125
	v_exp_f32_e32 v155, v154
	v_lshl_or_b32 v144, s92, 7, v148
	v_add_f32_e32 v153, 1.0, v153
	v_rcp_f32_e32 v154, v153
	v_add_f32_e32 v153, 1.0, v155
	v_mul_f32_e32 v155, 0xbfb8aa3b, v126
	v_exp_f32_e32 v156, v155
	v_mul_f32_e32 v155, 0xbfb8aa3b, v127
	v_exp_f32_e32 v157, v155
	v_rcp_f32_e32 v155, v153
	v_add_f32_e32 v153, 1.0, v156
	v_rcp_f32_e32 v156, v153
	v_add_f32_e32 v153, 1.0, v157
	v_rcp_f32_e32 v157, v153
	v_pk_mul_f32 v[124:125], v[124:125], v[154:155]
	v_ashrrev_i32_e32 v145, 31, v144
	v_pk_mul_f32 v[120:121], v[124:125], v[120:121]
	v_pk_mul_f32 v[124:125], v[126:127], v[156:157]
	v_cvt_pk_bf16_f32 v120, v120, v121
	v_mul_f32_e32 v121, 0xbfb8aa3b, v116
	v_pk_mul_f32 v[122:123], v[124:125], v[122:123]
	v_exp_f32_e32 v124, v121
	v_mul_f32_e32 v121, 0xbfb8aa3b, v117
	v_exp_f32_e32 v125, v121
	v_cvt_pk_bf16_f32 v121, v122, v123
	v_add_f32_e32 v122, 1.0, v124
	v_mul_f32_e32 v124, 0xbfb8aa3b, v118
	v_add_f32_e32 v123, 1.0, v125
	v_mul_f32_e32 v125, 0xbfb8aa3b, v119
	v_exp_f32_e32 v124, v124
	v_exp_f32_e32 v125, v125
	v_rcp_f32_e32 v122, v122
	v_rcp_f32_e32 v123, v123
	v_add_f32_e32 v124, 1.0, v124
	v_add_f32_e32 v125, 1.0, v125
	v_rcp_f32_e32 v124, v124
	v_rcp_f32_e32 v125, v125
	v_pk_mul_f32 v[116:117], v[116:117], v[122:123]
	v_lshl_add_u32 v152, s28, 8, v146
	v_pk_mul_f32 v[112:113], v[116:117], v[112:113]
	v_lshl_add_u64 v[144:145], v[144:145], 1, s[54:55]
	v_cvt_pk_bf16_f32 v122, v112, v113
	v_pk_mul_f32 v[112:113], v[118:119], v[124:125]
	v_or_b32_e32 v116, 16, v152
	v_pk_mul_f32 v[112:113], v[112:113], v[114:115]
	v_mul_f32_e32 v114, 0xbfb8aa3b, v110
	v_cvt_pk_bf16_f32 v123, v112, v113
	v_mad_i64_i32 v[112:113], s[14:15], v152, s91, v[144:145]
	global_store_dwordx4 v[112:113], v[120:123], off
	v_mul_f32_e32 v112, 0xbfb8aa3b, v108
	v_mul_f32_e32 v113, 0xbfb8aa3b, v109
	v_exp_f32_e32 v112, v112
	v_exp_f32_e32 v113, v113
; DI unsigned pk_bf16(float lo, float hi) { f32x2 v = {lo, hi}; return __builtin_bit_cast(unsigned, __builtin_convertvector(v, bf16v2)); }
; DI float fast_silu(float x) { return x * fast_sigmoid(x); }
;     DI void operator()(AccRef acc, const Unit& u, int wr, int wc, int fr, int fq) const {
;     ...
; #pragma unroll
;         for (int ai = 0; ai < 2; ++ai)
; #pragma unroll
;             for (int m = 0; m < 4; ++m) {
;                 const int row = row0 + ai * 128 + m * 16;
;                 const float r = RS ? rsc.r[ai][m] : 1.0f;
;                 const f32x4 a0 = acc[ai][0][m][0] * r, a1 = acc[ai][0][m][1] * r, b0 = acc[ai][1][m][0] * r, b1 = acc[ai][1][m][1] * r;
;                 u32x4 w;
;                 w.x = pk_bf16(fast_silu(a0[0]) * b0[0], fast_silu(a0[1]) * b0[1]); w.y = pk_bf16(fast_silu(a0[2]) * b0[2], fast_silu(a0[3]) * b0[3]);
;                 w.z = pk_bf16(fast_silu(a1[0]) * b1[0], fast_silu(a1[1]) * b1[1]); w.w = pk_bf16(fast_silu(a1[2]) * b1[2], fast_silu(a1[3]) * b1[3]);
;                 *(u32x4*)(G + (size_t)row * DFF + col) = w;
	v_mul_f32_e32 v115, 0xbfb8aa3b, v111
	v_exp_f32_e32 v114, v114
	v_exp_f32_e32 v115, v115
	v_add_f32_e32 v112, 1.0, v112
	v_add_f32_e32 v113, 1.0, v113
	v_rcp_f32_e32 v112, v112
	v_rcp_f32_e32 v113, v113
	v_add_f32_e32 v114, 1.0, v114
	v_add_f32_e32 v115, 1.0, v115
	v_rcp_f32_e32 v114, v114
	v_rcp_f32_e32 v115, v115
	v_pk_mul_f32 v[108:109], v[108:109], v[112:113]
	s_and_b64 vcc, exec, s[0:1]
	v_pk_mul_f32 v[104:105], v[108:109], v[104:105]
	v_pk_mul_f32 v[108:109], v[110:111], v[114:115]
	v_cvt_pk_bf16_f32 v104, v104, v105
	v_mul_f32_e32 v105, 0xbfb8aa3b, v100
	v_pk_mul_f32 v[106:107], v[108:109], v[106:107]
	v_exp_f32_e32 v108, v105
	v_mul_f32_e32 v105, 0xbfb8aa3b, v101
	v_exp_f32_e32 v109, v105
	v_cvt_pk_bf16_f32 v105, v106, v107
	v_add_f32_e32 v106, 1.0, v108
	v_mul_f32_e32 v108, 0xbfb8aa3b, v102
	v_add_f32_e32 v107, 1.0, v109
	v_mul_f32_e32 v109, 0xbfb8aa3b, v103
	v_exp_f32_e32 v108, v108
	v_exp_f32_e32 v109, v109
	v_rcp_f32_e32 v106, v106
	v_rcp_f32_e32 v107, v107
	v_add_f32_e32 v108, 1.0, v108
	v_add_f32_e32 v109, 1.0, v109
	v_rcp_f32_e32 v108, v108
	v_rcp_f32_e32 v109, v109
	v_pk_mul_f32 v[100:101], v[100:101], v[106:107]
	s_mov_b32 s92, s8
	v_pk_mul_f32 v[96:97], v[100:101], v[96:97]
	v_or_b32_e32 v100, 32, v152
	v_cvt_pk_bf16_f32 v106, v96, v97
	v_pk_mul_f32 v[96:97], v[102:103], v[108:109]
	s_mov_b32 s28, s10
	v_pk_mul_f32 v[96:97], v[96:97], v[98:99]
	v_mul_f32_e32 v98, 0xbfb8aa3b, v94
	v_cvt_pk_bf16_f32 v107, v96, v97
	v_mad_i64_i32 v[96:97], s[14:15], v116, s91, v[144:145]
	global_store_dwordx4 v[96:97], v[104:107], off
	v_mul_f32_e32 v96, 0xbfb8aa3b, v92
	v_mul_f32_e32 v97, 0xbfb8aa3b, v93
	v_exp_f32_e32 v96, v96
	v_exp_f32_e32 v97, v97
	v_mul_f32_e32 v99, 0xbfb8aa3b, v95
	v_exp_f32_e32 v98, v98
	v_exp_f32_e32 v99, v99
	v_add_f32_e32 v96, 1.0, v96
	v_add_f32_e32 v97, 1.0, v97
	v_rcp_f32_e32 v96, v96
	v_rcp_f32_e32 v97, v97
	v_add_f32_e32 v98, 1.0, v98
	v_add_f32_e32 v99, 1.0, v99
	v_rcp_f32_e32 v98, v98
	v_rcp_f32_e32 v99, v99
	v_pk_mul_f32 v[92:93], v[92:93], v[96:97]
	s_mov_b64 s[78:79], s[26:27]
	v_pk_mul_f32 v[88:89], v[92:93], v[88:89]
	v_pk_mul_f32 v[92:93], v[94:95], v[98:99]
	v_cvt_pk_bf16_f32 v88, v88, v89
	v_mul_f32_e32 v89, 0xbfb8aa3b, v84
	v_pk_mul_f32 v[90:91], v[92:93], v[90:91]
	v_exp_f32_e32 v92, v89
	v_mul_f32_e32 v89, 0xbfb8aa3b, v85
	v_exp_f32_e32 v93, v89
	v_cvt_pk_bf16_f32 v89, v90, v91
	v_add_f32_e32 v90, 1.0, v92
	v_mul_f32_e32 v92, 0xbfb8aa3b, v86
	v_add_f32_e32 v91, 1.0, v93
	v_mul_f32_e32 v93, 0xbfb8aa3b, v87
	v_exp_f32_e32 v92, v92
	v_exp_f32_e32 v93, v93
	v_rcp_f32_e32 v90, v90
	v_rcp_f32_e32 v91, v91
	v_add_f32_e32 v92, 1.0, v92
	v_add_f32_e32 v93, 1.0, v93
	v_rcp_f32_e32 v92, v92
	v_rcp_f32_e32 v93, v93
	v_pk_mul_f32 v[84:85], v[84:85], v[90:91]
	s_mov_b64 s[76:77], s[24:25]
	v_pk_mul_f32 v[80:81], v[84:85], v[80:81]
	v_or_b32_e32 v84, 48, v152
	v_cvt_pk_bf16_f32 v90, v80, v81
	v_pk_mul_f32 v[80:81], v[86:87], v[92:93]
	s_nop 0
	v_pk_mul_f32 v[80:81], v[80:81], v[82:83]
	v_mul_f32_e32 v82, 0xbfb8aa3b, v78
	v_cvt_pk_bf16_f32 v91, v80, v81
	v_mad_i64_i32 v[80:81], s[14:15], v100, s91, v[144:145]
	global_store_dwordx4 v[80:81], v[88:91], off
	v_mul_f32_e32 v80, 0xbfb8aa3b, v76
	v_mul_f32_e32 v81, 0xbfb8aa3b, v77
	v_exp_f32_e32 v80, v80
	v_exp_f32_e32 v81, v81
	v_mul_f32_e32 v83, 0xbfb8aa3b, v79
	v_exp_f32_e32 v82, v82
	v_exp_f32_e32 v83, v83
	v_add_f32_e32 v80, 1.0, v80
	v_add_f32_e32 v81, 1.0, v81
	v_rcp_f32_e32 v80, v80
	v_rcp_f32_e32 v81, v81
	v_add_f32_e32 v82, 1.0, v82
	v_add_f32_e32 v83, 1.0, v83
	v_rcp_f32_e32 v82, v82
	v_rcp_f32_e32 v83, v83
	v_pk_mul_f32 v[76:77], v[76:77], v[80:81]
	s_nop 0
	v_pk_mul_f32 v[72:73], v[76:77], v[72:73]
	v_pk_mul_f32 v[76:77], v[78:79], v[82:83]
	v_cvt_pk_bf16_f32 v72, v72, v73
	v_mul_f32_e32 v73, 0xbfb8aa3b, v68
	v_pk_mul_f32 v[74:75], v[76:77], v[74:75]
	v_exp_f32_e32 v76, v73
	v_mul_f32_e32 v73, 0xbfb8aa3b, v69
	v_exp_f32_e32 v77, v73
	v_cvt_pk_bf16_f32 v73, v74, v75
	v_add_f32_e32 v74, 1.0, v76
	v_mul_f32_e32 v76, 0xbfb8aa3b, v70
	v_add_f32_e32 v75, 1.0, v77
	v_mul_f32_e32 v77, 0xbfb8aa3b, v71
	v_exp_f32_e32 v76, v76
	v_exp_f32_e32 v77, v77
	v_rcp_f32_e32 v74, v74
	v_rcp_f32_e32 v75, v75
	v_add_f32_e32 v76, 1.0, v76
	v_add_f32_e32 v77, 1.0, v77
	v_rcp_f32_e32 v76, v76
	v_rcp_f32_e32 v77, v77
	v_pk_mul_f32 v[68:69], v[68:69], v[74:75]
	s_nop 0
	v_pk_mul_f32 v[64:65], v[68:69], v[64:65]
	v_add_u32_e32 v68, 0x80, v152
	v_cvt_pk_bf16_f32 v74, v64, v65
	v_pk_mul_f32 v[64:65], v[70:71], v[76:77]
	s_nop 0
	v_pk_mul_f32 v[64:65], v[64:65], v[66:67]
	v_mul_f32_e32 v66, 0xbfb8aa3b, v62
	v_cvt_pk_bf16_f32 v75, v64, v65
	v_mad_i64_i32 v[64:65], s[14:15], v84, s91, v[144:145]
	global_store_dwordx4 v[64:65], v[72:75], off
	v_mul_f32_e32 v64, 0xbfb8aa3b, v60
	v_mul_f32_e32 v65, 0xbfb8aa3b, v61
	v_exp_f32_e32 v64, v64
	v_exp_f32_e32 v65, v65
	v_mul_f32_e32 v67, 0xbfb8aa3b, v63
	v_exp_f32_e32 v66, v66
	v_exp_f32_e32 v67, v67
	v_add_f32_e32 v64, 1.0, v64
	v_add_f32_e32 v65, 1.0, v65
	v_rcp_f32_e32 v64, v64
	v_rcp_f32_e32 v65, v65
	v_add_f32_e32 v66, 1.0, v66
	v_add_f32_e32 v67, 1.0, v67
	v_rcp_f32_e32 v66, v66
	v_rcp_f32_e32 v67, v67
	v_pk_mul_f32 v[60:61], v[60:61], v[64:65]
	s_nop 0
	v_pk_mul_f32 v[56:57], v[60:61], v[56:57]
	v_pk_mul_f32 v[60:61], v[62:63], v[66:67]
	v_cvt_pk_bf16_f32 v56, v56, v57
	v_mul_f32_e32 v57, 0xbfb8aa3b, v52
	v_pk_mul_f32 v[58:59], v[60:61], v[58:59]
	v_exp_f32_e32 v60, v57
	v_mul_f32_e32 v57, 0xbfb8aa3b, v53
	v_exp_f32_e32 v61, v57
	v_cvt_pk_bf16_f32 v57, v58, v59
; DI unsigned pk_bf16(float lo, float hi) { f32x2 v = {lo, hi}; return __builtin_bit_cast(unsigned, __builtin_convertvector(v, bf16v2)); }
; DI float fast_silu(float x) { return x * fast_sigmoid(x); }
; #define PG8_WAIT_V(n) asm volatile("s_waitcnt vmcnt(" #n ")" ::: "memory")
; #define PG8_BAR __builtin_amdgcn_s_barrier()
; #define PG8_WAIT_V(n) asm volatile("s_waitcnt vmcnt(" #n ")" ::: "memory")
; #define PG8_BAR __builtin_amdgcn_s_barrier()
; template <class Epi>
; DI void gemm_phase(LAS unsigned char* lds, const Gemm g, const StaticOrder S, const Epi E) {
;     ...
;         if (!has_next) break;
; #pragma unroll
;         for (int a = 0; a < 2; ++a)
; #pragma unroll
;             for (int b = 0; b < 2; ++b)
; #pragma unroll
;                 for (int m = 0; m < 4; ++m)
; #pragma unroll
;                     for (int n = 0; n < 2; ++n) acc[a][b][m][n] = (f32x4){0.f, 0.f, 0.f, 0.f};
;         cur = nxt; cA = nA; cB = nB; ++ui;
;     }
;     PG8_WAIT_V(0);
;     if (wr == 0) PG8_BAR;
;     PG8_BAR;
;     DI void operator()(AccRef acc, const Unit& u, int wr, int wc, int fr, int fq) const {
;     ...
; #pragma unroll
;         for (int ai = 0; ai < 2; ++ai)
; #pragma unroll
;             for (int m = 0; m < 4; ++m) {
;                 const int row = row0 + ai * 128 + m * 16;
;                 const float r = RS ? rsc.r[ai][m] : 1.0f;
;                 const f32x4 a0 = acc[ai][0][m][0] * r, a1 = acc[ai][0][m][1] * r, b0 = acc[ai][1][m][0] * r, b1 = acc[ai][1][m][1] * r;
;                 u32x4 w;
;                 w.x = pk_bf16(fast_silu(a0[0]) * b0[0], fast_silu(a0[1]) * b0[1]); w.y = pk_bf16(fast_silu(a0[2]) * b0[2], fast_silu(a0[3]) * b0[3]);
;                 w.z = pk_bf16(fast_silu(a1[0]) * b1[0], fast_silu(a1[1]) * b1[1]); w.w = pk_bf16(fast_silu(a1[2]) * b1[2], fast_silu(a1[3]) * b1[3]);
;                 *(u32x4*)(G + (size_t)row * DFF + col) = w;
	v_add_f32_e32 v58, 1.0, v60
	v_mul_f32_e32 v60, 0xbfb8aa3b, v54
	v_add_f32_e32 v59, 1.0, v61
	v_mul_f32_e32 v61, 0xbfb8aa3b, v55
	v_exp_f32_e32 v60, v60
	v_exp_f32_e32 v61, v61
	v_rcp_f32_e32 v58, v58
	v_rcp_f32_e32 v59, v59
	v_add_f32_e32 v60, 1.0, v60
	v_add_f32_e32 v61, 1.0, v61
	v_rcp_f32_e32 v60, v60
	v_rcp_f32_e32 v61, v61
	v_pk_mul_f32 v[52:53], v[52:53], v[58:59]
	s_nop 0
	v_pk_mul_f32 v[48:49], v[52:53], v[48:49]
	v_add_u32_e32 v52, 0x90, v152
	v_cvt_pk_bf16_f32 v58, v48, v49
	v_pk_mul_f32 v[48:49], v[54:55], v[60:61]
	s_nop 0
	v_pk_mul_f32 v[48:49], v[48:49], v[50:51]
	v_mul_f32_e32 v50, 0xbfb8aa3b, v46
	v_cvt_pk_bf16_f32 v59, v48, v49
	v_mad_i64_i32 v[48:49], s[14:15], v68, s91, v[144:145]
	global_store_dwordx4 v[48:49], v[56:59], off
	v_mul_f32_e32 v48, 0xbfb8aa3b, v44
	v_mul_f32_e32 v49, 0xbfb8aa3b, v45
	v_exp_f32_e32 v48, v48
	v_exp_f32_e32 v49, v49
	v_mul_f32_e32 v51, 0xbfb8aa3b, v47
	v_exp_f32_e32 v50, v50
	v_exp_f32_e32 v51, v51
	v_add_f32_e32 v48, 1.0, v48
	v_add_f32_e32 v49, 1.0, v49
	v_rcp_f32_e32 v48, v48
	v_rcp_f32_e32 v49, v49
	v_add_f32_e32 v50, 1.0, v50
	v_add_f32_e32 v51, 1.0, v51
	v_rcp_f32_e32 v50, v50
	v_rcp_f32_e32 v51, v51
	v_pk_mul_f32 v[44:45], v[44:45], v[48:49]
	s_nop 0
	v_pk_mul_f32 v[40:41], v[44:45], v[40:41]
	v_pk_mul_f32 v[44:45], v[46:47], v[50:51]
	v_cvt_pk_bf16_f32 v40, v40, v41
	v_mul_f32_e32 v41, 0xbfb8aa3b, v36
	v_pk_mul_f32 v[42:43], v[44:45], v[42:43]
	v_exp_f32_e32 v44, v41
	v_mul_f32_e32 v41, 0xbfb8aa3b, v37
	v_exp_f32_e32 v45, v41
	v_cvt_pk_bf16_f32 v41, v42, v43
	v_add_f32_e32 v42, 1.0, v44
	v_mul_f32_e32 v44, 0xbfb8aa3b, v38
	v_add_f32_e32 v43, 1.0, v45
	v_mul_f32_e32 v45, 0xbfb8aa3b, v39
	v_exp_f32_e32 v44, v44
	v_exp_f32_e32 v45, v45
	v_rcp_f32_e32 v42, v42
	v_rcp_f32_e32 v43, v43
	v_add_f32_e32 v44, 1.0, v44
	v_add_f32_e32 v45, 1.0, v45
	v_rcp_f32_e32 v44, v44
	v_rcp_f32_e32 v45, v45
	v_pk_mul_f32 v[36:37], v[36:37], v[42:43]
	s_nop 0
	v_pk_mul_f32 v[32:33], v[36:37], v[32:33]
	v_add_u32_e32 v36, 0xa0, v152
	v_cvt_pk_bf16_f32 v42, v32, v33
	v_pk_mul_f32 v[32:33], v[38:39], v[44:45]
	s_nop 0
	v_pk_mul_f32 v[32:33], v[32:33], v[34:35]
	v_mul_f32_e32 v34, 0xbfb8aa3b, v30
	v_cvt_pk_bf16_f32 v43, v32, v33
	v_mad_i64_i32 v[32:33], s[14:15], v52, s91, v[144:145]
	global_store_dwordx4 v[32:33], v[40:43], off
	v_mul_f32_e32 v32, 0xbfb8aa3b, v28
	v_mul_f32_e32 v33, 0xbfb8aa3b, v29
	v_exp_f32_e32 v32, v32
	v_exp_f32_e32 v33, v33
	v_mul_f32_e32 v35, 0xbfb8aa3b, v31
	v_exp_f32_e32 v34, v34
	v_exp_f32_e32 v35, v35
	v_add_f32_e32 v32, 1.0, v32
	v_add_f32_e32 v33, 1.0, v33
	v_rcp_f32_e32 v32, v32
	v_rcp_f32_e32 v33, v33
	v_add_f32_e32 v34, 1.0, v34
	v_add_f32_e32 v35, 1.0, v35
	v_rcp_f32_e32 v34, v34
	v_rcp_f32_e32 v35, v35
	v_pk_mul_f32 v[28:29], v[28:29], v[32:33]
	s_nop 0
	v_pk_mul_f32 v[24:25], v[28:29], v[24:25]
	v_pk_mul_f32 v[28:29], v[30:31], v[34:35]
	v_cvt_pk_bf16_f32 v24, v24, v25
	v_mul_f32_e32 v25, 0xbfb8aa3b, v20
	v_pk_mul_f32 v[26:27], v[28:29], v[26:27]
	v_exp_f32_e32 v28, v25
	v_mul_f32_e32 v25, 0xbfb8aa3b, v21
	v_exp_f32_e32 v29, v25
	v_cvt_pk_bf16_f32 v25, v26, v27
	v_add_f32_e32 v26, 1.0, v28
	v_mul_f32_e32 v28, 0xbfb8aa3b, v22
	v_add_f32_e32 v27, 1.0, v29
	v_mul_f32_e32 v29, 0xbfb8aa3b, v23
	v_exp_f32_e32 v28, v28
	v_exp_f32_e32 v29, v29
	v_rcp_f32_e32 v26, v26
	v_rcp_f32_e32 v27, v27
	v_add_f32_e32 v28, 1.0, v28
	v_add_f32_e32 v29, 1.0, v29
	v_rcp_f32_e32 v28, v28
	v_rcp_f32_e32 v29, v29
	v_pk_mul_f32 v[20:21], v[20:21], v[26:27]
	s_nop 0
	v_pk_mul_f32 v[16:17], v[20:21], v[16:17]
	v_add_u32_e32 v20, 0xb0, v152
	v_cvt_pk_bf16_f32 v26, v16, v17
	v_pk_mul_f32 v[16:17], v[22:23], v[28:29]
	s_nop 0
	v_pk_mul_f32 v[16:17], v[16:17], v[18:19]
	v_mul_f32_e32 v18, 0xbfb8aa3b, v14
	v_cvt_pk_bf16_f32 v27, v16, v17
	v_mad_i64_i32 v[16:17], s[14:15], v36, s91, v[144:145]
	global_store_dwordx4 v[16:17], v[24:27], off
	v_mul_f32_e32 v16, 0xbfb8aa3b, v12
	v_mul_f32_e32 v17, 0xbfb8aa3b, v13
	v_exp_f32_e32 v16, v16
	v_exp_f32_e32 v17, v17
	v_mul_f32_e32 v19, 0xbfb8aa3b, v15
	v_exp_f32_e32 v18, v18
	v_exp_f32_e32 v19, v19
	v_add_f32_e32 v16, 1.0, v16
	v_add_f32_e32 v17, 1.0, v17
	v_rcp_f32_e32 v16, v16
	v_rcp_f32_e32 v17, v17
	v_add_f32_e32 v18, 1.0, v18
	v_add_f32_e32 v19, 1.0, v19
	v_rcp_f32_e32 v18, v18
	v_rcp_f32_e32 v19, v19
	v_pk_mul_f32 v[12:13], v[12:13], v[16:17]
	s_nop 0
	v_pk_mul_f32 v[8:9], v[12:13], v[8:9]
	v_pk_mul_f32 v[12:13], v[14:15], v[18:19]
	v_cvt_pk_bf16_f32 v8, v8, v9
	v_mul_f32_e32 v9, 0xbfb8aa3b, v4
	v_pk_mul_f32 v[10:11], v[12:13], v[10:11]
	v_exp_f32_e32 v12, v9
	v_mul_f32_e32 v9, 0xbfb8aa3b, v5
	v_exp_f32_e32 v13, v9
	v_cvt_pk_bf16_f32 v9, v10, v11
	v_add_f32_e32 v10, 1.0, v12
	v_mul_f32_e32 v12, 0xbfb8aa3b, v6
	v_add_f32_e32 v11, 1.0, v13
	v_mul_f32_e32 v13, 0xbfb8aa3b, v7
	v_exp_f32_e32 v12, v12
	v_exp_f32_e32 v13, v13
	v_rcp_f32_e32 v10, v10
	v_rcp_f32_e32 v11, v11
	v_add_f32_e32 v12, 1.0, v12
	v_add_f32_e32 v13, 1.0, v13
	v_rcp_f32_e32 v12, v12
	v_rcp_f32_e32 v13, v13
	v_pk_mul_f32 v[4:5], v[4:5], v[10:11]
	s_nop 0
	v_pk_mul_f32 v[0:1], v[4:5], v[0:1]
	s_nop 0
	v_cvt_pk_bf16_f32 v10, v0, v1
	v_pk_mul_f32 v[0:1], v[6:7], v[12:13]
	s_nop 0
	v_pk_mul_f32 v[0:1], v[0:1], v[2:3]
	s_nop 0
	v_cvt_pk_bf16_f32 v11, v0, v1
	v_mad_i64_i32 v[0:1], s[14:15], v20, s91, v[144:145]
	global_store_dwordx4 v[0:1], v[8:11], off
	s_cbranch_vccz .LBB0_104
	s_waitcnt vmcnt(0)
	v_readlane_b32 s92, v243, 8
	s_cmpk_gt_u32 s6, 0xff
	v_readlane_b32 s93, v243, 9
	s_cbranch_scc1 .LBB0_111
	s_barrier

; #define PG8_STAGE(bufoff, gbase, voff) do { _Pragma("unroll") for (int _i = 0; _i < 2; ++_i) \
;         __builtin_amdgcn_global_load_lds((const unsigned*)((const char*)(gbase) + (voff)[_i]), (LAS unsigned*)(lds + (bufoff) + ldsw + _i * 8192), 16, 0, 0); } while (0)
; #define PG8_LDA(dst, b, h) do { _Pragma("unroll") for (int m = 0; m < 4; ++m) _Pragma("unroll") for (int k = 0; k < 2; ++k) dst[m][k] = *(const LAS bf16x8*)(lds + PG8_SA(b, h) + aoff + m * 2048 + k * 1024); } while (0)
; #define PG8_LDB(dst, b, h) do { _Pragma("unroll") for (int n = 0; n < 2; ++n) _Pragma("unroll") for (int k = 0; k < 2; ++k) dst[n][k] = *(const LAS bf16x8*)(lds + PG8_SB(b, h) + boff + n * 2048 + k * 1024); } while (0)
; #define PG8_MMA(ai, bj, At, Bt) do { __builtin_amdgcn_s_setprio(1); _Pragma("unroll") for (int m = 0; m < 4; ++m) _Pragma("unroll") for (int n = 0; n < 2; ++n) _Pragma("unroll") for (int k = 0; k < 2; ++k) \
;         acc[ai][bj][m][n] = __builtin_amdgcn_mfma_f32_16x16x32_bf16(Bt[n][k], At[m][k], acc[ai][bj][m][n], 0, 0, 0); __builtin_amdgcn_s_setprio(0); } while (0)
; template <class Epi>
; DI void gemm_phase(LAS unsigned char* lds, const Gemm g, const StaticOrder S, const Epi E) {
;     ...
;         for (int t = 0; t < nt; t += 2) {
;             const bool last = (t == nt - 2);
;             const char* a1 = cA + (size_t)(t + 1) * kstep;
;             const char* a2 = last ? nA : cA + (size_t)(t + 2) * kstep; const char* b2 = last ? nB : cB + (size_t)(t + 2) * kstep;
;             const char* a3 = a2 + kstep; const char* b3 = b2 + kstep;
;             PG8_LDB(B0, 0, 0); PG8_SCHED; PG8_LDA(At, 0, 0); PG8_STAGE(PG8_SA(1, 1), a1 + hstep, voffA);
;             PG8_WAIT_L(8); PG8_BAR; PG8_WAIT_L(0); PG8_MMA(0, 0, At, B0); PG8_BAR; PG8_SCHED;
;             PG8_LDB(B1, 0, 1); PG8_STAGE(PG8_SB(0, 0), b2, voffB);
;             PG8_BAR; PG8_WAIT_L(0); PG8_MMA(0, 1, At, B1); PG8_BAR;
;             PG8_LDA(At, 0, 1); PG8_STAGE(PG8_SA(0, 0), a2, voffA);
;             PG8_BAR; PG8_WAIT_L(0); PG8_MMA(1, 0, At, B0); PG8_BAR; PG8_SCHED;
;             PG8_STAGE(PG8_SB(0, 1), b2 + hstep, voffB);
;             PG8_WAIT_V(6); PG8_BAR; PG8_MMA(1, 1, At, B1); PG8_BAR;
;             PG8_LDB(B0, 1, 0); PG8_SCHED; PG8_LDA(At, 1, 0); PG8_STAGE(PG8_SA(0, 1), a2 + hstep, voffA);
;             PG8_WAIT_L(8); PG8_BAR; PG8_WAIT_L(0); PG8_MMA(0, 0, At, B0); PG8_BAR; PG8_SCHED;
.LBB0_186:
	ds_read_b128 v[128:131], v207
	ds_read_b128 v[132:135], v207 offset:1024
	ds_read_b128 v[136:139], v207 offset:2048
	ds_read_b128 v[140:143], v207 offset:3072
	s_add_u32 s76, s28, 0x100
	s_addc_u32 s77, s29, 0
	s_cmp_eq_u32 s97, 40
	s_cselect_b32 s81, s9, s77
	s_cselect_b32 s80, s8, s76
	s_cselect_b32 s79, s11, s7
	s_cselect_b32 s78, s10, s6
	v_lshl_add_u64 v[192:193], s[28:29], 0, v[184:185]
	s_add_i32 m0, s82, 0xc000
	ds_read_b128 v[144:147], v208
	ds_read_b128 v[152:155], v208 offset:2048
	ds_read_b128 v[160:163], v208 offset:4096
	ds_read_b128 v[168:171], v208 offset:6144
	global_load_lds_dwordx4 v[192:193], off
	v_lshl_add_u64 v[192:193], s[28:29], 0, v[186:187]
	s_add_i32 m0, s82, 0xe000
	s_nop 0
	global_load_lds_dwordx4 v[192:193], off
	s_waitcnt lgkmcnt(4)
	s_setprio 1
	s_barrier
	ds_read_b128 v[148:151], v208 offset:1024
	ds_read_b128 v[156:159], v208 offset:3072
	ds_read_b128 v[164:167], v208 offset:5120
	ds_read_b128 v[172:175], v208 offset:7168
	s_waitcnt lgkmcnt(4)
	v_mfma_f32_16x16x32_bf16 v[124:127], v[128:131], v[144:147], v[124:127]
	v_mfma_f32_16x16x32_bf16 v[120:123], v[136:139], v[144:147], v[120:123]
	v_mfma_f32_16x16x32_bf16 v[108:111], v[128:131], v[152:155], v[108:111]
	v_mfma_f32_16x16x32_bf16 v[104:107], v[136:139], v[152:155], v[104:107]
	v_mfma_f32_16x16x32_bf16 v[92:95], v[128:131], v[160:163], v[92:95]
	v_mfma_f32_16x16x32_bf16 v[88:91], v[136:139], v[160:163], v[88:91]
	v_mfma_f32_16x16x32_bf16 v[76:79], v[128:131], v[168:171], v[76:79]
	v_mfma_f32_16x16x32_bf16 v[72:75], v[136:139], v[168:171], v[72:75]
	s_waitcnt lgkmcnt(3)
	v_mfma_f32_16x16x32_bf16 v[124:127], v[132:135], v[148:151], v[124:127]
	v_mfma_f32_16x16x32_bf16 v[120:123], v[140:143], v[148:151], v[120:123]
	s_waitcnt lgkmcnt(2)
	v_mfma_f32_16x16x32_bf16 v[108:111], v[132:135], v[156:159], v[108:111]
	v_mfma_f32_16x16x32_bf16 v[104:107], v[140:143], v[156:159], v[104:107]
	s_waitcnt lgkmcnt(1)
	v_mfma_f32_16x16x32_bf16 v[92:95], v[132:135], v[164:167], v[92:95]
	v_mfma_f32_16x16x32_bf16 v[88:91], v[140:143], v[164:167], v[88:91]
	s_waitcnt lgkmcnt(0)
	s_setprio 2
	s_barrier
	v_mfma_f32_16x16x32_bf16 v[76:79], v[132:135], v[172:175], v[76:79]
	v_mfma_f32_16x16x32_bf16 v[72:75], v[140:143], v[172:175], v[72:75]
	s_setprio 0
	s_add_i32 s14, s91, s59
	v_lshl_add_u64 v[216:217], s[78:79], 0, v[178:179]
	s_mov_b32 m0, s14
	ds_read_b128 v[192:195], v209
	ds_read_b128 v[196:199], v209 offset:1024
	ds_read_b128 v[200:203], v209 offset:2048
	ds_read_b128 v[212:215], v209 offset:3072
	global_load_lds_dwordx4 v[216:217], off
	v_lshl_add_u64 v[218:219], s[78:79], 0, v[182:183]
	s_add_i32 m0, s14, 0x2000
	s_nop 0
	global_load_lds_dwordx4 v[218:219], off
	s_setprio 1
	s_barrier
	s_waitcnt lgkmcnt(0)
	v_mfma_f32_16x16x32_bf16 v[116:119], v[192:195], v[144:147], v[116:119]
	v_mfma_f32_16x16x32_bf16 v[112:115], v[200:203], v[144:147], v[112:115]
	v_mfma_f32_16x16x32_bf16 v[100:103], v[192:195], v[152:155], v[100:103]
	v_mfma_f32_16x16x32_bf16 v[96:99], v[200:203], v[152:155], v[96:99]
	v_mfma_f32_16x16x32_bf16 v[84:87], v[192:195], v[160:163], v[84:87]
	v_mfma_f32_16x16x32_bf16 v[80:83], v[200:203], v[160:163], v[80:83]
	v_mfma_f32_16x16x32_bf16 v[68:71], v[192:195], v[168:171], v[68:71]
	v_mfma_f32_16x16x32_bf16 v[64:67], v[200:203], v[168:171], v[64:67]
	v_mfma_f32_16x16x32_bf16 v[116:119], v[196:199], v[148:151], v[116:119]
	v_mfma_f32_16x16x32_bf16 v[112:115], v[212:215], v[148:151], v[112:115]
	v_mfma_f32_16x16x32_bf16 v[100:103], v[196:199], v[156:159], v[100:103]
	v_mfma_f32_16x16x32_bf16 v[96:99], v[212:215], v[156:159], v[96:99]
	v_mfma_f32_16x16x32_bf16 v[84:87], v[196:199], v[164:167], v[84:87]
	v_mfma_f32_16x16x32_bf16 v[80:83], v[212:215], v[164:167], v[80:83]
	s_setprio 2
	s_barrier
	v_mfma_f32_16x16x32_bf16 v[68:71], v[196:199], v[172:175], v[68:71]
	v_mfma_f32_16x16x32_bf16 v[64:67], v[212:215], v[172:175], v[64:67]
	s_setprio 0
	s_mov_b32 m0, s82
	v_lshl_add_u64 v[220:221], s[80:81], 0, v[176:177]
	ds_read_b128 v[144:147], v208 offset:16384
	ds_read_b128 v[152:155], v208 offset:18432
	ds_read_b128 v[160:163], v208 offset:20480
	ds_read_b128 v[168:171], v208 offset:22528
	global_load_lds_dwordx4 v[220:221], off
	v_lshl_add_u64 v[224:225], s[80:81], 0, v[180:181]
	s_mov_b32 m0, s83
	s_nop 0
	global_load_lds_dwordx4 v[224:225], off
	s_setprio 1
	s_barrier
	ds_read_b128 v[148:151], v208 offset:17408
	ds_read_b128 v[156:159], v208 offset:19456
	ds_read_b128 v[164:167], v208 offset:21504
	ds_read_b128 v[172:175], v208 offset:23552
	s_waitcnt lgkmcnt(4)
	v_mfma_f32_16x16x32_bf16 v[60:63], v[128:131], v[144:147], v[60:63]
	v_mfma_f32_16x16x32_bf16 v[56:59], v[136:139], v[144:147], v[56:59]
	v_mfma_f32_16x16x32_bf16 v[44:47], v[128:131], v[152:155], v[44:47]
	v_mfma_f32_16x16x32_bf16 v[40:43], v[136:139], v[152:155], v[40:43]
	v_mfma_f32_16x16x32_bf16 v[28:31], v[128:131], v[160:163], v[28:31]
	v_mfma_f32_16x16x32_bf16 v[24:27], v[136:139], v[160:163], v[24:27]
	v_mfma_f32_16x16x32_bf16 v[12:15], v[128:131], v[168:171], v[12:15]
	v_mfma_f32_16x16x32_bf16 v[8:11], v[136:139], v[168:171], v[8:11]
	s_waitcnt lgkmcnt(3)
	v_mfma_f32_16x16x32_bf16 v[60:63], v[132:135], v[148:151], v[60:63]
	v_mfma_f32_16x16x32_bf16 v[56:59], v[140:143], v[148:151], v[56:59]
	s_waitcnt lgkmcnt(2)
	v_mfma_f32_16x16x32_bf16 v[44:47], v[132:135], v[156:159], v[44:47]
	v_mfma_f32_16x16x32_bf16 v[40:43], v[140:143], v[156:159], v[40:43]
	s_waitcnt lgkmcnt(1)
	v_mfma_f32_16x16x32_bf16 v[28:31], v[132:135], v[164:167], v[28:31]
	v_mfma_f32_16x16x32_bf16 v[24:27], v[140:143], v[164:167], v[24:27]
	s_waitcnt lgkmcnt(0)
	s_setprio 2
	s_barrier
; #define PG8_STAGE(bufoff, gbase, voff) do { _Pragma("unroll") for (int _i = 0; _i < 2; ++_i) \
;         __builtin_amdgcn_global_load_lds((const unsigned*)((const char*)(gbase) + (voff)[_i]), (LAS unsigned*)(lds + (bufoff) + ldsw + _i * 8192), 16, 0, 0); } while (0)
; #define PG8_LDA(dst, b, h) do { _Pragma("unroll") for (int m = 0; m < 4; ++m) _Pragma("unroll") for (int k = 0; k < 2; ++k) dst[m][k] = *(const LAS bf16x8*)(lds + PG8_SA(b, h) + aoff + m * 2048 + k * 1024); } while (0)
; #define PG8_LDB(dst, b, h) do { _Pragma("unroll") for (int n = 0; n < 2; ++n) _Pragma("unroll") for (int k = 0; k < 2; ++k) dst[n][k] = *(const LAS bf16x8*)(lds + PG8_SB(b, h) + boff + n * 2048 + k * 1024); } while (0)
; #define PG8_MMA(ai, bj, At, Bt) do { __builtin_amdgcn_s_setprio(1); _Pragma("unroll") for (int m = 0; m < 4; ++m) _Pragma("unroll") for (int n = 0; n < 2; ++n) _Pragma("unroll") for (int k = 0; k < 2; ++k) \
;         acc[ai][bj][m][n] = __builtin_amdgcn_mfma_f32_16x16x32_bf16(Bt[n][k], At[m][k], acc[ai][bj][m][n], 0, 0, 0); __builtin_amdgcn_s_setprio(0); } while (0)
; #define PG8_WAIT_V(n) asm volatile("s_waitcnt vmcnt(" #n ")" ::: "memory")
; #define PG8_WAIT_L(n) asm volatile("s_waitcnt lgkmcnt(" #n ")" ::: "memory")
; #define PG8_BAR __builtin_amdgcn_s_barrier()
; #define PG8_SCHED __builtin_amdgcn_sched_barrier(0)
; #define PG8_WAIT_V(n) asm volatile("s_waitcnt vmcnt(" #n ")" ::: "memory")
; #define PG8_WAIT_L(n) asm volatile("s_waitcnt lgkmcnt(" #n ")" ::: "memory")
; template <class Epi>
; DI void gemm_phase(LAS unsigned char* lds, const Gemm g, const StaticOrder S, const Epi E) {
;     ...
;             PG8_STAGE(PG8_SB(0, 1), b2 + hstep, voffB);
;             PG8_WAIT_V(6); PG8_BAR; PG8_MMA(1, 1, At, B1); PG8_BAR;
;             PG8_LDB(B0, 1, 0); PG8_SCHED; PG8_LDA(At, 1, 0); PG8_STAGE(PG8_SA(0, 1), a2 + hstep, voffA);
;             PG8_WAIT_L(8); PG8_BAR; PG8_WAIT_L(0); PG8_MMA(0, 0, At, B0); PG8_BAR; PG8_SCHED;
;             PG8_LDB(B1, 1, 1); PG8_STAGE(PG8_SB(1, 0), b3, voffB);
;             PG8_BAR; PG8_WAIT_L(0); PG8_MMA(0, 1, At, B1); PG8_BAR;
;             PG8_LDA(At, 1, 1); PG8_STAGE(PG8_SA(1, 0), a3, voffA);
;             PG8_BAR; PG8_WAIT_L(0); PG8_MMA(1, 0, At, B0); PG8_BAR; PG8_SCHED;
;             PG8_STAGE(PG8_SB(1, 1), b3 + hstep, voffB);
;             PG8_WAIT_V(6); PG8_BAR; PG8_MMA(1, 1, At, B1); PG8_BAR;
	v_mfma_f32_16x16x32_bf16 v[12:15], v[132:135], v[172:175], v[12:15]
	v_mfma_f32_16x16x32_bf16 v[8:11], v[140:143], v[172:175], v[8:11]
	s_setprio 0
	s_add_u32 s14, s78, 0xb0000
	s_addc_u32 s15, s79, 0
	s_add_i32 s28, s92, s59
	v_lshl_add_u64 v[128:129], s[14:15], 0, v[178:179]
	s_mov_b32 m0, s28
	s_nop 0
	global_load_lds_dwordx4 v[128:129], off
	v_lshl_add_u64 v[128:129], s[14:15], 0, v[182:183]
	s_add_i32 m0, s28, 0x2000
	s_nop 0
	global_load_lds_dwordx4 v[128:129], off
	s_waitcnt vmcnt(6)
	s_setprio 1
	s_barrier
	v_mfma_f32_16x16x32_bf16 v[52:55], v[192:195], v[144:147], v[52:55]
	v_mfma_f32_16x16x32_bf16 v[48:51], v[200:203], v[144:147], v[48:51]
	v_mfma_f32_16x16x32_bf16 v[36:39], v[192:195], v[152:155], v[36:39]
	v_mfma_f32_16x16x32_bf16 v[32:35], v[200:203], v[152:155], v[32:35]
	v_mfma_f32_16x16x32_bf16 v[20:23], v[192:195], v[160:163], v[20:23]
	v_mfma_f32_16x16x32_bf16 v[16:19], v[200:203], v[160:163], v[16:19]
	v_mfma_f32_16x16x32_bf16 v[4:7], v[192:195], v[168:171], v[4:7]
	v_mfma_f32_16x16x32_bf16 v[0:3], v[200:203], v[168:171], v[0:3]
	v_mfma_f32_16x16x32_bf16 v[52:55], v[196:199], v[148:151], v[52:55]
	v_mfma_f32_16x16x32_bf16 v[48:51], v[212:215], v[148:151], v[48:51]
	v_mfma_f32_16x16x32_bf16 v[36:39], v[196:199], v[156:159], v[36:39]
	v_mfma_f32_16x16x32_bf16 v[32:35], v[212:215], v[156:159], v[32:35]
	v_mfma_f32_16x16x32_bf16 v[20:23], v[196:199], v[164:167], v[20:23]
	v_mfma_f32_16x16x32_bf16 v[16:19], v[212:215], v[164:167], v[16:19]
	s_setprio 2
	s_barrier
	v_mfma_f32_16x16x32_bf16 v[4:7], v[196:199], v[172:175], v[4:7]
	v_mfma_f32_16x16x32_bf16 v[0:3], v[212:215], v[172:175], v[0:3]
	s_setprio 0
	s_add_i32 s28, 0, 0x18000
	v_add_u32_e32 v140, s28, v205
	ds_read_b128 v[128:131], v140
	ds_read_b128 v[132:135], v140 offset:1024
	ds_read_b128 v[136:139], v140 offset:2048
	ds_read_b128 v[140:143], v140 offset:3072
	s_add_u32 s14, s80, 0xb0000
	s_addc_u32 s15, s81, 0
	s_mov_b32 m0, s84
	v_lshl_add_u64 v[192:193], s[14:15], 0, v[176:177]
	ds_read_b128 v[144:147], v208 offset:32768
	ds_read_b128 v[152:155], v208 offset:34816
	ds_read_b128 v[160:163], v208 offset:36864
	ds_read_b128 v[168:171], v208 offset:38912
	global_load_lds_dwordx4 v[192:193], off
	v_lshl_add_u64 v[192:193], s[14:15], 0, v[180:181]
	s_mov_b32 m0, s85
	s_nop 0
	global_load_lds_dwordx4 v[192:193], off
	s_waitcnt lgkmcnt(4)
	s_setprio 1
	s_barrier
	ds_read_b128 v[148:151], v208 offset:33792
	ds_read_b128 v[156:159], v208 offset:35840
	ds_read_b128 v[164:167], v208 offset:37888
	ds_read_b128 v[172:175], v208 offset:39936
	s_waitcnt lgkmcnt(4)
	v_mfma_f32_16x16x32_bf16 v[124:127], v[128:131], v[144:147], v[124:127]
	v_mfma_f32_16x16x32_bf16 v[120:123], v[136:139], v[144:147], v[120:123]
	v_mfma_f32_16x16x32_bf16 v[108:111], v[128:131], v[152:155], v[108:111]
	v_mfma_f32_16x16x32_bf16 v[104:107], v[136:139], v[152:155], v[104:107]
	v_mfma_f32_16x16x32_bf16 v[92:95], v[128:131], v[160:163], v[92:95]
	v_mfma_f32_16x16x32_bf16 v[88:91], v[136:139], v[160:163], v[88:91]
	v_mfma_f32_16x16x32_bf16 v[76:79], v[128:131], v[168:171], v[76:79]
	v_mfma_f32_16x16x32_bf16 v[72:75], v[136:139], v[168:171], v[72:75]
	s_waitcnt lgkmcnt(3)
	v_mfma_f32_16x16x32_bf16 v[124:127], v[132:135], v[148:151], v[124:127]
	v_mfma_f32_16x16x32_bf16 v[120:123], v[140:143], v[148:151], v[120:123]
	s_waitcnt lgkmcnt(2)
	v_mfma_f32_16x16x32_bf16 v[108:111], v[132:135], v[156:159], v[108:111]
	v_mfma_f32_16x16x32_bf16 v[104:107], v[140:143], v[156:159], v[104:107]
	s_waitcnt lgkmcnt(1)
	v_mfma_f32_16x16x32_bf16 v[92:95], v[132:135], v[164:167], v[92:95]
	v_mfma_f32_16x16x32_bf16 v[88:91], v[140:143], v[164:167], v[88:91]
	s_waitcnt lgkmcnt(0)
	s_setprio 2
	s_barrier
	v_mfma_f32_16x16x32_bf16 v[76:79], v[132:135], v[172:175], v[76:79]
	v_mfma_f32_16x16x32_bf16 v[72:75], v[140:143], v[172:175], v[72:75]
	s_setprio 0
	s_add_i32 s29, 0, 0x1c000
	s_add_i32 s14, s28, s59
	v_add_u32_e32 v211, s29, v205
	v_lshl_add_u64 v[216:217], v[216:217], 0, s[24:25]
	s_mov_b32 m0, s14
	ds_read_b128 v[192:195], v211
	ds_read_b128 v[196:199], v211 offset:1024
	ds_read_b128 v[200:203], v211 offset:2048
	ds_read_b128 v[212:215], v211 offset:3072
	global_load_lds_dwordx4 v[216:217], off
	v_lshl_add_u64 v[216:217], v[218:219], 0, s[24:25]
	s_add_i32 m0, s14, 0x2000
	s_nop 0
	global_load_lds_dwordx4 v[216:217], off
	s_setprio 1
	s_barrier
	s_waitcnt lgkmcnt(0)
	v_mfma_f32_16x16x32_bf16 v[116:119], v[192:195], v[144:147], v[116:119]
	v_mfma_f32_16x16x32_bf16 v[112:115], v[200:203], v[144:147], v[112:115]
	v_mfma_f32_16x16x32_bf16 v[100:103], v[192:195], v[152:155], v[100:103]
	v_mfma_f32_16x16x32_bf16 v[96:99], v[200:203], v[152:155], v[96:99]
	v_mfma_f32_16x16x32_bf16 v[84:87], v[192:195], v[160:163], v[84:87]
	v_mfma_f32_16x16x32_bf16 v[80:83], v[200:203], v[160:163], v[80:83]
	v_mfma_f32_16x16x32_bf16 v[68:71], v[192:195], v[168:171], v[68:71]
	v_mfma_f32_16x16x32_bf16 v[64:67], v[200:203], v[168:171], v[64:67]
	v_mfma_f32_16x16x32_bf16 v[116:119], v[196:199], v[148:151], v[116:119]
	v_mfma_f32_16x16x32_bf16 v[112:115], v[212:215], v[148:151], v[112:115]
	v_mfma_f32_16x16x32_bf16 v[100:103], v[196:199], v[156:159], v[100:103]
	v_mfma_f32_16x16x32_bf16 v[96:99], v[212:215], v[156:159], v[96:99]
	v_mfma_f32_16x16x32_bf16 v[84:87], v[196:199], v[164:167], v[84:87]
	v_mfma_f32_16x16x32_bf16 v[80:83], v[212:215], v[164:167], v[80:83]
	s_setprio 2
	s_barrier
; #define PG8_STAGE(bufoff, gbase, voff) do { _Pragma("unroll") for (int _i = 0; _i < 2; ++_i) \
;         __builtin_amdgcn_global_load_lds((const unsigned*)((const char*)(gbase) + (voff)[_i]), (LAS unsigned*)(lds + (bufoff) + ldsw + _i * 8192), 16, 0, 0); } while (0)
; #define PG8_LDA(dst, b, h) do { _Pragma("unroll") for (int m = 0; m < 4; ++m) _Pragma("unroll") for (int k = 0; k < 2; ++k) dst[m][k] = *(const LAS bf16x8*)(lds + PG8_SA(b, h) + aoff + m * 2048 + k * 1024); } while (0)
; #define PG8_LDB(dst, b, h) do { _Pragma("unroll") for (int n = 0; n < 2; ++n) _Pragma("unroll") for (int k = 0; k < 2; ++k) dst[n][k] = *(const LAS bf16x8*)(lds + PG8_SB(b, h) + boff + n * 2048 + k * 1024); } while (0)
; #define PG8_MMA(ai, bj, At, Bt) do { __builtin_amdgcn_s_setprio(1); _Pragma("unroll") for (int m = 0; m < 4; ++m) _Pragma("unroll") for (int n = 0; n < 2; ++n) _Pragma("unroll") for (int k = 0; k < 2; ++k) \
;         acc[ai][bj][m][n] = __builtin_amdgcn_mfma_f32_16x16x32_bf16(Bt[n][k], At[m][k], acc[ai][bj][m][n], 0, 0, 0); __builtin_amdgcn_s_setprio(0); } while (0)
; #define PG8_WAIT_V(n) asm volatile("s_waitcnt vmcnt(" #n ")" ::: "memory")
; #define PG8_WAIT_L(n) asm volatile("s_waitcnt lgkmcnt(" #n ")" ::: "memory")
; #define PG8_BAR __builtin_amdgcn_s_barrier()
; #define PG8_SCHED __builtin_amdgcn_sched_barrier(0)
; #define PG8_STAGE(bufoff, gbase, voff) do { _Pragma("unroll") for (int _i = 0; _i < 2; ++_i) \
;         __builtin_amdgcn_global_load_lds((const unsigned*)((const char*)(gbase) + (voff)[_i]), (LAS unsigned*)(lds + (bufoff) + ldsw + _i * 8192), 16, 0, 0); } while (0)
; #define PG8_WAIT_V(n) asm volatile("s_waitcnt vmcnt(" #n ")" ::: "memory")
; #define PG8_WAIT_L(n) asm volatile("s_waitcnt lgkmcnt(" #n ")" ::: "memory")
; template <class Epi>
; DI void gemm_phase(LAS unsigned char* lds, const Gemm g, const StaticOrder S, const Epi E) {
;     ...
;             PG8_WAIT_L(8); PG8_BAR; PG8_WAIT_L(0); PG8_MMA(0, 0, At, B0); PG8_BAR; PG8_SCHED;
;             PG8_LDB(B1, 1, 1); PG8_STAGE(PG8_SB(1, 0), b3, voffB);
;             PG8_BAR; PG8_WAIT_L(0); PG8_MMA(0, 1, At, B1); PG8_BAR;
;             PG8_LDA(At, 1, 1); PG8_STAGE(PG8_SA(1, 0), a3, voffA);
;             PG8_BAR; PG8_WAIT_L(0); PG8_MMA(1, 0, At, B0); PG8_BAR; PG8_SCHED;
;             PG8_STAGE(PG8_SB(1, 1), b3 + hstep, voffB);
;             PG8_WAIT_V(6); PG8_BAR; PG8_MMA(1, 1, At, B1); PG8_BAR;
	v_mfma_f32_16x16x32_bf16 v[68:71], v[196:199], v[172:175], v[68:71]
	v_mfma_f32_16x16x32_bf16 v[64:67], v[212:215], v[172:175], v[64:67]
	s_setprio 0
	s_mov_b32 m0, s87
	v_lshl_add_u64 v[216:217], v[220:221], 0, s[24:25]
	ds_read_b128 v[144:147], v208 offset:49152
	ds_read_b128 v[152:155], v208 offset:51200
	ds_read_b128 v[160:163], v208 offset:53248
	ds_read_b128 v[168:171], v208 offset:55296
	global_load_lds_dwordx4 v[216:217], off
	v_lshl_add_u64 v[216:217], v[224:225], 0, s[24:25]
	s_mov_b32 m0, s88
	s_nop 0
	global_load_lds_dwordx4 v[216:217], off
	s_setprio 1
	s_barrier
	ds_read_b128 v[148:151], v208 offset:50176
	ds_read_b128 v[156:159], v208 offset:52224
	ds_read_b128 v[164:167], v208 offset:54272
	ds_read_b128 v[172:175], v208 offset:56320
	s_waitcnt lgkmcnt(4)
	v_mfma_f32_16x16x32_bf16 v[60:63], v[128:131], v[144:147], v[60:63]
	v_mfma_f32_16x16x32_bf16 v[56:59], v[136:139], v[144:147], v[56:59]
	v_mfma_f32_16x16x32_bf16 v[44:47], v[128:131], v[152:155], v[44:47]
	v_mfma_f32_16x16x32_bf16 v[40:43], v[136:139], v[152:155], v[40:43]
	v_mfma_f32_16x16x32_bf16 v[28:31], v[128:131], v[160:163], v[28:31]
	v_mfma_f32_16x16x32_bf16 v[24:27], v[136:139], v[160:163], v[24:27]
	v_mfma_f32_16x16x32_bf16 v[12:15], v[128:131], v[168:171], v[12:15]
	v_mfma_f32_16x16x32_bf16 v[8:11], v[136:139], v[168:171], v[8:11]
	s_waitcnt lgkmcnt(3)
	v_mfma_f32_16x16x32_bf16 v[60:63], v[132:135], v[148:151], v[60:63]
	v_mfma_f32_16x16x32_bf16 v[56:59], v[140:143], v[148:151], v[56:59]
	s_waitcnt lgkmcnt(2)
	v_mfma_f32_16x16x32_bf16 v[44:47], v[132:135], v[156:159], v[44:47]
	v_mfma_f32_16x16x32_bf16 v[40:43], v[140:143], v[156:159], v[40:43]
	s_waitcnt lgkmcnt(1)
	v_mfma_f32_16x16x32_bf16 v[28:31], v[132:135], v[164:167], v[28:31]
	v_mfma_f32_16x16x32_bf16 v[24:27], v[140:143], v[164:167], v[24:27]
	s_waitcnt lgkmcnt(0)
	s_setprio 2
	s_barrier
	v_mfma_f32_16x16x32_bf16 v[12:15], v[132:135], v[172:175], v[12:15]
	v_mfma_f32_16x16x32_bf16 v[8:11], v[140:143], v[172:175], v[8:11]
	s_setprio 0
	s_add_u32 s14, s78, 0xb0080
	s_addc_u32 s15, s79, 0
	s_add_i32 s28, s29, s59
	v_lshl_add_u64 v[128:129], s[14:15], 0, v[178:179]
	s_mov_b32 m0, s28
	s_nop 0
	global_load_lds_dwordx4 v[128:129], off
	v_lshl_add_u64 v[128:129], s[14:15], 0, v[182:183]
	s_add_i32 m0, s28, 0x2000
	s_nop 0
	global_load_lds_dwordx4 v[128:129], off
	s_waitcnt vmcnt(6)
	s_setprio 1
	s_barrier
	v_mfma_f32_16x16x32_bf16 v[52:55], v[192:195], v[144:147], v[52:55]
	v_mfma_f32_16x16x32_bf16 v[48:51], v[200:203], v[144:147], v[48:51]
	v_mfma_f32_16x16x32_bf16 v[36:39], v[192:195], v[152:155], v[36:39]
	v_mfma_f32_16x16x32_bf16 v[32:35], v[200:203], v[152:155], v[32:35]
	v_mfma_f32_16x16x32_bf16 v[20:23], v[192:195], v[160:163], v[20:23]
	v_mfma_f32_16x16x32_bf16 v[16:19], v[200:203], v[160:163], v[16:19]
	v_mfma_f32_16x16x32_bf16 v[4:7], v[192:195], v[168:171], v[4:7]
	v_mfma_f32_16x16x32_bf16 v[0:3], v[200:203], v[168:171], v[0:3]
	v_mfma_f32_16x16x32_bf16 v[52:55], v[196:199], v[148:151], v[52:55]
	v_mfma_f32_16x16x32_bf16 v[48:51], v[212:215], v[148:151], v[48:51]
	v_mfma_f32_16x16x32_bf16 v[36:39], v[196:199], v[156:159], v[36:39]
	v_mfma_f32_16x16x32_bf16 v[32:35], v[212:215], v[156:159], v[32:35]
	v_mfma_f32_16x16x32_bf16 v[20:23], v[196:199], v[164:167], v[20:23]
	v_mfma_f32_16x16x32_bf16 v[16:19], v[212:215], v[164:167], v[16:19]
	s_setprio 2
	s_barrier
	v_mfma_f32_16x16x32_bf16 v[4:7], v[196:199], v[172:175], v[4:7]
	v_mfma_f32_16x16x32_bf16 v[0:3], v[212:215], v[172:175], v[0:3]
	s_setprio 0
	s_add_i32 s97, s97, 2
	s_add_u32 s6, s6, 0x100
	s_addc_u32 s7, s7, 0
	s_cmp_gt_u32 s97, 41
	s_mov_b64 s[28:29], s[76:77]
	s_cbranch_scc0 .LBB0_186
; DI unsigned pk_bf16(float lo, float hi) { f32x2 v = {lo, hi}; return __builtin_bit_cast(unsigned, __builtin_convertvector(v, bf16v2)); }
; DI f32x4 bf_lo4(u32x4 w) { f32x4 r; r[0] = bf_lo(w.x); r[1] = bf_hi(w.x); r[2] = bf_lo(w.y); r[3] = bf_hi(w.y); return r; }
; DI f32x4 bf_hi4(u32x4 w) { f32x4 r; r[0] = bf_lo(w.z); r[1] = bf_hi(w.z); r[2] = bf_lo(w.w); r[3] = bf_hi(w.w); return r; }
;     DI void operator()(AccRef acc, const Unit& u, int wr, int wc, int fr, int fq) const {
;     ...
; #pragma unroll
;         for (int ai = 0; ai < 2; ++ai) {
;             f32x4 bv[4][2][2];
; #pragma unroll
;             for (int m = 0; m < 4; ++m)
; #pragma unroll
;                 for (int bj = 0; bj < 2; ++bj) {
;                     const size_t o = (size_t)(row0 + ai * 128 + m * 16) * DM + col0 + bj * 128;
;                     if (BASEF32) { bv[m][bj][0] = *(const f32x4*)(basef + o); bv[m][bj][1] = *(const f32x4*)(basef + o + 4); }
;                     else { const u32x4 h = *(const u32x4*)(xnb + o); bv[m][bj][0] = bf_lo4(h); bv[m][bj][1] = bf_hi4(h); }
;                 }
; #pragma unroll
;             for (int m = 0; m < 4; ++m) {
;                 const int row = row0 + ai * 128 + m * 16;
;                 float q = 0.f;
; #pragma unroll
;                 for (int bj = 0; bj < 2; ++bj) {
;                     const size_t o = (size_t)row * DM + col0 + bj * 128;
;                     const f32x4 r0 = bv[m][bj][0] + scale * acc[ai][bj][m][0], r1 = bv[m][bj][1] + scale * acc[ai][bj][m][1];
;                     u32x4 w; w.x = pk_bf16(r0[0], r0[1]); w.y = pk_bf16(r0[2], r0[3]); w.z = pk_bf16(r1[0], r1[1]); w.w = pk_bf16(r1[2], r1[3]);
;                     *(u32x4*)(xnb + o) = w;
;                     if (STATS) q += r0[0] * r0[0] + r0[1] * r0[1] + r0[2] * r0[2] + r0[3] * r0[3] + r1[0] * r1[0] + r1[1] * r1[1] + r1[2] * r1[2] + r1[3] * r1[3];
;                 }
;                 if (STATS) { q += __shfl_xor(q, 16); q += __shfl_xor(q, 32); if (fq == 0) atomicAdd(ss + row, q); }
	v_lshl_add_u32 v194, s96, 8, v204
	v_lshl_or_b32 v192, s95, 8, v206
	v_ashrrev_i32_e32 v193, 31, v192
	v_ashrrev_i32_e32 v195, 31, v194
	v_lshl_add_u64 v[196:197], v[192:193], 2, s[52:53]
	v_lshlrev_b64 v[128:129], 12, v[194:195]
	v_lshl_add_u64 v[128:129], v[196:197], 0, v[128:129]
	global_load_dwordx4 v[214:217], v[128:129], off
	global_load_dwordx4 v[218:221], v[128:129], off offset:16
	global_load_dwordx4 v[224:227], v[128:129], off offset:512
	global_load_dwordx4 v[228:231], v[128:129], off offset:528
	v_or_b32_e32 v202, 16, v194
	v_or_b32_e32 v200, 32, v194
	v_or_b32_e32 v198, 48, v194
	v_ashrrev_i32_e32 v203, 31, v202
	v_ashrrev_i32_e32 v201, 31, v200
	v_ashrrev_i32_e32 v199, 31, v198
	v_lshlrev_b64 v[128:129], 12, v[202:203]
	v_lshlrev_b64 v[130:131], 12, v[200:201]
	v_lshlrev_b64 v[132:133], 12, v[198:199]
	v_lshl_add_u64 v[128:129], v[196:197], 0, v[128:129]
	v_lshl_add_u64 v[130:131], v[196:197], 0, v[130:131]
	v_lshl_add_u64 v[132:133], v[196:197], 0, v[132:133]
	global_load_dwordx4 v[168:171], v[128:129], off offset:16
	global_load_dwordx4 v[172:175], v[128:129], off
	global_load_dwordx4 v[160:163], v[128:129], off offset:528
	global_load_dwordx4 v[164:167], v[128:129], off offset:512
	global_load_dwordx4 v[152:155], v[130:131], off offset:16
	global_load_dwordx4 v[156:159], v[130:131], off
	global_load_dwordx4 v[144:147], v[130:131], off offset:528
	global_load_dwordx4 v[148:151], v[130:131], off offset:512
	global_load_dwordx4 v[136:139], v[132:133], off offset:16
	global_load_dwordx4 v[140:143], v[132:133], off
	s_nop 0
	global_load_dwordx4 v[128:131], v[132:133], off offset:528
	s_nop 0
	global_load_dwordx4 v[132:135], v[132:133], off offset:512
	v_and_b32_e32 v212, 64, v210
	v_xor_b32_e32 v211, 16, v210
	v_add_u32_e32 v212, 64, v212
	v_xor_b32_e32 v213, 32, v210
	v_cmp_lt_i32_e32 vcc, v211, v212
	v_lshlrev_b64 v[232:233], 11, v[194:195]
	s_waitcnt vmcnt(0)
	v_pk_fma_f32 v[124:125], v[124:125], 0.5, v[214:215] op_sel_hi:[1,0,1]
	v_cndmask_b32_e32 v211, v210, v211, vcc
	v_cmp_lt_i32_e32 vcc, v213, v212
	v_pk_fma_f32 v[116:117], v[116:117], 0.5, v[224:225] op_sel_hi:[1,0,1]
	v_lshlrev_b32_e32 v212, 2, v211
	v_cndmask_b32_e32 v213, v210, v213, vcc
	v_lshlrev_b32_e32 v211, 2, v213
	v_pk_fma_f32 v[126:127], v[126:127], 0.5, v[216:217] op_sel_hi:[1,0,1]
	v_pk_fma_f32 v[216:217], v[112:113], 0.5, v[228:229] op_sel_hi:[1,0,1]
	v_cvt_pk_bf16_f32 v112, v124, v125
	v_mul_f32_e32 v125, v125, v125
	v_mul_f32_e32 v213, v117, v117
	v_pk_fma_f32 v[118:119], v[118:119], 0.5, v[226:227] op_sel_hi:[1,0,1]
	v_fmac_f32_e32 v125, v124, v124
	v_fmac_f32_e32 v213, v116, v116
	v_fmac_f32_e32 v125, v126, v126
	v_fmac_f32_e32 v213, v118, v118
	v_pk_fma_f32 v[120:121], v[120:121], 0.5, v[218:219] op_sel_hi:[1,0,1]
	v_fmac_f32_e32 v125, v127, v127
	v_fmac_f32_e32 v213, v119, v119
	v_fmac_f32_e32 v125, v120, v120
	v_fmac_f32_e32 v213, v216, v216
	v_pk_fma_f32 v[122:123], v[122:123], 0.5, v[220:221] op_sel_hi:[1,0,1]
	v_pk_fma_f32 v[214:215], v[114:115], 0.5, v[230:231] op_sel_hi:[1,0,1]
	v_fmac_f32_e32 v125, v121, v121
	v_fmac_f32_e32 v213, v217, v217
	v_fmac_f32_e32 v125, v122, v122
	v_fmac_f32_e32 v213, v214, v214
	v_fmac_f32_e32 v125, v123, v123
	v_fmac_f32_e32 v213, v215, v215
	v_cvt_pk_bf16_f32 v115, v122, v123
	v_add_f32_e32 v122, v125, v213
	ds_bpermute_b32 v123, v212, v122
	v_cvt_pk_bf16_f32 v114, v120, v121
	v_lshl_add_u64 v[120:121], s[56:57], 0, v[232:233]
	v_cvt_pk_bf16_f32 v113, v126, v127
	v_lshl_add_u64 v[120:121], v[192:193], 1, v[120:121]
	global_store_dwordx4 v[120:121], v[112:115], off
	s_waitcnt lgkmcnt(0)
	s_nop 0
	v_add_f32_e32 v112, v122, v123
	ds_bpermute_b32 v113, v211, v112
	v_cvt_pk_bf16_f32 v114, v116, v117
	v_cvt_pk_bf16_f32 v115, v118, v119
	v_cvt_pk_bf16_f32 v116, v216, v217
	v_cvt_pk_bf16_f32 v117, v214, v215
	global_store_dwordx4 v[120:121], v[114:117], off offset:256
	s_and_saveexec_b64 s[6:7], s[0:1]
	s_cbranch_execz .LBB0_189
	v_lshl_add_u64 v[114:115], v[194:195], 2, s[60:61]
	s_waitcnt lgkmcnt(0)
	v_add_f32_e32 v112, v112, v113
	global_atomic_add_f32 v[114:115], v112, off

; #define PG8_STAGE(bufoff, gbase, voff) do { _Pragma("unroll") for (int _i = 0; _i < 2; ++_i) \
;         __builtin_amdgcn_global_load_lds((const unsigned*)((const char*)(gbase) + (voff)[_i]), (LAS unsigned*)(lds + (bufoff) + ldsw + _i * 8192), 16, 0, 0); } while (0)
; #define PG8_LDA(dst, b, h) do { _Pragma("unroll") for (int m = 0; m < 4; ++m) _Pragma("unroll") for (int k = 0; k < 2; ++k) dst[m][k] = *(const LAS bf16x8*)(lds + PG8_SA(b, h) + aoff + m * 2048 + k * 1024); } while (0)
; #define PG8_LDB(dst, b, h) do { _Pragma("unroll") for (int n = 0; n < 2; ++n) _Pragma("unroll") for (int k = 0; k < 2; ++k) dst[n][k] = *(const LAS bf16x8*)(lds + PG8_SB(b, h) + boff + n * 2048 + k * 1024); } while (0)
; #define PG8_MMA(ai, bj, At, Bt) do { __builtin_amdgcn_s_setprio(1); _Pragma("unroll") for (int m = 0; m < 4; ++m) _Pragma("unroll") for (int n = 0; n < 2; ++n) _Pragma("unroll") for (int k = 0; k < 2; ++k) \
;         acc[ai][bj][m][n] = __builtin_amdgcn_mfma_f32_16x16x32_bf16(Bt[n][k], At[m][k], acc[ai][bj][m][n], 0, 0, 0); __builtin_amdgcn_s_setprio(0); } while (0)
; template <class Epi>
; DI void gemm_phase(LAS unsigned char* lds, const Gemm g, const StaticOrder S, const Epi E) {
;     ...
;         for (int t = 0; t < nt; t += 2) {
;             const bool last = (t == nt - 2);
;             const char* a1 = cA + (size_t)(t + 1) * kstep;
;             const char* a2 = last ? nA : cA + (size_t)(t + 2) * kstep; const char* b2 = last ? nB : cB + (size_t)(t + 2) * kstep;
;             const char* a3 = a2 + kstep; const char* b3 = b2 + kstep;
;             PG8_LDB(B0, 0, 0); PG8_SCHED; PG8_LDA(At, 0, 0); PG8_STAGE(PG8_SA(1, 1), a1 + hstep, voffA);
;             PG8_WAIT_L(8); PG8_BAR; PG8_WAIT_L(0); PG8_MMA(0, 0, At, B0); PG8_BAR; PG8_SCHED;
;             PG8_LDB(B1, 0, 1); PG8_STAGE(PG8_SB(0, 0), b2, voffB);
;             PG8_BAR; PG8_WAIT_L(0); PG8_MMA(0, 1, At, B1); PG8_BAR;
;             PG8_LDA(At, 0, 1); PG8_STAGE(PG8_SA(0, 0), a2, voffA);
;             PG8_BAR; PG8_WAIT_L(0); PG8_MMA(1, 0, At, B0); PG8_BAR; PG8_SCHED;
;             PG8_STAGE(PG8_SB(0, 1), b2 + hstep, voffB);
;             PG8_WAIT_V(6); PG8_BAR; PG8_MMA(1, 1, At, B1); PG8_BAR;
;             PG8_LDB(B0, 1, 0); PG8_SCHED; PG8_LDA(At, 1, 0); PG8_STAGE(PG8_SA(0, 1), a2 + hstep, voffA);
;             PG8_WAIT_L(8); PG8_BAR; PG8_WAIT_L(0); PG8_MMA(0, 0, At, B0); PG8_BAR; PG8_SCHED;
.LBB0_274:
	ds_read_b128 v[100:103], v227
	ds_read_b128 v[134:137], v227 offset:1024
	ds_read_b128 v[138:141], v227 offset:2048
	ds_read_b128 v[142:145], v227 offset:3072
	s_add_u32 s14, s8, 0xfffc0080
	s_addc_u32 s15, s9, -1
	s_cmp_eq_u32 s95, 12
	s_cselect_b32 s77, s1, s15
	s_cselect_b32 s76, s6, s14
	s_cselect_b32 s53, s7, s94
	s_cselect_b32 s52, s21, s23
	v_lshl_add_u64 v[104:105], s[8:9], 0, v[212:213]
	s_add_i32 m0, s78, 0xc000
	ds_read_b128 v[146:149], v228
	ds_read_b128 v[154:157], v228 offset:2048
	ds_read_b128 v[162:165], v228 offset:4096
	ds_read_b128 v[170:173], v228 offset:6144
	global_load_lds_dwordx4 v[104:105], off
	v_lshl_add_u64 v[104:105], s[8:9], 0, v[214:215]
	s_add_i32 m0, s78, 0xe000
	s_nop 0
	global_load_lds_dwordx4 v[104:105], off
	s_waitcnt lgkmcnt(4)
	s_setprio 1
	s_barrier
	ds_read_b128 v[150:153], v228 offset:1024
	ds_read_b128 v[158:161], v228 offset:3072
	ds_read_b128 v[166:169], v228 offset:5120
	ds_read_b128 v[174:177], v228 offset:7168
	s_waitcnt lgkmcnt(4)
	v_mfma_f32_16x16x32_bf16 v[130:133], v[100:103], v[146:149], v[130:133]
	v_mfma_f32_16x16x32_bf16 v[126:129], v[138:141], v[146:149], v[126:129]
	v_mfma_f32_16x16x32_bf16 v[114:117], v[100:103], v[154:157], v[114:117]
	v_mfma_f32_16x16x32_bf16 v[110:113], v[138:141], v[154:157], v[110:113]
	v_mfma_f32_16x16x32_bf16 v[92:95], v[100:103], v[162:165], v[92:95]
	v_mfma_f32_16x16x32_bf16 v[88:91], v[138:141], v[162:165], v[88:91]
	v_mfma_f32_16x16x32_bf16 v[76:79], v[100:103], v[170:173], v[76:79]
	v_mfma_f32_16x16x32_bf16 v[72:75], v[138:141], v[170:173], v[72:75]
	s_waitcnt lgkmcnt(3)
	v_mfma_f32_16x16x32_bf16 v[130:133], v[134:137], v[150:153], v[130:133]
	v_mfma_f32_16x16x32_bf16 v[126:129], v[142:145], v[150:153], v[126:129]
	s_waitcnt lgkmcnt(2)
	v_mfma_f32_16x16x32_bf16 v[114:117], v[134:137], v[158:161], v[114:117]
	v_mfma_f32_16x16x32_bf16 v[110:113], v[142:145], v[158:161], v[110:113]
	s_waitcnt lgkmcnt(1)
	v_mfma_f32_16x16x32_bf16 v[92:95], v[134:137], v[166:169], v[92:95]
	v_mfma_f32_16x16x32_bf16 v[88:91], v[142:145], v[166:169], v[88:91]
	s_waitcnt lgkmcnt(0)
	s_setprio 2
	s_barrier
	v_mfma_f32_16x16x32_bf16 v[76:79], v[134:137], v[174:177], v[76:79]
	v_mfma_f32_16x16x32_bf16 v[72:75], v[142:145], v[174:177], v[72:75]
	s_setprio 0
	s_add_i32 s14, s87, s59
	v_lshl_add_u64 v[194:195], s[52:53], 0, v[200:201]
	s_mov_b32 m0, s14
	ds_read_b128 v[178:181], v229
	ds_read_b128 v[182:185], v229 offset:1024
	ds_read_b128 v[186:189], v229 offset:2048
	ds_read_b128 v[190:193], v229 offset:3072
	global_load_lds_dwordx4 v[194:195], off
	v_lshl_add_u64 v[196:197], s[52:53], 0, v[204:205]
	s_add_i32 m0, s14, 0x2000
	s_nop 0
	global_load_lds_dwordx4 v[196:197], off
	s_setprio 1
	s_barrier
	s_waitcnt lgkmcnt(0)
	v_mfma_f32_16x16x32_bf16 v[122:125], v[178:181], v[146:149], v[122:125]
	v_mfma_f32_16x16x32_bf16 v[118:121], v[186:189], v[146:149], v[118:121]
	v_mfma_f32_16x16x32_bf16 v[104:107], v[178:181], v[154:157], v[106:109]
	v_mfma_f32_16x16x32_bf16 v[96:99], v[186:189], v[154:157], v[96:99]
	v_mfma_f32_16x16x32_bf16 v[84:87], v[178:181], v[162:165], v[84:87]
	v_mfma_f32_16x16x32_bf16 v[80:83], v[186:189], v[162:165], v[80:83]
	v_mfma_f32_16x16x32_bf16 v[68:71], v[178:181], v[170:173], v[68:71]
	v_mfma_f32_16x16x32_bf16 v[64:67], v[186:189], v[170:173], v[64:67]
	v_mfma_f32_16x16x32_bf16 v[122:125], v[182:185], v[150:153], v[122:125]
	v_mfma_f32_16x16x32_bf16 v[118:121], v[190:193], v[150:153], v[118:121]
	v_mfma_f32_16x16x32_bf16 v[104:107], v[182:185], v[158:161], v[104:107]
	v_mfma_f32_16x16x32_bf16 v[96:99], v[190:193], v[158:161], v[96:99]
	v_mfma_f32_16x16x32_bf16 v[84:87], v[182:185], v[166:169], v[84:87]
	v_mfma_f32_16x16x32_bf16 v[80:83], v[190:193], v[166:169], v[80:83]
	s_setprio 2
	s_barrier
	v_mfma_f32_16x16x32_bf16 v[68:71], v[182:185], v[174:177], v[68:71]
	v_mfma_f32_16x16x32_bf16 v[64:67], v[190:193], v[174:177], v[64:67]
	s_setprio 0
	s_mov_b32 m0, s78
	v_lshl_add_u64 v[220:221], s[76:77], 0, v[198:199]
	ds_read_b128 v[146:149], v228 offset:16384
	ds_read_b128 v[154:157], v228 offset:18432
	ds_read_b128 v[162:165], v228 offset:20480
	ds_read_b128 v[170:173], v228 offset:22528
	global_load_lds_dwordx4 v[220:221], off
	v_lshl_add_u64 v[232:233], s[76:77], 0, v[202:203]
	s_mov_b32 m0, s79
	s_nop 0
	global_load_lds_dwordx4 v[232:233], off
	s_setprio 1
	s_barrier
	ds_read_b128 v[150:153], v228 offset:17408
	ds_read_b128 v[158:161], v228 offset:19456
	ds_read_b128 v[166:169], v228 offset:21504
	ds_read_b128 v[174:177], v228 offset:23552
	s_waitcnt lgkmcnt(4)
	v_mfma_f32_16x16x32_bf16 v[60:63], v[100:103], v[146:149], v[60:63]
	v_mfma_f32_16x16x32_bf16 v[56:59], v[138:141], v[146:149], v[56:59]
	v_mfma_f32_16x16x32_bf16 v[44:47], v[100:103], v[154:157], v[44:47]
	v_mfma_f32_16x16x32_bf16 v[40:43], v[138:141], v[154:157], v[40:43]
	v_mfma_f32_16x16x32_bf16 v[28:31], v[100:103], v[162:165], v[28:31]
	v_mfma_f32_16x16x32_bf16 v[24:27], v[138:141], v[162:165], v[24:27]
	v_mfma_f32_16x16x32_bf16 v[12:15], v[100:103], v[170:173], v[12:15]
	v_mfma_f32_16x16x32_bf16 v[8:11], v[138:141], v[170:173], v[8:11]
	s_waitcnt lgkmcnt(3)
	v_mfma_f32_16x16x32_bf16 v[60:63], v[134:137], v[150:153], v[60:63]
	v_mfma_f32_16x16x32_bf16 v[56:59], v[142:145], v[150:153], v[56:59]
	s_waitcnt lgkmcnt(2)
	v_mfma_f32_16x16x32_bf16 v[44:47], v[134:137], v[158:161], v[44:47]
	v_mfma_f32_16x16x32_bf16 v[40:43], v[142:145], v[158:161], v[40:43]
	s_waitcnt lgkmcnt(1)
	v_mfma_f32_16x16x32_bf16 v[28:31], v[134:137], v[166:169], v[28:31]
	v_mfma_f32_16x16x32_bf16 v[24:27], v[142:145], v[166:169], v[24:27]
	s_waitcnt lgkmcnt(0)
	s_setprio 2
	s_barrier
; #define PG8_STAGE(bufoff, gbase, voff) do { _Pragma("unroll") for (int _i = 0; _i < 2; ++_i) \
;         __builtin_amdgcn_global_load_lds((const unsigned*)((const char*)(gbase) + (voff)[_i]), (LAS unsigned*)(lds + (bufoff) + ldsw + _i * 8192), 16, 0, 0); } while (0)
; #define PG8_LDA(dst, b, h) do { _Pragma("unroll") for (int m = 0; m < 4; ++m) _Pragma("unroll") for (int k = 0; k < 2; ++k) dst[m][k] = *(const LAS bf16x8*)(lds + PG8_SA(b, h) + aoff + m * 2048 + k * 1024); } while (0)
; #define PG8_LDB(dst, b, h) do { _Pragma("unroll") for (int n = 0; n < 2; ++n) _Pragma("unroll") for (int k = 0; k < 2; ++k) dst[n][k] = *(const LAS bf16x8*)(lds + PG8_SB(b, h) + boff + n * 2048 + k * 1024); } while (0)
; #define PG8_MMA(ai, bj, At, Bt) do { __builtin_amdgcn_s_setprio(1); _Pragma("unroll") for (int m = 0; m < 4; ++m) _Pragma("unroll") for (int n = 0; n < 2; ++n) _Pragma("unroll") for (int k = 0; k < 2; ++k) \
;         acc[ai][bj][m][n] = __builtin_amdgcn_mfma_f32_16x16x32_bf16(Bt[n][k], At[m][k], acc[ai][bj][m][n], 0, 0, 0); __builtin_amdgcn_s_setprio(0); } while (0)
; #define PG8_WAIT_V(n) asm volatile("s_waitcnt vmcnt(" #n ")" ::: "memory")
; #define PG8_WAIT_L(n) asm volatile("s_waitcnt lgkmcnt(" #n ")" ::: "memory")
; #define PG8_BAR __builtin_amdgcn_s_barrier()
; #define PG8_SCHED __builtin_amdgcn_sched_barrier(0)
; #define PG8_WAIT_V(n) asm volatile("s_waitcnt vmcnt(" #n ")" ::: "memory")
; #define PG8_WAIT_L(n) asm volatile("s_waitcnt lgkmcnt(" #n ")" ::: "memory")
; template <class Epi>
; DI void gemm_phase(LAS unsigned char* lds, const Gemm g, const StaticOrder S, const Epi E) {
;     ...
;             PG8_STAGE(PG8_SB(0, 1), b2 + hstep, voffB);
;             PG8_WAIT_V(6); PG8_BAR; PG8_MMA(1, 1, At, B1); PG8_BAR;
;             PG8_LDB(B0, 1, 0); PG8_SCHED; PG8_LDA(At, 1, 0); PG8_STAGE(PG8_SA(0, 1), a2 + hstep, voffA);
;             PG8_WAIT_L(8); PG8_BAR; PG8_WAIT_L(0); PG8_MMA(0, 0, At, B0); PG8_BAR; PG8_SCHED;
;             PG8_LDB(B1, 1, 1); PG8_STAGE(PG8_SB(1, 0), b3, voffB);
;             PG8_BAR; PG8_WAIT_L(0); PG8_MMA(0, 1, At, B1); PG8_BAR;
;             PG8_LDA(At, 1, 1); PG8_STAGE(PG8_SA(1, 0), a3, voffA);
;             PG8_BAR; PG8_WAIT_L(0); PG8_MMA(1, 0, At, B0); PG8_BAR; PG8_SCHED;
;             PG8_STAGE(PG8_SB(1, 1), b3 + hstep, voffB);
;             PG8_WAIT_V(6); PG8_BAR; PG8_MMA(1, 1, At, B1); PG8_BAR;
	v_mfma_f32_16x16x32_bf16 v[12:15], v[134:137], v[174:177], v[12:15]
	v_mfma_f32_16x16x32_bf16 v[8:11], v[142:145], v[174:177], v[8:11]
	s_setprio 0
	s_add_u32 s14, s52, 0x40000
	s_addc_u32 s15, s53, 0
	s_add_i32 s35, s90, s59
	v_lshl_add_u64 v[100:101], s[14:15], 0, v[200:201]
	s_mov_b32 m0, s35
	s_nop 0
	global_load_lds_dwordx4 v[100:101], off
	v_lshl_add_u64 v[100:101], s[14:15], 0, v[204:205]
	s_add_i32 m0, s35, 0x2000
	s_nop 0
	global_load_lds_dwordx4 v[100:101], off
	s_waitcnt vmcnt(6)
	s_setprio 1
	s_barrier
	v_mfma_f32_16x16x32_bf16 v[52:55], v[178:181], v[146:149], v[52:55]
	v_mfma_f32_16x16x32_bf16 v[48:51], v[186:189], v[146:149], v[48:51]
	v_mfma_f32_16x16x32_bf16 v[36:39], v[178:181], v[154:157], v[36:39]
	v_mfma_f32_16x16x32_bf16 v[32:35], v[186:189], v[154:157], v[32:35]
	v_mfma_f32_16x16x32_bf16 v[20:23], v[178:181], v[162:165], v[20:23]
	v_mfma_f32_16x16x32_bf16 v[16:19], v[186:189], v[162:165], v[16:19]
	v_mfma_f32_16x16x32_bf16 v[4:7], v[178:181], v[170:173], v[4:7]
	v_mfma_f32_16x16x32_bf16 v[0:3], v[186:189], v[170:173], v[0:3]
	v_mfma_f32_16x16x32_bf16 v[52:55], v[182:185], v[150:153], v[52:55]
	v_mfma_f32_16x16x32_bf16 v[48:51], v[190:193], v[150:153], v[48:51]
	v_mfma_f32_16x16x32_bf16 v[36:39], v[182:185], v[158:161], v[36:39]
	v_mfma_f32_16x16x32_bf16 v[32:35], v[190:193], v[158:161], v[32:35]
	v_mfma_f32_16x16x32_bf16 v[20:23], v[182:185], v[166:169], v[20:23]
	v_mfma_f32_16x16x32_bf16 v[16:19], v[190:193], v[166:169], v[16:19]
	s_setprio 2
	s_barrier
	v_mfma_f32_16x16x32_bf16 v[4:7], v[182:185], v[174:177], v[4:7]
	v_mfma_f32_16x16x32_bf16 v[0:3], v[190:193], v[174:177], v[0:3]
	s_setprio 0
	s_add_i32 s35, 0, 0x18000
	v_add_u32_e32 v108, s35, v225
	ds_read_b128 v[100:103], v108
	ds_read_b128 v[134:137], v108 offset:1024
	ds_read_b128 v[138:141], v108 offset:2048
	ds_read_b128 v[142:145], v108 offset:3072
	s_add_u32 s14, s76, 0x40000
	s_addc_u32 s15, s77, 0
	s_mov_b32 m0, s80
	v_lshl_add_u64 v[108:109], s[14:15], 0, v[198:199]
	ds_read_b128 v[146:149], v228 offset:32768
	ds_read_b128 v[154:157], v228 offset:34816
	ds_read_b128 v[162:165], v228 offset:36864
	ds_read_b128 v[170:173], v228 offset:38912
	global_load_lds_dwordx4 v[108:109], off
	v_lshl_add_u64 v[108:109], s[14:15], 0, v[202:203]
	s_mov_b32 m0, s81
	s_nop 0
	global_load_lds_dwordx4 v[108:109], off
	s_waitcnt lgkmcnt(4)
	s_setprio 1
	s_barrier
	ds_read_b128 v[150:153], v228 offset:33792
	ds_read_b128 v[158:161], v228 offset:35840
	ds_read_b128 v[166:169], v228 offset:37888
	ds_read_b128 v[174:177], v228 offset:39936
	s_waitcnt lgkmcnt(4)
	v_mfma_f32_16x16x32_bf16 v[130:133], v[100:103], v[146:149], v[130:133]
	v_mfma_f32_16x16x32_bf16 v[126:129], v[138:141], v[146:149], v[126:129]
	v_mfma_f32_16x16x32_bf16 v[114:117], v[100:103], v[154:157], v[114:117]
	v_mfma_f32_16x16x32_bf16 v[108:111], v[138:141], v[154:157], v[110:113]
	v_mfma_f32_16x16x32_bf16 v[92:95], v[100:103], v[162:165], v[92:95]
	v_mfma_f32_16x16x32_bf16 v[88:91], v[138:141], v[162:165], v[88:91]
	v_mfma_f32_16x16x32_bf16 v[76:79], v[100:103], v[170:173], v[76:79]
	v_mfma_f32_16x16x32_bf16 v[72:75], v[138:141], v[170:173], v[72:75]
	s_waitcnt lgkmcnt(3)
	v_mfma_f32_16x16x32_bf16 v[130:133], v[134:137], v[150:153], v[130:133]
	v_mfma_f32_16x16x32_bf16 v[126:129], v[142:145], v[150:153], v[126:129]
	s_waitcnt lgkmcnt(2)
	v_mfma_f32_16x16x32_bf16 v[114:117], v[134:137], v[158:161], v[114:117]
	v_mfma_f32_16x16x32_bf16 v[110:113], v[142:145], v[158:161], v[108:111]
	s_waitcnt lgkmcnt(1)
	v_mfma_f32_16x16x32_bf16 v[92:95], v[134:137], v[166:169], v[92:95]
	v_mfma_f32_16x16x32_bf16 v[88:91], v[142:145], v[166:169], v[88:91]
	s_waitcnt lgkmcnt(0)
	s_setprio 2
	s_barrier
	v_mfma_f32_16x16x32_bf16 v[76:79], v[134:137], v[174:177], v[76:79]
	v_mfma_f32_16x16x32_bf16 v[72:75], v[142:145], v[174:177], v[72:75]
	s_setprio 0
	s_add_i32 s76, 0, 0x1c000
	v_add_u32_e32 v108, s76, v225
	s_add_i32 s14, s35, s59
	ds_read_b128 v[178:181], v108
	ds_read_b128 v[182:185], v108 offset:1024
	ds_read_b128 v[186:189], v108 offset:2048
	ds_read_b128 v[190:193], v108 offset:3072
	v_lshl_add_u64 v[108:109], v[194:195], 0, s[18:19]
	s_mov_b32 m0, s14
	s_nop 0
	global_load_lds_dwordx4 v[108:109], off
	v_lshl_add_u64 v[108:109], v[196:197], 0, s[18:19]
	s_add_i32 m0, s14, 0x2000
	s_nop 0
	global_load_lds_dwordx4 v[108:109], off
	s_setprio 1
	s_barrier
	s_waitcnt lgkmcnt(0)
	v_mfma_f32_16x16x32_bf16 v[122:125], v[178:181], v[146:149], v[122:125]
	v_mfma_f32_16x16x32_bf16 v[118:121], v[186:189], v[146:149], v[118:121]
	v_mfma_f32_16x16x32_bf16 v[104:107], v[178:181], v[154:157], v[104:107]
	v_mfma_f32_16x16x32_bf16 v[96:99], v[186:189], v[154:157], v[96:99]
	v_mfma_f32_16x16x32_bf16 v[84:87], v[178:181], v[162:165], v[84:87]
	v_mfma_f32_16x16x32_bf16 v[80:83], v[186:189], v[162:165], v[80:83]
	v_mfma_f32_16x16x32_bf16 v[68:71], v[178:181], v[170:173], v[68:71]
	v_mfma_f32_16x16x32_bf16 v[64:67], v[186:189], v[170:173], v[64:67]
	v_mfma_f32_16x16x32_bf16 v[122:125], v[182:185], v[150:153], v[122:125]
	v_mfma_f32_16x16x32_bf16 v[118:121], v[190:193], v[150:153], v[118:121]
	v_mfma_f32_16x16x32_bf16 v[106:109], v[182:185], v[158:161], v[104:107]
	v_mfma_f32_16x16x32_bf16 v[96:99], v[190:193], v[158:161], v[96:99]
	v_mfma_f32_16x16x32_bf16 v[84:87], v[182:185], v[166:169], v[84:87]
	v_mfma_f32_16x16x32_bf16 v[80:83], v[190:193], v[166:169], v[80:83]
	s_setprio 2
	s_barrier
; #define PG8_STAGE(bufoff, gbase, voff) do { _Pragma("unroll") for (int _i = 0; _i < 2; ++_i) \
;         __builtin_amdgcn_global_load_lds((const unsigned*)((const char*)(gbase) + (voff)[_i]), (LAS unsigned*)(lds + (bufoff) + ldsw + _i * 8192), 16, 0, 0); } while (0)
; #define PG8_LDA(dst, b, h) do { _Pragma("unroll") for (int m = 0; m < 4; ++m) _Pragma("unroll") for (int k = 0; k < 2; ++k) dst[m][k] = *(const LAS bf16x8*)(lds + PG8_SA(b, h) + aoff + m * 2048 + k * 1024); } while (0)
; #define PG8_MMA(ai, bj, At, Bt) do { __builtin_amdgcn_s_setprio(1); _Pragma("unroll") for (int m = 0; m < 4; ++m) _Pragma("unroll") for (int n = 0; n < 2; ++n) _Pragma("unroll") for (int k = 0; k < 2; ++k) \
;         acc[ai][bj][m][n] = __builtin_amdgcn_mfma_f32_16x16x32_bf16(Bt[n][k], At[m][k], acc[ai][bj][m][n], 0, 0, 0); __builtin_amdgcn_s_setprio(0); } while (0)
; #define PG8_WAIT_V(n) asm volatile("s_waitcnt vmcnt(" #n ")" ::: "memory")
; #define PG8_WAIT_L(n) asm volatile("s_waitcnt lgkmcnt(" #n ")" ::: "memory")
; #define PG8_BAR __builtin_amdgcn_s_barrier()
; #define PG8_SCHED __builtin_amdgcn_sched_barrier(0)
; #define PG8_STAGE(bufoff, gbase, voff) do { _Pragma("unroll") for (int _i = 0; _i < 2; ++_i) \
;         __builtin_amdgcn_global_load_lds((const unsigned*)((const char*)(gbase) + (voff)[_i]), (LAS unsigned*)(lds + (bufoff) + ldsw + _i * 8192), 16, 0, 0); } while (0)
; #define PG8_LDA(dst, b, h) do { _Pragma("unroll") for (int m = 0; m < 4; ++m) _Pragma("unroll") for (int k = 0; k < 2; ++k) dst[m][k] = *(const LAS bf16x8*)(lds + PG8_SA(b, h) + aoff + m * 2048 + k * 1024); } while (0)
; #define PG8_WAIT_V(n) asm volatile("s_waitcnt vmcnt(" #n ")" ::: "memory")
; #define PG8_WAIT_L(n) asm volatile("s_waitcnt lgkmcnt(" #n ")" ::: "memory")
; #define PG8_BAR __builtin_amdgcn_s_barrier()
; #define PG8_SCHED __builtin_amdgcn_sched_barrier(0)
; template <class Epi>
; DI void gemm_phase(LAS unsigned char* lds, const Gemm g, const StaticOrder S, const Epi E) {
;     ...
;             PG8_BAR; PG8_WAIT_L(0); PG8_MMA(0, 1, At, B1); PG8_BAR;
;             PG8_LDA(At, 1, 1); PG8_STAGE(PG8_SA(1, 0), a3, voffA);
;             PG8_BAR; PG8_WAIT_L(0); PG8_MMA(1, 0, At, B0); PG8_BAR; PG8_SCHED;
;             PG8_STAGE(PG8_SB(1, 1), b3 + hstep, voffB);
;             PG8_WAIT_V(6); PG8_BAR; PG8_MMA(1, 1, At, B1); PG8_BAR;
;         }
	v_mfma_f32_16x16x32_bf16 v[68:71], v[182:185], v[174:177], v[68:71]
	v_mfma_f32_16x16x32_bf16 v[64:67], v[190:193], v[174:177], v[64:67]
	s_setprio 0
	s_mov_b32 m0, s83
	v_lshl_add_u64 v[104:105], v[220:221], 0, s[18:19]
	ds_read_b128 v[146:149], v228 offset:49152
	ds_read_b128 v[154:157], v228 offset:51200
	ds_read_b128 v[162:165], v228 offset:53248
	ds_read_b128 v[170:173], v228 offset:55296
	global_load_lds_dwordx4 v[104:105], off
	v_lshl_add_u64 v[104:105], v[232:233], 0, s[18:19]
	s_mov_b32 m0, s84
	s_nop 0
	global_load_lds_dwordx4 v[104:105], off
	s_setprio 1
	s_barrier
	ds_read_b128 v[150:153], v228 offset:50176
	ds_read_b128 v[158:161], v228 offset:52224
	ds_read_b128 v[166:169], v228 offset:54272
	ds_read_b128 v[174:177], v228 offset:56320
	s_waitcnt lgkmcnt(4)
	v_mfma_f32_16x16x32_bf16 v[60:63], v[100:103], v[146:149], v[60:63]
	v_mfma_f32_16x16x32_bf16 v[56:59], v[138:141], v[146:149], v[56:59]
	v_mfma_f32_16x16x32_bf16 v[44:47], v[100:103], v[154:157], v[44:47]
	v_mfma_f32_16x16x32_bf16 v[40:43], v[138:141], v[154:157], v[40:43]
	v_mfma_f32_16x16x32_bf16 v[28:31], v[100:103], v[162:165], v[28:31]
	v_mfma_f32_16x16x32_bf16 v[24:27], v[138:141], v[162:165], v[24:27]
	v_mfma_f32_16x16x32_bf16 v[12:15], v[100:103], v[170:173], v[12:15]
	v_mfma_f32_16x16x32_bf16 v[8:11], v[138:141], v[170:173], v[8:11]
	s_waitcnt lgkmcnt(3)
	v_mfma_f32_16x16x32_bf16 v[60:63], v[134:137], v[150:153], v[60:63]
	v_mfma_f32_16x16x32_bf16 v[56:59], v[142:145], v[150:153], v[56:59]
	s_waitcnt lgkmcnt(2)
	v_mfma_f32_16x16x32_bf16 v[44:47], v[134:137], v[158:161], v[44:47]
	v_mfma_f32_16x16x32_bf16 v[40:43], v[142:145], v[158:161], v[40:43]
	s_waitcnt lgkmcnt(1)
	v_mfma_f32_16x16x32_bf16 v[28:31], v[134:137], v[166:169], v[28:31]
	v_mfma_f32_16x16x32_bf16 v[24:27], v[142:145], v[166:169], v[24:27]
	s_waitcnt lgkmcnt(0)
	s_setprio 2
	s_barrier
	v_mfma_f32_16x16x32_bf16 v[12:15], v[134:137], v[174:177], v[12:15]
	v_mfma_f32_16x16x32_bf16 v[8:11], v[142:145], v[174:177], v[8:11]
	s_setprio 0
	s_add_u32 s14, s52, 0x40080
	s_addc_u32 s15, s53, 0
	s_add_i32 s35, s76, s59
	v_lshl_add_u64 v[100:101], s[14:15], 0, v[200:201]
	s_mov_b32 m0, s35
	s_nop 0
	global_load_lds_dwordx4 v[100:101], off
	v_lshl_add_u64 v[100:101], s[14:15], 0, v[204:205]
	s_add_i32 m0, s35, 0x2000
	s_nop 0
	global_load_lds_dwordx4 v[100:101], off
	s_waitcnt vmcnt(6)
	s_setprio 1
	s_barrier
	v_mfma_f32_16x16x32_bf16 v[52:55], v[178:181], v[146:149], v[52:55]
	v_mfma_f32_16x16x32_bf16 v[48:51], v[186:189], v[146:149], v[48:51]
	v_mfma_f32_16x16x32_bf16 v[36:39], v[178:181], v[154:157], v[36:39]
	v_mfma_f32_16x16x32_bf16 v[32:35], v[186:189], v[154:157], v[32:35]
	v_mfma_f32_16x16x32_bf16 v[20:23], v[178:181], v[162:165], v[20:23]
	v_mfma_f32_16x16x32_bf16 v[16:19], v[186:189], v[162:165], v[16:19]
	v_mfma_f32_16x16x32_bf16 v[4:7], v[178:181], v[170:173], v[4:7]
	v_mfma_f32_16x16x32_bf16 v[0:3], v[186:189], v[170:173], v[0:3]
	v_mfma_f32_16x16x32_bf16 v[52:55], v[182:185], v[150:153], v[52:55]
	v_mfma_f32_16x16x32_bf16 v[48:51], v[190:193], v[150:153], v[48:51]
	v_mfma_f32_16x16x32_bf16 v[36:39], v[182:185], v[158:161], v[36:39]
	v_mfma_f32_16x16x32_bf16 v[32:35], v[190:193], v[158:161], v[32:35]
	v_mfma_f32_16x16x32_bf16 v[20:23], v[182:185], v[166:169], v[20:23]
	v_mfma_f32_16x16x32_bf16 v[16:19], v[190:193], v[166:169], v[16:19]
	s_setprio 2
	s_barrier
	v_mfma_f32_16x16x32_bf16 v[4:7], v[182:185], v[174:177], v[4:7]
	v_mfma_f32_16x16x32_bf16 v[0:3], v[190:193], v[174:177], v[0:3]
	s_setprio 0
	s_add_i32 s95, s95, 2
	s_add_u32 s8, s8, 0x100
	s_addc_u32 s9, s9, 0
	s_add_u32 s23, s23, 0x100
	s_addc_u32 s94, s94, 0
	s_cmp_gt_u32 s95, 13
	s_cbranch_scc0 .LBB0_274
;     DI void operator()(AccRef acc, const Unit& u, int wr, int wc, int fr, int fq) const {
;         const int X = u.pn >> 2, h = u.pn & 3, isk = wc >> 1, i0 = (wc & 1) * 32 + 8 * fq;
;         bf16_t* dst = (X ? qkoB : qkoA) + h * 256 + isk * 128 + i0;
;         const float qs0 = isk ? 1.0f : 0.08838834764831845f;
;         const int row0 = u.pm * 256 + wr * 64 + fr;
;         const RowScales rsc = load_rowscales(ss, row0);
; #pragma unroll
;         for (int ai = 0; ai < 2; ++ai) {
;             f32x4 cs[4][2], sn[4][2];
;             if (X == 0) {
; #pragma unroll
;                 for (int m = 0; m < 4; ++m) {
;                     const int pos = (row0 + ai * 128 + m * 16) & (SEQ - 1);
;                     cs[m][0] = *(const f32x4*)(cosT + pos * 64 + i0); cs[m][1] = *(const f32x4*)(cosT + pos * 64 + i0 + 4);
;                     sn[m][0] = *(const f32x4*)(sinT + pos * 64 + i0); sn[m][1] = *(const f32x4*)(sinT + pos * 64 + i0 + 4);
;                 }
;             } else {
; #pragma unroll
;                 for (int m = 0; m < 4; ++m) { cs[m][0] = cs[m][1] = (f32x4){1.f, 1.f, 1.f, 1.f}; sn[m][0] = sn[m][1] = (f32x4){0.f, 0.f, 0.f, 0.f}; }
;             }
	v_lshl_add_u32 v102, s0, 8, v224
	v_ashrrev_i32_e32 v103, 31, v102
	v_lshl_add_u64 v[134:135], v[102:103], 2, s[60:61]
	global_load_dword v237, v[134:135], off
	global_load_dword v236, v[134:135], off offset:64
	global_load_dword v105, v[134:135], off offset:128
	global_load_dword v101, v[134:135], off offset:192
	global_load_dword v231, v[134:135], off offset:512
	global_load_dword v232, v[134:135], off offset:576
	global_load_dword v233, v[134:135], off offset:640
	global_load_dword v234, v[134:135], off offset:704
	s_cmp_lt_u32 s93, 4
	s_cselect_b64 s[0:1], -1, 0
	s_cmp_gt_u32 s93, 3
	v_lshlrev_b32_e32 v235, 6, v102
	v_mov_b32_e32 v100, 1.0
	v_mov_b32_e32 v104, 0
	v_mov_b32_e32 v134, 0
	v_mov_b32_e32 v135, 0
	v_mov_b32_e32 v136, 0
	v_mov_b32_e32 v137, 0
	v_mov_b32_e32 v142, 0
	v_mov_b32_e32 v143, 0
	v_mov_b32_e32 v144, 0
	v_mov_b32_e32 v145, 0
	v_mov_b32_e32 v146, 0
	v_mov_b32_e32 v147, 0
	v_mov_b32_e32 v148, 0
	v_mov_b32_e32 v149, 0
	v_mov_b32_e32 v154, 0
	v_mov_b32_e32 v155, 0
	v_mov_b32_e32 v156, 0
	v_mov_b32_e32 v157, 0
	v_mov_b32_e32 v162, 0
	v_mov_b32_e32 v163, 0
	v_mov_b32_e32 v164, 0
	v_mov_b32_e32 v165, 0
	v_mov_b32_e32 v174, 0
	v_mov_b32_e32 v175, 0
	v_mov_b32_e32 v176, 0
	v_mov_b32_e32 v177, 0
	v_mov_b32_e32 v182, 0
	v_mov_b32_e32 v183, 0
	v_mov_b32_e32 v184, 0
	v_mov_b32_e32 v185, 0
	v_mov_b32_e32 v194, 0
	v_mov_b32_e32 v195, 0
	v_mov_b32_e32 v196, 0
	v_mov_b32_e32 v197, 0
	v_mov_b32_e32 v138, 1.0
	v_mov_b32_e32 v139, 1.0
	v_mov_b32_e32 v140, 1.0
	v_mov_b32_e32 v141, 1.0
	v_mov_b32_e32 v190, 1.0
	v_mov_b32_e32 v191, 1.0
	v_mov_b32_e32 v192, 1.0
	v_mov_b32_e32 v193, 1.0
	v_mov_b32_e32 v186, 1.0
	v_mov_b32_e32 v187, 1.0
	v_mov_b32_e32 v188, 1.0
	v_mov_b32_e32 v189, 1.0
	v_mov_b32_e32 v178, 1.0
	v_mov_b32_e32 v179, 1.0
	v_mov_b32_e32 v180, 1.0
	v_mov_b32_e32 v181, 1.0
	v_mov_b32_e32 v170, 1.0
	v_mov_b32_e32 v171, 1.0
	v_mov_b32_e32 v172, 1.0
	v_mov_b32_e32 v173, 1.0
	v_mov_b32_e32 v166, 1.0
	v_mov_b32_e32 v167, 1.0
	v_mov_b32_e32 v168, 1.0
	v_mov_b32_e32 v169, 1.0
	v_mov_b32_e32 v158, 1.0
	v_mov_b32_e32 v159, 1.0
	v_mov_b32_e32 v160, 1.0
	v_mov_b32_e32 v161, 1.0
	v_mov_b32_e32 v150, 1.0
	v_mov_b32_e32 v151, 1.0
	v_mov_b32_e32 v152, 1.0
	v_mov_b32_e32 v153, 1.0
	s_cbranch_scc1 .LBB0_277
	v_lshlrev_b32_e32 v134, 2, v235
	v_and_b32_e32 v134, 0x1fcf00, v134
	v_mov_b32_e32 v135, v207
	v_lshl_add_u64 v[136:137], v[208:209], 0, v[134:135]
	global_load_dwordx4 v[190:193], v[136:137], off
	global_load_dwordx4 v[186:189], v[136:137], off offset:16
	v_lshl_add_u64 v[136:137], v[210:211], 0, v[134:135]
	global_load_dwordx4 v[182:185], v[136:137], off offset:16
	global_load_dwordx4 v[194:197], v[136:137], off
	v_or_b32_e32 v136, 0x1000, v134
	v_mov_b32_e32 v137, v207
	v_lshl_add_u64 v[138:139], v[208:209], 0, v[136:137]
	v_lshl_add_u64 v[136:137], v[210:211], 0, v[136:137]
	global_load_dwordx4 v[178:181], v[138:139], off
	global_load_dwordx4 v[170:173], v[138:139], off offset:16
	global_load_dwordx4 v[162:165], v[136:137], off offset:16
	global_load_dwordx4 v[174:177], v[136:137], off
	v_or_b32_e32 v136, 0x2000, v134
	v_mov_b32_e32 v137, v207
	v_lshl_add_u64 v[138:139], v[208:209], 0, v[136:137]
	v_lshl_add_u64 v[136:137], v[210:211], 0, v[136:137]
	v_or_b32_e32 v134, 0x3000, v134
	global_load_dwordx4 v[166:169], v[138:139], off
	global_load_dwordx4 v[158:161], v[138:139], off offset:16
	global_load_dwordx4 v[146:149], v[136:137], off offset:16
	global_load_dwordx4 v[154:157], v[136:137], off
	v_lshl_add_u64 v[136:137], v[208:209], 0, v[134:135]
	v_lshl_add_u64 v[142:143], v[210:211], 0, v[134:135]
	global_load_dwordx4 v[138:141], v[136:137], off offset:16
	global_load_dwordx4 v[150:153], v[136:137], off
	s_nop 0
	global_load_dwordx4 v[134:137], v[142:143], off offset:16
	s_nop 0
	global_load_dwordx4 v[142:145], v[142:143], off

; #define PG8_STAGE(bufoff, gbase, voff) do { _Pragma("unroll") for (int _i = 0; _i < 2; ++_i) \
;         __builtin_amdgcn_global_load_lds((const unsigned*)((const char*)(gbase) + (voff)[_i]), (LAS unsigned*)(lds + (bufoff) + ldsw + _i * 8192), 16, 0, 0); } while (0)
; #define PG8_LDA(dst, b, h) do { _Pragma("unroll") for (int m = 0; m < 4; ++m) _Pragma("unroll") for (int k = 0; k < 2; ++k) dst[m][k] = *(const LAS bf16x8*)(lds + PG8_SA(b, h) + aoff + m * 2048 + k * 1024); } while (0)
; #define PG8_LDB(dst, b, h) do { _Pragma("unroll") for (int n = 0; n < 2; ++n) _Pragma("unroll") for (int k = 0; k < 2; ++k) dst[n][k] = *(const LAS bf16x8*)(lds + PG8_SB(b, h) + boff + n * 2048 + k * 1024); } while (0)
; #define PG8_MMA(ai, bj, At, Bt) do { __builtin_amdgcn_s_setprio(1); _Pragma("unroll") for (int m = 0; m < 4; ++m) _Pragma("unroll") for (int n = 0; n < 2; ++n) _Pragma("unroll") for (int k = 0; k < 2; ++k) \
;         acc[ai][bj][m][n] = __builtin_amdgcn_mfma_f32_16x16x32_bf16(Bt[n][k], At[m][k], acc[ai][bj][m][n], 0, 0, 0); __builtin_amdgcn_s_setprio(0); } while (0)
; #define PG8_WAIT_L(n) asm volatile("s_waitcnt lgkmcnt(" #n ")" ::: "memory")
; #define PG8_BAR __builtin_amdgcn_s_barrier()
; #define PG8_SCHED __builtin_amdgcn_sched_barrier(0)
; #define PG8_STAGE(bufoff, gbase, voff) do { _Pragma("unroll") for (int _i = 0; _i < 2; ++_i) \
;         __builtin_amdgcn_global_load_lds((const unsigned*)((const char*)(gbase) + (voff)[_i]), (LAS unsigned*)(lds + (bufoff) + ldsw + _i * 8192), 16, 0, 0); } while (0)
; #define PG8_LDA(dst, b, h) do { _Pragma("unroll") for (int m = 0; m < 4; ++m) _Pragma("unroll") for (int k = 0; k < 2; ++k) dst[m][k] = *(const LAS bf16x8*)(lds + PG8_SA(b, h) + aoff + m * 2048 + k * 1024); } while (0)
; template <class Epi>
; DI void gemm_phase(LAS unsigned char* lds, const Gemm g, const StaticOrder S, const Epi E) {
;     ...
;             PG8_LDB(B0, 0, 0); PG8_SCHED; PG8_LDA(At, 0, 0); PG8_STAGE(PG8_SA(1, 1), a1 + hstep, voffA);
;             PG8_WAIT_L(8); PG8_BAR; PG8_WAIT_L(0); PG8_MMA(0, 0, At, B0); PG8_BAR; PG8_SCHED;
;             PG8_LDB(B1, 0, 1); PG8_STAGE(PG8_SB(0, 0), b2, voffB);
;             PG8_BAR; PG8_WAIT_L(0); PG8_MMA(0, 1, At, B1); PG8_BAR;
;             PG8_LDA(At, 0, 1); PG8_STAGE(PG8_SA(0, 0), a2, voffA);
;             PG8_BAR; PG8_WAIT_L(0); PG8_MMA(1, 0, At, B0); PG8_BAR; PG8_SCHED;
.LBB0_298:
	ds_read_b128 v[128:131], v168
	ds_read_b128 v[132:135], v168 offset:1024
	ds_read_b128 v[154:157], v168 offset:2048
	ds_read_b128 v[158:161], v168 offset:3072
	s_add_u32 s5, s8, 0xfffc0080
	s_addc_u32 s14, s9, -1
	s_cmp_eq_u32 s4, 12
	s_cselect_b32 s81, s6, s14
	s_cselect_b32 s80, s7, s5
	s_cselect_b32 s79, s21, vcc_hi
	s_cselect_b32 s78, s23, vcc_lo
	v_lshl_add_u64 v[162:163], s[8:9], 0, v[146:147]
	s_add_i32 m0, s58, 0xc000
	ds_read_b128 v[172:175], v169
	ds_read_b128 v[180:183], v169 offset:2048
	ds_read_b128 v[188:191], v169 offset:4096
	ds_read_b128 v[196:199], v169 offset:6144
	global_load_lds_dwordx4 v[162:163], off
	v_lshl_add_u64 v[162:163], s[8:9], 0, v[148:149]
	s_add_i32 m0, s58, 0xe000
	s_nop 0
	global_load_lds_dwordx4 v[162:163], off
	s_waitcnt lgkmcnt(4)
	s_setprio 1
	s_barrier
	ds_read_b128 v[176:179], v169 offset:1024
	ds_read_b128 v[184:187], v169 offset:3072
	ds_read_b128 v[192:195], v169 offset:5120
	ds_read_b128 v[200:203], v169 offset:7168
	s_waitcnt lgkmcnt(4)
	v_mfma_f32_16x16x32_bf16 v[124:127], v[128:131], v[172:175], v[124:127]
	v_mfma_f32_16x16x32_bf16 v[120:123], v[154:157], v[172:175], v[120:123]
	v_mfma_f32_16x16x32_bf16 v[112:115], v[128:131], v[180:183], v[112:115]
	v_mfma_f32_16x16x32_bf16 v[104:107], v[154:157], v[180:183], v[104:107]
	v_mfma_f32_16x16x32_bf16 v[96:99], v[128:131], v[188:191], v[96:99]
	v_mfma_f32_16x16x32_bf16 v[88:91], v[154:157], v[188:191], v[88:91]
	v_mfma_f32_16x16x32_bf16 v[80:83], v[128:131], v[196:199], v[80:83]
	v_mfma_f32_16x16x32_bf16 v[72:75], v[154:157], v[196:199], v[72:75]
	s_waitcnt lgkmcnt(3)
	v_mfma_f32_16x16x32_bf16 v[124:127], v[132:135], v[176:179], v[124:127]
	v_mfma_f32_16x16x32_bf16 v[120:123], v[158:161], v[176:179], v[120:123]
	s_waitcnt lgkmcnt(2)
	v_mfma_f32_16x16x32_bf16 v[112:115], v[132:135], v[184:187], v[112:115]
	v_mfma_f32_16x16x32_bf16 v[104:107], v[158:161], v[184:187], v[104:107]
	s_waitcnt lgkmcnt(1)
	v_mfma_f32_16x16x32_bf16 v[96:99], v[132:135], v[192:195], v[96:99]
	v_mfma_f32_16x16x32_bf16 v[88:91], v[158:161], v[192:195], v[88:91]
	s_waitcnt lgkmcnt(0)
	s_setprio 2
	s_barrier
	v_mfma_f32_16x16x32_bf16 v[80:83], v[132:135], v[200:203], v[80:83]
	v_mfma_f32_16x16x32_bf16 v[72:75], v[158:161], v[200:203], v[72:75]
	s_setprio 0
	s_add_i32 s5, s94, s19
	v_lshl_add_u64 v[162:163], s[78:79], 0, v[138:139]
	s_mov_b32 m0, s5
	ds_read_b128 v[204:207], v170
	ds_read_b128 v[208:211], v170 offset:1024
	ds_read_b128 v[212:215], v170 offset:2048
	ds_read_b128 v[216:219], v170 offset:3072
	global_load_lds_dwordx4 v[162:163], off
	v_lshl_add_u64 v[220:221], s[78:79], 0, v[142:143]
	s_add_i32 m0, s5, 0x2000
	s_nop 0
	global_load_lds_dwordx4 v[220:221], off
	s_setprio 1
	s_barrier
	s_waitcnt lgkmcnt(0)
	v_mfma_f32_16x16x32_bf16 v[116:119], v[204:207], v[172:175], v[116:119]
	v_mfma_f32_16x16x32_bf16 v[108:111], v[212:215], v[172:175], v[108:111]
	v_mfma_f32_16x16x32_bf16 v[100:103], v[204:207], v[180:183], v[100:103]
	v_mfma_f32_16x16x32_bf16 v[92:95], v[212:215], v[180:183], v[92:95]
	v_mfma_f32_16x16x32_bf16 v[84:87], v[204:207], v[188:191], v[84:87]
	v_mfma_f32_16x16x32_bf16 v[76:79], v[212:215], v[188:191], v[76:79]
	v_mfma_f32_16x16x32_bf16 v[68:71], v[204:207], v[196:199], v[68:71]
	v_mfma_f32_16x16x32_bf16 v[64:67], v[212:215], v[196:199], v[64:67]
	v_mfma_f32_16x16x32_bf16 v[116:119], v[208:211], v[176:179], v[116:119]
	v_mfma_f32_16x16x32_bf16 v[108:111], v[216:219], v[176:179], v[108:111]
	v_mfma_f32_16x16x32_bf16 v[100:103], v[208:211], v[184:187], v[100:103]
	v_mfma_f32_16x16x32_bf16 v[92:95], v[216:219], v[184:187], v[92:95]
	v_mfma_f32_16x16x32_bf16 v[84:87], v[208:211], v[192:195], v[84:87]
	v_mfma_f32_16x16x32_bf16 v[76:79], v[216:219], v[192:195], v[76:79]
	s_setprio 2
	s_barrier
	v_mfma_f32_16x16x32_bf16 v[68:71], v[208:211], v[200:203], v[68:71]
	v_mfma_f32_16x16x32_bf16 v[64:67], v[216:219], v[200:203], v[64:67]
	s_setprio 0
	s_mov_b32 m0, s58
	v_lshl_add_u64 v[224:225], s[80:81], 0, v[136:137]
	ds_read_b128 v[172:175], v169 offset:16384
	ds_read_b128 v[180:183], v169 offset:18432
	ds_read_b128 v[188:191], v169 offset:20480
	ds_read_b128 v[196:199], v169 offset:22528
	global_load_lds_dwordx4 v[224:225], off
	v_lshl_add_u64 v[226:227], s[80:81], 0, v[140:141]
	s_mov_b32 m0, s59
	s_nop 0
	global_load_lds_dwordx4 v[226:227], off
	s_setprio 1
	s_barrier
	ds_read_b128 v[176:179], v169 offset:17408
	ds_read_b128 v[184:187], v169 offset:19456
	ds_read_b128 v[192:195], v169 offset:21504
	ds_read_b128 v[200:203], v169 offset:23552
	s_waitcnt lgkmcnt(4)
	v_mfma_f32_16x16x32_bf16 v[60:63], v[128:131], v[172:175], v[60:63]
	v_mfma_f32_16x16x32_bf16 v[56:59], v[154:157], v[172:175], v[56:59]
	v_mfma_f32_16x16x32_bf16 v[48:51], v[128:131], v[180:183], v[48:51]
	v_mfma_f32_16x16x32_bf16 v[40:43], v[154:157], v[180:183], v[40:43]
	v_mfma_f32_16x16x32_bf16 v[32:35], v[128:131], v[188:191], v[32:35]
	v_mfma_f32_16x16x32_bf16 v[24:27], v[154:157], v[188:191], v[24:27]
	v_mfma_f32_16x16x32_bf16 v[16:19], v[128:131], v[196:199], v[16:19]
	v_mfma_f32_16x16x32_bf16 v[8:11], v[154:157], v[196:199], v[8:11]
	s_waitcnt lgkmcnt(3)
	v_mfma_f32_16x16x32_bf16 v[60:63], v[132:135], v[176:179], v[60:63]
	v_mfma_f32_16x16x32_bf16 v[56:59], v[158:161], v[176:179], v[56:59]
	s_waitcnt lgkmcnt(2)
	v_mfma_f32_16x16x32_bf16 v[48:51], v[132:135], v[184:187], v[48:51]
	v_mfma_f32_16x16x32_bf16 v[40:43], v[158:161], v[184:187], v[40:43]
	s_waitcnt lgkmcnt(1)
	v_mfma_f32_16x16x32_bf16 v[32:35], v[132:135], v[192:195], v[32:35]
	v_mfma_f32_16x16x32_bf16 v[24:27], v[158:161], v[192:195], v[24:27]
	s_waitcnt lgkmcnt(0)
	s_setprio 2
	s_barrier
; #define PG8_STAGE(bufoff, gbase, voff) do { _Pragma("unroll") for (int _i = 0; _i < 2; ++_i) \
;         __builtin_amdgcn_global_load_lds((const unsigned*)((const char*)(gbase) + (voff)[_i]), (LAS unsigned*)(lds + (bufoff) + ldsw + _i * 8192), 16, 0, 0); } while (0)
; #define PG8_LDA(dst, b, h) do { _Pragma("unroll") for (int m = 0; m < 4; ++m) _Pragma("unroll") for (int k = 0; k < 2; ++k) dst[m][k] = *(const LAS bf16x8*)(lds + PG8_SA(b, h) + aoff + m * 2048 + k * 1024); } while (0)
; #define PG8_LDB(dst, b, h) do { _Pragma("unroll") for (int n = 0; n < 2; ++n) _Pragma("unroll") for (int k = 0; k < 2; ++k) dst[n][k] = *(const LAS bf16x8*)(lds + PG8_SB(b, h) + boff + n * 2048 + k * 1024); } while (0)
; #define PG8_MMA(ai, bj, At, Bt) do { __builtin_amdgcn_s_setprio(1); _Pragma("unroll") for (int m = 0; m < 4; ++m) _Pragma("unroll") for (int n = 0; n < 2; ++n) _Pragma("unroll") for (int k = 0; k < 2; ++k) \
;         acc[ai][bj][m][n] = __builtin_amdgcn_mfma_f32_16x16x32_bf16(Bt[n][k], At[m][k], acc[ai][bj][m][n], 0, 0, 0); __builtin_amdgcn_s_setprio(0); } while (0)
; #define PG8_WAIT_V(n) asm volatile("s_waitcnt vmcnt(" #n ")" ::: "memory")
; #define PG8_WAIT_L(n) asm volatile("s_waitcnt lgkmcnt(" #n ")" ::: "memory")
; #define PG8_BAR __builtin_amdgcn_s_barrier()
; #define PG8_SCHED __builtin_amdgcn_sched_barrier(0)
; #define PG8_STAGE(bufoff, gbase, voff) do { _Pragma("unroll") for (int _i = 0; _i < 2; ++_i) \
;         __builtin_amdgcn_global_load_lds((const unsigned*)((const char*)(gbase) + (voff)[_i]), (LAS unsigned*)(lds + (bufoff) + ldsw + _i * 8192), 16, 0, 0); } while (0)
; #define PG8_WAIT_V(n) asm volatile("s_waitcnt vmcnt(" #n ")" ::: "memory")
; template <class Epi>
; DI void gemm_phase(LAS unsigned char* lds, const Gemm g, const StaticOrder S, const Epi E) {
;     ...
;             PG8_BAR; PG8_WAIT_L(0); PG8_MMA(1, 0, At, B0); PG8_BAR; PG8_SCHED;
;             PG8_STAGE(PG8_SB(0, 1), b2 + hstep, voffB);
;             PG8_WAIT_V(6); PG8_BAR; PG8_MMA(1, 1, At, B1); PG8_BAR;
;             PG8_LDB(B0, 1, 0); PG8_SCHED; PG8_LDA(At, 1, 0); PG8_STAGE(PG8_SA(0, 1), a2 + hstep, voffA);
;             PG8_WAIT_L(8); PG8_BAR; PG8_WAIT_L(0); PG8_MMA(0, 0, At, B0); PG8_BAR; PG8_SCHED;
;             PG8_LDB(B1, 1, 1); PG8_STAGE(PG8_SB(1, 0), b3, voffB);
;             PG8_BAR; PG8_WAIT_L(0); PG8_MMA(0, 1, At, B1); PG8_BAR;
	v_mfma_f32_16x16x32_bf16 v[16:19], v[132:135], v[200:203], v[16:19]
	v_mfma_f32_16x16x32_bf16 v[8:11], v[158:161], v[200:203], v[8:11]
	s_setprio 0
	s_add_u32 s14, s78, 0x40000
	s_addc_u32 s15, s79, 0
	s_add_i32 s5, s95, s19
	v_lshl_add_u64 v[128:129], s[14:15], 0, v[138:139]
	s_mov_b32 m0, s5
	s_nop 0
	global_load_lds_dwordx4 v[128:129], off
	v_lshl_add_u64 v[128:129], s[14:15], 0, v[142:143]
	s_add_i32 m0, s5, 0x2000
	s_nop 0
	global_load_lds_dwordx4 v[128:129], off
	s_waitcnt vmcnt(6)
	s_setprio 1
	s_barrier
	v_mfma_f32_16x16x32_bf16 v[52:55], v[204:207], v[172:175], v[52:55]
	v_mfma_f32_16x16x32_bf16 v[44:47], v[212:215], v[172:175], v[44:47]
	v_mfma_f32_16x16x32_bf16 v[36:39], v[204:207], v[180:183], v[36:39]
	v_mfma_f32_16x16x32_bf16 v[28:31], v[212:215], v[180:183], v[28:31]
	v_mfma_f32_16x16x32_bf16 v[20:23], v[204:207], v[188:191], v[20:23]
	v_mfma_f32_16x16x32_bf16 v[12:15], v[212:215], v[188:191], v[12:15]
	v_mfma_f32_16x16x32_bf16 v[4:7], v[204:207], v[196:199], v[4:7]
	v_mfma_f32_16x16x32_bf16 v[0:3], v[212:215], v[196:199], v[0:3]
	v_mfma_f32_16x16x32_bf16 v[52:55], v[208:211], v[176:179], v[52:55]
	v_mfma_f32_16x16x32_bf16 v[44:47], v[216:219], v[176:179], v[44:47]
	v_mfma_f32_16x16x32_bf16 v[36:39], v[208:211], v[184:187], v[36:39]
	v_mfma_f32_16x16x32_bf16 v[28:31], v[216:219], v[184:187], v[28:31]
	v_mfma_f32_16x16x32_bf16 v[20:23], v[208:211], v[192:195], v[20:23]
	v_mfma_f32_16x16x32_bf16 v[12:15], v[216:219], v[192:195], v[12:15]
	s_setprio 2
	s_barrier
	v_mfma_f32_16x16x32_bf16 v[4:7], v[208:211], v[200:203], v[4:7]
	v_mfma_f32_16x16x32_bf16 v[0:3], v[216:219], v[200:203], v[0:3]
	s_setprio 0
	s_add_i32 s5, 0, 0x18000
	v_add_u32_e32 v158, s5, v165
	ds_read_b128 v[128:131], v158
	ds_read_b128 v[132:135], v158 offset:1024
	ds_read_b128 v[154:157], v158 offset:2048
	ds_read_b128 v[158:161], v158 offset:3072
	s_add_u32 s14, s80, 0x40000
	s_addc_u32 s15, s81, 0
	s_mov_b32 m0, s77
	v_lshl_add_u64 v[204:205], s[14:15], 0, v[136:137]
	ds_read_b128 v[172:175], v169 offset:32768
	ds_read_b128 v[180:183], v169 offset:34816
	ds_read_b128 v[188:191], v169 offset:36864
	ds_read_b128 v[196:199], v169 offset:38912
	global_load_lds_dwordx4 v[204:205], off
	v_lshl_add_u64 v[204:205], s[14:15], 0, v[140:141]
	s_mov_b32 m0, s82
	s_nop 0
	global_load_lds_dwordx4 v[204:205], off
	s_waitcnt lgkmcnt(4)
	s_setprio 1
	s_barrier
	ds_read_b128 v[176:179], v169 offset:33792
	ds_read_b128 v[184:187], v169 offset:35840
	ds_read_b128 v[192:195], v169 offset:37888
	ds_read_b128 v[200:203], v169 offset:39936
	s_waitcnt lgkmcnt(4)
	v_mfma_f32_16x16x32_bf16 v[124:127], v[128:131], v[172:175], v[124:127]
	v_mfma_f32_16x16x32_bf16 v[120:123], v[154:157], v[172:175], v[120:123]
	v_mfma_f32_16x16x32_bf16 v[112:115], v[128:131], v[180:183], v[112:115]
	v_mfma_f32_16x16x32_bf16 v[104:107], v[154:157], v[180:183], v[104:107]
	v_mfma_f32_16x16x32_bf16 v[96:99], v[128:131], v[188:191], v[96:99]
	v_mfma_f32_16x16x32_bf16 v[88:91], v[154:157], v[188:191], v[88:91]
	v_mfma_f32_16x16x32_bf16 v[80:83], v[128:131], v[196:199], v[80:83]
	v_mfma_f32_16x16x32_bf16 v[72:75], v[154:157], v[196:199], v[72:75]
	s_waitcnt lgkmcnt(3)
	v_mfma_f32_16x16x32_bf16 v[124:127], v[132:135], v[176:179], v[124:127]
	v_mfma_f32_16x16x32_bf16 v[120:123], v[158:161], v[176:179], v[120:123]
	s_waitcnt lgkmcnt(2)
	v_mfma_f32_16x16x32_bf16 v[112:115], v[132:135], v[184:187], v[112:115]
	v_mfma_f32_16x16x32_bf16 v[104:107], v[158:161], v[184:187], v[104:107]
	s_waitcnt lgkmcnt(1)
	v_mfma_f32_16x16x32_bf16 v[96:99], v[132:135], v[192:195], v[96:99]
	v_mfma_f32_16x16x32_bf16 v[88:91], v[158:161], v[192:195], v[88:91]
	s_waitcnt lgkmcnt(0)
	s_setprio 2
	s_barrier
	v_mfma_f32_16x16x32_bf16 v[80:83], v[132:135], v[200:203], v[80:83]
	v_mfma_f32_16x16x32_bf16 v[72:75], v[158:161], v[200:203], v[72:75]
	s_setprio 0
	s_add_i32 s35, 0, 0x1c000
	s_add_i32 s5, s5, s19
	v_add_u32_e32 v171, s35, v165
	v_lshl_add_u64 v[162:163], v[162:163], 0, s[10:11]
	s_mov_b32 m0, s5
	ds_read_b128 v[204:207], v171
	ds_read_b128 v[208:211], v171 offset:1024
	ds_read_b128 v[212:215], v171 offset:2048
	ds_read_b128 v[216:219], v171 offset:3072
	global_load_lds_dwordx4 v[162:163], off
	v_lshl_add_u64 v[162:163], v[220:221], 0, s[10:11]
	s_add_i32 m0, s5, 0x2000
	s_nop 0
	global_load_lds_dwordx4 v[162:163], off
	s_setprio 1
	s_barrier
	s_waitcnt lgkmcnt(0)
	v_mfma_f32_16x16x32_bf16 v[116:119], v[204:207], v[172:175], v[116:119]
	v_mfma_f32_16x16x32_bf16 v[108:111], v[212:215], v[172:175], v[108:111]
	v_mfma_f32_16x16x32_bf16 v[100:103], v[204:207], v[180:183], v[100:103]
	v_mfma_f32_16x16x32_bf16 v[92:95], v[212:215], v[180:183], v[92:95]
	v_mfma_f32_16x16x32_bf16 v[84:87], v[204:207], v[188:191], v[84:87]
	v_mfma_f32_16x16x32_bf16 v[76:79], v[212:215], v[188:191], v[76:79]
	v_mfma_f32_16x16x32_bf16 v[68:71], v[204:207], v[196:199], v[68:71]
	v_mfma_f32_16x16x32_bf16 v[64:67], v[212:215], v[196:199], v[64:67]
	v_mfma_f32_16x16x32_bf16 v[116:119], v[208:211], v[176:179], v[116:119]
	v_mfma_f32_16x16x32_bf16 v[108:111], v[216:219], v[176:179], v[108:111]
	v_mfma_f32_16x16x32_bf16 v[100:103], v[208:211], v[184:187], v[100:103]
	v_mfma_f32_16x16x32_bf16 v[92:95], v[216:219], v[184:187], v[92:95]
	v_mfma_f32_16x16x32_bf16 v[84:87], v[208:211], v[192:195], v[84:87]
	v_mfma_f32_16x16x32_bf16 v[76:79], v[216:219], v[192:195], v[76:79]
	s_setprio 2
	s_barrier
; #define PG8_STAGE(bufoff, gbase, voff) do { _Pragma("unroll") for (int _i = 0; _i < 2; ++_i) \
;         __builtin_amdgcn_global_load_lds((const unsigned*)((const char*)(gbase) + (voff)[_i]), (LAS unsigned*)(lds + (bufoff) + ldsw + _i * 8192), 16, 0, 0); } while (0)
; #define PG8_LDA(dst, b, h) do { _Pragma("unroll") for (int m = 0; m < 4; ++m) _Pragma("unroll") for (int k = 0; k < 2; ++k) dst[m][k] = *(const LAS bf16x8*)(lds + PG8_SA(b, h) + aoff + m * 2048 + k * 1024); } while (0)
; #define PG8_MMA(ai, bj, At, Bt) do { __builtin_amdgcn_s_setprio(1); _Pragma("unroll") for (int m = 0; m < 4; ++m) _Pragma("unroll") for (int n = 0; n < 2; ++n) _Pragma("unroll") for (int k = 0; k < 2; ++k) \
;         acc[ai][bj][m][n] = __builtin_amdgcn_mfma_f32_16x16x32_bf16(Bt[n][k], At[m][k], acc[ai][bj][m][n], 0, 0, 0); __builtin_amdgcn_s_setprio(0); } while (0)
; #define PG8_WAIT_V(n) asm volatile("s_waitcnt vmcnt(" #n ")" ::: "memory")
; #define PG8_WAIT_L(n) asm volatile("s_waitcnt lgkmcnt(" #n ")" ::: "memory")
; #define PG8_BAR __builtin_amdgcn_s_barrier()
; #define PG8_SCHED __builtin_amdgcn_sched_barrier(0)
; #define PG8_STAGE(bufoff, gbase, voff) do { _Pragma("unroll") for (int _i = 0; _i < 2; ++_i) \
;         __builtin_amdgcn_global_load_lds((const unsigned*)((const char*)(gbase) + (voff)[_i]), (LAS unsigned*)(lds + (bufoff) + ldsw + _i * 8192), 16, 0, 0); } while (0)
; #define PG8_LDA(dst, b, h) do { _Pragma("unroll") for (int m = 0; m < 4; ++m) _Pragma("unroll") for (int k = 0; k < 2; ++k) dst[m][k] = *(const LAS bf16x8*)(lds + PG8_SA(b, h) + aoff + m * 2048 + k * 1024); } while (0)
; #define PG8_WAIT_V(n) asm volatile("s_waitcnt vmcnt(" #n ")" ::: "memory")
; template <class Epi>
; DI void gemm_phase(LAS unsigned char* lds, const Gemm g, const StaticOrder S, const Epi E) {
;     ...
;             PG8_LDA(At, 1, 1); PG8_STAGE(PG8_SA(1, 0), a3, voffA);
;             PG8_BAR; PG8_WAIT_L(0); PG8_MMA(1, 0, At, B0); PG8_BAR; PG8_SCHED;
;             PG8_STAGE(PG8_SB(1, 1), b3 + hstep, voffB);
;             PG8_WAIT_V(6); PG8_BAR; PG8_MMA(1, 1, At, B1); PG8_BAR;
;         }
;     DI void operator()(AccRef acc, const Unit& u, int wr, int wc, int fr, int fq) const {
;     ...
;         for (int bj = 0; bj < 2; ++bj) { const int tok = u.pn * 256 + bj * 128 + wc * 32 + 8 * fq; ts[bj][0] = *(const f32x4*)(ss + tok); ts[bj][1] = *(const f32x4*)(ss + tok + 4); }
	v_mfma_f32_16x16x32_bf16 v[68:71], v[208:211], v[200:203], v[68:71]
	v_mfma_f32_16x16x32_bf16 v[64:67], v[216:219], v[200:203], v[64:67]
	s_setprio 0
	s_mov_b32 m0, s86
	v_lshl_add_u64 v[162:163], v[224:225], 0, s[10:11]
	ds_read_b128 v[172:175], v169 offset:49152
	ds_read_b128 v[180:183], v169 offset:51200
	ds_read_b128 v[188:191], v169 offset:53248
	ds_read_b128 v[196:199], v169 offset:55296
	global_load_lds_dwordx4 v[162:163], off
	v_lshl_add_u64 v[162:163], v[226:227], 0, s[10:11]
	s_mov_b32 m0, s87
	s_nop 0
	global_load_lds_dwordx4 v[162:163], off
	s_setprio 1
	s_barrier
	ds_read_b128 v[176:179], v169 offset:50176
	ds_read_b128 v[184:187], v169 offset:52224
	ds_read_b128 v[192:195], v169 offset:54272
	ds_read_b128 v[200:203], v169 offset:56320
	s_waitcnt lgkmcnt(4)
	v_mfma_f32_16x16x32_bf16 v[60:63], v[128:131], v[172:175], v[60:63]
	v_mfma_f32_16x16x32_bf16 v[56:59], v[154:157], v[172:175], v[56:59]
	v_mfma_f32_16x16x32_bf16 v[48:51], v[128:131], v[180:183], v[48:51]
	v_mfma_f32_16x16x32_bf16 v[40:43], v[154:157], v[180:183], v[40:43]
	v_mfma_f32_16x16x32_bf16 v[32:35], v[128:131], v[188:191], v[32:35]
	v_mfma_f32_16x16x32_bf16 v[24:27], v[154:157], v[188:191], v[24:27]
	v_mfma_f32_16x16x32_bf16 v[16:19], v[128:131], v[196:199], v[16:19]
	v_mfma_f32_16x16x32_bf16 v[8:11], v[154:157], v[196:199], v[8:11]
	s_waitcnt lgkmcnt(3)
	v_mfma_f32_16x16x32_bf16 v[60:63], v[132:135], v[176:179], v[60:63]
	v_mfma_f32_16x16x32_bf16 v[56:59], v[158:161], v[176:179], v[56:59]
	s_waitcnt lgkmcnt(2)
	v_mfma_f32_16x16x32_bf16 v[48:51], v[132:135], v[184:187], v[48:51]
	v_mfma_f32_16x16x32_bf16 v[40:43], v[158:161], v[184:187], v[40:43]
	s_waitcnt lgkmcnt(1)
	v_mfma_f32_16x16x32_bf16 v[32:35], v[132:135], v[192:195], v[32:35]
	v_mfma_f32_16x16x32_bf16 v[24:27], v[158:161], v[192:195], v[24:27]
	s_waitcnt lgkmcnt(0)
	s_setprio 2
	s_barrier
	v_mfma_f32_16x16x32_bf16 v[16:19], v[132:135], v[200:203], v[16:19]
	v_mfma_f32_16x16x32_bf16 v[8:11], v[158:161], v[200:203], v[8:11]
	s_setprio 0
	s_add_u32 s14, s78, 0x40080
	s_addc_u32 s15, s79, 0
	s_add_i32 s5, s35, s19
	v_lshl_add_u64 v[128:129], s[14:15], 0, v[138:139]
	s_mov_b32 m0, s5
	s_nop 0
	global_load_lds_dwordx4 v[128:129], off
	v_lshl_add_u64 v[128:129], s[14:15], 0, v[142:143]
	s_add_i32 m0, s5, 0x2000
	s_nop 0
	global_load_lds_dwordx4 v[128:129], off
	s_waitcnt vmcnt(6)
	s_setprio 1
	s_barrier
	v_mfma_f32_16x16x32_bf16 v[52:55], v[204:207], v[172:175], v[52:55]
	v_mfma_f32_16x16x32_bf16 v[44:47], v[212:215], v[172:175], v[44:47]
	v_mfma_f32_16x16x32_bf16 v[36:39], v[204:207], v[180:183], v[36:39]
	v_mfma_f32_16x16x32_bf16 v[28:31], v[212:215], v[180:183], v[28:31]
	v_mfma_f32_16x16x32_bf16 v[20:23], v[204:207], v[188:191], v[20:23]
	v_mfma_f32_16x16x32_bf16 v[12:15], v[212:215], v[188:191], v[12:15]
	v_mfma_f32_16x16x32_bf16 v[4:7], v[204:207], v[196:199], v[4:7]
	v_mfma_f32_16x16x32_bf16 v[0:3], v[212:215], v[196:199], v[0:3]
	v_mfma_f32_16x16x32_bf16 v[52:55], v[208:211], v[176:179], v[52:55]
	v_mfma_f32_16x16x32_bf16 v[44:47], v[216:219], v[176:179], v[44:47]
	v_mfma_f32_16x16x32_bf16 v[36:39], v[208:211], v[184:187], v[36:39]
	v_mfma_f32_16x16x32_bf16 v[28:31], v[216:219], v[184:187], v[28:31]
	v_mfma_f32_16x16x32_bf16 v[20:23], v[208:211], v[192:195], v[20:23]
	v_mfma_f32_16x16x32_bf16 v[12:15], v[216:219], v[192:195], v[12:15]
	s_setprio 2
	s_barrier
	v_mfma_f32_16x16x32_bf16 v[4:7], v[208:211], v[200:203], v[4:7]
	v_mfma_f32_16x16x32_bf16 v[0:3], v[216:219], v[200:203], v[0:3]
	s_setprio 0
	s_add_i32 s4, s4, 2
	s_add_u32 s8, s8, 0x100
	s_addc_u32 s9, s9, 0
	s_add_u32 vcc_lo, vcc_lo, 0x100
	s_addc_u32 vcc_hi, vcc_hi, 0
	s_cmp_gt_u32 s4, 13
	s_cbranch_scc0 .LBB0_298
	s_lshl_b32 s4, s97, 8
	v_or_b32_e32 v128, s4, v166
	v_ashrrev_i32_e32 v129, 31, v128
	v_lshl_add_u64 v[132:133], v[128:129], 2, s[60:61]
	global_load_dwordx4 v[158:161], v[132:133], off offset:16
	global_load_dwordx4 v[154:157], v[132:133], off
	global_load_dwordx4 v[128:131], v[132:133], off offset:528
	s_nop 0
	global_load_dwordx4 v[132:135], v[132:133], off offset:512
	s_mov_b32 s6, 0x358637bd
	v_mov_b64_e32 v[162:163], s[6:7]
	s_lshl_b32 s6, s76, 8
	s_add_i32 s6, s6, s84
	s_lshr_b32 s5, s97, 3
	s_and_b32 s7, s5, 0x1fffc
	s_bfe_u32 s5, s6, 0x20008
	s_or_b32 s4, s4, s85
	s_or_b32 s5, s5, s7
	s_cmpk_lt_u32 s6, 0x400
	s_mov_b32 s97, s20
	s_mov_b32 s76, s22
	s_mov_b64 s[78:79], s[28:29]
	s_waitcnt vmcnt(0)
; DI unsigned pk_bf16(float lo, float hi) { f32x2 v = {lo, hi}; return __builtin_bit_cast(unsigned, __builtin_convertvector(v, bf16v2)); }
;     DI void operator()(AccRef acc, const Unit& u, int wr, int wc, int fr, int fq) const {
;     ...
;         for (int bj = 0; bj < 2; ++bj) { const int tok = u.pn * 256 + bj * 128 + wc * 32 + 8 * fq; ts[bj][0] = *(const f32x4*)(ss + tok); ts[bj][1] = *(const f32x4*)(ss + tok + 4); }
; #pragma unroll
;         for (int bj = 0; bj < 2; ++bj)
; #pragma unroll
;             for (int n = 0; n < 2; ++n)
; #pragma unroll
;                 for (int e = 0; e < 4; ++e) ts[bj][n][e] = rsqrtf(ts[bj][n][e] * (1.0f / 1024.0f) + 1e-6f);
; #pragma unroll
;         for (int ai = 0; ai < 2; ++ai)
; #pragma unroll
;             for (int m = 0; m < 4; ++m) {
;                 const int R = u.pm * 256 + ai * 128 + wr * 64 + m * 16 + fr, X = R >> 10, hv = R & 1023;
; #pragma unroll
;                 for (int bj = 0; bj < 2; ++bj) {
;                     const int tok = u.pn * 256 + bj * 128 + wc * 32 + 8 * fq, b = tok >> 13, s = tok & (SEQ - 1);
;                     bf16_t* dst = (X ? vtB : vtA) + ((size_t)(((b * 4 + (hv >> 8)) * 128 + (s >> 6)) * 256 + (hv & 255))) * 64 + (s & 63);
;                     const f32x4 v0 = acc[ai][bj][m][0] * ts[bj][0], v1 = acc[ai][bj][m][1] * ts[bj][1];
;                     u32x4 w; w.x = pk_bf16(v0[0], v0[1]); w.y = pk_bf16(v0[2], v0[3]); w.z = pk_bf16(v1[0], v1[1]); w.w = pk_bf16(v1[2], v1[3]);
;                     *(u32x4*)dst = w;
	v_pk_fma_f32 v[158:159], v[158:159], s[16:17], v[162:163] op_sel_hi:[1,0,0]
	v_pk_fma_f32 v[154:155], v[154:155], s[16:17], v[162:163] op_sel_hi:[1,0,0]
	v_pk_fma_f32 v[156:157], v[156:157], s[16:17], v[162:163] op_sel_hi:[1,0,0]
	v_mul_f32_e32 v171, 0x4b800000, v154
	v_cmp_gt_f32_e64 s[8:9], s96, v154
	v_cmp_gt_f32_e32 vcc, s96, v155
	v_pk_fma_f32 v[160:161], v[160:161], s[16:17], v[162:163] op_sel_hi:[1,0,0]
	v_cndmask_b32_e64 v154, v154, v171, s[8:9]
	v_mul_f32_e32 v171, 0x4b800000, v155
	v_cndmask_b32_e32 v155, v155, v171, vcc
	v_rsq_f32_e32 v154, v154
	v_rsq_f32_e32 v155, v155
	v_mul_f32_e32 v171, 0x4b800000, v156
	v_pk_fma_f32 v[132:133], v[132:133], s[16:17], v[162:163] op_sel_hi:[1,0,0]
	v_pk_fma_f32 v[134:135], v[134:135], s[16:17], v[162:163] op_sel_hi:[1,0,0]
	v_pk_mul_f32 v[172:173], v[154:155], s[18:19] op_sel_hi:[1,0]
	v_pk_fma_f32 v[128:129], v[128:129], s[16:17], v[162:163] op_sel_hi:[1,0,0]
	v_cndmask_b32_e64 v154, v154, v172, s[8:9]
	v_cmp_gt_f32_e64 s[8:9], s96, v156
	v_cndmask_b32_e32 v155, v155, v173, vcc
	v_cmp_gt_f32_e32 vcc, s96, v157
	v_cndmask_b32_e64 v156, v156, v171, s[8:9]
	v_mul_f32_e32 v171, 0x4b800000, v157
	v_cndmask_b32_e32 v157, v157, v171, vcc
	v_rsq_f32_e32 v156, v156
	v_rsq_f32_e32 v157, v157
	v_mul_f32_e32 v171, 0x4b800000, v158
	v_pk_fma_f32 v[130:131], v[130:131], s[16:17], v[162:163] op_sel_hi:[1,0,0]
	v_pk_mul_f32 v[124:125], v[124:125], v[154:155]
	v_pk_mul_f32 v[172:173], v[156:157], s[18:19] op_sel_hi:[1,0]
	v_mul_f32_e32 v162, 0x4b800000, v130
	v_cndmask_b32_e64 v156, v156, v172, s[8:9]
	v_cmp_gt_f32_e64 s[8:9], s96, v158
	v_cndmask_b32_e32 v157, v157, v173, vcc
	v_cmp_gt_f32_e32 vcc, s96, v159
	v_cndmask_b32_e64 v158, v158, v171, s[8:9]
	v_mul_f32_e32 v171, 0x4b800000, v159
	v_cndmask_b32_e32 v159, v159, v171, vcc
	v_rsq_f32_e32 v158, v158
	v_rsq_f32_e32 v159, v159
	v_mul_f32_e32 v171, 0x4b800000, v160
	v_pk_mul_f32 v[126:127], v[126:127], v[156:157]
	v_pk_mul_f32 v[112:113], v[112:113], v[154:155]
	v_pk_mul_f32 v[172:173], v[158:159], s[18:19] op_sel_hi:[1,0]
	v_pk_mul_f32 v[96:97], v[96:97], v[154:155]
	v_cndmask_b32_e64 v158, v158, v172, s[8:9]
	v_cmp_gt_f32_e64 s[8:9], s96, v160
	v_cndmask_b32_e32 v159, v159, v173, vcc
	v_cmp_gt_f32_e32 vcc, s96, v161
	v_cndmask_b32_e64 v160, v160, v171, s[8:9]
	v_mul_f32_e32 v171, 0x4b800000, v161
	v_cndmask_b32_e32 v161, v161, v171, vcc
	v_rsq_f32_e32 v160, v160
	v_rsq_f32_e32 v161, v161
	v_mul_f32_e32 v171, 0x4b800000, v132
	v_pk_mul_f32 v[80:81], v[80:81], v[154:155]
	v_pk_mul_f32 v[62:63], v[62:63], v[156:157]
	v_pk_mul_f32 v[172:173], v[160:161], s[18:19] op_sel_hi:[1,0]
	v_pk_mul_f32 v[60:61], v[60:61], v[154:155]
	v_cndmask_b32_e64 v160, v160, v172, s[8:9]
	v_cmp_gt_f32_e64 s[8:9], s96, v132
	v_cndmask_b32_e32 v161, v161, v173, vcc
	v_cmp_gt_f32_e32 vcc, s96, v133
	v_cndmask_b32_e64 v132, v132, v171, s[8:9]
	v_mul_f32_e32 v171, 0x4b800000, v133
	v_cndmask_b32_e32 v133, v133, v171, vcc
	v_rsq_f32_e32 v132, v132
	v_rsq_f32_e32 v133, v133
	v_mul_f32_e32 v171, 0x4b800000, v134
	v_pk_mul_f32 v[48:49], v[48:49], v[154:155]
	v_pk_mul_f32 v[32:33], v[32:33], v[154:155]
	v_pk_mul_f32 v[172:173], v[132:133], s[18:19] op_sel_hi:[1,0]
	v_pk_mul_f32 v[16:17], v[16:17], v[154:155]
	v_cndmask_b32_e64 v132, v132, v172, s[8:9]
	v_cmp_gt_f32_e64 s[8:9], s96, v134
	v_cndmask_b32_e32 v133, v133, v173, vcc
	v_cmp_gt_f32_e32 vcc, s96, v135
	v_cndmask_b32_e64 v134, v134, v171, s[8:9]
	v_mul_f32_e32 v171, 0x4b800000, v135
	v_cndmask_b32_e32 v135, v135, v171, vcc
	v_rsq_f32_e32 v134, v134
	v_rsq_f32_e32 v135, v135
	v_mul_f32_e32 v171, 0x4b800000, v128
	v_pk_mul_f32 v[116:117], v[116:117], v[132:133]
	v_pk_mul_f32 v[100:101], v[100:101], v[132:133]
	v_pk_mul_f32 v[172:173], v[134:135], s[18:19] op_sel_hi:[1,0]
	v_pk_mul_f32 v[84:85], v[84:85], v[132:133]
	v_cndmask_b32_e64 v134, v134, v172, s[8:9]
	v_cmp_gt_f32_e64 s[8:9], s96, v128
	v_cndmask_b32_e32 v135, v135, v173, vcc
	v_cmp_gt_f32_e32 vcc, s96, v129
	v_cndmask_b32_e64 v128, v128, v171, s[8:9]
	v_mul_f32_e32 v171, 0x4b800000, v129
	v_cndmask_b32_e32 v129, v129, v171, vcc
	v_rsq_f32_e32 v128, v128
	v_rsq_f32_e32 v129, v129
	v_lshl_or_b32 v171, s5, 15, v167
	v_pk_mul_f32 v[118:119], v[118:119], v[134:135]
	v_pk_mul_f32 v[102:103], v[102:103], v[134:135]
	v_pk_mul_f32 v[172:173], v[128:129], s[18:19] op_sel_hi:[1,0]
	v_pk_mul_f32 v[86:87], v[86:87], v[134:135]
	v_cndmask_b32_e64 v128, v128, v172, s[8:9]
	v_cmp_gt_f32_e64 s[8:9], s96, v130
	v_cndmask_b32_e32 v129, v129, v173, vcc
	v_cmp_gt_f32_e32 vcc, s96, v131
	v_cndmask_b32_e64 v130, v130, v162, s[8:9]
	v_mul_f32_e32 v162, 0x4b800000, v131
	v_cndmask_b32_e32 v131, v131, v162, vcc
	v_rsq_f32_e32 v130, v130
	v_rsq_f32_e32 v131, v131
	v_pk_mul_f32 v[172:173], v[122:123], v[160:161]
	v_pk_mul_f32 v[122:123], v[120:121], v[158:159]
	v_cvt_pk_bf16_f32 v120, v124, v125
	v_pk_mul_f32 v[162:163], v[130:131], s[18:19] op_sel_hi:[1,0]
	v_cvt_pk_bf16_f32 v121, v126, v127
	v_cndmask_b32_e64 v130, v130, v162, s[8:9]
	s_cselect_b32 s9, s53, s91
	s_cselect_b32 s8, s52, s90
	s_lshl_b32 s4, s4, 2
	s_and_b32 s4, s4, 0x7d00
	v_or_b32_e32 v162, s4, v171
	v_cndmask_b32_e32 v131, v131, v163, vcc
	v_ashrrev_i32_e32 v163, 31, v162
	v_lshlrev_b64 v[162:163], 7, v[162:163]
	v_lshl_add_u64 v[162:163], s[8:9], 0, v[162:163]
	v_lshl_add_u64 v[162:163], v[162:163], 0, v[144:145]
	v_cvt_pk_bf16_f32 v122, v122, v123
	v_cvt_pk_bf16_f32 v123, v172, v173
	s_or_b32 s5, s4, 0x200
	global_store_dwordx4 v[162:163], v[120:123], off
	s_addk_i32 s6, 0x80
	v_pk_mul_f32 v[70:71], v[70:71], v[134:135]
	v_or_b32_e32 v120, s5, v171
	v_ashrrev_i32_e32 v121, 31, v120
	v_lshlrev_b64 v[120:121], 7, v[120:121]
; DI unsigned pk_bf16(float lo, float hi) { f32x2 v = {lo, hi}; return __builtin_bit_cast(unsigned, __builtin_convertvector(v, bf16v2)); }
;     DI void operator()(AccRef acc, const Unit& u, int wr, int wc, int fr, int fq) const {
;     ...
;         for (int ai = 0; ai < 2; ++ai)
; #pragma unroll
;             for (int m = 0; m < 4; ++m) {
;                 const int R = u.pm * 256 + ai * 128 + wr * 64 + m * 16 + fr, X = R >> 10, hv = R & 1023;
; #pragma unroll
;                 for (int bj = 0; bj < 2; ++bj) {
;                     const int tok = u.pn * 256 + bj * 128 + wc * 32 + 8 * fq, b = tok >> 13, s = tok & (SEQ - 1);
;                     bf16_t* dst = (X ? vtB : vtA) + ((size_t)(((b * 4 + (hv >> 8)) * 128 + (s >> 6)) * 256 + (hv & 255))) * 64 + (s & 63);
;                     const f32x4 v0 = acc[ai][bj][m][0] * ts[bj][0], v1 = acc[ai][bj][m][1] * ts[bj][1];
;                     u32x4 w; w.x = pk_bf16(v0[0], v0[1]); w.y = pk_bf16(v0[2], v0[3]); w.z = pk_bf16(v1[0], v1[1]); w.w = pk_bf16(v1[2], v1[3]);
;                     *(u32x4*)dst = w;
	v_lshl_add_u64 v[120:121], s[8:9], 0, v[120:121]
	v_pk_mul_f32 v[122:123], v[110:111], v[130:131]
	v_pk_mul_f32 v[110:111], v[108:109], v[128:129]
	v_lshl_add_u64 v[120:121], v[120:121], 0, v[144:145]
	v_cvt_pk_bf16_f32 v108, v116, v117
	v_cvt_pk_bf16_f32 v109, v118, v119
	v_cvt_pk_bf16_f32 v110, v110, v111
	v_cvt_pk_bf16_f32 v111, v122, v123
	v_or_b32_e32 v116, 16, v171
	global_store_dwordx4 v[120:121], v[108:111], off
	v_pk_mul_f32 v[68:69], v[68:69], v[132:133]
	v_pk_mul_f32 v[54:55], v[54:55], v[134:135]
	v_or_b32_e32 v108, s4, v116
	v_ashrrev_i32_e32 v109, 31, v108
	v_lshlrev_b64 v[108:109], 7, v[108:109]
	v_lshl_add_u64 v[108:109], s[8:9], 0, v[108:109]
	v_pk_mul_f32 v[110:111], v[114:115], v[156:157]
	v_pk_mul_f32 v[114:115], v[106:107], v[160:161]
	v_pk_mul_f32 v[106:107], v[104:105], v[158:159]
	v_lshl_add_u64 v[108:109], v[108:109], 0, v[144:145]
	v_cvt_pk_bf16_f32 v104, v112, v113
	v_cvt_pk_bf16_f32 v105, v110, v111
	v_cvt_pk_bf16_f32 v106, v106, v107
	v_cvt_pk_bf16_f32 v107, v114, v115
	global_store_dwordx4 v[108:109], v[104:107], off
	v_pk_mul_f32 v[52:53], v[52:53], v[132:133]
	v_pk_mul_f32 v[38:39], v[38:39], v[134:135]
	v_or_b32_e32 v104, s5, v116
	v_ashrrev_i32_e32 v105, 31, v104
	v_lshlrev_b64 v[104:105], 7, v[104:105]
	v_lshl_add_u64 v[104:105], s[8:9], 0, v[104:105]
	v_pk_mul_f32 v[106:107], v[94:95], v[130:131]
	v_pk_mul_f32 v[94:95], v[92:93], v[128:129]
	v_lshl_add_u64 v[104:105], v[104:105], 0, v[144:145]
	v_cvt_pk_bf16_f32 v92, v100, v101
	v_cvt_pk_bf16_f32 v93, v102, v103
	v_cvt_pk_bf16_f32 v94, v94, v95
	v_cvt_pk_bf16_f32 v95, v106, v107
	v_or_b32_e32 v100, 32, v171
	global_store_dwordx4 v[104:105], v[92:95], off
	v_pk_mul_f32 v[36:37], v[36:37], v[132:133]
	v_pk_mul_f32 v[22:23], v[22:23], v[134:135]
	v_or_b32_e32 v92, s4, v100
	v_ashrrev_i32_e32 v93, 31, v92
	v_lshlrev_b64 v[92:93], 7, v[92:93]
	v_lshl_add_u64 v[92:93], s[8:9], 0, v[92:93]
	v_pk_mul_f32 v[94:95], v[98:99], v[156:157]
	v_pk_mul_f32 v[98:99], v[90:91], v[160:161]
	v_pk_mul_f32 v[90:91], v[88:89], v[158:159]
	v_lshl_add_u64 v[92:93], v[92:93], 0, v[144:145]
	v_cvt_pk_bf16_f32 v88, v96, v97
	v_cvt_pk_bf16_f32 v89, v94, v95
	v_cvt_pk_bf16_f32 v90, v90, v91
	v_cvt_pk_bf16_f32 v91, v98, v99
	global_store_dwordx4 v[92:93], v[88:91], off
	v_pk_mul_f32 v[20:21], v[20:21], v[132:133]
	v_pk_mul_f32 v[6:7], v[6:7], v[134:135]
	v_or_b32_e32 v88, s5, v100
	v_ashrrev_i32_e32 v89, 31, v88
	v_lshlrev_b64 v[88:89], 7, v[88:89]
	v_lshl_add_u64 v[88:89], s[8:9], 0, v[88:89]
	v_pk_mul_f32 v[90:91], v[78:79], v[130:131]
	v_pk_mul_f32 v[78:79], v[76:77], v[128:129]
	v_lshl_add_u64 v[88:89], v[88:89], 0, v[144:145]
	v_cvt_pk_bf16_f32 v76, v84, v85
	v_cvt_pk_bf16_f32 v77, v86, v87
	v_cvt_pk_bf16_f32 v78, v78, v79
	v_cvt_pk_bf16_f32 v79, v90, v91
	v_or_b32_e32 v84, 48, v171
	global_store_dwordx4 v[88:89], v[76:79], off
	v_pk_mul_f32 v[4:5], v[4:5], v[132:133]
	s_nop 0
	v_or_b32_e32 v76, s4, v84
	v_ashrrev_i32_e32 v77, 31, v76
	v_lshlrev_b64 v[76:77], 7, v[76:77]
	v_lshl_add_u64 v[76:77], s[8:9], 0, v[76:77]
	v_pk_mul_f32 v[78:79], v[82:83], v[156:157]
	v_pk_mul_f32 v[82:83], v[74:75], v[160:161]
	v_pk_mul_f32 v[74:75], v[72:73], v[158:159]
	v_lshl_add_u64 v[76:77], v[76:77], 0, v[144:145]
	v_cvt_pk_bf16_f32 v72, v80, v81
	v_cvt_pk_bf16_f32 v73, v78, v79
	v_cvt_pk_bf16_f32 v74, v74, v75
	v_cvt_pk_bf16_f32 v75, v82, v83
	global_store_dwordx4 v[76:77], v[72:75], off
	s_nop 1
	v_or_b32_e32 v72, s5, v84
	v_ashrrev_i32_e32 v73, 31, v72
	v_lshlrev_b64 v[72:73], 7, v[72:73]
	v_lshl_add_u64 v[72:73], s[8:9], 0, v[72:73]
	s_bfe_u32 s8, s6, 0x20008
	s_or_b32 s7, s8, s7
	s_lshl_b32 s7, s7, 15
	s_and_b32 s8, s6, 0xc0
	v_pk_mul_f32 v[74:75], v[66:67], v[130:131]
	v_pk_mul_f32 v[66:67], v[64:65], v[128:129]
	s_or_b32 s7, s7, s8
	v_lshl_add_u64 v[72:73], v[72:73], 0, v[144:145]
	v_cvt_pk_bf16_f32 v64, v68, v69
	v_cvt_pk_bf16_f32 v65, v70, v71
	v_cvt_pk_bf16_f32 v66, v66, v67
	v_cvt_pk_bf16_f32 v67, v74, v75
	v_or_b32_e32 v68, s7, v164
	global_store_dwordx4 v[72:73], v[64:67], off
	s_cmpk_lt_u32 s6, 0x400
	s_cselect_b32 s9, s53, s91
	v_or_b32_e32 v64, s4, v68
; DI unsigned pk_bf16(float lo, float hi) { f32x2 v = {lo, hi}; return __builtin_bit_cast(unsigned, __builtin_convertvector(v, bf16v2)); }
; #define PG8_WAIT_V(n) asm volatile("s_waitcnt vmcnt(" #n ")" ::: "memory")
; #define PG8_BAR __builtin_amdgcn_s_barrier()
; #define PG8_WAIT_V(n) asm volatile("s_waitcnt vmcnt(" #n ")" ::: "memory")
; #define PG8_BAR __builtin_amdgcn_s_barrier()
; template <class Epi>
; DI void gemm_phase(LAS unsigned char* lds, const Gemm g, const StaticOrder S, const Epi E) {
;     ...
;     PG8_WAIT_V(0);
;     if (wr == 0) PG8_BAR;
;     PG8_BAR;
;     DI void operator()(AccRef acc, const Unit& u, int wr, int wc, int fr, int fq) const {
;     ...
;         for (int ai = 0; ai < 2; ++ai)
; #pragma unroll
;             for (int m = 0; m < 4; ++m) {
;                 const int R = u.pm * 256 + ai * 128 + wr * 64 + m * 16 + fr, X = R >> 10, hv = R & 1023;
; #pragma unroll
;                 for (int bj = 0; bj < 2; ++bj) {
;                     const int tok = u.pn * 256 + bj * 128 + wc * 32 + 8 * fq, b = tok >> 13, s = tok & (SEQ - 1);
;                     bf16_t* dst = (X ? vtB : vtA) + ((size_t)(((b * 4 + (hv >> 8)) * 128 + (s >> 6)) * 256 + (hv & 255))) * 64 + (s & 63);
;                     const f32x4 v0 = acc[ai][bj][m][0] * ts[bj][0], v1 = acc[ai][bj][m][1] * ts[bj][1];
;                     u32x4 w; w.x = pk_bf16(v0[0], v0[1]); w.y = pk_bf16(v0[2], v0[3]); w.z = pk_bf16(v1[0], v1[1]); w.w = pk_bf16(v1[2], v1[3]);
;                     *(u32x4*)dst = w;
;                 }
	v_ashrrev_i32_e32 v65, 31, v64
	s_cselect_b32 s8, s52, s90
	v_lshlrev_b64 v[64:65], 7, v[64:65]
	v_lshl_add_u64 v[64:65], s[8:9], 0, v[64:65]
	v_pk_mul_f32 v[66:67], v[58:59], v[160:161]
	v_pk_mul_f32 v[58:59], v[56:57], v[158:159]
	v_lshl_add_u64 v[64:65], v[64:65], 0, v[144:145]
	v_cvt_pk_bf16_f32 v56, v60, v61
	v_cvt_pk_bf16_f32 v57, v62, v63
	v_cvt_pk_bf16_f32 v58, v58, v59
	v_cvt_pk_bf16_f32 v59, v66, v67
	global_store_dwordx4 v[64:65], v[56:59], off
	s_and_b64 vcc, exec, s[0:1]
	s_nop 0
	v_or_b32_e32 v56, s5, v68
	v_ashrrev_i32_e32 v57, 31, v56
	v_lshlrev_b64 v[56:57], 7, v[56:57]
	v_lshl_add_u64 v[56:57], s[8:9], 0, v[56:57]
	v_pk_mul_f32 v[58:59], v[46:47], v[130:131]
	v_pk_mul_f32 v[46:47], v[44:45], v[128:129]
	v_lshl_add_u64 v[56:57], v[56:57], 0, v[144:145]
	v_cvt_pk_bf16_f32 v44, v52, v53
	v_cvt_pk_bf16_f32 v45, v54, v55
	v_cvt_pk_bf16_f32 v46, v46, v47
	v_cvt_pk_bf16_f32 v47, v58, v59
	v_or_b32_e32 v52, 16, v68
	global_store_dwordx4 v[56:57], v[44:47], off
	s_nop 1
	v_or_b32_e32 v44, s4, v52
	v_ashrrev_i32_e32 v45, 31, v44
	v_lshlrev_b64 v[44:45], 7, v[44:45]
	v_lshl_add_u64 v[44:45], s[8:9], 0, v[44:45]
	v_pk_mul_f32 v[46:47], v[50:51], v[156:157]
	v_pk_mul_f32 v[50:51], v[42:43], v[160:161]
	v_pk_mul_f32 v[42:43], v[40:41], v[158:159]
	v_lshl_add_u64 v[44:45], v[44:45], 0, v[144:145]
	v_cvt_pk_bf16_f32 v40, v48, v49
	v_cvt_pk_bf16_f32 v41, v46, v47
	v_cvt_pk_bf16_f32 v42, v42, v43
	v_cvt_pk_bf16_f32 v43, v50, v51
	global_store_dwordx4 v[44:45], v[40:43], off
	s_nop 1
	v_or_b32_e32 v40, s5, v52
	v_ashrrev_i32_e32 v41, 31, v40
	v_lshlrev_b64 v[40:41], 7, v[40:41]
	v_lshl_add_u64 v[40:41], s[8:9], 0, v[40:41]
	v_pk_mul_f32 v[42:43], v[30:31], v[130:131]
	v_pk_mul_f32 v[30:31], v[28:29], v[128:129]
	v_lshl_add_u64 v[40:41], v[40:41], 0, v[144:145]
	v_cvt_pk_bf16_f32 v28, v36, v37
	v_cvt_pk_bf16_f32 v29, v38, v39
	v_cvt_pk_bf16_f32 v30, v30, v31
	v_cvt_pk_bf16_f32 v31, v42, v43
	v_or_b32_e32 v36, 32, v68
	global_store_dwordx4 v[40:41], v[28:31], off
	s_nop 1
	v_or_b32_e32 v28, s4, v36
	v_ashrrev_i32_e32 v29, 31, v28
	v_lshlrev_b64 v[28:29], 7, v[28:29]
	v_lshl_add_u64 v[28:29], s[8:9], 0, v[28:29]
	v_pk_mul_f32 v[30:31], v[34:35], v[156:157]
	v_pk_mul_f32 v[34:35], v[26:27], v[160:161]
	v_pk_mul_f32 v[26:27], v[24:25], v[158:159]
	v_lshl_add_u64 v[28:29], v[28:29], 0, v[144:145]
	v_cvt_pk_bf16_f32 v24, v32, v33
	v_cvt_pk_bf16_f32 v25, v30, v31
	v_cvt_pk_bf16_f32 v26, v26, v27
	v_cvt_pk_bf16_f32 v27, v34, v35
	global_store_dwordx4 v[28:29], v[24:27], off
	s_nop 1
	v_or_b32_e32 v24, s5, v36
	v_ashrrev_i32_e32 v25, 31, v24
	v_lshlrev_b64 v[24:25], 7, v[24:25]
	v_lshl_add_u64 v[24:25], s[8:9], 0, v[24:25]
	v_pk_mul_f32 v[26:27], v[14:15], v[130:131]
	v_pk_mul_f32 v[14:15], v[12:13], v[128:129]
	v_lshl_add_u64 v[24:25], v[24:25], 0, v[144:145]
	v_cvt_pk_bf16_f32 v12, v20, v21
	v_cvt_pk_bf16_f32 v13, v22, v23
	v_cvt_pk_bf16_f32 v14, v14, v15
	v_cvt_pk_bf16_f32 v15, v26, v27
	v_or_b32_e32 v20, 48, v68
	global_store_dwordx4 v[24:25], v[12:15], off
	s_nop 1
	v_or_b32_e32 v12, s4, v20
	v_ashrrev_i32_e32 v13, 31, v12
	v_lshlrev_b64 v[12:13], 7, v[12:13]
	v_lshl_add_u64 v[12:13], s[8:9], 0, v[12:13]
	v_pk_mul_f32 v[14:15], v[18:19], v[156:157]
	v_pk_mul_f32 v[18:19], v[10:11], v[160:161]
	v_pk_mul_f32 v[10:11], v[8:9], v[158:159]
	v_lshl_add_u64 v[12:13], v[12:13], 0, v[144:145]
	v_cvt_pk_bf16_f32 v8, v16, v17
	v_cvt_pk_bf16_f32 v9, v14, v15
	v_cvt_pk_bf16_f32 v10, v10, v11
	v_cvt_pk_bf16_f32 v11, v18, v19
	global_store_dwordx4 v[12:13], v[8:11], off
	s_nop 1
	v_or_b32_e32 v8, s5, v20
	v_ashrrev_i32_e32 v9, 31, v8
	v_lshlrev_b64 v[8:9], 7, v[8:9]
	v_lshl_add_u64 v[8:9], s[8:9], 0, v[8:9]
	v_pk_mul_f32 v[10:11], v[2:3], v[130:131]
	v_pk_mul_f32 v[2:3], v[0:1], v[128:129]
	v_lshl_add_u64 v[8:9], v[8:9], 0, v[144:145]
	v_cvt_pk_bf16_f32 v0, v4, v5
	v_cvt_pk_bf16_f32 v1, v6, v7
	v_cvt_pk_bf16_f32 v2, v2, v3
	v_cvt_pk_bf16_f32 v3, v10, v11
	s_mov_b64 s[8:9], s[24:25]
	global_store_dwordx4 v[8:9], v[0:3], off
	s_cbranch_vccz .LBB0_291
	s_waitcnt vmcnt(0)
	s_cmpk_gt_u32 s17, 0xff
	s_cbranch_scc1 .LBB0_302
	s_barrier

; #define PG8_STAGE(bufoff, gbase, voff) do { _Pragma("unroll") for (int _i = 0; _i < 2; ++_i) \
;         __builtin_amdgcn_global_load_lds((const unsigned*)((const char*)(gbase) + (voff)[_i]), (LAS unsigned*)(lds + (bufoff) + ldsw + _i * 8192), 16, 0, 0); } while (0)
; #define PG8_LDA(dst, b, h) do { _Pragma("unroll") for (int m = 0; m < 4; ++m) _Pragma("unroll") for (int k = 0; k < 2; ++k) dst[m][k] = *(const LAS bf16x8*)(lds + PG8_SA(b, h) + aoff + m * 2048 + k * 1024); } while (0)
; #define PG8_LDB(dst, b, h) do { _Pragma("unroll") for (int n = 0; n < 2; ++n) _Pragma("unroll") for (int k = 0; k < 2; ++k) dst[n][k] = *(const LAS bf16x8*)(lds + PG8_SB(b, h) + boff + n * 2048 + k * 1024); } while (0)
; #define PG8_MMA(ai, bj, At, Bt) do { __builtin_amdgcn_s_setprio(1); _Pragma("unroll") for (int m = 0; m < 4; ++m) _Pragma("unroll") for (int n = 0; n < 2; ++n) _Pragma("unroll") for (int k = 0; k < 2; ++k) \
;         acc[ai][bj][m][n] = __builtin_amdgcn_mfma_f32_16x16x32_bf16(Bt[n][k], At[m][k], acc[ai][bj][m][n], 0, 0, 0); __builtin_amdgcn_s_setprio(0); } while (0)
; #define PG8_WAIT_L(n) asm volatile("s_waitcnt lgkmcnt(" #n ")" ::: "memory")
; #define PG8_BAR __builtin_amdgcn_s_barrier()
; #define PG8_SCHED __builtin_amdgcn_sched_barrier(0)
; #define PG8_STAGE(bufoff, gbase, voff) do { _Pragma("unroll") for (int _i = 0; _i < 2; ++_i) \
;         __builtin_amdgcn_global_load_lds((const unsigned*)((const char*)(gbase) + (voff)[_i]), (LAS unsigned*)(lds + (bufoff) + ldsw + _i * 8192), 16, 0, 0); } while (0)
; #define PG8_WAIT_L(n) asm volatile("s_waitcnt lgkmcnt(" #n ")" ::: "memory")
; #define PG8_BAR __builtin_amdgcn_s_barrier()
; #define PG8_SCHED __builtin_amdgcn_sched_barrier(0)
; template <class Epi0, class Epi1>
; DI void gemm_phase_dual(LAS unsigned char* lds, const Gemm g, const Gemm g1, const StaticOrder S, const Epi0 E0, const Epi1 E1) {
;     ...
;             PG8_LDB(B0, 0, 0); PG8_SCHED; PG8_LDA(At, 0, 0); PG8_STAGE(PG8_SA(1, 1), a1 + hstep, voffA);
;             PG8_WAIT_L(8); PG8_BAR; PG8_WAIT_L(0); PG8_MMA(0, 0, At, B0); PG8_BAR; PG8_SCHED;
;             PG8_LDB(B1, 0, 1); PG8_STAGE(PG8_SB(0, 0), b2, voffB);
;             PG8_BAR; PG8_WAIT_L(0); PG8_MMA(0, 1, At, B1); PG8_BAR;
;             PG8_LDA(At, 0, 1); PG8_STAGE(PG8_SA(0, 0), a2, voffA);
;             PG8_BAR; PG8_WAIT_L(0); PG8_MMA(1, 0, At, B0); PG8_BAR; PG8_SCHED;
.LBB0_632:
	ds_read_b128 v[128:131], v181
	ds_read_b128 v[132:135], v181 offset:1024
	ds_read_b128 v[136:139], v181 offset:2048
	ds_read_b128 v[140:143], v181 offset:3072
	s_add_u32 s12, s10, 0xfffc0080
	s_addc_u32 s13, s11, -1
	s_cmp_eq_u32 s19, 12
	s_cselect_b32 s15, s1, s13
	s_cselect_b32 s14, s6, s12
	s_cselect_b32 s13, s7, s18
	s_cselect_b32 s12, s16, s17
	v_lshl_add_u64 v[190:191], s[10:11], 0, v[168:169]
	s_add_i32 m0, s49, 0xc000
	ds_read_b128 v[144:147], v183
	ds_read_b128 v[152:155], v183 offset:2048
	ds_read_b128 v[194:197], v183 offset:4096
	ds_read_b128 v[202:205], v183 offset:6144
	global_load_lds_dwordx4 v[190:191], off
	v_lshl_add_u64 v[190:191], s[10:11], 0, v[170:171]
	s_add_i32 m0, s49, 0xe000
	s_nop 0
	global_load_lds_dwordx4 v[190:191], off
	s_waitcnt lgkmcnt(4)
	s_setprio 1
	s_barrier
	ds_read_b128 v[148:151], v183 offset:1024
	ds_read_b128 v[184:187], v183 offset:3072
	ds_read_b128 v[198:201], v183 offset:5120
	ds_read_b128 v[206:209], v183 offset:7168
	s_waitcnt lgkmcnt(4)
	v_mfma_f32_16x16x32_bf16 v[124:127], v[128:131], v[144:147], v[124:127]
	v_mfma_f32_16x16x32_bf16 v[120:123], v[136:139], v[144:147], v[120:123]
	v_mfma_f32_16x16x32_bf16 v[108:111], v[128:131], v[152:155], v[108:111]
	v_mfma_f32_16x16x32_bf16 v[104:107], v[136:139], v[152:155], v[104:107]
	v_mfma_f32_16x16x32_bf16 v[92:95], v[128:131], v[194:197], v[92:95]
	v_mfma_f32_16x16x32_bf16 v[88:91], v[136:139], v[194:197], v[88:91]
	v_mfma_f32_16x16x32_bf16 v[76:79], v[128:131], v[202:205], v[76:79]
	v_mfma_f32_16x16x32_bf16 v[72:75], v[136:139], v[202:205], v[72:75]
	s_waitcnt lgkmcnt(3)
	v_mfma_f32_16x16x32_bf16 v[124:127], v[132:135], v[148:151], v[124:127]
	v_mfma_f32_16x16x32_bf16 v[120:123], v[140:143], v[148:151], v[120:123]
	s_waitcnt lgkmcnt(2)
	v_mfma_f32_16x16x32_bf16 v[108:111], v[132:135], v[184:187], v[108:111]
	v_mfma_f32_16x16x32_bf16 v[104:107], v[140:143], v[184:187], v[104:107]
	s_waitcnt lgkmcnt(1)
	v_mfma_f32_16x16x32_bf16 v[92:95], v[132:135], v[198:201], v[92:95]
	v_mfma_f32_16x16x32_bf16 v[88:91], v[140:143], v[198:201], v[88:91]
	s_waitcnt lgkmcnt(0)
	s_setprio 2
	s_barrier
	v_mfma_f32_16x16x32_bf16 v[76:79], v[132:135], v[206:209], v[76:79]
	v_mfma_f32_16x16x32_bf16 v[72:75], v[140:143], v[206:209], v[72:75]
	s_setprio 0
	s_add_i32 s41, s78, s48
	v_lshl_add_u64 v[190:191], s[12:13], 0, v[158:159]
	s_mov_b32 m0, s41
	ds_read_b128 v[210:213], v189
	ds_read_b128 v[214:217], v189 offset:1024
	ds_read_b128 v[218:221], v189 offset:2048
	ds_read_b128 v[224:227], v189 offset:3072
	global_load_lds_dwordx4 v[190:191], off
	v_lshl_add_u64 v[228:229], s[12:13], 0, v[162:163]
	s_add_i32 m0, s41, 0x2000
	s_nop 0
	global_load_lds_dwordx4 v[228:229], off
	s_setprio 1
	s_barrier
	s_waitcnt lgkmcnt(0)
	v_mfma_f32_16x16x32_bf16 v[116:119], v[210:213], v[144:147], v[116:119]
	v_mfma_f32_16x16x32_bf16 v[112:115], v[218:221], v[144:147], v[112:115]
	v_mfma_f32_16x16x32_bf16 v[100:103], v[210:213], v[152:155], v[100:103]
	v_mfma_f32_16x16x32_bf16 v[96:99], v[218:221], v[152:155], v[96:99]
	v_mfma_f32_16x16x32_bf16 v[84:87], v[210:213], v[194:197], v[84:87]
	v_mfma_f32_16x16x32_bf16 v[80:83], v[218:221], v[194:197], v[80:83]
	v_mfma_f32_16x16x32_bf16 v[68:71], v[210:213], v[202:205], v[68:71]
	v_mfma_f32_16x16x32_bf16 v[64:67], v[218:221], v[202:205], v[64:67]
	v_mfma_f32_16x16x32_bf16 v[116:119], v[214:217], v[148:151], v[116:119]
	v_mfma_f32_16x16x32_bf16 v[112:115], v[224:227], v[148:151], v[112:115]
	v_mfma_f32_16x16x32_bf16 v[100:103], v[214:217], v[184:187], v[100:103]
	v_mfma_f32_16x16x32_bf16 v[96:99], v[224:227], v[184:187], v[96:99]
	v_mfma_f32_16x16x32_bf16 v[84:87], v[214:217], v[198:201], v[84:87]
	v_mfma_f32_16x16x32_bf16 v[80:83], v[224:227], v[198:201], v[80:83]
	s_setprio 2
	s_barrier
	v_mfma_f32_16x16x32_bf16 v[68:71], v[214:217], v[206:209], v[68:71]
	v_mfma_f32_16x16x32_bf16 v[64:67], v[224:227], v[206:209], v[64:67]
	s_setprio 0
	s_mov_b32 m0, s49
	v_lshl_add_u64 v[230:231], s[14:15], 0, v[156:157]
	ds_read_b128 v[144:147], v183 offset:16384
	ds_read_b128 v[152:155], v183 offset:18432
	ds_read_b128 v[194:197], v183 offset:20480
	ds_read_b128 v[202:205], v183 offset:22528
	global_load_lds_dwordx4 v[230:231], off
	v_lshl_add_u64 v[232:233], s[14:15], 0, v[160:161]
	s_mov_b32 m0, s50
	s_nop 0
	global_load_lds_dwordx4 v[232:233], off
	s_setprio 1
	s_barrier
	ds_read_b128 v[148:151], v183 offset:17408
	ds_read_b128 v[184:187], v183 offset:19456
	ds_read_b128 v[198:201], v183 offset:21504
	ds_read_b128 v[206:209], v183 offset:23552
	s_waitcnt lgkmcnt(4)
	v_mfma_f32_16x16x32_bf16 v[60:63], v[128:131], v[144:147], v[60:63]
	v_mfma_f32_16x16x32_bf16 v[56:59], v[136:139], v[144:147], v[56:59]
	v_mfma_f32_16x16x32_bf16 v[44:47], v[128:131], v[152:155], v[44:47]
	v_mfma_f32_16x16x32_bf16 v[40:43], v[136:139], v[152:155], v[40:43]
	v_mfma_f32_16x16x32_bf16 v[28:31], v[128:131], v[194:197], v[28:31]
	v_mfma_f32_16x16x32_bf16 v[24:27], v[136:139], v[194:197], v[24:27]
	v_mfma_f32_16x16x32_bf16 v[12:15], v[128:131], v[202:205], v[12:15]
	v_mfma_f32_16x16x32_bf16 v[8:11], v[136:139], v[202:205], v[8:11]
	s_waitcnt lgkmcnt(3)
	v_mfma_f32_16x16x32_bf16 v[60:63], v[132:135], v[148:151], v[60:63]
	v_mfma_f32_16x16x32_bf16 v[56:59], v[140:143], v[148:151], v[56:59]
	s_waitcnt lgkmcnt(2)
	v_mfma_f32_16x16x32_bf16 v[44:47], v[132:135], v[184:187], v[44:47]
	v_mfma_f32_16x16x32_bf16 v[40:43], v[140:143], v[184:187], v[40:43]
	s_waitcnt lgkmcnt(1)
	v_mfma_f32_16x16x32_bf16 v[28:31], v[132:135], v[198:201], v[28:31]
	v_mfma_f32_16x16x32_bf16 v[24:27], v[140:143], v[198:201], v[24:27]
	s_waitcnt lgkmcnt(0)
	s_setprio 2
	s_barrier
; #define PG8_STAGE(bufoff, gbase, voff) do { _Pragma("unroll") for (int _i = 0; _i < 2; ++_i) \
;         __builtin_amdgcn_global_load_lds((const unsigned*)((const char*)(gbase) + (voff)[_i]), (LAS unsigned*)(lds + (bufoff) + ldsw + _i * 8192), 16, 0, 0); } while (0)
; #define PG8_LDA(dst, b, h) do { _Pragma("unroll") for (int m = 0; m < 4; ++m) _Pragma("unroll") for (int k = 0; k < 2; ++k) dst[m][k] = *(const LAS bf16x8*)(lds + PG8_SA(b, h) + aoff + m * 2048 + k * 1024); } while (0)
; #define PG8_LDB(dst, b, h) do { _Pragma("unroll") for (int n = 0; n < 2; ++n) _Pragma("unroll") for (int k = 0; k < 2; ++k) dst[n][k] = *(const LAS bf16x8*)(lds + PG8_SB(b, h) + boff + n * 2048 + k * 1024); } while (0)
; #define PG8_MMA(ai, bj, At, Bt) do { __builtin_amdgcn_s_setprio(1); _Pragma("unroll") for (int m = 0; m < 4; ++m) _Pragma("unroll") for (int n = 0; n < 2; ++n) _Pragma("unroll") for (int k = 0; k < 2; ++k) \
;         acc[ai][bj][m][n] = __builtin_amdgcn_mfma_f32_16x16x32_bf16(Bt[n][k], At[m][k], acc[ai][bj][m][n], 0, 0, 0); __builtin_amdgcn_s_setprio(0); } while (0)
; #define PG8_WAIT_V(n) asm volatile("s_waitcnt vmcnt(" #n ")" ::: "memory")
; #define PG8_WAIT_L(n) asm volatile("s_waitcnt lgkmcnt(" #n ")" ::: "memory")
; #define PG8_BAR __builtin_amdgcn_s_barrier()
; #define PG8_SCHED __builtin_amdgcn_sched_barrier(0)
; #define PG8_STAGE(bufoff, gbase, voff) do { _Pragma("unroll") for (int _i = 0; _i < 2; ++_i) \
;         __builtin_amdgcn_global_load_lds((const unsigned*)((const char*)(gbase) + (voff)[_i]), (LAS unsigned*)(lds + (bufoff) + ldsw + _i * 8192), 16, 0, 0); } while (0)
; #define PG8_BAR __builtin_amdgcn_s_barrier()
; template <class Epi0, class Epi1>
; DI void gemm_phase_dual(LAS unsigned char* lds, const Gemm g, const Gemm g1, const StaticOrder S, const Epi0 E0, const Epi1 E1) {
;     ...
;             PG8_BAR; PG8_WAIT_L(0); PG8_MMA(1, 0, At, B0); PG8_BAR; PG8_SCHED;
;             PG8_STAGE(PG8_SB(0, 1), b2 + hstep, voffB);
;             PG8_WAIT_V(6); PG8_BAR; PG8_MMA(1, 1, At, B1); PG8_BAR;
;             PG8_LDB(B0, 1, 0); PG8_SCHED; PG8_LDA(At, 1, 0); PG8_STAGE(PG8_SA(0, 1), a2 + hstep, voffA);
;             PG8_WAIT_L(8); PG8_BAR; PG8_WAIT_L(0); PG8_MMA(0, 0, At, B0); PG8_BAR; PG8_SCHED;
;             PG8_LDB(B1, 1, 1); PG8_STAGE(PG8_SB(1, 0), b3, voffB);
;             PG8_BAR; PG8_WAIT_L(0); PG8_MMA(0, 1, At, B1); PG8_BAR;
	v_mfma_f32_16x16x32_bf16 v[12:15], v[132:135], v[206:209], v[12:15]
	v_mfma_f32_16x16x32_bf16 v[8:11], v[140:143], v[206:209], v[8:11]
	s_setprio 0
	s_add_u32 s90, s12, 0x40000
	s_addc_u32 s91, s13, 0
	s_add_i32 s41, s79, s48
	v_lshl_add_u64 v[128:129], s[90:91], 0, v[158:159]
	s_mov_b32 m0, s41
	s_nop 0
	global_load_lds_dwordx4 v[128:129], off
	v_lshl_add_u64 v[128:129], s[90:91], 0, v[162:163]
	s_add_i32 m0, s41, 0x2000
	s_nop 0
	global_load_lds_dwordx4 v[128:129], off
	s_waitcnt vmcnt(6)
	s_setprio 1
	s_barrier
	v_mfma_f32_16x16x32_bf16 v[52:55], v[210:213], v[144:147], v[52:55]
	v_mfma_f32_16x16x32_bf16 v[48:51], v[218:221], v[144:147], v[48:51]
	v_mfma_f32_16x16x32_bf16 v[36:39], v[210:213], v[152:155], v[36:39]
	v_mfma_f32_16x16x32_bf16 v[32:35], v[218:221], v[152:155], v[32:35]
	v_mfma_f32_16x16x32_bf16 v[20:23], v[210:213], v[194:197], v[20:23]
	v_mfma_f32_16x16x32_bf16 v[16:19], v[218:221], v[194:197], v[16:19]
	v_mfma_f32_16x16x32_bf16 v[4:7], v[210:213], v[202:205], v[4:7]
	v_mfma_f32_16x16x32_bf16 v[0:3], v[218:221], v[202:205], v[0:3]
	v_mfma_f32_16x16x32_bf16 v[52:55], v[214:217], v[148:151], v[52:55]
	v_mfma_f32_16x16x32_bf16 v[48:51], v[224:227], v[148:151], v[48:51]
	v_mfma_f32_16x16x32_bf16 v[36:39], v[214:217], v[184:187], v[36:39]
	v_mfma_f32_16x16x32_bf16 v[32:35], v[224:227], v[184:187], v[32:35]
	v_mfma_f32_16x16x32_bf16 v[20:23], v[214:217], v[198:201], v[20:23]
	v_mfma_f32_16x16x32_bf16 v[16:19], v[224:227], v[198:201], v[16:19]
	s_setprio 2
	s_barrier
	v_mfma_f32_16x16x32_bf16 v[4:7], v[214:217], v[206:209], v[4:7]
	v_mfma_f32_16x16x32_bf16 v[0:3], v[224:227], v[206:209], v[0:3]
	s_setprio 0
	s_add_i32 s41, 0, 0x18000
	v_add_u32_e32 v140, s41, v179
	ds_read_b128 v[128:131], v140
	ds_read_b128 v[132:135], v140 offset:1024
	ds_read_b128 v[136:139], v140 offset:2048
	ds_read_b128 v[140:143], v140 offset:3072
	s_add_u32 s14, s14, 0x40000
	s_addc_u32 s15, s15, 0
	s_mov_b32 m0, s51
	v_lshl_add_u64 v[210:211], s[14:15], 0, v[156:157]
	ds_read_b128 v[144:147], v183 offset:32768
	ds_read_b128 v[152:155], v183 offset:34816
	ds_read_b128 v[194:197], v183 offset:36864
	ds_read_b128 v[202:205], v183 offset:38912
	global_load_lds_dwordx4 v[210:211], off
	v_lshl_add_u64 v[210:211], s[14:15], 0, v[160:161]
	s_mov_b32 m0, s58
	s_nop 0
	global_load_lds_dwordx4 v[210:211], off
	s_waitcnt lgkmcnt(4)
	s_setprio 1
	s_barrier
	ds_read_b128 v[148:151], v183 offset:33792
	ds_read_b128 v[184:187], v183 offset:35840
	ds_read_b128 v[198:201], v183 offset:37888
	ds_read_b128 v[206:209], v183 offset:39936
	s_waitcnt lgkmcnt(4)
	v_mfma_f32_16x16x32_bf16 v[124:127], v[128:131], v[144:147], v[124:127]
	v_mfma_f32_16x16x32_bf16 v[120:123], v[136:139], v[144:147], v[120:123]
	v_mfma_f32_16x16x32_bf16 v[108:111], v[128:131], v[152:155], v[108:111]
	v_mfma_f32_16x16x32_bf16 v[104:107], v[136:139], v[152:155], v[104:107]
	v_mfma_f32_16x16x32_bf16 v[92:95], v[128:131], v[194:197], v[92:95]
	v_mfma_f32_16x16x32_bf16 v[88:91], v[136:139], v[194:197], v[88:91]
	v_mfma_f32_16x16x32_bf16 v[76:79], v[128:131], v[202:205], v[76:79]
	v_mfma_f32_16x16x32_bf16 v[72:75], v[136:139], v[202:205], v[72:75]
	s_waitcnt lgkmcnt(3)
	v_mfma_f32_16x16x32_bf16 v[124:127], v[132:135], v[148:151], v[124:127]
	v_mfma_f32_16x16x32_bf16 v[120:123], v[140:143], v[148:151], v[120:123]
	s_waitcnt lgkmcnt(2)
	v_mfma_f32_16x16x32_bf16 v[108:111], v[132:135], v[184:187], v[108:111]
	v_mfma_f32_16x16x32_bf16 v[104:107], v[140:143], v[184:187], v[104:107]
	s_waitcnt lgkmcnt(1)
	v_mfma_f32_16x16x32_bf16 v[92:95], v[132:135], v[198:201], v[92:95]
	v_mfma_f32_16x16x32_bf16 v[88:91], v[140:143], v[198:201], v[88:91]
	s_waitcnt lgkmcnt(0)
	s_setprio 2
	s_barrier
	v_mfma_f32_16x16x32_bf16 v[76:79], v[132:135], v[206:209], v[76:79]
	v_mfma_f32_16x16x32_bf16 v[72:75], v[140:143], v[206:209], v[72:75]
	s_setprio 0
	s_add_i32 s14, 0, 0x1c000
	s_add_i32 s15, s41, s48
	v_add_u32_e32 v176, s14, v179
	v_lshl_add_u64 v[190:191], v[190:191], 0, s[22:23]
	s_mov_b32 m0, s15
	ds_read_b128 v[210:213], v176
	ds_read_b128 v[214:217], v176 offset:1024
	ds_read_b128 v[218:221], v176 offset:2048
	ds_read_b128 v[224:227], v176 offset:3072
	global_load_lds_dwordx4 v[190:191], off
	v_lshl_add_u64 v[190:191], v[228:229], 0, s[22:23]
	s_add_i32 m0, s15, 0x2000
	s_nop 0
	global_load_lds_dwordx4 v[190:191], off
	s_setprio 1
	s_barrier
	s_waitcnt lgkmcnt(0)
	v_mfma_f32_16x16x32_bf16 v[116:119], v[210:213], v[144:147], v[116:119]
	v_mfma_f32_16x16x32_bf16 v[112:115], v[218:221], v[144:147], v[112:115]
	v_mfma_f32_16x16x32_bf16 v[100:103], v[210:213], v[152:155], v[100:103]
	v_mfma_f32_16x16x32_bf16 v[96:99], v[218:221], v[152:155], v[96:99]
	v_mfma_f32_16x16x32_bf16 v[84:87], v[210:213], v[194:197], v[84:87]
	v_mfma_f32_16x16x32_bf16 v[80:83], v[218:221], v[194:197], v[80:83]
	v_mfma_f32_16x16x32_bf16 v[68:71], v[210:213], v[202:205], v[68:71]
	v_mfma_f32_16x16x32_bf16 v[64:67], v[218:221], v[202:205], v[64:67]
	v_mfma_f32_16x16x32_bf16 v[116:119], v[214:217], v[148:151], v[116:119]
	v_mfma_f32_16x16x32_bf16 v[112:115], v[224:227], v[148:151], v[112:115]
	v_mfma_f32_16x16x32_bf16 v[100:103], v[214:217], v[184:187], v[100:103]
	v_mfma_f32_16x16x32_bf16 v[96:99], v[224:227], v[184:187], v[96:99]
	v_mfma_f32_16x16x32_bf16 v[84:87], v[214:217], v[198:201], v[84:87]
	v_mfma_f32_16x16x32_bf16 v[80:83], v[224:227], v[198:201], v[80:83]
	s_setprio 2
	s_barrier
; #define PG8_STAGE(bufoff, gbase, voff) do { _Pragma("unroll") for (int _i = 0; _i < 2; ++_i) \
;         __builtin_amdgcn_global_load_lds((const unsigned*)((const char*)(gbase) + (voff)[_i]), (LAS unsigned*)(lds + (bufoff) + ldsw + _i * 8192), 16, 0, 0); } while (0)
; #define PG8_LDA(dst, b, h) do { _Pragma("unroll") for (int m = 0; m < 4; ++m) _Pragma("unroll") for (int k = 0; k < 2; ++k) dst[m][k] = *(const LAS bf16x8*)(lds + PG8_SA(b, h) + aoff + m * 2048 + k * 1024); } while (0)
; #define PG8_MMA(ai, bj, At, Bt) do { __builtin_amdgcn_s_setprio(1); _Pragma("unroll") for (int m = 0; m < 4; ++m) _Pragma("unroll") for (int n = 0; n < 2; ++n) _Pragma("unroll") for (int k = 0; k < 2; ++k) \
;         acc[ai][bj][m][n] = __builtin_amdgcn_mfma_f32_16x16x32_bf16(Bt[n][k], At[m][k], acc[ai][bj][m][n], 0, 0, 0); __builtin_amdgcn_s_setprio(0); } while (0)
; #define PG8_WAIT_V(n) asm volatile("s_waitcnt vmcnt(" #n ")" ::: "memory")
; #define PG8_WAIT_L(n) asm volatile("s_waitcnt lgkmcnt(" #n ")" ::: "memory")
; #define PG8_BAR __builtin_amdgcn_s_barrier()
; #define PG8_SCHED __builtin_amdgcn_sched_barrier(0)
; #define PG8_STAGE(bufoff, gbase, voff) do { _Pragma("unroll") for (int _i = 0; _i < 2; ++_i) \
;         __builtin_amdgcn_global_load_lds((const unsigned*)((const char*)(gbase) + (voff)[_i]), (LAS unsigned*)(lds + (bufoff) + ldsw + _i * 8192), 16, 0, 0); } while (0)
; #define PG8_WAIT_V(n) asm volatile("s_waitcnt vmcnt(" #n ")" ::: "memory")
; #define PG8_WAIT_L(n) asm volatile("s_waitcnt lgkmcnt(" #n ")" ::: "memory")
; template <class Epi0, class Epi1>
; DI void gemm_phase_dual(LAS unsigned char* lds, const Gemm g, const Gemm g1, const StaticOrder S, const Epi0 E0, const Epi1 E1) {
;     ...
;             PG8_LDA(At, 1, 1); PG8_STAGE(PG8_SA(1, 0), a3, voffA);
;             PG8_BAR; PG8_WAIT_L(0); PG8_MMA(1, 0, At, B0); PG8_BAR; PG8_SCHED;
;             PG8_STAGE(PG8_SB(1, 1), b3 + hstep, voffB);
;             PG8_WAIT_V(6); PG8_BAR; PG8_MMA(1, 1, At, B1); PG8_BAR;
;         }
;         if (ui & 1) E1(acc, cur, wr, wc, fr, fq); else E0(acc, cur, wr, wc, fr, fq);
;     DI void operator()(AccRef acc, const Unit& u, int wr, int wc, int fr, int fq) const {
;         const int row0 = u.pm * 256 + wr * 64 + fr;
;         bf16_t* Gp = gab + (size_t)(u.pm * 8 + u.pn) * 65536 + (wr * 64 + fr) * 256 + wc * 32 + 8 * fq;
;         const RowScales rsc = load_rowscales(ss, row0);
	v_mfma_f32_16x16x32_bf16 v[68:71], v[214:217], v[206:209], v[68:71]
	v_mfma_f32_16x16x32_bf16 v[64:67], v[224:227], v[206:209], v[64:67]
	s_setprio 0
	s_mov_b32 m0, s76
	v_lshl_add_u64 v[190:191], v[230:231], 0, s[22:23]
	ds_read_b128 v[144:147], v183 offset:49152
	ds_read_b128 v[152:155], v183 offset:51200
	ds_read_b128 v[194:197], v183 offset:53248
	ds_read_b128 v[202:205], v183 offset:55296
	global_load_lds_dwordx4 v[190:191], off
	v_lshl_add_u64 v[190:191], v[232:233], 0, s[22:23]
	s_mov_b32 m0, s77
	s_nop 0
	global_load_lds_dwordx4 v[190:191], off
	s_setprio 1
	s_barrier
	ds_read_b128 v[148:151], v183 offset:50176
	ds_read_b128 v[184:187], v183 offset:52224
	ds_read_b128 v[198:201], v183 offset:54272
	ds_read_b128 v[206:209], v183 offset:56320
	s_waitcnt lgkmcnt(4)
	v_mfma_f32_16x16x32_bf16 v[60:63], v[128:131], v[144:147], v[60:63]
	v_mfma_f32_16x16x32_bf16 v[56:59], v[136:139], v[144:147], v[56:59]
	v_mfma_f32_16x16x32_bf16 v[44:47], v[128:131], v[152:155], v[44:47]
	v_mfma_f32_16x16x32_bf16 v[40:43], v[136:139], v[152:155], v[40:43]
	v_mfma_f32_16x16x32_bf16 v[28:31], v[128:131], v[194:197], v[28:31]
	v_mfma_f32_16x16x32_bf16 v[24:27], v[136:139], v[194:197], v[24:27]
	v_mfma_f32_16x16x32_bf16 v[12:15], v[128:131], v[202:205], v[12:15]
	v_mfma_f32_16x16x32_bf16 v[8:11], v[136:139], v[202:205], v[8:11]
	s_waitcnt lgkmcnt(3)
	v_mfma_f32_16x16x32_bf16 v[60:63], v[132:135], v[148:151], v[60:63]
	v_mfma_f32_16x16x32_bf16 v[56:59], v[140:143], v[148:151], v[56:59]
	s_waitcnt lgkmcnt(2)
	v_mfma_f32_16x16x32_bf16 v[44:47], v[132:135], v[184:187], v[44:47]
	v_mfma_f32_16x16x32_bf16 v[40:43], v[140:143], v[184:187], v[40:43]
	s_waitcnt lgkmcnt(1)
	v_mfma_f32_16x16x32_bf16 v[28:31], v[132:135], v[198:201], v[28:31]
	v_mfma_f32_16x16x32_bf16 v[24:27], v[140:143], v[198:201], v[24:27]
	s_waitcnt lgkmcnt(0)
	s_setprio 2
	s_barrier
	v_mfma_f32_16x16x32_bf16 v[12:15], v[132:135], v[206:209], v[12:15]
	v_mfma_f32_16x16x32_bf16 v[8:11], v[140:143], v[206:209], v[8:11]
	s_setprio 0
	s_add_u32 s12, s12, 0x40080
	s_addc_u32 s13, s13, 0
	s_add_i32 s14, s14, s48
	v_lshl_add_u64 v[128:129], s[12:13], 0, v[158:159]
	s_mov_b32 m0, s14
	s_nop 0
	global_load_lds_dwordx4 v[128:129], off
	v_lshl_add_u64 v[128:129], s[12:13], 0, v[162:163]
	s_add_i32 m0, s14, 0x2000
	s_nop 0
	global_load_lds_dwordx4 v[128:129], off
	s_waitcnt vmcnt(6)
	s_setprio 1
	s_barrier
	v_mfma_f32_16x16x32_bf16 v[52:55], v[210:213], v[144:147], v[52:55]
	v_mfma_f32_16x16x32_bf16 v[48:51], v[218:221], v[144:147], v[48:51]
	v_mfma_f32_16x16x32_bf16 v[36:39], v[210:213], v[152:155], v[36:39]
	v_mfma_f32_16x16x32_bf16 v[32:35], v[218:221], v[152:155], v[32:35]
	v_mfma_f32_16x16x32_bf16 v[20:23], v[210:213], v[194:197], v[20:23]
	v_mfma_f32_16x16x32_bf16 v[16:19], v[218:221], v[194:197], v[16:19]
	v_mfma_f32_16x16x32_bf16 v[4:7], v[210:213], v[202:205], v[4:7]
	v_mfma_f32_16x16x32_bf16 v[0:3], v[218:221], v[202:205], v[0:3]
	v_mfma_f32_16x16x32_bf16 v[52:55], v[214:217], v[148:151], v[52:55]
	v_mfma_f32_16x16x32_bf16 v[48:51], v[224:227], v[148:151], v[48:51]
	v_mfma_f32_16x16x32_bf16 v[36:39], v[214:217], v[184:187], v[36:39]
	v_mfma_f32_16x16x32_bf16 v[32:35], v[224:227], v[184:187], v[32:35]
	v_mfma_f32_16x16x32_bf16 v[20:23], v[214:217], v[198:201], v[20:23]
	v_mfma_f32_16x16x32_bf16 v[16:19], v[224:227], v[198:201], v[16:19]
	s_setprio 2
	s_barrier
	v_mfma_f32_16x16x32_bf16 v[4:7], v[214:217], v[206:209], v[4:7]
	v_mfma_f32_16x16x32_bf16 v[0:3], v[224:227], v[206:209], v[0:3]
	s_setprio 0
	s_add_i32 s19, s19, 2
	s_add_u32 s10, s10, 0x100
	s_addc_u32 s11, s11, 0
	s_add_u32 s17, s17, 0x100
	s_addc_u32 s18, s18, 0
	s_cmp_gt_u32 s19, 13
	s_cbranch_scc0 .LBB0_632
	v_lshl_add_u32 v128, s0, 8, v177
	s_mov_b64 s[6:7], -1
	s_and_b64 vcc, exec, s[8:9]
	v_ashrrev_i32_e32 v129, 31, v128
	s_cbranch_vccz .LBB0_635
	v_lshl_add_u64 v[130:131], v[128:129], 2, s[60:61]
	global_load_dword v132, v[130:131], off
	global_load_dword v133, v[130:131], off offset:64
	global_load_dword v134, v[130:131], off offset:128
	global_load_dword v135, v[130:131], off offset:192
	global_load_dword v136, v[130:131], off offset:512
	global_load_dword v137, v[130:131], off offset:576
	global_load_dword v138, v[130:131], off offset:640
	global_load_dword v139, v[130:131], off offset:704
	s_lshl_b32 s0, s0, 3
	s_add_i32 s0, s0, s87
	s_ashr_i32 s1, s0, 31
	s_lshl_b64 s[0:1], s[0:1], 17
	v_lshl_add_u64 v[130:131], v[166:167], 0, s[0:1]
	s_mov_b64 s[6:7], 0
	s_waitcnt vmcnt(0)
; DI unsigned pk_bf16(float lo, float hi) { f32x2 v = {lo, hi}; return __builtin_bit_cast(unsigned, __builtin_convertvector(v, bf16v2)); }
; DI float fast_sigmoid(float x) { return __builtin_amdgcn_rcpf(1.0f + __expf(-x)); }
;     DI void operator()(AccRef acc, const Unit& u, int wr, int wc, int fr, int fq) const {
;         const int row0 = u.pm * 256 + wr * 64 + fr;
;         bf16_t* Gp = gab + (size_t)(u.pm * 8 + u.pn) * 65536 + (wr * 64 + fr) * 256 + wc * 32 + 8 * fq;
;         const RowScales rsc = load_rowscales(ss, row0);
; #pragma unroll
;         for (int ai = 0; ai < 2; ++ai)
; #pragma unroll
;             for (int m = 0; m < 4; ++m)
; #pragma unroll
;                 for (int bj = 0; bj < 2; ++bj) {
;                     const float rs = rsc.r[ai][m];
;                     const f32x4 r0 = acc[ai][bj][m][0] * rs, r1 = acc[ai][bj][m][1] * rs;
;                     u32x4 w;
;                     w.x = pk_bf16(fast_sigmoid(r0[0]), fast_sigmoid(r0[1])); w.y = pk_bf16(fast_sigmoid(r0[2]), fast_sigmoid(r0[3]));
;                     w.z = pk_bf16(fast_sigmoid(r1[0]), fast_sigmoid(r1[1])); w.w = pk_bf16(fast_sigmoid(r1[2]), fast_sigmoid(r1[3]));
;                     *(u32x4*)(Gp + (ai * 128 + m * 16) * 256 + bj * 128) = w;
;                 }
	v_fmamk_f32 v132, v132, 0x3a800000, v193
	v_mul_f32_e32 v140, 0x4b800000, v132
	v_cmp_gt_f32_e32 vcc, s80, v132
	v_fmamk_f32 v134, v134, 0x3a800000, v193
	v_fmamk_f32 v136, v136, 0x3a800000, v193
	v_fmamk_f32 v137, v137, 0x3a800000, v193
	v_fmamk_f32 v138, v138, 0x3a800000, v193
	v_fmamk_f32 v139, v139, 0x3a800000, v193
	v_mul_f32_e32 v144, 0x4b800000, v136
	v_mul_f32_e32 v145, 0x4b800000, v137
	v_cndmask_b32_e32 v132, v132, v140, vcc
	v_cmp_gt_f32_e64 s[12:13], s80, v136
	v_cmp_gt_f32_e64 s[14:15], s80, v137
	v_fmamk_f32 v133, v133, 0x3a800000, v193
	v_fmamk_f32 v135, v135, 0x3a800000, v193
	v_mul_f32_e32 v142, 0x4b800000, v134
	v_mul_f32_e32 v146, 0x4b800000, v138
	v_mul_f32_e32 v147, 0x4b800000, v139
	v_cmp_gt_f32_e64 s[8:9], s80, v134
	v_cndmask_b32_e64 v136, v136, v144, s[12:13]
	v_cndmask_b32_e64 v137, v137, v145, s[14:15]
	v_cmp_gt_f32_e64 s[16:17], s80, v138
	v_cmp_gt_f32_e64 s[18:19], s80, v139
	v_rsq_f32_e32 v132, v132
	v_mul_f32_e32 v141, 0x4b800000, v133
	v_mul_f32_e32 v143, 0x4b800000, v135
	v_cmp_gt_f32_e64 s[0:1], s80, v133
	v_cndmask_b32_e64 v134, v134, v142, s[8:9]
	v_cmp_gt_f32_e64 s[10:11], s80, v135
	v_cndmask_b32_e64 v138, v138, v146, s[16:17]
	v_cndmask_b32_e64 v139, v139, v147, s[18:19]
	v_rsq_f32_e32 v136, v136
	v_rsq_f32_e32 v137, v137
	v_cndmask_b32_e64 v133, v133, v141, s[0:1]
	v_cndmask_b32_e64 v135, v135, v143, s[10:11]
	v_rsq_f32_e32 v134, v134
	v_rsq_f32_e32 v141, v138
	v_rsq_f32_e32 v139, v139
	v_rsq_f32_e32 v133, v133
	v_rsq_f32_e32 v135, v135
	v_mul_f32_e32 v138, 0x45800000, v132
	v_mul_f32_e32 v144, 0x45800000, v136
	v_mul_f32_e32 v145, 0x45800000, v137
	v_cndmask_b32_e32 v148, v132, v138, vcc
	v_mul_f32_e32 v142, 0x45800000, v134
	v_mul_f32_e32 v146, 0x45800000, v141
	v_mul_f32_e32 v147, 0x45800000, v139
	v_cndmask_b32_e64 v138, v136, v144, s[12:13]
	v_cndmask_b32_e64 v136, v137, v145, s[14:15]
	v_pk_mul_f32 v[144:145], v[126:127], v[148:149] op_sel_hi:[1,0]
	v_pk_mul_f32 v[152:153], v[122:123], v[148:149] op_sel_hi:[1,0]
	v_mul_f32_e32 v140, 0x45800000, v133
	v_mul_f32_e32 v143, 0x45800000, v135
	v_cndmask_b32_e64 v142, v134, v142, s[8:9]
	v_cndmask_b32_e64 v134, v141, v146, s[16:17]
	v_cndmask_b32_e64 v132, v139, v147, s[18:19]
	v_pk_mul_f32 v[146:147], v[124:125], v[148:149] op_sel_hi:[1,0]
	v_pk_mul_f32 v[154:155], v[120:121], v[148:149] op_sel_hi:[1,0]
	v_mul_f32_e32 v137, 0xbfb8aa3b, v144
	v_mul_f32_e32 v144, 0xbfb8aa3b, v152
	v_cndmask_b32_e64 v150, v133, v140, s[0:1]
	v_cndmask_b32_e64 v140, v135, v143, s[10:11]
	v_mul_f32_e32 v133, 0xbfb8aa3b, v146
	v_mul_f32_e32 v135, 0xbfb8aa3b, v147
	v_mul_f32_e32 v139, 0xbfb8aa3b, v145
	v_mul_f32_e32 v141, 0xbfb8aa3b, v154
	v_mul_f32_e32 v143, 0xbfb8aa3b, v155
	v_exp_f32_e32 v144, v144
	v_mul_f32_e32 v145, 0xbfb8aa3b, v153
	v_exp_f32_e32 v133, v133
	v_exp_f32_e32 v135, v135
	v_exp_f32_e32 v137, v137
	v_exp_f32_e32 v139, v139
	v_exp_f32_e32 v141, v141
	v_exp_f32_e32 v143, v143
	v_exp_f32_e32 v145, v145
	v_add_f32_e32 v144, 1.0, v144
	v_add_f32_e32 v133, 1.0, v133
	v_add_f32_e32 v135, 1.0, v135
	v_add_f32_e32 v137, 1.0, v137
	v_add_f32_e32 v139, 1.0, v139
	v_add_f32_e32 v141, 1.0, v141
	v_add_f32_e32 v143, 1.0, v143
	v_rcp_f32_e32 v147, v144
	v_add_f32_e32 v144, 1.0, v145
	v_rcp_f32_e32 v133, v133
	v_rcp_f32_e32 v135, v135
	v_rcp_f32_e32 v137, v137
	v_rcp_f32_e32 v139, v139
	v_rcp_f32_e32 v141, v141
	v_rcp_f32_e32 v143, v143
	v_rcp_f32_e32 v149, v144
	v_cvt_pk_bf16_f32 v144, v133, v135
	v_cvt_pk_bf16_f32 v145, v137, v139
	v_cvt_pk_bf16_f32 v146, v141, v143
	v_cvt_pk_bf16_f32 v147, v147, v149
	global_store_dwordx4 v[130:131], v[144:147], off
	v_pk_mul_f32 v[152:153], v[114:115], v[148:149] op_sel_hi:[1,0]
	s_nop 0
	v_pk_mul_f32 v[144:145], v[118:119], v[148:149] op_sel_hi:[1,0]
	v_pk_mul_f32 v[146:147], v[116:117], v[148:149] op_sel_hi:[1,0]
	v_mul_f32_e32 v137, 0xbfb8aa3b, v144
	v_mul_f32_e32 v133, 0xbfb8aa3b, v146
	v_mul_f32_e32 v135, 0xbfb8aa3b, v147
	v_pk_mul_f32 v[146:147], v[112:113], v[148:149] op_sel_hi:[1,0]
	v_mul_f32_e32 v144, 0xbfb8aa3b, v152
	v_mul_f32_e32 v139, 0xbfb8aa3b, v145
	v_mul_f32_e32 v141, 0xbfb8aa3b, v146
	v_mul_f32_e32 v143, 0xbfb8aa3b, v147
	v_exp_f32_e32 v144, v144
	v_mul_f32_e32 v145, 0xbfb8aa3b, v153
	v_exp_f32_e32 v133, v133
	v_exp_f32_e32 v135, v135
	v_exp_f32_e32 v137, v137
	v_exp_f32_e32 v139, v139
	v_exp_f32_e32 v141, v141
	v_exp_f32_e32 v143, v143
	v_exp_f32_e32 v145, v145
	v_add_f32_e32 v144, 1.0, v144
	v_add_f32_e32 v133, 1.0, v133
	v_add_f32_e32 v135, 1.0, v135
	v_add_f32_e32 v137, 1.0, v137
	v_add_f32_e32 v139, 1.0, v139
	v_add_f32_e32 v141, 1.0, v141
	v_add_f32_e32 v143, 1.0, v143
	v_rcp_f32_e32 v147, v144
	v_add_f32_e32 v144, 1.0, v145
	v_rcp_f32_e32 v133, v133
	v_rcp_f32_e32 v135, v135
	v_rcp_f32_e32 v137, v137
	v_rcp_f32_e32 v139, v139
	v_rcp_f32_e32 v141, v141
	v_rcp_f32_e32 v143, v143
	v_rcp_f32_e32 v148, v144
	v_cvt_pk_bf16_f32 v144, v133, v135
	v_cvt_pk_bf16_f32 v145, v137, v139
	v_cvt_pk_bf16_f32 v146, v141, v143
	v_cvt_pk_bf16_f32 v147, v147, v148
	global_store_dwordx4 v[130:131], v[144:147], off offset:256
	v_pk_mul_f32 v[148:149], v[106:107], v[150:151] op_sel_hi:[1,0]
	v_pk_mul_f32 v[152:153], v[98:99], v[150:151] op_sel_hi:[1,0]
	v_pk_mul_f32 v[144:145], v[110:111], v[150:151] op_sel_hi:[1,0]
	v_pk_mul_f32 v[146:147], v[108:109], v[150:151] op_sel_hi:[1,0]
	v_mul_f32_e32 v137, 0xbfb8aa3b, v144
	v_mul_f32_e32 v144, 0xbfb8aa3b, v148
	v_mul_f32_e32 v133, 0xbfb8aa3b, v146
	v_mul_f32_e32 v135, 0xbfb8aa3b, v147
	v_pk_mul_f32 v[146:147], v[104:105], v[150:151] op_sel_hi:[1,0]
	v_mul_f32_e32 v139, 0xbfb8aa3b, v145
	v_exp_f32_e32 v144, v144
	v_mul_f32_e32 v145, 0xbfb8aa3b, v149
	v_mul_f32_e32 v141, 0xbfb8aa3b, v146
; DI unsigned pk_bf16(float lo, float hi) { f32x2 v = {lo, hi}; return __builtin_bit_cast(unsigned, __builtin_convertvector(v, bf16v2)); }
; DI float fast_sigmoid(float x) { return __builtin_amdgcn_rcpf(1.0f + __expf(-x)); }
;     DI void operator()(AccRef acc, const Unit& u, int wr, int wc, int fr, int fq) const {
;     ...
;         for (int ai = 0; ai < 2; ++ai)
; #pragma unroll
;             for (int m = 0; m < 4; ++m)
; #pragma unroll
;                 for (int bj = 0; bj < 2; ++bj) {
;                     const float rs = rsc.r[ai][m];
;                     const f32x4 r0 = acc[ai][bj][m][0] * rs, r1 = acc[ai][bj][m][1] * rs;
;                     u32x4 w;
;                     w.x = pk_bf16(fast_sigmoid(r0[0]), fast_sigmoid(r0[1])); w.y = pk_bf16(fast_sigmoid(r0[2]), fast_sigmoid(r0[3]));
;                     w.z = pk_bf16(fast_sigmoid(r1[0]), fast_sigmoid(r1[1])); w.w = pk_bf16(fast_sigmoid(r1[2]), fast_sigmoid(r1[3]));
;                     *(u32x4*)(Gp + (ai * 128 + m * 16) * 256 + bj * 128) = w;
;                 }
	v_mul_f32_e32 v143, 0xbfb8aa3b, v147
	v_exp_f32_e32 v145, v145
	v_exp_f32_e32 v133, v133
	v_exp_f32_e32 v135, v135
	v_exp_f32_e32 v137, v137
	v_exp_f32_e32 v139, v139
	v_exp_f32_e32 v141, v141
	v_exp_f32_e32 v143, v143
	v_add_f32_e32 v144, 1.0, v144
	v_rcp_f32_e32 v147, v144
	v_add_f32_e32 v144, 1.0, v145
	v_add_f32_e32 v133, 1.0, v133
	v_add_f32_e32 v135, 1.0, v135
	v_add_f32_e32 v137, 1.0, v137
	v_add_f32_e32 v139, 1.0, v139
	v_add_f32_e32 v141, 1.0, v141
	v_add_f32_e32 v143, 1.0, v143
	v_rcp_f32_e32 v148, v144
	v_rcp_f32_e32 v133, v133
	v_rcp_f32_e32 v135, v135
	v_rcp_f32_e32 v137, v137
	v_rcp_f32_e32 v139, v139
	v_rcp_f32_e32 v141, v141
	v_rcp_f32_e32 v143, v143
	v_cvt_pk_bf16_f32 v147, v147, v148
	v_add_co_u32_e32 v148, vcc, s59, v130
	v_cvt_pk_bf16_f32 v144, v133, v135
	v_cvt_pk_bf16_f32 v145, v137, v139
	v_cvt_pk_bf16_f32 v146, v141, v143
	v_addc_co_u32_e32 v149, vcc, 0, v131, vcc
	global_store_dwordx4 v[148:149], v[144:147], off
	s_nop 1
	v_pk_mul_f32 v[144:145], v[102:103], v[150:151] op_sel_hi:[1,0]
	v_pk_mul_f32 v[146:147], v[100:101], v[150:151] op_sel_hi:[1,0]
	v_mul_f32_e32 v137, 0xbfb8aa3b, v144
	v_mul_f32_e32 v133, 0xbfb8aa3b, v146
	v_mul_f32_e32 v135, 0xbfb8aa3b, v147
	v_pk_mul_f32 v[146:147], v[96:97], v[150:151] op_sel_hi:[1,0]
	v_mul_f32_e32 v144, 0xbfb8aa3b, v152
	v_mul_f32_e32 v139, 0xbfb8aa3b, v145
	v_mul_f32_e32 v141, 0xbfb8aa3b, v146
	v_mul_f32_e32 v143, 0xbfb8aa3b, v147
	v_exp_f32_e32 v144, v144
	v_mul_f32_e32 v145, 0xbfb8aa3b, v153
	v_exp_f32_e32 v133, v133
	v_exp_f32_e32 v135, v135
	v_exp_f32_e32 v137, v137
	v_exp_f32_e32 v139, v139
	v_exp_f32_e32 v141, v141
	v_exp_f32_e32 v143, v143
	v_exp_f32_e32 v145, v145
	v_add_f32_e32 v144, 1.0, v144
	v_add_f32_e32 v133, 1.0, v133
	v_add_f32_e32 v135, 1.0, v135
	v_add_f32_e32 v137, 1.0, v137
	v_add_f32_e32 v139, 1.0, v139
	v_add_f32_e32 v141, 1.0, v141
	v_add_f32_e32 v143, 1.0, v143
	v_rcp_f32_e32 v147, v144
	v_add_f32_e32 v144, 1.0, v145
	v_rcp_f32_e32 v133, v133
	v_rcp_f32_e32 v135, v135
	v_rcp_f32_e32 v137, v137
	v_rcp_f32_e32 v139, v139
	v_rcp_f32_e32 v141, v141
	v_rcp_f32_e32 v143, v143
	v_rcp_f32_e32 v150, v144
	v_cvt_pk_bf16_f32 v144, v133, v135
	v_cvt_pk_bf16_f32 v145, v137, v139
	v_cvt_pk_bf16_f32 v146, v141, v143
	v_cvt_pk_bf16_f32 v147, v147, v150
	global_store_dwordx4 v[148:149], v[144:147], off offset:256
	v_pk_mul_f32 v[148:149], v[90:91], v[142:143] op_sel_hi:[1,0]
	s_nop 0
	v_pk_mul_f32 v[144:145], v[94:95], v[142:143] op_sel_hi:[1,0]
	v_pk_mul_f32 v[146:147], v[92:93], v[142:143] op_sel_hi:[1,0]
	v_mul_f32_e32 v137, 0xbfb8aa3b, v144
	v_mul_f32_e32 v144, 0xbfb8aa3b, v148
	v_mul_f32_e32 v133, 0xbfb8aa3b, v146
	v_mul_f32_e32 v135, 0xbfb8aa3b, v147
	v_pk_mul_f32 v[146:147], v[88:89], v[142:143] op_sel_hi:[1,0]
	v_mul_f32_e32 v139, 0xbfb8aa3b, v145
	v_exp_f32_e32 v144, v144
	v_mul_f32_e32 v145, 0xbfb8aa3b, v149
	v_mul_f32_e32 v141, 0xbfb8aa3b, v146
	v_mul_f32_e32 v143, 0xbfb8aa3b, v147
	v_exp_f32_e32 v145, v145
	v_exp_f32_e32 v133, v133
	v_exp_f32_e32 v135, v135
	v_exp_f32_e32 v137, v137
	v_exp_f32_e32 v139, v139
	v_exp_f32_e32 v141, v141
	v_exp_f32_e32 v143, v143
	v_add_f32_e32 v144, 1.0, v144
	v_rcp_f32_e32 v147, v144
	v_add_f32_e32 v144, 1.0, v145
	v_add_f32_e32 v133, 1.0, v133
	v_add_f32_e32 v135, 1.0, v135
	v_add_f32_e32 v137, 1.0, v137
	v_add_f32_e32 v139, 1.0, v139
	v_add_f32_e32 v141, 1.0, v141
	v_add_f32_e32 v143, 1.0, v143
	v_rcp_f32_e32 v148, v144
	v_rcp_f32_e32 v133, v133
	v_rcp_f32_e32 v135, v135
	v_rcp_f32_e32 v137, v137
	v_rcp_f32_e32 v139, v139
	v_rcp_f32_e32 v141, v141
	v_rcp_f32_e32 v143, v143
	v_cvt_pk_bf16_f32 v147, v147, v148
	v_add_co_u32_e32 v148, vcc, s66, v130
	v_cvt_pk_bf16_f32 v144, v133, v135
	v_cvt_pk_bf16_f32 v145, v137, v139
	v_cvt_pk_bf16_f32 v146, v141, v143
	v_addc_co_u32_e32 v149, vcc, 0, v131, vcc
	global_store_dwordx4 v[148:149], v[144:147], off
	v_pk_mul_f32 v[150:151], v[82:83], v[142:143] op_sel_hi:[1,0]
	s_nop 0
	v_pk_mul_f32 v[144:145], v[86:87], v[142:143] op_sel_hi:[1,0]
	v_pk_mul_f32 v[146:147], v[84:85], v[142:143] op_sel_hi:[1,0]
	v_pk_mul_f32 v[142:143], v[80:81], v[142:143] op_sel_hi:[1,0]
	v_mul_f32_e32 v133, 0xbfb8aa3b, v146
	v_mul_f32_e32 v141, 0xbfb8aa3b, v142
	v_mul_f32_e32 v142, 0xbfb8aa3b, v143
	v_exp_f32_e32 v142, v142
	v_mul_f32_e32 v143, 0xbfb8aa3b, v150
	v_mul_f32_e32 v135, 0xbfb8aa3b, v147
	v_mul_f32_e32 v137, 0xbfb8aa3b, v144
	v_mul_f32_e32 v139, 0xbfb8aa3b, v145
	v_exp_f32_e32 v143, v143
	v_mul_f32_e32 v144, 0xbfb8aa3b, v151
	v_exp_f32_e32 v133, v133
	v_exp_f32_e32 v135, v135
	v_exp_f32_e32 v137, v137
	v_exp_f32_e32 v139, v139
	v_exp_f32_e32 v141, v141
	v_exp_f32_e32 v144, v144
	v_add_f32_e32 v142, 1.0, v142
	v_rcp_f32_e32 v145, v142
	v_add_f32_e32 v142, 1.0, v143
	v_add_f32_e32 v133, 1.0, v133
	v_add_f32_e32 v135, 1.0, v135
	v_add_f32_e32 v137, 1.0, v137
	v_add_f32_e32 v139, 1.0, v139
	v_add_f32_e32 v141, 1.0, v141
	v_rcp_f32_e32 v146, v142
	v_add_f32_e32 v142, 1.0, v144
	v_rcp_f32_e32 v133, v133
	v_rcp_f32_e32 v135, v135
	v_rcp_f32_e32 v137, v137
	v_rcp_f32_e32 v139, v139
	v_rcp_f32_e32 v141, v141
	v_rcp_f32_e32 v147, v142
	v_cvt_pk_bf16_f32 v142, v133, v135
	v_cvt_pk_bf16_f32 v143, v137, v139
	v_cvt_pk_bf16_f32 v144, v141, v145
	v_cvt_pk_bf16_f32 v145, v146, v147
	global_store_dwordx4 v[148:149], v[142:145], off offset:256
	v_pk_mul_f32 v[146:147], v[74:75], v[140:141] op_sel_hi:[1,0]
	s_nop 0
	v_pk_mul_f32 v[144:145], v[76:77], v[140:141] op_sel_hi:[1,0]
	v_pk_mul_f32 v[142:143], v[78:79], v[140:141] op_sel_hi:[1,0]
	v_mul_f32_e32 v133, 0xbfb8aa3b, v144
	v_mul_f32_e32 v135, 0xbfb8aa3b, v145
	v_pk_mul_f32 v[144:145], v[72:73], v[140:141] op_sel_hi:[1,0]
	v_mul_f32_e32 v137, 0xbfb8aa3b, v142
; DI unsigned pk_bf16(float lo, float hi) { f32x2 v = {lo, hi}; return __builtin_bit_cast(unsigned, __builtin_convertvector(v, bf16v2)); }
; DI float fast_sigmoid(float x) { return __builtin_amdgcn_rcpf(1.0f + __expf(-x)); }
;     DI void operator()(AccRef acc, const Unit& u, int wr, int wc, int fr, int fq) const {
;     ...
;         for (int ai = 0; ai < 2; ++ai)
; #pragma unroll
;             for (int m = 0; m < 4; ++m)
; #pragma unroll
;                 for (int bj = 0; bj < 2; ++bj) {
;                     const float rs = rsc.r[ai][m];
;                     const f32x4 r0 = acc[ai][bj][m][0] * rs, r1 = acc[ai][bj][m][1] * rs;
;                     u32x4 w;
;                     w.x = pk_bf16(fast_sigmoid(r0[0]), fast_sigmoid(r0[1])); w.y = pk_bf16(fast_sigmoid(r0[2]), fast_sigmoid(r0[3]));
;                     w.z = pk_bf16(fast_sigmoid(r1[0]), fast_sigmoid(r1[1])); w.w = pk_bf16(fast_sigmoid(r1[2]), fast_sigmoid(r1[3]));
;                     *(u32x4*)(Gp + (ai * 128 + m * 16) * 256 + bj * 128) = w;
;                 }
	v_mul_f32_e32 v142, 0xbfb8aa3b, v145
	v_mul_f32_e32 v139, 0xbfb8aa3b, v143
	v_exp_f32_e32 v142, v142
	v_mul_f32_e32 v143, 0xbfb8aa3b, v146
	v_mul_f32_e32 v141, 0xbfb8aa3b, v144
	v_exp_f32_e32 v143, v143
	v_mul_f32_e32 v144, 0xbfb8aa3b, v147
	v_exp_f32_e32 v141, v141
	v_exp_f32_e32 v144, v144
	v_exp_f32_e32 v133, v133
	v_exp_f32_e32 v135, v135
	v_exp_f32_e32 v137, v137
	v_exp_f32_e32 v139, v139
	v_add_f32_e32 v142, 1.0, v142
	v_rcp_f32_e32 v145, v142
	v_add_f32_e32 v142, 1.0, v143
	v_add_f32_e32 v141, 1.0, v141
	v_rcp_f32_e32 v146, v142
	v_add_f32_e32 v142, 1.0, v144
	v_add_f32_e32 v133, 1.0, v133
	v_add_f32_e32 v135, 1.0, v135
	v_add_f32_e32 v137, 1.0, v137
	v_add_f32_e32 v139, 1.0, v139
	v_rcp_f32_e32 v141, v141
	v_rcp_f32_e32 v147, v142
	v_rcp_f32_e32 v133, v133
	v_rcp_f32_e32 v135, v135
	v_rcp_f32_e32 v137, v137
	v_rcp_f32_e32 v139, v139
	v_cvt_pk_bf16_f32 v144, v141, v145
	v_cvt_pk_bf16_f32 v145, v146, v147
	v_add_co_u32_e32 v146, vcc, s67, v130
	v_cvt_pk_bf16_f32 v142, v133, v135
	v_cvt_pk_bf16_f32 v143, v137, v139
	v_addc_co_u32_e32 v147, vcc, 0, v131, vcc
	global_store_dwordx4 v[146:147], v[142:145], off
	v_pk_mul_f32 v[148:149], v[66:67], v[140:141] op_sel_hi:[1,0]
	s_nop 0
	v_pk_mul_f32 v[142:143], v[70:71], v[140:141] op_sel_hi:[1,0]
	v_pk_mul_f32 v[144:145], v[68:69], v[140:141] op_sel_hi:[1,0]
	v_pk_mul_f32 v[140:141], v[64:65], v[140:141] op_sel_hi:[1,0]
	v_mul_f32_e32 v137, 0xbfb8aa3b, v142
	v_mul_f32_e32 v140, 0xbfb8aa3b, v140
	v_exp_f32_e32 v140, v140
	v_mul_f32_e32 v141, 0xbfb8aa3b, v141
	v_exp_f32_e32 v141, v141
	v_mul_f32_e32 v133, 0xbfb8aa3b, v144
	v_add_f32_e32 v140, 1.0, v140
	v_rcp_f32_e32 v142, v140
	v_add_f32_e32 v140, 1.0, v141
	v_mul_f32_e32 v141, 0xbfb8aa3b, v148
	v_mul_f32_e32 v135, 0xbfb8aa3b, v145
	v_mul_f32_e32 v139, 0xbfb8aa3b, v143
	v_exp_f32_e32 v141, v141
	v_mul_f32_e32 v143, 0xbfb8aa3b, v149
	v_exp_f32_e32 v133, v133
	v_exp_f32_e32 v135, v135
	v_exp_f32_e32 v137, v137
	v_exp_f32_e32 v139, v139
	v_exp_f32_e32 v143, v143
	v_rcp_f32_e32 v144, v140
	v_add_f32_e32 v140, 1.0, v141
	v_add_f32_e32 v133, 1.0, v133
	v_add_f32_e32 v135, 1.0, v135
	v_add_f32_e32 v137, 1.0, v137
	v_add_f32_e32 v139, 1.0, v139
	v_rcp_f32_e32 v145, v140
	v_add_f32_e32 v140, 1.0, v143
	v_rcp_f32_e32 v133, v133
	v_rcp_f32_e32 v135, v135
	v_rcp_f32_e32 v137, v137
	v_rcp_f32_e32 v139, v139
	v_rcp_f32_e32 v143, v140
	v_cvt_pk_bf16_f32 v140, v133, v135
	v_cvt_pk_bf16_f32 v142, v142, v144
	v_cvt_pk_bf16_f32 v141, v137, v139
	v_cvt_pk_bf16_f32 v143, v145, v143
	global_store_dwordx4 v[146:147], v[140:143], off offset:256
	v_pk_mul_f32 v[144:145], v[58:59], v[138:139] op_sel_hi:[1,0]
	s_nop 0
	v_pk_mul_f32 v[142:143], v[60:61], v[138:139] op_sel_hi:[1,0]
	v_pk_mul_f32 v[140:141], v[62:63], v[138:139] op_sel_hi:[1,0]
	v_mul_f32_e32 v133, 0xbfb8aa3b, v142
	v_mul_f32_e32 v135, 0xbfb8aa3b, v143
	v_pk_mul_f32 v[142:143], v[56:57], v[138:139] op_sel_hi:[1,0]
	v_mul_f32_e32 v137, 0xbfb8aa3b, v140
	v_mul_f32_e32 v140, 0xbfb8aa3b, v142
	v_mul_f32_e32 v139, 0xbfb8aa3b, v141
	v_exp_f32_e32 v140, v140
	v_mul_f32_e32 v141, 0xbfb8aa3b, v143
	v_exp_f32_e32 v141, v141
	v_mul_f32_e32 v143, 0xbfb8aa3b, v145
	v_add_f32_e32 v140, 1.0, v140
	v_rcp_f32_e32 v142, v140
	v_add_f32_e32 v140, 1.0, v141
	v_mul_f32_e32 v141, 0xbfb8aa3b, v144
	v_exp_f32_e32 v141, v141
	v_exp_f32_e32 v133, v133
	v_exp_f32_e32 v135, v135
	v_exp_f32_e32 v137, v137
	v_exp_f32_e32 v139, v139
	v_exp_f32_e32 v143, v143
	v_rcp_f32_e32 v144, v140
	v_add_f32_e32 v140, 1.0, v141
	v_add_f32_e32 v133, 1.0, v133
	v_add_f32_e32 v135, 1.0, v135
	v_add_f32_e32 v137, 1.0, v137
	v_add_f32_e32 v139, 1.0, v139
	v_rcp_f32_e32 v145, v140
	v_add_f32_e32 v140, 1.0, v143
	v_rcp_f32_e32 v133, v133
	v_rcp_f32_e32 v135, v135
	v_rcp_f32_e32 v137, v137
	v_rcp_f32_e32 v139, v139
	v_rcp_f32_e32 v143, v140
	v_cvt_pk_bf16_f32 v142, v142, v144
	v_add_co_u32_e32 v144, vcc, s62, v130
	v_cvt_pk_bf16_f32 v140, v133, v135
	v_cvt_pk_bf16_f32 v141, v137, v139
	v_cvt_pk_bf16_f32 v143, v145, v143
	v_addc_co_u32_e32 v145, vcc, 0, v131, vcc
	global_store_dwordx4 v[144:145], v[140:143], off
	v_pk_mul_f32 v[146:147], v[50:51], v[138:139] op_sel_hi:[1,0]
	s_nop 0
	v_pk_mul_f32 v[140:141], v[54:55], v[138:139] op_sel_hi:[1,0]
	v_pk_mul_f32 v[142:143], v[52:53], v[138:139] op_sel_hi:[1,0]
	v_pk_mul_f32 v[138:139], v[48:49], v[138:139] op_sel_hi:[1,0]
	v_mul_f32_e32 v137, 0xbfb8aa3b, v140
	v_mul_f32_e32 v138, 0xbfb8aa3b, v138
	v_exp_f32_e32 v138, v138
	v_mul_f32_e32 v139, 0xbfb8aa3b, v139
	v_exp_f32_e32 v139, v139
	v_mul_f32_e32 v140, 0xbfb8aa3b, v141
	v_add_f32_e32 v138, 1.0, v138
	v_rcp_f32_e32 v141, v138
	v_add_f32_e32 v138, 1.0, v139
	v_mul_f32_e32 v139, 0xbfb8aa3b, v146
	v_mul_f32_e32 v133, 0xbfb8aa3b, v142
	v_mul_f32_e32 v135, 0xbfb8aa3b, v143
	v_exp_f32_e32 v139, v139
	v_mul_f32_e32 v142, 0xbfb8aa3b, v147
	v_exp_f32_e32 v133, v133
	v_exp_f32_e32 v135, v135
	v_exp_f32_e32 v137, v137
	v_exp_f32_e32 v140, v140
	v_exp_f32_e32 v142, v142
	v_rcp_f32_e32 v143, v138
	v_add_f32_e32 v138, 1.0, v139
	v_add_f32_e32 v133, 1.0, v133
	v_add_f32_e32 v135, 1.0, v135
	v_add_f32_e32 v137, 1.0, v137
	v_add_f32_e32 v140, 1.0, v140
	v_rcp_f32_e32 v146, v138
	v_add_f32_e32 v138, 1.0, v142
	v_rcp_f32_e32 v133, v133
	v_rcp_f32_e32 v135, v135
	v_rcp_f32_e32 v137, v137
	v_rcp_f32_e32 v140, v140
	v_rcp_f32_e32 v142, v138
	v_cvt_pk_bf16_f32 v138, v133, v135
	v_cvt_pk_bf16_f32 v139, v137, v140
	v_cvt_pk_bf16_f32 v140, v141, v143
	v_cvt_pk_bf16_f32 v141, v146, v142
	global_store_dwordx4 v[144:145], v[138:141], off offset:256
	v_pk_mul_f32 v[142:143], v[42:43], v[136:137] op_sel_hi:[1,0]
	s_nop 0
	v_pk_mul_f32 v[138:139], v[46:47], v[136:137] op_sel_hi:[1,0]
; DI unsigned pk_bf16(float lo, float hi) { f32x2 v = {lo, hi}; return __builtin_bit_cast(unsigned, __builtin_convertvector(v, bf16v2)); }
; DI float fast_sigmoid(float x) { return __builtin_amdgcn_rcpf(1.0f + __expf(-x)); }
;     DI void operator()(AccRef acc, const Unit& u, int wr, int wc, int fr, int fq) const {
;     ...
;         for (int ai = 0; ai < 2; ++ai)
; #pragma unroll
;             for (int m = 0; m < 4; ++m)
; #pragma unroll
;                 for (int bj = 0; bj < 2; ++bj) {
;                     const float rs = rsc.r[ai][m];
;                     const f32x4 r0 = acc[ai][bj][m][0] * rs, r1 = acc[ai][bj][m][1] * rs;
;                     u32x4 w;
;                     w.x = pk_bf16(fast_sigmoid(r0[0]), fast_sigmoid(r0[1])); w.y = pk_bf16(fast_sigmoid(r0[2]), fast_sigmoid(r0[3]));
;                     w.z = pk_bf16(fast_sigmoid(r1[0]), fast_sigmoid(r1[1])); w.w = pk_bf16(fast_sigmoid(r1[2]), fast_sigmoid(r1[3]));
;                     *(u32x4*)(Gp + (ai * 128 + m * 16) * 256 + bj * 128) = w;
;                 }
	v_pk_mul_f32 v[140:141], v[44:45], v[136:137] op_sel_hi:[1,0]
	s_nop 0
	v_mul_f32_e32 v133, 0xbfb8aa3b, v140
	v_mul_f32_e32 v135, 0xbfb8aa3b, v141
	v_pk_mul_f32 v[140:141], v[40:41], v[136:137] op_sel_hi:[1,0]
	v_mul_f32_e32 v137, 0xbfb8aa3b, v138
	v_mul_f32_e32 v138, 0xbfb8aa3b, v139
	v_exp_f32_e32 v138, v138
	v_mul_f32_e32 v139, 0xbfb8aa3b, v140
	v_exp_f32_e32 v139, v139
	v_mul_f32_e32 v140, 0xbfb8aa3b, v141
	v_exp_f32_e32 v140, v140
	v_add_f32_e32 v138, 1.0, v138
	v_rcp_f32_e32 v141, v138
	v_add_f32_e32 v138, 1.0, v139
	v_mul_f32_e32 v139, 0xbfb8aa3b, v142
	v_rcp_f32_e32 v144, v138
	v_add_f32_e32 v138, 1.0, v140
	v_exp_f32_e32 v139, v139
	v_mul_f32_e32 v140, 0xbfb8aa3b, v143
	v_exp_f32_e32 v133, v133
	v_exp_f32_e32 v135, v135
	v_exp_f32_e32 v137, v137
	v_exp_f32_e32 v140, v140
	v_rcp_f32_e32 v142, v138
	v_add_f32_e32 v138, 1.0, v139
	v_add_f32_e32 v133, 1.0, v133
	v_add_f32_e32 v135, 1.0, v135
	v_add_f32_e32 v137, 1.0, v137
	v_rcp_f32_e32 v143, v138
	v_add_f32_e32 v138, 1.0, v140
	v_rcp_f32_e32 v133, v133
	v_rcp_f32_e32 v135, v135
	v_rcp_f32_e32 v137, v137
	v_rcp_f32_e32 v145, v138
	v_cvt_pk_bf16_f32 v140, v144, v142
	v_add_co_u32_e32 v142, vcc, s63, v130
	v_cvt_pk_bf16_f32 v138, v133, v135
	v_cvt_pk_bf16_f32 v139, v137, v141
	v_cvt_pk_bf16_f32 v141, v143, v145
	v_addc_co_u32_e32 v143, vcc, 0, v131, vcc
	global_store_dwordx4 v[142:143], v[138:141], off
	v_pk_mul_f32 v[144:145], v[34:35], v[136:137] op_sel_hi:[1,0]
	s_nop 0
	v_pk_mul_f32 v[138:139], v[38:39], v[136:137] op_sel_hi:[1,0]
	v_pk_mul_f32 v[140:141], v[36:37], v[136:137] op_sel_hi:[1,0]
	v_pk_mul_f32 v[136:137], v[32:33], v[136:137] op_sel_hi:[1,0]
	v_mul_f32_e32 v133, 0xbfb8aa3b, v140
	v_mul_f32_e32 v136, 0xbfb8aa3b, v136
	v_exp_f32_e32 v136, v136
	v_mul_f32_e32 v137, 0xbfb8aa3b, v137
	v_exp_f32_e32 v137, v137
	v_mul_f32_e32 v135, 0xbfb8aa3b, v141
	v_add_f32_e32 v136, 1.0, v136
	v_rcp_f32_e32 v140, v136
	v_add_f32_e32 v136, 1.0, v137
	v_mul_f32_e32 v137, 0xbfb8aa3b, v144
	v_mul_f32_e32 v138, 0xbfb8aa3b, v138
	v_mul_f32_e32 v139, 0xbfb8aa3b, v139
	v_exp_f32_e32 v137, v137
	v_mul_f32_e32 v141, 0xbfb8aa3b, v145
	v_exp_f32_e32 v133, v133
	v_exp_f32_e32 v135, v135
	v_exp_f32_e32 v138, v138
	v_exp_f32_e32 v139, v139
	v_exp_f32_e32 v141, v141
	v_rcp_f32_e32 v144, v136
	v_add_f32_e32 v136, 1.0, v137
	v_add_f32_e32 v133, 1.0, v133
	v_add_f32_e32 v135, 1.0, v135
	v_add_f32_e32 v138, 1.0, v138
	v_add_f32_e32 v139, 1.0, v139
	v_rcp_f32_e32 v145, v136
	v_add_f32_e32 v136, 1.0, v141
	v_rcp_f32_e32 v133, v133
	v_rcp_f32_e32 v135, v135
	v_rcp_f32_e32 v138, v138
	v_rcp_f32_e32 v139, v139
	v_rcp_f32_e32 v141, v136
	v_cvt_pk_bf16_f32 v136, v133, v135
	v_cvt_pk_bf16_f32 v137, v138, v139
	v_cvt_pk_bf16_f32 v138, v140, v144
	v_cvt_pk_bf16_f32 v139, v145, v141
	global_store_dwordx4 v[142:143], v[136:139], off offset:256
	v_pk_mul_f32 v[140:141], v[26:27], v[134:135] op_sel_hi:[1,0]
	s_nop 0
	v_pk_mul_f32 v[136:137], v[30:31], v[134:135] op_sel_hi:[1,0]
	v_pk_mul_f32 v[138:139], v[28:29], v[134:135] op_sel_hi:[1,0]
	v_mul_f32_e32 v136, 0xbfb8aa3b, v136
	v_mul_f32_e32 v135, 0xbfb8aa3b, v139
	v_exp_f32_e32 v135, v135
	v_exp_f32_e32 v136, v136
	v_mul_f32_e32 v137, 0xbfb8aa3b, v137
	v_exp_f32_e32 v137, v137
	v_mul_f32_e32 v133, 0xbfb8aa3b, v138
	v_pk_mul_f32 v[138:139], v[24:25], v[134:135] op_sel_hi:[1,0]
	v_add_f32_e32 v136, 1.0, v136
	v_rcp_f32_e32 v142, v136
	v_add_f32_e32 v136, 1.0, v137
	v_mul_f32_e32 v137, 0xbfb8aa3b, v138
	v_exp_f32_e32 v137, v137
	v_mul_f32_e32 v138, 0xbfb8aa3b, v139
	v_exp_f32_e32 v138, v138
	v_rcp_f32_e32 v139, v136
	v_add_f32_e32 v136, 1.0, v137
	v_mul_f32_e32 v137, 0xbfb8aa3b, v140
	v_rcp_f32_e32 v143, v136
	v_add_f32_e32 v136, 1.0, v138
	v_exp_f32_e32 v137, v137
	v_mul_f32_e32 v138, 0xbfb8aa3b, v141
	v_exp_f32_e32 v133, v133
	v_exp_f32_e32 v138, v138
	v_rcp_f32_e32 v140, v136
	v_add_f32_e32 v136, 1.0, v137
	v_add_f32_e32 v133, 1.0, v133
	v_add_f32_e32 v135, 1.0, v135
	v_rcp_f32_e32 v141, v136
	v_add_f32_e32 v136, 1.0, v138
	v_rcp_f32_e32 v133, v133
	v_rcp_f32_e32 v135, v135
	v_rcp_f32_e32 v144, v136
	v_cvt_pk_bf16_f32 v138, v143, v140
	v_add_co_u32_e32 v140, vcc, s64, v130
	v_cvt_pk_bf16_f32 v136, v133, v135
	v_cvt_pk_bf16_f32 v137, v142, v139
	v_cvt_pk_bf16_f32 v139, v141, v144
	v_addc_co_u32_e32 v141, vcc, 0, v131, vcc
	global_store_dwordx4 v[140:141], v[136:139], off
; DI unsigned pk_bf16(float lo, float hi) { f32x2 v = {lo, hi}; return __builtin_bit_cast(unsigned, __builtin_convertvector(v, bf16v2)); }
; DI float fast_sigmoid(float x) { return __builtin_amdgcn_rcpf(1.0f + __expf(-x)); }
;     DI void operator()(AccRef acc, const Unit& u, int wr, int wc, int fr, int fq) const {
;     ...
;         for (int ai = 0; ai < 2; ++ai)
; #pragma unroll
;             for (int m = 0; m < 4; ++m)
; #pragma unroll
;                 for (int bj = 0; bj < 2; ++bj) {
;                     const float rs = rsc.r[ai][m];
;                     const f32x4 r0 = acc[ai][bj][m][0] * rs, r1 = acc[ai][bj][m][1] * rs;
;                     u32x4 w;
;                     w.x = pk_bf16(fast_sigmoid(r0[0]), fast_sigmoid(r0[1])); w.y = pk_bf16(fast_sigmoid(r0[2]), fast_sigmoid(r0[3]));
;                     w.z = pk_bf16(fast_sigmoid(r1[0]), fast_sigmoid(r1[1])); w.w = pk_bf16(fast_sigmoid(r1[2]), fast_sigmoid(r1[3]));
;                     *(u32x4*)(Gp + (ai * 128 + m * 16) * 256 + bj * 128) = w;
;                 }
	v_pk_mul_f32 v[142:143], v[18:19], v[134:135] op_sel_hi:[1,0]
	s_nop 0
	v_pk_mul_f32 v[138:139], v[20:21], v[134:135] op_sel_hi:[1,0]
	v_pk_mul_f32 v[136:137], v[22:23], v[134:135] op_sel_hi:[1,0]
	v_mul_f32_e32 v135, 0xbfb8aa3b, v139
	v_mul_f32_e32 v133, 0xbfb8aa3b, v138
	v_exp_f32_e32 v138, v135
	v_pk_mul_f32 v[134:135], v[16:17], v[134:135] op_sel_hi:[1,0]
	v_mul_f32_e32 v136, 0xbfb8aa3b, v136
	v_mul_f32_e32 v134, 0xbfb8aa3b, v134
	v_exp_f32_e32 v134, v134
	v_mul_f32_e32 v135, 0xbfb8aa3b, v135
	v_exp_f32_e32 v135, v135
	v_mul_f32_e32 v137, 0xbfb8aa3b, v137
	v_add_f32_e32 v134, 1.0, v134
	v_rcp_f32_e32 v139, v134
	v_add_f32_e32 v134, 1.0, v135
	v_mul_f32_e32 v135, 0xbfb8aa3b, v142
	v_exp_f32_e32 v135, v135
	v_mul_f32_e32 v142, 0xbfb8aa3b, v143
	v_exp_f32_e32 v133, v133
	v_exp_f32_e32 v136, v136
	v_exp_f32_e32 v137, v137
	v_exp_f32_e32 v142, v142
	v_rcp_f32_e32 v143, v134
	v_add_f32_e32 v134, 1.0, v135
	v_add_f32_e32 v133, 1.0, v133
	v_add_f32_e32 v138, 1.0, v138
	v_add_f32_e32 v136, 1.0, v136
	v_add_f32_e32 v137, 1.0, v137
	v_rcp_f32_e32 v144, v134
	v_add_f32_e32 v134, 1.0, v142
	v_rcp_f32_e32 v133, v133
	v_rcp_f32_e32 v138, v138
	v_rcp_f32_e32 v136, v136
	v_rcp_f32_e32 v137, v137
	v_rcp_f32_e32 v142, v134
	v_cvt_pk_bf16_f32 v134, v133, v138
	v_cvt_pk_bf16_f32 v135, v136, v137
	v_cvt_pk_bf16_f32 v136, v139, v143
	v_cvt_pk_bf16_f32 v137, v144, v142
	global_store_dwordx4 v[140:141], v[134:137], off offset:256
	v_pk_mul_f32 v[138:139], v[10:11], v[132:133] op_sel_hi:[1,0]
	s_nop 0
	v_pk_mul_f32 v[134:135], v[14:15], v[132:133] op_sel_hi:[1,0]
	v_pk_mul_f32 v[136:137], v[12:13], v[132:133] op_sel_hi:[1,0]
	v_mul_f32_e32 v134, 0xbfb8aa3b, v134
	v_mul_f32_e32 v133, 0xbfb8aa3b, v136
	v_exp_f32_e32 v133, v133
	v_exp_f32_e32 v134, v134
	v_mul_f32_e32 v135, 0xbfb8aa3b, v135
	v_exp_f32_e32 v135, v135
	v_mul_f32_e32 v136, 0xbfb8aa3b, v137
	v_exp_f32_e32 v140, v136
	v_pk_mul_f32 v[136:137], v[8:9], v[132:133] op_sel_hi:[1,0]
	v_add_f32_e32 v134, 1.0, v134
	v_rcp_f32_e32 v141, v134
	v_add_f32_e32 v134, 1.0, v135
	v_mul_f32_e32 v135, 0xbfb8aa3b, v136
	v_exp_f32_e32 v135, v135
	v_mul_f32_e32 v136, 0xbfb8aa3b, v137
	v_exp_f32_e32 v136, v136
	v_rcp_f32_e32 v137, v134
	v_add_f32_e32 v134, 1.0, v135
	v_mul_f32_e32 v135, 0xbfb8aa3b, v138
	v_rcp_f32_e32 v142, v134
	v_add_f32_e32 v134, 1.0, v136
	v_exp_f32_e32 v135, v135
	v_mul_f32_e32 v136, 0xbfb8aa3b, v139
	v_exp_f32_e32 v136, v136
	v_rcp_f32_e32 v138, v134
	v_add_f32_e32 v134, 1.0, v135
	v_add_f32_e32 v133, 1.0, v133
	v_rcp_f32_e32 v139, v134
	v_add_f32_e32 v134, 1.0, v136
	v_rcp_f32_e32 v133, v133
	v_rcp_f32_e32 v143, v134
	v_add_f32_e32 v140, 1.0, v140
	v_rcp_f32_e32 v140, v140
	v_cvt_pk_bf16_f32 v136, v142, v138
	v_add_co_u32_e32 v138, vcc, s65, v130
	v_cvt_pk_bf16_f32 v135, v141, v137
	v_cvt_pk_bf16_f32 v137, v139, v143
	v_addc_co_u32_e32 v139, vcc, 0, v131, vcc
	v_pk_mul_f32 v[130:131], v[6:7], v[132:133] op_sel_hi:[1,0]
	v_cvt_pk_bf16_f32 v134, v133, v140
	v_mul_f32_e32 v130, 0xbfb8aa3b, v130
	v_exp_f32_e32 v130, v130
	v_mul_f32_e32 v131, 0xbfb8aa3b, v131
	global_store_dwordx4 v[138:139], v[134:137], off
	v_exp_f32_e32 v131, v131
	v_add_f32_e32 v130, 1.0, v130
	v_pk_mul_f32 v[134:135], v[4:5], v[132:133] op_sel_hi:[1,0]
	v_pk_mul_f32 v[136:137], v[2:3], v[132:133] op_sel_hi:[1,0]
	v_mul_f32_e32 v133, 0xbfb8aa3b, v134
	v_exp_f32_e32 v134, v133
	v_mul_f32_e32 v133, 0xbfb8aa3b, v135
	v_exp_f32_e32 v135, v133
	v_pk_mul_f32 v[132:133], v[0:1], v[132:133] op_sel_hi:[1,0]
	v_rcp_f32_e32 v140, v130
	v_add_f32_e32 v130, 1.0, v131
	v_mul_f32_e32 v131, 0xbfb8aa3b, v132
	v_exp_f32_e32 v131, v131
	v_mul_f32_e32 v132, 0xbfb8aa3b, v133
	v_exp_f32_e32 v132, v132
	v_rcp_f32_e32 v133, v130
	v_add_f32_e32 v130, 1.0, v131
	v_mul_f32_e32 v131, 0xbfb8aa3b, v136
	v_rcp_f32_e32 v141, v130
	v_add_f32_e32 v130, 1.0, v132
	v_exp_f32_e32 v131, v131
	v_mul_f32_e32 v132, 0xbfb8aa3b, v137
	v_exp_f32_e32 v132, v132
	v_rcp_f32_e32 v136, v130
	v_add_f32_e32 v130, 1.0, v131
	v_add_f32_e32 v134, 1.0, v134
	v_add_f32_e32 v135, 1.0, v135
	v_rcp_f32_e32 v137, v130
	v_add_f32_e32 v130, 1.0, v132
	v_rcp_f32_e32 v134, v134
	v_rcp_f32_e32 v135, v135
	v_rcp_f32_e32 v142, v130
	v_cvt_pk_bf16_f32 v131, v140, v133
	v_cvt_pk_bf16_f32 v132, v141, v136
	v_cvt_pk_bf16_f32 v130, v134, v135
	v_cvt_pk_bf16_f32 v133, v137, v142
	global_store_dwordx4 v[138:139], v[130:133], off offset:256

; #define PG8_STAGE(bufoff, gbase, voff) do { _Pragma("unroll") for (int _i = 0; _i < 2; ++_i) \
;         __builtin_amdgcn_global_load_lds((const unsigned*)((const char*)(gbase) + (voff)[_i]), (LAS unsigned*)(lds + (bufoff) + ldsw + _i * 8192), 16, 0, 0); } while (0)
; #define PG8_LDA(dst, b, h) do { _Pragma("unroll") for (int m = 0; m < 4; ++m) _Pragma("unroll") for (int k = 0; k < 2; ++k) dst[m][k] = *(const LAS bf16x8*)(lds + PG8_SA(b, h) + aoff + m * 2048 + k * 1024); } while (0)
; #define PG8_LDB(dst, b, h) do { _Pragma("unroll") for (int n = 0; n < 2; ++n) _Pragma("unroll") for (int k = 0; k < 2; ++k) dst[n][k] = *(const LAS bf16x8*)(lds + PG8_SB(b, h) + boff + n * 2048 + k * 1024); } while (0)
; #define PG8_MMA(ai, bj, At, Bt) do { __builtin_amdgcn_s_setprio(1); _Pragma("unroll") for (int m = 0; m < 4; ++m) _Pragma("unroll") for (int n = 0; n < 2; ++n) _Pragma("unroll") for (int k = 0; k < 2; ++k) \
;         acc[ai][bj][m][n] = __builtin_amdgcn_mfma_f32_16x16x32_bf16(Bt[n][k], At[m][k], acc[ai][bj][m][n], 0, 0, 0); __builtin_amdgcn_s_setprio(0); } while (0)
; #define PG8_WAIT_L(n) asm volatile("s_waitcnt lgkmcnt(" #n ")" ::: "memory")
; #define PG8_BAR __builtin_amdgcn_s_barrier()
; #define PG8_SCHED __builtin_amdgcn_sched_barrier(0)
; #define PG8_STAGE(bufoff, gbase, voff) do { _Pragma("unroll") for (int _i = 0; _i < 2; ++_i) \
;         __builtin_amdgcn_global_load_lds((const unsigned*)((const char*)(gbase) + (voff)[_i]), (LAS unsigned*)(lds + (bufoff) + ldsw + _i * 8192), 16, 0, 0); } while (0)
; #define PG8_WAIT_L(n) asm volatile("s_waitcnt lgkmcnt(" #n ")" ::: "memory")
; #define PG8_BAR __builtin_amdgcn_s_barrier()
; #define PG8_SCHED __builtin_amdgcn_sched_barrier(0)
; template <class Epi0, class Epi1>
; DI void gemm_phase_dual(LAS unsigned char* lds, const Gemm g, const Gemm g1, const StaticOrder S, const Epi0 E0, const Epi1 E1) {
;     ...
;             PG8_LDB(B0, 0, 0); PG8_SCHED; PG8_LDA(At, 0, 0); PG8_STAGE(PG8_SA(1, 1), a1 + hstep, voffA);
;             PG8_WAIT_L(8); PG8_BAR; PG8_WAIT_L(0); PG8_MMA(0, 0, At, B0); PG8_BAR; PG8_SCHED;
;             PG8_LDB(B1, 0, 1); PG8_STAGE(PG8_SB(0, 0), b2, voffB);
;             PG8_BAR; PG8_WAIT_L(0); PG8_MMA(0, 1, At, B1); PG8_BAR;
;             PG8_LDA(At, 0, 1); PG8_STAGE(PG8_SA(0, 0), a2, voffA);
;             PG8_BAR; PG8_WAIT_L(0); PG8_MMA(1, 0, At, B0); PG8_BAR; PG8_SCHED;
.LBB0_708:
	ds_read_b128 v[156:159], v179
	ds_read_b128 v[160:163], v179 offset:1024
	ds_read_b128 v[164:167], v179 offset:2048
	ds_read_b128 v[168:171], v179 offset:3072
	s_add_u32 s40, s38, 0xfffc0080
	s_addc_u32 s41, s39, -1
	s_cmp_eq_u32 s69, 12
	s_cselect_b32 s43, s6, s41
	s_cselect_b32 s42, s7, s40
	s_cselect_b32 s41, s17, s68
	s_cselect_b32 s40, s19, s67
	v_lshl_add_u64 v[210:211], s[38:39], 0, v[148:149]
	s_add_i32 m0, s25, 0xc000
	ds_read_b128 v[172:175], v180
	ds_read_b128 v[186:189], v180 offset:2048
	ds_read_b128 v[194:197], v180 offset:4096
	ds_read_b128 v[202:205], v180 offset:6144
	global_load_lds_dwordx4 v[210:211], off
	v_lshl_add_u64 v[210:211], s[38:39], 0, v[150:151]
	s_add_i32 m0, s25, 0xe000
	s_nop 0
	global_load_lds_dwordx4 v[210:211], off
	s_waitcnt lgkmcnt(4)
	s_setprio 1
	s_barrier
	ds_read_b128 v[182:185], v180 offset:1024
	ds_read_b128 v[190:193], v180 offset:3072
	ds_read_b128 v[198:201], v180 offset:5120
	ds_read_b128 v[206:209], v180 offset:7168
	s_waitcnt lgkmcnt(4)
	v_mfma_f32_16x16x32_bf16 v[124:127], v[156:159], v[172:175], v[124:127]
	v_mfma_f32_16x16x32_bf16 v[120:123], v[164:167], v[172:175], v[120:123]
	v_mfma_f32_16x16x32_bf16 v[108:111], v[156:159], v[186:189], v[108:111]
	v_mfma_f32_16x16x32_bf16 v[104:107], v[164:167], v[186:189], v[104:107]
	v_mfma_f32_16x16x32_bf16 v[92:95], v[156:159], v[194:197], v[92:95]
	v_mfma_f32_16x16x32_bf16 v[88:91], v[164:167], v[194:197], v[88:91]
	v_mfma_f32_16x16x32_bf16 v[84:87], v[156:159], v[202:205], v[84:87]
	v_mfma_f32_16x16x32_bf16 v[80:83], v[164:167], v[202:205], v[80:83]
	s_waitcnt lgkmcnt(3)
	v_mfma_f32_16x16x32_bf16 v[124:127], v[160:163], v[182:185], v[124:127]
	v_mfma_f32_16x16x32_bf16 v[120:123], v[168:171], v[182:185], v[120:123]
	s_waitcnt lgkmcnt(2)
	v_mfma_f32_16x16x32_bf16 v[108:111], v[160:163], v[190:193], v[108:111]
	v_mfma_f32_16x16x32_bf16 v[104:107], v[168:171], v[190:193], v[104:107]
	s_waitcnt lgkmcnt(1)
	v_mfma_f32_16x16x32_bf16 v[92:95], v[160:163], v[198:201], v[92:95]
	v_mfma_f32_16x16x32_bf16 v[88:91], v[168:171], v[198:201], v[88:91]
	s_waitcnt lgkmcnt(0)
	s_setprio 2
	s_barrier
	v_mfma_f32_16x16x32_bf16 v[84:87], v[160:163], v[206:209], v[84:87]
	v_mfma_f32_16x16x32_bf16 v[80:83], v[168:171], v[206:209], v[80:83]
	s_setprio 0
	s_add_i32 s76, s52, s44
	v_lshl_add_u64 v[228:229], s[40:41], 0, v[130:131]
	s_mov_b32 m0, s76
	ds_read_b128 v[210:213], v181
	ds_read_b128 v[214:217], v181 offset:1024
	ds_read_b128 v[218:221], v181 offset:2048
	ds_read_b128 v[224:227], v181 offset:3072
	global_load_lds_dwordx4 v[228:229], off
	v_lshl_add_u64 v[230:231], s[40:41], 0, v[134:135]
	s_add_i32 m0, s76, 0x2000
	s_nop 0
	global_load_lds_dwordx4 v[230:231], off
	s_setprio 1
	s_barrier
	s_waitcnt lgkmcnt(0)
	v_mfma_f32_16x16x32_bf16 v[116:119], v[210:213], v[172:175], v[116:119]
	v_mfma_f32_16x16x32_bf16 v[112:115], v[218:221], v[172:175], v[112:115]
	v_mfma_f32_16x16x32_bf16 v[100:103], v[210:213], v[186:189], v[100:103]
	v_mfma_f32_16x16x32_bf16 v[96:99], v[218:221], v[186:189], v[96:99]
	v_mfma_f32_16x16x32_bf16 v[76:79], v[210:213], v[194:197], v[76:79]
	v_mfma_f32_16x16x32_bf16 v[72:75], v[218:221], v[194:197], v[72:75]
	v_mfma_f32_16x16x32_bf16 v[68:71], v[210:213], v[202:205], v[68:71]
	v_mfma_f32_16x16x32_bf16 v[64:67], v[218:221], v[202:205], v[64:67]
	v_mfma_f32_16x16x32_bf16 v[116:119], v[214:217], v[182:185], v[116:119]
	v_mfma_f32_16x16x32_bf16 v[112:115], v[224:227], v[182:185], v[112:115]
	v_mfma_f32_16x16x32_bf16 v[100:103], v[214:217], v[190:193], v[100:103]
	v_mfma_f32_16x16x32_bf16 v[96:99], v[224:227], v[190:193], v[96:99]
	v_mfma_f32_16x16x32_bf16 v[76:79], v[214:217], v[198:201], v[76:79]
	v_mfma_f32_16x16x32_bf16 v[72:75], v[224:227], v[198:201], v[72:75]
	s_setprio 2
	s_barrier
	v_mfma_f32_16x16x32_bf16 v[68:71], v[214:217], v[206:209], v[68:71]
	v_mfma_f32_16x16x32_bf16 v[64:67], v[224:227], v[206:209], v[64:67]
	s_setprio 0
	s_mov_b32 m0, s25
	v_lshl_add_u64 v[232:233], s[42:43], 0, v[128:129]
	ds_read_b128 v[172:175], v180 offset:16384
	ds_read_b128 v[186:189], v180 offset:18432
	ds_read_b128 v[194:197], v180 offset:20480
	ds_read_b128 v[202:205], v180 offset:22528
	global_load_lds_dwordx4 v[232:233], off
	v_lshl_add_u64 v[234:235], s[42:43], 0, v[132:133]
	s_mov_b32 m0, s45
	s_nop 0
	global_load_lds_dwordx4 v[234:235], off
	s_setprio 1
	s_barrier
	ds_read_b128 v[182:185], v180 offset:17408
	ds_read_b128 v[190:193], v180 offset:19456
	ds_read_b128 v[198:201], v180 offset:21504
	ds_read_b128 v[206:209], v180 offset:23552
	s_waitcnt lgkmcnt(4)
	v_mfma_f32_16x16x32_bf16 v[60:63], v[156:159], v[172:175], v[60:63]
	v_mfma_f32_16x16x32_bf16 v[56:59], v[164:167], v[172:175], v[56:59]
	v_mfma_f32_16x16x32_bf16 v[52:55], v[156:159], v[186:189], v[52:55]
	v_mfma_f32_16x16x32_bf16 v[48:51], v[164:167], v[186:189], v[48:51]
	v_mfma_f32_16x16x32_bf16 v[28:31], v[156:159], v[194:197], v[28:31]
	v_mfma_f32_16x16x32_bf16 v[24:27], v[164:167], v[194:197], v[24:27]
	v_mfma_f32_16x16x32_bf16 v[20:23], v[156:159], v[202:205], v[20:23]
	v_mfma_f32_16x16x32_bf16 v[16:19], v[164:167], v[202:205], v[16:19]
	s_waitcnt lgkmcnt(3)
	v_mfma_f32_16x16x32_bf16 v[60:63], v[160:163], v[182:185], v[60:63]
	v_mfma_f32_16x16x32_bf16 v[56:59], v[168:171], v[182:185], v[56:59]
	s_waitcnt lgkmcnt(2)
	v_mfma_f32_16x16x32_bf16 v[52:55], v[160:163], v[190:193], v[52:55]
	v_mfma_f32_16x16x32_bf16 v[48:51], v[168:171], v[190:193], v[48:51]
	s_waitcnt lgkmcnt(1)
	v_mfma_f32_16x16x32_bf16 v[28:31], v[160:163], v[198:201], v[28:31]
	v_mfma_f32_16x16x32_bf16 v[24:27], v[168:171], v[198:201], v[24:27]
	s_waitcnt lgkmcnt(0)
	s_setprio 2
	s_barrier
; #define PG8_STAGE(bufoff, gbase, voff) do { _Pragma("unroll") for (int _i = 0; _i < 2; ++_i) \
;         __builtin_amdgcn_global_load_lds((const unsigned*)((const char*)(gbase) + (voff)[_i]), (LAS unsigned*)(lds + (bufoff) + ldsw + _i * 8192), 16, 0, 0); } while (0)
; #define PG8_LDA(dst, b, h) do { _Pragma("unroll") for (int m = 0; m < 4; ++m) _Pragma("unroll") for (int k = 0; k < 2; ++k) dst[m][k] = *(const LAS bf16x8*)(lds + PG8_SA(b, h) + aoff + m * 2048 + k * 1024); } while (0)
; #define PG8_LDB(dst, b, h) do { _Pragma("unroll") for (int n = 0; n < 2; ++n) _Pragma("unroll") for (int k = 0; k < 2; ++k) dst[n][k] = *(const LAS bf16x8*)(lds + PG8_SB(b, h) + boff + n * 2048 + k * 1024); } while (0)
; #define PG8_MMA(ai, bj, At, Bt) do { __builtin_amdgcn_s_setprio(1); _Pragma("unroll") for (int m = 0; m < 4; ++m) _Pragma("unroll") for (int n = 0; n < 2; ++n) _Pragma("unroll") for (int k = 0; k < 2; ++k) \
;         acc[ai][bj][m][n] = __builtin_amdgcn_mfma_f32_16x16x32_bf16(Bt[n][k], At[m][k], acc[ai][bj][m][n], 0, 0, 0); __builtin_amdgcn_s_setprio(0); } while (0)
; #define PG8_WAIT_V(n) asm volatile("s_waitcnt vmcnt(" #n ")" ::: "memory")
; #define PG8_WAIT_L(n) asm volatile("s_waitcnt lgkmcnt(" #n ")" ::: "memory")
; #define PG8_BAR __builtin_amdgcn_s_barrier()
; #define PG8_SCHED __builtin_amdgcn_sched_barrier(0)
; #define PG8_STAGE(bufoff, gbase, voff) do { _Pragma("unroll") for (int _i = 0; _i < 2; ++_i) \
;         __builtin_amdgcn_global_load_lds((const unsigned*)((const char*)(gbase) + (voff)[_i]), (LAS unsigned*)(lds + (bufoff) + ldsw + _i * 8192), 16, 0, 0); } while (0)
; #define PG8_BAR __builtin_amdgcn_s_barrier()
; template <class Epi0, class Epi1>
; DI void gemm_phase_dual(LAS unsigned char* lds, const Gemm g, const Gemm g1, const StaticOrder S, const Epi0 E0, const Epi1 E1) {
;     ...
;             PG8_BAR; PG8_WAIT_L(0); PG8_MMA(1, 0, At, B0); PG8_BAR; PG8_SCHED;
;             PG8_STAGE(PG8_SB(0, 1), b2 + hstep, voffB);
;             PG8_WAIT_V(6); PG8_BAR; PG8_MMA(1, 1, At, B1); PG8_BAR;
;             PG8_LDB(B0, 1, 0); PG8_SCHED; PG8_LDA(At, 1, 0); PG8_STAGE(PG8_SA(0, 1), a2 + hstep, voffA);
;             PG8_WAIT_L(8); PG8_BAR; PG8_WAIT_L(0); PG8_MMA(0, 0, At, B0); PG8_BAR; PG8_SCHED;
;             PG8_LDB(B1, 1, 1); PG8_STAGE(PG8_SB(1, 0), b3, voffB);
;             PG8_BAR; PG8_WAIT_L(0); PG8_MMA(0, 1, At, B1); PG8_BAR;
	v_mfma_f32_16x16x32_bf16 v[20:23], v[160:163], v[206:209], v[20:23]
	v_mfma_f32_16x16x32_bf16 v[16:19], v[168:171], v[206:209], v[16:19]
	s_setprio 0
	s_add_u32 s76, s40, 0x40000
	s_addc_u32 s77, s41, 0
	s_add_i32 s78, s53, s44
	v_lshl_add_u64 v[156:157], s[76:77], 0, v[130:131]
	s_mov_b32 m0, s78
	s_nop 0
	global_load_lds_dwordx4 v[156:157], off
	v_lshl_add_u64 v[156:157], s[76:77], 0, v[134:135]
	s_add_i32 m0, s78, 0x2000
	s_nop 0
	global_load_lds_dwordx4 v[156:157], off
	s_waitcnt vmcnt(6)
	s_setprio 1
	s_barrier
	v_mfma_f32_16x16x32_bf16 v[44:47], v[210:213], v[172:175], v[44:47]
	v_mfma_f32_16x16x32_bf16 v[40:43], v[218:221], v[172:175], v[40:43]
	v_mfma_f32_16x16x32_bf16 v[36:39], v[210:213], v[186:189], v[36:39]
	v_mfma_f32_16x16x32_bf16 v[32:35], v[218:221], v[186:189], v[32:35]
	v_mfma_f32_16x16x32_bf16 v[12:15], v[210:213], v[194:197], v[12:15]
	v_mfma_f32_16x16x32_bf16 v[8:11], v[218:221], v[194:197], v[8:11]
	v_mfma_f32_16x16x32_bf16 v[4:7], v[210:213], v[202:205], v[4:7]
	v_mfma_f32_16x16x32_bf16 v[0:3], v[218:221], v[202:205], v[0:3]
	v_mfma_f32_16x16x32_bf16 v[44:47], v[214:217], v[182:185], v[44:47]
	v_mfma_f32_16x16x32_bf16 v[40:43], v[224:227], v[182:185], v[40:43]
	v_mfma_f32_16x16x32_bf16 v[36:39], v[214:217], v[190:193], v[36:39]
	v_mfma_f32_16x16x32_bf16 v[32:35], v[224:227], v[190:193], v[32:35]
	v_mfma_f32_16x16x32_bf16 v[12:15], v[214:217], v[198:201], v[12:15]
	v_mfma_f32_16x16x32_bf16 v[8:11], v[224:227], v[198:201], v[8:11]
	s_setprio 2
	s_barrier
	v_mfma_f32_16x16x32_bf16 v[4:7], v[214:217], v[206:209], v[4:7]
	v_mfma_f32_16x16x32_bf16 v[0:3], v[224:227], v[206:209], v[0:3]
	s_setprio 0
	s_add_i32 s76, 0, 0x18000
	v_add_u32_e32 v168, s76, v177
	ds_read_b128 v[156:159], v168
	ds_read_b128 v[160:163], v168 offset:1024
	ds_read_b128 v[164:167], v168 offset:2048
	ds_read_b128 v[168:171], v168 offset:3072
	s_add_u32 s42, s42, 0x40000
	s_addc_u32 s43, s43, 0
	s_mov_b32 m0, s46
	v_lshl_add_u64 v[210:211], s[42:43], 0, v[128:129]
	ds_read_b128 v[172:175], v180 offset:32768
	ds_read_b128 v[186:189], v180 offset:34816
	ds_read_b128 v[194:197], v180 offset:36864
	ds_read_b128 v[202:205], v180 offset:38912
	global_load_lds_dwordx4 v[210:211], off
	v_lshl_add_u64 v[210:211], s[42:43], 0, v[132:133]
	s_mov_b32 m0, s47
	s_nop 0
	global_load_lds_dwordx4 v[210:211], off
	s_waitcnt lgkmcnt(4)
	s_setprio 1
	s_barrier
	ds_read_b128 v[182:185], v180 offset:33792
	ds_read_b128 v[190:193], v180 offset:35840
	ds_read_b128 v[198:201], v180 offset:37888
	ds_read_b128 v[206:209], v180 offset:39936
	s_waitcnt lgkmcnt(4)
	v_mfma_f32_16x16x32_bf16 v[124:127], v[156:159], v[172:175], v[124:127]
	v_mfma_f32_16x16x32_bf16 v[120:123], v[164:167], v[172:175], v[120:123]
	v_mfma_f32_16x16x32_bf16 v[108:111], v[156:159], v[186:189], v[108:111]
	v_mfma_f32_16x16x32_bf16 v[104:107], v[164:167], v[186:189], v[104:107]
	v_mfma_f32_16x16x32_bf16 v[92:95], v[156:159], v[194:197], v[92:95]
	v_mfma_f32_16x16x32_bf16 v[88:91], v[164:167], v[194:197], v[88:91]
	v_mfma_f32_16x16x32_bf16 v[84:87], v[156:159], v[202:205], v[84:87]
	v_mfma_f32_16x16x32_bf16 v[80:83], v[164:167], v[202:205], v[80:83]
	s_waitcnt lgkmcnt(3)
	v_mfma_f32_16x16x32_bf16 v[124:127], v[160:163], v[182:185], v[124:127]
	v_mfma_f32_16x16x32_bf16 v[120:123], v[168:171], v[182:185], v[120:123]
	s_waitcnt lgkmcnt(2)
	v_mfma_f32_16x16x32_bf16 v[108:111], v[160:163], v[190:193], v[108:111]
	v_mfma_f32_16x16x32_bf16 v[104:107], v[168:171], v[190:193], v[104:107]
	s_waitcnt lgkmcnt(1)
	v_mfma_f32_16x16x32_bf16 v[92:95], v[160:163], v[198:201], v[92:95]
	v_mfma_f32_16x16x32_bf16 v[88:91], v[168:171], v[198:201], v[88:91]
	s_waitcnt lgkmcnt(0)
	s_setprio 2
	s_barrier
	v_mfma_f32_16x16x32_bf16 v[84:87], v[160:163], v[206:209], v[84:87]
	v_mfma_f32_16x16x32_bf16 v[80:83], v[168:171], v[206:209], v[80:83]
	s_setprio 0
	s_add_i32 s42, 0, 0x1c000
	s_add_i32 s43, s76, s44
	v_add_u32_e32 v224, s42, v177
	v_lshl_add_u64 v[228:229], v[228:229], 0, s[8:9]
	s_mov_b32 m0, s43
	ds_read_b128 v[210:213], v224
	ds_read_b128 v[214:217], v224 offset:1024
	ds_read_b128 v[218:221], v224 offset:2048
	ds_read_b128 v[224:227], v224 offset:3072
	global_load_lds_dwordx4 v[228:229], off
	v_lshl_add_u64 v[228:229], v[230:231], 0, s[8:9]
	s_add_i32 m0, s43, 0x2000
	s_nop 0
	global_load_lds_dwordx4 v[228:229], off
	s_setprio 1
	s_barrier
	s_waitcnt lgkmcnt(0)
	v_mfma_f32_16x16x32_bf16 v[116:119], v[210:213], v[172:175], v[116:119]
	v_mfma_f32_16x16x32_bf16 v[112:115], v[218:221], v[172:175], v[112:115]
	v_mfma_f32_16x16x32_bf16 v[100:103], v[210:213], v[186:189], v[100:103]
	v_mfma_f32_16x16x32_bf16 v[96:99], v[218:221], v[186:189], v[96:99]
	v_mfma_f32_16x16x32_bf16 v[76:79], v[210:213], v[194:197], v[76:79]
	v_mfma_f32_16x16x32_bf16 v[72:75], v[218:221], v[194:197], v[72:75]
	v_mfma_f32_16x16x32_bf16 v[68:71], v[210:213], v[202:205], v[68:71]
	v_mfma_f32_16x16x32_bf16 v[64:67], v[218:221], v[202:205], v[64:67]
	v_mfma_f32_16x16x32_bf16 v[116:119], v[214:217], v[182:185], v[116:119]
	v_mfma_f32_16x16x32_bf16 v[112:115], v[224:227], v[182:185], v[112:115]
	v_mfma_f32_16x16x32_bf16 v[100:103], v[214:217], v[190:193], v[100:103]
	v_mfma_f32_16x16x32_bf16 v[96:99], v[224:227], v[190:193], v[96:99]
	v_mfma_f32_16x16x32_bf16 v[76:79], v[214:217], v[198:201], v[76:79]
	v_mfma_f32_16x16x32_bf16 v[72:75], v[224:227], v[198:201], v[72:75]
	s_setprio 2
	s_barrier
; #define PG8_STAGE(bufoff, gbase, voff) do { _Pragma("unroll") for (int _i = 0; _i < 2; ++_i) \
;         __builtin_amdgcn_global_load_lds((const unsigned*)((const char*)(gbase) + (voff)[_i]), (LAS unsigned*)(lds + (bufoff) + ldsw + _i * 8192), 16, 0, 0); } while (0)
; #define PG8_LDA(dst, b, h) do { _Pragma("unroll") for (int m = 0; m < 4; ++m) _Pragma("unroll") for (int k = 0; k < 2; ++k) dst[m][k] = *(const LAS bf16x8*)(lds + PG8_SA(b, h) + aoff + m * 2048 + k * 1024); } while (0)
; #define PG8_MMA(ai, bj, At, Bt) do { __builtin_amdgcn_s_setprio(1); _Pragma("unroll") for (int m = 0; m < 4; ++m) _Pragma("unroll") for (int n = 0; n < 2; ++n) _Pragma("unroll") for (int k = 0; k < 2; ++k) \
;         acc[ai][bj][m][n] = __builtin_amdgcn_mfma_f32_16x16x32_bf16(Bt[n][k], At[m][k], acc[ai][bj][m][n], 0, 0, 0); __builtin_amdgcn_s_setprio(0); } while (0)
; #define PG8_WAIT_V(n) asm volatile("s_waitcnt vmcnt(" #n ")" ::: "memory")
; template <class Epi0, class Epi1>
; DI void gemm_phase_dual(LAS unsigned char* lds, const Gemm g, const Gemm g1, const StaticOrder S, const Epi0 E0, const Epi1 E1) {
;     ...
;             PG8_LDA(At, 1, 1); PG8_STAGE(PG8_SA(1, 0), a3, voffA);
;             PG8_BAR; PG8_WAIT_L(0); PG8_MMA(1, 0, At, B0); PG8_BAR; PG8_SCHED;
;             PG8_STAGE(PG8_SB(1, 1), b3 + hstep, voffB);
;             PG8_WAIT_V(6); PG8_BAR; PG8_MMA(1, 1, At, B1); PG8_BAR;
;         }
;         if (ui & 1) E1(acc, cur, wr, wc, fr, fq); else E0(acc, cur, wr, wc, fr, fq);
;     DI void operator()(AccRef acc, const Unit& u, int wr, int wc, int fr, int fq) const {
;         const int row0 = u.pm * 256 + wr * 64 + fr, col0 = u.pn * 256 + wc * 32 + 8 * fq;
; #pragma unroll
;         for (int ai = 0; ai < 2; ++ai)
; #pragma unroll
;             for (int mh = 0; mh < 2; ++mh) {
;                 u32x4 gv[2][2], mv[2][2];
; #pragma unroll
;                 for (int mm = 0; mm < 2; ++mm)
; #pragma unroll
;                     for (int bj = 0; bj < 2; ++bj) {
;                         const size_t row = (size_t)(row0 + ai * 128 + (mh * 2 + mm) * 16); const int col = col0 + bj * 128;
;                         gv[mm][bj] = *(const u32x4*)(gab + (size_t)(u.pm * 8 + SECOND * 4 + u.pn) * 65536 + (wr * 64 + fr + ai * 128 + (mh * 2 + mm) * 16) * 256 + wc * 32 + 8 * fq + bj * 128);
;                         if (SECOND) mv[mm][bj] = *(const u32x4*)(mrg + row * 1024 + col);
	v_mfma_f32_16x16x32_bf16 v[68:71], v[214:217], v[206:209], v[68:71]
	v_mfma_f32_16x16x32_bf16 v[64:67], v[224:227], v[206:209], v[64:67]
	s_setprio 0
	s_mov_b32 m0, s59
	v_lshl_add_u64 v[228:229], v[232:233], 0, s[8:9]
	ds_read_b128 v[172:175], v180 offset:49152
	ds_read_b128 v[186:189], v180 offset:51200
	ds_read_b128 v[194:197], v180 offset:53248
	ds_read_b128 v[202:205], v180 offset:55296
	global_load_lds_dwordx4 v[228:229], off
	v_lshl_add_u64 v[228:229], v[234:235], 0, s[8:9]
	s_mov_b32 m0, s60
	s_nop 0
	global_load_lds_dwordx4 v[228:229], off
	s_setprio 1
	s_barrier
	ds_read_b128 v[182:185], v180 offset:50176
	ds_read_b128 v[190:193], v180 offset:52224
	ds_read_b128 v[198:201], v180 offset:54272
	ds_read_b128 v[206:209], v180 offset:56320
	s_waitcnt lgkmcnt(4)
	v_mfma_f32_16x16x32_bf16 v[60:63], v[156:159], v[172:175], v[60:63]
	v_mfma_f32_16x16x32_bf16 v[56:59], v[164:167], v[172:175], v[56:59]
	v_mfma_f32_16x16x32_bf16 v[52:55], v[156:159], v[186:189], v[52:55]
	v_mfma_f32_16x16x32_bf16 v[48:51], v[164:167], v[186:189], v[48:51]
	v_mfma_f32_16x16x32_bf16 v[28:31], v[156:159], v[194:197], v[28:31]
	v_mfma_f32_16x16x32_bf16 v[24:27], v[164:167], v[194:197], v[24:27]
	v_mfma_f32_16x16x32_bf16 v[20:23], v[156:159], v[202:205], v[20:23]
	v_mfma_f32_16x16x32_bf16 v[16:19], v[164:167], v[202:205], v[16:19]
	s_waitcnt lgkmcnt(3)
	v_mfma_f32_16x16x32_bf16 v[60:63], v[160:163], v[182:185], v[60:63]
	v_mfma_f32_16x16x32_bf16 v[56:59], v[168:171], v[182:185], v[56:59]
	s_waitcnt lgkmcnt(2)
	v_mfma_f32_16x16x32_bf16 v[52:55], v[160:163], v[190:193], v[52:55]
	v_mfma_f32_16x16x32_bf16 v[48:51], v[168:171], v[190:193], v[48:51]
	s_waitcnt lgkmcnt(1)
	v_mfma_f32_16x16x32_bf16 v[28:31], v[160:163], v[198:201], v[28:31]
	v_mfma_f32_16x16x32_bf16 v[24:27], v[168:171], v[198:201], v[24:27]
	s_waitcnt lgkmcnt(0)
	s_setprio 2
	s_barrier
	v_mfma_f32_16x16x32_bf16 v[20:23], v[160:163], v[206:209], v[20:23]
	v_mfma_f32_16x16x32_bf16 v[16:19], v[168:171], v[206:209], v[16:19]
	s_setprio 0
	s_add_u32 s40, s40, 0x40080
	s_addc_u32 s41, s41, 0
	s_add_i32 s42, s42, s44
	v_lshl_add_u64 v[156:157], s[40:41], 0, v[130:131]
	s_mov_b32 m0, s42
	s_nop 0
	global_load_lds_dwordx4 v[156:157], off
	v_lshl_add_u64 v[156:157], s[40:41], 0, v[134:135]
	s_add_i32 m0, s42, 0x2000
	s_nop 0
	global_load_lds_dwordx4 v[156:157], off
	s_waitcnt vmcnt(6)
	s_setprio 1
	s_barrier
	v_mfma_f32_16x16x32_bf16 v[44:47], v[210:213], v[172:175], v[44:47]
	v_mfma_f32_16x16x32_bf16 v[40:43], v[218:221], v[172:175], v[40:43]
	v_mfma_f32_16x16x32_bf16 v[36:39], v[210:213], v[186:189], v[36:39]
	v_mfma_f32_16x16x32_bf16 v[32:35], v[218:221], v[186:189], v[32:35]
	v_mfma_f32_16x16x32_bf16 v[12:15], v[210:213], v[194:197], v[12:15]
	v_mfma_f32_16x16x32_bf16 v[8:11], v[218:221], v[194:197], v[8:11]
	v_mfma_f32_16x16x32_bf16 v[4:7], v[210:213], v[202:205], v[4:7]
	v_mfma_f32_16x16x32_bf16 v[0:3], v[218:221], v[202:205], v[0:3]
	v_mfma_f32_16x16x32_bf16 v[44:47], v[214:217], v[182:185], v[44:47]
	v_mfma_f32_16x16x32_bf16 v[40:43], v[224:227], v[182:185], v[40:43]
	v_mfma_f32_16x16x32_bf16 v[36:39], v[214:217], v[190:193], v[36:39]
	v_mfma_f32_16x16x32_bf16 v[32:35], v[224:227], v[190:193], v[32:35]
	v_mfma_f32_16x16x32_bf16 v[12:15], v[214:217], v[198:201], v[12:15]
	v_mfma_f32_16x16x32_bf16 v[8:11], v[224:227], v[198:201], v[8:11]
	s_setprio 2
	s_barrier
	v_mfma_f32_16x16x32_bf16 v[4:7], v[214:217], v[206:209], v[4:7]
	v_mfma_f32_16x16x32_bf16 v[0:3], v[224:227], v[206:209], v[0:3]
	s_setprio 0
	s_add_i32 s69, s69, 2
	s_add_u32 s38, s38, 0x100
	s_addc_u32 s39, s39, 0
	s_add_u32 s67, s67, 0x100
	s_addc_u32 s68, s68, 0
	s_cmp_gt_u32 s69, 13
	s_cbranch_scc0 .LBB0_708
	v_lshl_add_u32 v164, s24, 8, v176
	s_lshl_b32 s17, s66, 8
	v_or_b32_e32 v162, s17, v178
	v_or_b32_e32 v160, 16, v164
	s_mov_b64 s[6:7], -1
	s_and_b64 vcc, exec, s[28:29]
	v_ashrrev_i32_e32 v165, 31, v164
	v_ashrrev_i32_e32 v163, 31, v162
	v_ashrrev_i32_e32 v161, 31, v160
	v_or_b32_e32 v158, 32, v164
	v_or_b32_e32 v156, 48, v164
	s_cbranch_vccz .LBB0_711
	s_lshl_b32 s6, s24, 3
	s_add_i32 s6, s66, s6
	s_add_i32 s6, s6, 4
	v_lshlrev_b64 v[168:169], 11, v[160:161]
	s_ashr_i32 s7, s6, 31
	v_lshlrev_b64 v[166:167], 11, v[164:165]
	v_lshlrev_b64 v[170:171], 1, v[162:163]
	v_lshl_add_u64 v[168:169], s[36:37], 0, v[168:169]
	s_lshl_b64 s[6:7], s[6:7], 17
	v_lshl_add_u64 v[166:167], s[36:37], 0, v[166:167]
	v_lshl_add_u64 v[174:175], v[168:169], 0, v[170:171]
	v_lshl_add_u64 v[168:169], v[136:137], 0, s[6:7]
	v_lshl_add_u64 v[166:167], v[166:167], 0, v[170:171]
	v_lshl_add_u64 v[172:173], v[138:139], 1, v[168:169]
	global_load_dwordx4 v[182:185], v[166:167], off
	global_load_dwordx4 v[186:189], v[166:167], off offset:256
	global_load_dwordx4 v[190:193], v[174:175], off
	global_load_dwordx4 v[194:197], v[172:173], off
	global_load_dwordx4 v[198:201], v[172:173], off offset:256
	v_add_co_u32_e32 v206, vcc, s48, v172
	v_ashrrev_i32_e32 v159, 31, v158
	s_nop 0
	v_addc_co_u32_e32 v207, vcc, 0, v173, vcc
	global_load_dwordx4 v[202:205], v[206:207], off
	s_nop 0
	global_load_dwordx4 v[206:209], v[206:207], off offset:256
	s_nop 0
	global_load_dwordx4 v[210:213], v[174:175], off offset:256
	v_ashrrev_i32_e32 v157, 31, v156
	s_mov_b64 s[6:7], 0
	s_waitcnt vmcnt(0)
; DI unsigned pk_bf16(float lo, float hi) { f32x2 v = {lo, hi}; return __builtin_bit_cast(unsigned, __builtin_convertvector(v, bf16v2)); }
; DI float bf_lo(unsigned w) { return __uint_as_float(w << 16); }
; DI float bf_hi(unsigned w) { return __uint_as_float(w & 0xffff0000u); }
;     DI void operator()(AccRef acc, const Unit& u, int wr, int wc, int fr, int fq) const {
;     ...
;                 u32x4 gv[2][2], mv[2][2];
; #pragma unroll
;                 for (int mm = 0; mm < 2; ++mm)
; #pragma unroll
;                     for (int bj = 0; bj < 2; ++bj) {
;                         const size_t row = (size_t)(row0 + ai * 128 + (mh * 2 + mm) * 16); const int col = col0 + bj * 128;
;                         gv[mm][bj] = *(const u32x4*)(gab + (size_t)(u.pm * 8 + SECOND * 4 + u.pn) * 65536 + (wr * 64 + fr + ai * 128 + (mh * 2 + mm) * 16) * 256 + wc * 32 + 8 * fq + bj * 128);
;                         if (SECOND) mv[mm][bj] = *(const u32x4*)(mrg + row * 1024 + col);
;                     }
; #pragma unroll
;                 for (int mm = 0; mm < 2; ++mm)
; #pragma unroll
;                     for (int bj = 0; bj < 2; ++bj) {
;                         const int m = mh * 2 + mm;
;                         const size_t row = (size_t)(row0 + ai * 128 + m * 16); const int col = col0 + bj * 128;
;                         const u32x4 gt = gv[mm][bj];
;                         const f32x4 r0 = acc[ai][bj][m][0], r1 = acc[ai][bj][m][1];
;                         float v[8] = {bf_lo(gt.x) * r0[0], bf_hi(gt.x) * r0[1], bf_lo(gt.y) * r0[2], bf_hi(gt.y) * r0[3], bf_lo(gt.z) * r1[0], bf_hi(gt.z) * r1[1], bf_lo(gt.w) * r1[2], bf_hi(gt.w) * r1[3]};
;                         if (SECOND) { const u32x4 o = mv[mm][bj]; v[0] += bf_lo(o.x); v[1] += bf_hi(o.x); v[2] += bf_lo(o.y); v[3] += bf_hi(o.y); v[4] += bf_lo(o.z); v[5] += bf_hi(o.z); v[6] += bf_lo(o.w); v[7] += bf_hi(o.w); }
;                         u32x4 w; w.x = pk_bf16(v[0], v[1]); w.y = pk_bf16(v[2], v[3]); w.z = pk_bf16(v[4], v[5]); w.w = pk_bf16(v[6], v[7]);
;                         *(u32x4*)(mrg + row * 1024 + col) = w;
;                     }
	v_lshlrev_b32_e32 v214, 16, v182
	v_and_b32_e32 v215, 0xffff0000, v182
	v_lshlrev_b32_e32 v182, 16, v183
	v_and_b32_e32 v183, 0xffff0000, v183
	v_lshlrev_b32_e32 v216, 16, v184
	v_and_b32_e32 v217, 0xffff0000, v184
	v_lshlrev_b32_e32 v184, 16, v185
	v_and_b32_e32 v185, 0xffff0000, v185
	v_lshlrev_b32_e32 v228, 16, v194
	v_and_b32_e32 v229, 0xffff0000, v194
	v_lshlrev_b32_e32 v194, 16, v195
	v_and_b32_e32 v195, 0xffff0000, v195
	v_lshlrev_b32_e32 v230, 16, v196
	v_and_b32_e32 v231, 0xffff0000, v196
	v_lshlrev_b32_e32 v196, 16, v197
	v_and_b32_e32 v197, 0xffff0000, v197
	v_lshlrev_b32_e32 v218, 16, v186
	v_and_b32_e32 v219, 0xffff0000, v186
	v_lshlrev_b32_e32 v186, 16, v187
	v_and_b32_e32 v187, 0xffff0000, v187
	v_lshlrev_b32_e32 v220, 16, v188
	v_and_b32_e32 v221, 0xffff0000, v188
	v_lshlrev_b32_e32 v188, 16, v189
	v_and_b32_e32 v189, 0xffff0000, v189
	v_lshlrev_b32_e32 v232, 16, v198
	v_and_b32_e32 v233, 0xffff0000, v198
	v_lshlrev_b32_e32 v198, 16, v199
	v_and_b32_e32 v199, 0xffff0000, v199
	v_lshlrev_b32_e32 v234, 16, v200
	v_and_b32_e32 v235, 0xffff0000, v200
	v_lshlrev_b32_e32 v200, 16, v201
	v_and_b32_e32 v201, 0xffff0000, v201
	v_pk_fma_f32 v[214:215], v[124:125], v[228:229], v[214:215]
	v_pk_fma_f32 v[194:195], v[126:127], v[194:195], v[182:183]
	v_pk_fma_f32 v[216:217], v[120:121], v[230:231], v[216:217]
	v_pk_fma_f32 v[196:197], v[122:123], v[196:197], v[184:185]
	v_pk_fma_f32 v[218:219], v[116:117], v[232:233], v[218:219]
	v_pk_fma_f32 v[198:199], v[118:119], v[198:199], v[186:187]
	v_pk_fma_f32 v[220:221], v[112:113], v[234:235], v[220:221]
	v_pk_fma_f32 v[200:201], v[114:115], v[200:201], v[188:189]
	v_cvt_pk_bf16_f32 v182, v214, v215
	v_cvt_pk_bf16_f32 v183, v194, v195
	v_cvt_pk_bf16_f32 v184, v216, v217
	v_cvt_pk_bf16_f32 v185, v196, v197
	v_lshlrev_b32_e32 v224, 16, v190
	v_and_b32_e32 v225, 0xffff0000, v190
	v_lshlrev_b32_e32 v190, 16, v191
	v_and_b32_e32 v191, 0xffff0000, v191
	v_lshlrev_b32_e32 v226, 16, v192
	v_and_b32_e32 v227, 0xffff0000, v192
	v_lshlrev_b32_e32 v228, 16, v202
	v_and_b32_e32 v229, 0xffff0000, v202
	v_lshlrev_b32_e32 v202, 16, v203
	v_and_b32_e32 v203, 0xffff0000, v203
	v_lshlrev_b32_e32 v230, 16, v204
	v_and_b32_e32 v231, 0xffff0000, v204
	v_cvt_pk_bf16_f32 v186, v218, v219
	v_cvt_pk_bf16_f32 v187, v198, v199
	v_cvt_pk_bf16_f32 v188, v220, v221
	v_cvt_pk_bf16_f32 v189, v200, v201
	global_store_dwordx4 v[166:167], v[182:185], off
	global_store_dwordx4 v[166:167], v[186:189], off offset:256
	v_pk_fma_f32 v[194:195], v[108:109], v[228:229], v[224:225]
	v_lshlrev_b32_e32 v182, 16, v205
	v_and_b32_e32 v183, 0xffff0000, v205
	v_lshlrev_b32_e32 v184, 16, v193
	v_and_b32_e32 v185, 0xffff0000, v193
	v_pk_fma_f32 v[190:191], v[110:111], v[202:203], v[190:191]
	v_pk_fma_f32 v[196:197], v[104:105], v[230:231], v[226:227]
	v_pk_fma_f32 v[186:187], v[106:107], v[182:183], v[184:185]
	v_cvt_pk_bf16_f32 v182, v194, v195
	v_cvt_pk_bf16_f32 v183, v190, v191
	v_cvt_pk_bf16_f32 v184, v196, v197
	v_cvt_pk_bf16_f32 v185, v186, v187
	global_store_dwordx4 v[174:175], v[182:185], off
	v_lshlrev_b32_e32 v186, 16, v211
	v_and_b32_e32 v187, 0xffff0000, v211
	v_lshlrev_b32_e32 v182, 16, v206
	v_and_b32_e32 v183, 0xffff0000, v206
	v_lshlrev_b32_e32 v184, 16, v210
	v_and_b32_e32 v185, 0xffff0000, v210
	v_pk_fma_f32 v[182:183], v[100:101], v[182:183], v[184:185]
	v_lshlrev_b32_e32 v184, 16, v207
	v_and_b32_e32 v185, 0xffff0000, v207
	v_pk_fma_f32 v[184:185], v[102:103], v[184:185], v[186:187]
	v_lshlrev_b32_e32 v186, 16, v208
	v_and_b32_e32 v187, 0xffff0000, v208
	v_lshlrev_b32_e32 v188, 16, v212
	v_and_b32_e32 v189, 0xffff0000, v212
	v_pk_fma_f32 v[190:191], v[96:97], v[186:187], v[188:189]
	v_lshlrev_b32_e32 v186, 16, v209
	v_and_b32_e32 v187, 0xffff0000, v209
	v_lshlrev_b32_e32 v188, 16, v213
	v_and_b32_e32 v189, 0xffff0000, v213
	v_cvt_pk_bf16_f32 v182, v182, v183
	v_cvt_pk_bf16_f32 v183, v184, v185
	v_lshlrev_b64 v[184:185], 11, v[158:159]
	v_pk_fma_f32 v[192:193], v[98:99], v[186:187], v[188:189]
	v_lshl_add_u64 v[184:185], s[36:37], 0, v[184:185]
	v_lshl_add_u64 v[210:211], v[184:185], 0, v[170:171]
	v_cvt_pk_bf16_f32 v184, v190, v191
	v_cvt_pk_bf16_f32 v185, v192, v193
	global_load_dwordx4 v[186:189], v[210:211], off
	s_waitcnt vmcnt(0)
	v_lshlrev_b32_e32 v214, 16, v188
	global_store_dwordx4 v[174:175], v[182:185], off offset:256
	v_add_co_u32_e32 v174, vcc, s49, v172
	v_and_b32_e32 v215, 0xffff0000, v188
	s_nop 0
	v_addc_co_u32_e32 v175, vcc, 0, v173, vcc
	global_load_dwordx4 v[182:185], v[174:175], off
	global_load_dwordx4 v[190:193], v[174:175], off offset:256
	global_load_dwordx4 v[194:197], v[210:211], off offset:256
	v_add_co_u32_e32 v202, vcc, s50, v172
	v_lshlrev_b64 v[174:175], 11, v[156:157]
	s_nop 0
	v_addc_co_u32_e32 v203, vcc, 0, v173, vcc
	v_lshl_add_u64 v[198:199], s[36:37], 0, v[174:175]
	global_load_dwordx4 v[172:175], v[202:203], off
	v_lshl_add_u64 v[212:213], v[198:199], 0, v[170:171]
	global_load_dwordx4 v[198:201], v[212:213], off
	s_nop 0
	global_load_dwordx4 v[202:205], v[202:203], off offset:256
	s_nop 0
	global_load_dwordx4 v[206:209], v[212:213], off offset:256
	v_lshlrev_b32_e32 v170, 16, v186
	v_and_b32_e32 v171, 0xffff0000, v186
	v_lshlrev_b32_e32 v186, 16, v187
	v_and_b32_e32 v187, 0xffff0000, v187
	v_lshlrev_b32_e32 v188, 16, v189
	v_and_b32_e32 v189, 0xffff0000, v189
	s_waitcnt vmcnt(0)
; DI unsigned pk_bf16(float lo, float hi) { f32x2 v = {lo, hi}; return __builtin_bit_cast(unsigned, __builtin_convertvector(v, bf16v2)); }
; DI float bf_lo(unsigned w) { return __uint_as_float(w << 16); }
; DI float bf_hi(unsigned w) { return __uint_as_float(w & 0xffff0000u); }
;     DI void operator()(AccRef acc, const Unit& u, int wr, int wc, int fr, int fq) const {
;     ...
;                 u32x4 gv[2][2], mv[2][2];
; #pragma unroll
;                 for (int mm = 0; mm < 2; ++mm)
; #pragma unroll
;                     for (int bj = 0; bj < 2; ++bj) {
;                         const size_t row = (size_t)(row0 + ai * 128 + (mh * 2 + mm) * 16); const int col = col0 + bj * 128;
;                         gv[mm][bj] = *(const u32x4*)(gab + (size_t)(u.pm * 8 + SECOND * 4 + u.pn) * 65536 + (wr * 64 + fr + ai * 128 + (mh * 2 + mm) * 16) * 256 + wc * 32 + 8 * fq + bj * 128);
;                         if (SECOND) mv[mm][bj] = *(const u32x4*)(mrg + row * 1024 + col);
;                     }
; #pragma unroll
;                 for (int mm = 0; mm < 2; ++mm)
; #pragma unroll
;                     for (int bj = 0; bj < 2; ++bj) {
;                         const int m = mh * 2 + mm;
;                         const size_t row = (size_t)(row0 + ai * 128 + m * 16); const int col = col0 + bj * 128;
;                         const u32x4 gt = gv[mm][bj];
;                         const f32x4 r0 = acc[ai][bj][m][0], r1 = acc[ai][bj][m][1];
;                         float v[8] = {bf_lo(gt.x) * r0[0], bf_hi(gt.x) * r0[1], bf_lo(gt.y) * r0[2], bf_hi(gt.y) * r0[3], bf_lo(gt.z) * r1[0], bf_hi(gt.z) * r1[1], bf_lo(gt.w) * r1[2], bf_hi(gt.w) * r1[3]};
;                         if (SECOND) { const u32x4 o = mv[mm][bj]; v[0] += bf_lo(o.x); v[1] += bf_hi(o.x); v[2] += bf_lo(o.y); v[3] += bf_hi(o.y); v[4] += bf_lo(o.z); v[5] += bf_hi(o.z); v[6] += bf_lo(o.w); v[7] += bf_hi(o.w); }
;                         u32x4 w; w.x = pk_bf16(v[0], v[1]); w.y = pk_bf16(v[2], v[3]); w.z = pk_bf16(v[4], v[5]); w.w = pk_bf16(v[6], v[7]);
;                         *(u32x4*)(mrg + row * 1024 + col) = w;
;                     }
	v_lshlrev_b32_e32 v216, 16, v182
	v_and_b32_e32 v217, 0xffff0000, v182
	v_lshlrev_b32_e32 v182, 16, v183
	v_and_b32_e32 v183, 0xffff0000, v183
	v_lshlrev_b32_e32 v218, 16, v184
	v_and_b32_e32 v219, 0xffff0000, v184
	v_lshlrev_b32_e32 v184, 16, v185
	v_and_b32_e32 v185, 0xffff0000, v185
	v_pk_fma_f32 v[170:171], v[92:93], v[216:217], v[170:171]
	v_pk_fma_f32 v[186:187], v[94:95], v[182:183], v[186:187]
	v_pk_fma_f32 v[214:215], v[88:89], v[218:219], v[214:215]
	v_pk_fma_f32 v[188:189], v[90:91], v[184:185], v[188:189]
	v_cvt_pk_bf16_f32 v182, v170, v171
	v_cvt_pk_bf16_f32 v183, v186, v187
	v_cvt_pk_bf16_f32 v184, v214, v215
	v_cvt_pk_bf16_f32 v185, v188, v189
	global_store_dwordx4 v[210:211], v[182:185], off
	v_lshlrev_b32_e32 v186, 16, v196
	v_and_b32_e32 v187, 0xffff0000, v196
	v_lshlrev_b32_e32 v182, 16, v191
	v_and_b32_e32 v183, 0xffff0000, v191
	v_lshlrev_b32_e32 v184, 16, v195
	v_and_b32_e32 v185, 0xffff0000, v195
	v_pk_fma_f32 v[184:185], v[78:79], v[182:183], v[184:185]
	v_lshlrev_b32_e32 v182, 16, v192
	v_and_b32_e32 v183, 0xffff0000, v192
	v_lshlrev_b32_e32 v220, 16, v190
	v_and_b32_e32 v221, 0xffff0000, v190
	v_lshlrev_b32_e32 v170, 16, v194
	v_and_b32_e32 v171, 0xffff0000, v194
	v_pk_fma_f32 v[186:187], v[72:73], v[182:183], v[186:187]
	v_lshlrev_b32_e32 v182, 16, v193
	v_and_b32_e32 v183, 0xffff0000, v193
	v_lshlrev_b32_e32 v188, 16, v197
	v_and_b32_e32 v189, 0xffff0000, v197
	v_pk_fma_f32 v[170:171], v[76:77], v[220:221], v[170:171]
	v_pk_fma_f32 v[188:189], v[74:75], v[182:183], v[188:189]
	v_cvt_pk_bf16_f32 v182, v170, v171
	v_cvt_pk_bf16_f32 v183, v184, v185
	v_cvt_pk_bf16_f32 v184, v186, v187
	v_cvt_pk_bf16_f32 v185, v188, v189
	global_store_dwordx4 v[210:211], v[182:185], off offset:256
	v_lshlrev_b32_e32 v170, 16, v172
	v_and_b32_e32 v171, 0xffff0000, v172
	v_lshlrev_b32_e32 v182, 16, v198
	v_and_b32_e32 v183, 0xffff0000, v198
	v_pk_fma_f32 v[170:171], v[84:85], v[170:171], v[182:183]
	v_lshlrev_b32_e32 v172, 16, v173
	v_and_b32_e32 v173, 0xffff0000, v173
	v_lshlrev_b32_e32 v182, 16, v199
	v_and_b32_e32 v183, 0xffff0000, v199
	v_pk_fma_f32 v[172:173], v[86:87], v[172:173], v[182:183]
	v_lshlrev_b32_e32 v182, 16, v174
	v_and_b32_e32 v183, 0xffff0000, v174
	v_lshlrev_b32_e32 v184, 16, v200
	v_and_b32_e32 v185, 0xffff0000, v200
	v_pk_fma_f32 v[182:183], v[80:81], v[182:183], v[184:185]
	v_lshlrev_b32_e32 v174, 16, v175
	v_and_b32_e32 v175, 0xffff0000, v175
	v_lshlrev_b32_e32 v184, 16, v201
	v_and_b32_e32 v185, 0xffff0000, v201
	v_pk_fma_f32 v[174:175], v[82:83], v[174:175], v[184:185]
	v_cvt_pk_bf16_f32 v170, v170, v171
	v_cvt_pk_bf16_f32 v171, v172, v173
	v_cvt_pk_bf16_f32 v172, v182, v183
	v_cvt_pk_bf16_f32 v173, v174, v175
	global_store_dwordx4 v[212:213], v[170:173], off
	v_lshlrev_b32_e32 v174, 16, v207
	v_and_b32_e32 v175, 0xffff0000, v207
	v_lshlrev_b32_e32 v170, 16, v202
	v_and_b32_e32 v171, 0xffff0000, v202
	v_lshlrev_b32_e32 v172, 16, v206
	v_and_b32_e32 v173, 0xffff0000, v206
	v_pk_fma_f32 v[170:171], v[68:69], v[170:171], v[172:173]
	v_lshlrev_b32_e32 v172, 16, v203
	v_and_b32_e32 v173, 0xffff0000, v203
	v_pk_fma_f32 v[172:173], v[70:71], v[172:173], v[174:175]
	v_lshlrev_b32_e32 v174, 16, v204
	v_and_b32_e32 v175, 0xffff0000, v204
	v_lshlrev_b32_e32 v182, 16, v208
	v_and_b32_e32 v183, 0xffff0000, v208
	v_pk_fma_f32 v[174:175], v[64:65], v[174:175], v[182:183]
	v_lshlrev_b32_e32 v182, 16, v205
	v_and_b32_e32 v183, 0xffff0000, v205
	v_lshlrev_b32_e32 v184, 16, v209
	v_and_b32_e32 v185, 0xffff0000, v209
	v_pk_fma_f32 v[182:183], v[66:67], v[182:183], v[184:185]
	v_cvt_pk_bf16_f32 v170, v170, v171
	v_cvt_pk_bf16_f32 v171, v172, v173
	v_cvt_pk_bf16_f32 v172, v174, v175
	v_cvt_pk_bf16_f32 v173, v182, v183
	global_store_dwordx4 v[212:213], v[170:173], off offset:256
	v_lshl_add_u64 v[174:175], v[140:141], 1, v[168:169]
	v_add_co_u32_e32 v210, vcc, s61, v166
	global_load_dwordx4 v[170:173], v[174:175], off
	s_nop 0
	v_addc_co_u32_e32 v211, vcc, 0, v167, vcc
	global_load_dwordx4 v[182:185], v[210:211], off
	global_load_dwordx4 v[186:189], v[174:175], off offset:256
	v_lshl_add_u64 v[174:175], v[166:167], 0, s[0:1]
	global_load_dwordx4 v[190:193], v[174:175], off offset:256
	v_lshl_add_u64 v[202:203], v[142:143], 1, v[168:169]
	v_add_co_u32_e32 v212, vcc, s62, v166
	global_load_dwordx4 v[194:197], v[202:203], off
	s_nop 0
	v_addc_co_u32_e32 v213, vcc, 0, v167, vcc
	global_load_dwordx4 v[198:201], v[212:213], off
	s_nop 0
	global_load_dwordx4 v[202:205], v[202:203], off offset:256
	v_lshl_add_u64 v[214:215], v[166:167], 0, s[10:11]
	global_load_dwordx4 v[206:209], v[214:215], off offset:256
	s_waitcnt vmcnt(0)
; DI unsigned pk_bf16(float lo, float hi) { f32x2 v = {lo, hi}; return __builtin_bit_cast(unsigned, __builtin_convertvector(v, bf16v2)); }
; DI float bf_lo(unsigned w) { return __uint_as_float(w << 16); }
; DI float bf_hi(unsigned w) { return __uint_as_float(w & 0xffff0000u); }
;     DI void operator()(AccRef acc, const Unit& u, int wr, int wc, int fr, int fq) const {
;     ...
;                 u32x4 gv[2][2], mv[2][2];
; #pragma unroll
;                 for (int mm = 0; mm < 2; ++mm)
; #pragma unroll
;                     for (int bj = 0; bj < 2; ++bj) {
;                         const size_t row = (size_t)(row0 + ai * 128 + (mh * 2 + mm) * 16); const int col = col0 + bj * 128;
;                         gv[mm][bj] = *(const u32x4*)(gab + (size_t)(u.pm * 8 + SECOND * 4 + u.pn) * 65536 + (wr * 64 + fr + ai * 128 + (mh * 2 + mm) * 16) * 256 + wc * 32 + 8 * fq + bj * 128);
;                         if (SECOND) mv[mm][bj] = *(const u32x4*)(mrg + row * 1024 + col);
;                     }
; #pragma unroll
;                 for (int mm = 0; mm < 2; ++mm)
; #pragma unroll
;                     for (int bj = 0; bj < 2; ++bj) {
;                         const int m = mh * 2 + mm;
;                         const size_t row = (size_t)(row0 + ai * 128 + m * 16); const int col = col0 + bj * 128;
;                         const u32x4 gt = gv[mm][bj];
;                         const f32x4 r0 = acc[ai][bj][m][0], r1 = acc[ai][bj][m][1];
;                         float v[8] = {bf_lo(gt.x) * r0[0], bf_hi(gt.x) * r0[1], bf_lo(gt.y) * r0[2], bf_hi(gt.y) * r0[3], bf_lo(gt.z) * r1[0], bf_hi(gt.z) * r1[1], bf_lo(gt.w) * r1[2], bf_hi(gt.w) * r1[3]};
;                         if (SECOND) { const u32x4 o = mv[mm][bj]; v[0] += bf_lo(o.x); v[1] += bf_hi(o.x); v[2] += bf_lo(o.y); v[3] += bf_hi(o.y); v[4] += bf_lo(o.z); v[5] += bf_hi(o.z); v[6] += bf_lo(o.w); v[7] += bf_hi(o.w); }
;                         u32x4 w; w.x = pk_bf16(v[0], v[1]); w.y = pk_bf16(v[2], v[3]); w.z = pk_bf16(v[4], v[5]); w.w = pk_bf16(v[6], v[7]);
;                         *(u32x4*)(mrg + row * 1024 + col) = w;
;                     }
	v_lshlrev_b32_e32 v216, 16, v170
	v_and_b32_e32 v217, 0xffff0000, v170
	v_lshlrev_b32_e32 v218, 16, v182
	v_and_b32_e32 v219, 0xffff0000, v182
	v_lshlrev_b32_e32 v170, 16, v171
	v_and_b32_e32 v171, 0xffff0000, v171
	v_lshlrev_b32_e32 v182, 16, v183
	v_and_b32_e32 v183, 0xffff0000, v183
	v_pk_fma_f32 v[216:217], v[60:61], v[216:217], v[218:219]
	v_pk_fma_f32 v[182:183], v[62:63], v[170:171], v[182:183]
	v_lshlrev_b32_e32 v170, 16, v172
	v_and_b32_e32 v171, 0xffff0000, v172
	v_lshlrev_b32_e32 v218, 16, v184
	v_and_b32_e32 v219, 0xffff0000, v184
	v_pk_fma_f32 v[218:219], v[56:57], v[170:171], v[218:219]
	v_lshlrev_b32_e32 v170, 16, v173
	v_and_b32_e32 v171, 0xffff0000, v173
	v_lshlrev_b32_e32 v172, 16, v185
	v_and_b32_e32 v173, 0xffff0000, v185
	v_pk_fma_f32 v[184:185], v[58:59], v[170:171], v[172:173]
	v_cvt_pk_bf16_f32 v170, v216, v217
	v_cvt_pk_bf16_f32 v171, v182, v183
	v_cvt_pk_bf16_f32 v172, v218, v219
	v_cvt_pk_bf16_f32 v173, v184, v185
	global_store_dwordx4 v[210:211], v[170:173], off
	v_lshlrev_b32_e32 v182, 16, v191
	v_and_b32_e32 v183, 0xffff0000, v191
	v_lshlrev_b32_e32 v170, 16, v186
	v_and_b32_e32 v171, 0xffff0000, v186
	v_lshlrev_b32_e32 v172, 16, v190
	v_and_b32_e32 v173, 0xffff0000, v190
	v_pk_fma_f32 v[170:171], v[44:45], v[170:171], v[172:173]
	v_lshlrev_b32_e32 v172, 16, v187
	v_and_b32_e32 v173, 0xffff0000, v187
	v_pk_fma_f32 v[172:173], v[46:47], v[172:173], v[182:183]
	v_lshlrev_b32_e32 v182, 16, v188
	v_and_b32_e32 v183, 0xffff0000, v188
	v_lshlrev_b32_e32 v184, 16, v192
	v_and_b32_e32 v185, 0xffff0000, v192
	v_pk_fma_f32 v[182:183], v[40:41], v[182:183], v[184:185]
	v_lshlrev_b32_e32 v184, 16, v189
	v_and_b32_e32 v185, 0xffff0000, v189
	v_lshlrev_b32_e32 v186, 16, v193
	v_and_b32_e32 v187, 0xffff0000, v193
	v_pk_fma_f32 v[184:185], v[42:43], v[184:185], v[186:187]
	v_cvt_pk_bf16_f32 v170, v170, v171
	v_cvt_pk_bf16_f32 v171, v172, v173
	v_cvt_pk_bf16_f32 v172, v182, v183
	v_cvt_pk_bf16_f32 v173, v184, v185
	global_store_dwordx4 v[174:175], v[170:173], off offset:256
	v_lshlrev_b32_e32 v174, 16, v199
	v_and_b32_e32 v175, 0xffff0000, v199
	v_lshlrev_b32_e32 v170, 16, v194
	v_and_b32_e32 v171, 0xffff0000, v194
	v_lshlrev_b32_e32 v172, 16, v198
	v_and_b32_e32 v173, 0xffff0000, v198
	v_pk_fma_f32 v[170:171], v[52:53], v[170:171], v[172:173]
	v_lshlrev_b32_e32 v172, 16, v195
	v_and_b32_e32 v173, 0xffff0000, v195
	v_pk_fma_f32 v[172:173], v[54:55], v[172:173], v[174:175]
	v_lshlrev_b32_e32 v174, 16, v196
	v_and_b32_e32 v175, 0xffff0000, v196
	v_lshlrev_b32_e32 v182, 16, v200
	v_and_b32_e32 v183, 0xffff0000, v200
	v_pk_fma_f32 v[174:175], v[48:49], v[174:175], v[182:183]
	v_lshlrev_b32_e32 v182, 16, v197
	v_and_b32_e32 v183, 0xffff0000, v197
	v_lshlrev_b32_e32 v184, 16, v201
	v_and_b32_e32 v185, 0xffff0000, v201
	v_pk_fma_f32 v[182:183], v[50:51], v[182:183], v[184:185]
	v_cvt_pk_bf16_f32 v170, v170, v171
	v_cvt_pk_bf16_f32 v171, v172, v173
	v_cvt_pk_bf16_f32 v172, v174, v175
	v_cvt_pk_bf16_f32 v173, v182, v183
	global_store_dwordx4 v[212:213], v[170:173], off
	v_lshlrev_b32_e32 v174, 16, v207
	v_and_b32_e32 v175, 0xffff0000, v207
	v_lshlrev_b32_e32 v170, 16, v202
	v_and_b32_e32 v171, 0xffff0000, v202
	v_lshlrev_b32_e32 v172, 16, v206
	v_and_b32_e32 v173, 0xffff0000, v206
	v_pk_fma_f32 v[170:171], v[36:37], v[170:171], v[172:173]
	v_lshlrev_b32_e32 v172, 16, v203
	v_and_b32_e32 v173, 0xffff0000, v203
	v_pk_fma_f32 v[172:173], v[38:39], v[172:173], v[174:175]
	v_lshlrev_b32_e32 v174, 16, v204
	v_and_b32_e32 v175, 0xffff0000, v204
	v_lshlrev_b32_e32 v182, 16, v208
	v_and_b32_e32 v183, 0xffff0000, v208
	v_pk_fma_f32 v[174:175], v[32:33], v[174:175], v[182:183]
	v_lshlrev_b32_e32 v182, 16, v205
	v_and_b32_e32 v183, 0xffff0000, v205
	v_lshlrev_b32_e32 v184, 16, v209
	v_and_b32_e32 v185, 0xffff0000, v209
	v_pk_fma_f32 v[182:183], v[34:35], v[182:183], v[184:185]
	v_cvt_pk_bf16_f32 v170, v170, v171
	v_cvt_pk_bf16_f32 v171, v172, v173
	v_cvt_pk_bf16_f32 v172, v174, v175
	v_cvt_pk_bf16_f32 v173, v182, v183
	global_store_dwordx4 v[214:215], v[170:173], off offset:256
	v_lshl_add_u64 v[174:175], v[144:145], 1, v[168:169]
	v_add_co_u32_e32 v206, vcc, s63, v166
	global_load_dwordx4 v[170:173], v[174:175], off
	s_nop 0
	v_addc_co_u32_e32 v207, vcc, 0, v167, vcc
	global_load_dwordx4 v[182:185], v[206:207], off
	global_load_dwordx4 v[186:189], v[174:175], off offset:256
	v_lshl_add_u64 v[174:175], v[166:167], 0, s[12:13]
	global_load_dwordx4 v[190:193], v[174:175], off offset:256
	v_lshl_add_u64 v[168:169], v[146:147], 1, v[168:169]
	v_add_co_u32_e32 v208, vcc, s64, v166
	global_load_dwordx4 v[194:197], v[168:169], off
	s_nop 0
	v_addc_co_u32_e32 v209, vcc, 0, v167, vcc
	global_load_dwordx4 v[198:201], v[208:209], off
	global_load_dwordx4 v[202:205], v[168:169], off offset:256
	v_lshl_add_u64 v[210:211], v[166:167], 0, s[14:15]
	global_load_dwordx4 v[166:169], v[210:211], off offset:256
	s_waitcnt vmcnt(0)
; DI unsigned pk_bf16(float lo, float hi) { f32x2 v = {lo, hi}; return __builtin_bit_cast(unsigned, __builtin_convertvector(v, bf16v2)); }
; DI float bf_lo(unsigned w) { return __uint_as_float(w << 16); }
; DI float bf_hi(unsigned w) { return __uint_as_float(w & 0xffff0000u); }
;     DI void operator()(AccRef acc, const Unit& u, int wr, int wc, int fr, int fq) const {
;     ...
;                 u32x4 gv[2][2], mv[2][2];
; #pragma unroll
;                 for (int mm = 0; mm < 2; ++mm)
; #pragma unroll
;                     for (int bj = 0; bj < 2; ++bj) {
;                         const size_t row = (size_t)(row0 + ai * 128 + (mh * 2 + mm) * 16); const int col = col0 + bj * 128;
;                         gv[mm][bj] = *(const u32x4*)(gab + (size_t)(u.pm * 8 + SECOND * 4 + u.pn) * 65536 + (wr * 64 + fr + ai * 128 + (mh * 2 + mm) * 16) * 256 + wc * 32 + 8 * fq + bj * 128);
;                         if (SECOND) mv[mm][bj] = *(const u32x4*)(mrg + row * 1024 + col);
;                     }
; #pragma unroll
;                 for (int mm = 0; mm < 2; ++mm)
; #pragma unroll
;                     for (int bj = 0; bj < 2; ++bj) {
;                         const int m = mh * 2 + mm;
;                         const size_t row = (size_t)(row0 + ai * 128 + m * 16); const int col = col0 + bj * 128;
;                         const u32x4 gt = gv[mm][bj];
;                         const f32x4 r0 = acc[ai][bj][m][0], r1 = acc[ai][bj][m][1];
;                         float v[8] = {bf_lo(gt.x) * r0[0], bf_hi(gt.x) * r0[1], bf_lo(gt.y) * r0[2], bf_hi(gt.y) * r0[3], bf_lo(gt.z) * r1[0], bf_hi(gt.z) * r1[1], bf_lo(gt.w) * r1[2], bf_hi(gt.w) * r1[3]};
;                         if (SECOND) { const u32x4 o = mv[mm][bj]; v[0] += bf_lo(o.x); v[1] += bf_hi(o.x); v[2] += bf_lo(o.y); v[3] += bf_hi(o.y); v[4] += bf_lo(o.z); v[5] += bf_hi(o.z); v[6] += bf_lo(o.w); v[7] += bf_hi(o.w); }
;                         u32x4 w; w.x = pk_bf16(v[0], v[1]); w.y = pk_bf16(v[2], v[3]); w.z = pk_bf16(v[4], v[5]); w.w = pk_bf16(v[6], v[7]);
;                         *(u32x4*)(mrg + row * 1024 + col) = w;
;                     }
	v_lshlrev_b32_e32 v212, 16, v170
	v_and_b32_e32 v213, 0xffff0000, v170
	v_lshlrev_b32_e32 v214, 16, v182
	v_and_b32_e32 v215, 0xffff0000, v182
	v_lshlrev_b32_e32 v170, 16, v171
	v_and_b32_e32 v171, 0xffff0000, v171
	v_lshlrev_b32_e32 v182, 16, v183
	v_and_b32_e32 v183, 0xffff0000, v183
	v_pk_fma_f32 v[212:213], v[28:29], v[212:213], v[214:215]
	v_pk_fma_f32 v[182:183], v[30:31], v[170:171], v[182:183]
	v_lshlrev_b32_e32 v170, 16, v172
	v_and_b32_e32 v171, 0xffff0000, v172
	v_lshlrev_b32_e32 v214, 16, v184
	v_and_b32_e32 v215, 0xffff0000, v184
	v_pk_fma_f32 v[214:215], v[24:25], v[170:171], v[214:215]
	v_lshlrev_b32_e32 v170, 16, v173
	v_and_b32_e32 v171, 0xffff0000, v173
	v_lshlrev_b32_e32 v172, 16, v185
	v_and_b32_e32 v173, 0xffff0000, v185
	v_pk_fma_f32 v[184:185], v[26:27], v[170:171], v[172:173]
	v_cvt_pk_bf16_f32 v170, v212, v213
	v_cvt_pk_bf16_f32 v171, v182, v183
	v_cvt_pk_bf16_f32 v172, v214, v215
	v_cvt_pk_bf16_f32 v173, v184, v185
	global_store_dwordx4 v[206:207], v[170:173], off
	v_lshlrev_b32_e32 v182, 16, v191
	v_and_b32_e32 v183, 0xffff0000, v191
	v_lshlrev_b32_e32 v170, 16, v186
	v_and_b32_e32 v171, 0xffff0000, v186
	v_lshlrev_b32_e32 v172, 16, v190
	v_and_b32_e32 v173, 0xffff0000, v190
	v_pk_fma_f32 v[170:171], v[12:13], v[170:171], v[172:173]
	v_lshlrev_b32_e32 v172, 16, v187
	v_and_b32_e32 v173, 0xffff0000, v187
	v_pk_fma_f32 v[172:173], v[14:15], v[172:173], v[182:183]
	v_lshlrev_b32_e32 v182, 16, v188
	v_and_b32_e32 v183, 0xffff0000, v188
	v_lshlrev_b32_e32 v184, 16, v192
	v_and_b32_e32 v185, 0xffff0000, v192
	v_pk_fma_f32 v[182:183], v[8:9], v[182:183], v[184:185]
	v_lshlrev_b32_e32 v184, 16, v189
	v_and_b32_e32 v185, 0xffff0000, v189
	v_lshlrev_b32_e32 v186, 16, v193
	v_and_b32_e32 v187, 0xffff0000, v193
	v_pk_fma_f32 v[184:185], v[10:11], v[184:185], v[186:187]
	v_cvt_pk_bf16_f32 v170, v170, v171
	v_cvt_pk_bf16_f32 v171, v172, v173
	v_cvt_pk_bf16_f32 v172, v182, v183
	v_cvt_pk_bf16_f32 v173, v184, v185
	global_store_dwordx4 v[174:175], v[170:173], off offset:256
	v_lshlrev_b32_e32 v174, 16, v199
	v_and_b32_e32 v175, 0xffff0000, v199
	v_lshlrev_b32_e32 v170, 16, v194
	v_and_b32_e32 v171, 0xffff0000, v194
	v_lshlrev_b32_e32 v172, 16, v198
	v_and_b32_e32 v173, 0xffff0000, v198
	v_pk_fma_f32 v[170:171], v[20:21], v[170:171], v[172:173]
	v_lshlrev_b32_e32 v172, 16, v195
	v_and_b32_e32 v173, 0xffff0000, v195
	v_pk_fma_f32 v[172:173], v[22:23], v[172:173], v[174:175]
	v_lshlrev_b32_e32 v174, 16, v196
	v_and_b32_e32 v175, 0xffff0000, v196
	v_lshlrev_b32_e32 v182, 16, v200
	v_and_b32_e32 v183, 0xffff0000, v200
	v_pk_fma_f32 v[174:175], v[16:17], v[174:175], v[182:183]
	v_lshlrev_b32_e32 v182, 16, v197
	v_and_b32_e32 v183, 0xffff0000, v197
	v_lshlrev_b32_e32 v184, 16, v201
	v_and_b32_e32 v185, 0xffff0000, v201
	v_pk_fma_f32 v[182:183], v[18:19], v[182:183], v[184:185]
	v_cvt_pk_bf16_f32 v170, v170, v171
	v_cvt_pk_bf16_f32 v171, v172, v173
	v_cvt_pk_bf16_f32 v172, v174, v175
	v_cvt_pk_bf16_f32 v173, v182, v183
	global_store_dwordx4 v[208:209], v[170:173], off
	v_lshlrev_b32_e32 v174, 16, v168
	v_and_b32_e32 v175, 0xffff0000, v168
	v_lshlrev_b32_e32 v170, 16, v202
	v_and_b32_e32 v171, 0xffff0000, v202
	v_lshlrev_b32_e32 v172, 16, v166
	v_and_b32_e32 v173, 0xffff0000, v166
	v_pk_fma_f32 v[170:171], v[4:5], v[170:171], v[172:173]
	v_lshlrev_b32_e32 v172, 16, v203
	v_and_b32_e32 v173, 0xffff0000, v203
	v_lshlrev_b32_e32 v166, 16, v167
	v_and_b32_e32 v167, 0xffff0000, v167
	v_pk_fma_f32 v[172:173], v[6:7], v[172:173], v[166:167]
	v_lshlrev_b32_e32 v166, 16, v204
	v_and_b32_e32 v167, 0xffff0000, v204
	v_pk_fma_f32 v[174:175], v[0:1], v[166:167], v[174:175]
	v_lshlrev_b32_e32 v166, 16, v205
	v_and_b32_e32 v167, 0xffff0000, v205
	v_lshlrev_b32_e32 v168, 16, v169
	v_and_b32_e32 v169, 0xffff0000, v169
	v_pk_fma_f32 v[182:183], v[2:3], v[166:167], v[168:169]
	v_cvt_pk_bf16_f32 v166, v170, v171
	v_cvt_pk_bf16_f32 v167, v172, v173
	v_cvt_pk_bf16_f32 v168, v174, v175
	v_cvt_pk_bf16_f32 v169, v182, v183
	global_store_dwordx4 v[210:211], v[166:169], off offset:256

; #define PG8_STAGE(bufoff, gbase, voff) do { _Pragma("unroll") for (int _i = 0; _i < 2; ++_i) \
;         __builtin_amdgcn_global_load_lds((const unsigned*)((const char*)(gbase) + (voff)[_i]), (LAS unsigned*)(lds + (bufoff) + ldsw + _i * 8192), 16, 0, 0); } while (0)
; #define PG8_LDA(dst, b, h) do { _Pragma("unroll") for (int m = 0; m < 4; ++m) _Pragma("unroll") for (int k = 0; k < 2; ++k) dst[m][k] = *(const LAS bf16x8*)(lds + PG8_SA(b, h) + aoff + m * 2048 + k * 1024); } while (0)
; #define PG8_LDB(dst, b, h) do { _Pragma("unroll") for (int n = 0; n < 2; ++n) _Pragma("unroll") for (int k = 0; k < 2; ++k) dst[n][k] = *(const LAS bf16x8*)(lds + PG8_SB(b, h) + boff + n * 2048 + k * 1024); } while (0)
; #define PG8_MMA(ai, bj, At, Bt) do { __builtin_amdgcn_s_setprio(1); _Pragma("unroll") for (int m = 0; m < 4; ++m) _Pragma("unroll") for (int n = 0; n < 2; ++n) _Pragma("unroll") for (int k = 0; k < 2; ++k) \
;         acc[ai][bj][m][n] = __builtin_amdgcn_mfma_f32_16x16x32_bf16(Bt[n][k], At[m][k], acc[ai][bj][m][n], 0, 0, 0); __builtin_amdgcn_s_setprio(0); } while (0)
; #define PG8_WAIT_L(n) asm volatile("s_waitcnt lgkmcnt(" #n ")" ::: "memory")
; #define PG8_BAR __builtin_amdgcn_s_barrier()
; #define PG8_SCHED __builtin_amdgcn_sched_barrier(0)
; #define PG8_STAGE(bufoff, gbase, voff) do { _Pragma("unroll") for (int _i = 0; _i < 2; ++_i) \
;         __builtin_amdgcn_global_load_lds((const unsigned*)((const char*)(gbase) + (voff)[_i]), (LAS unsigned*)(lds + (bufoff) + ldsw + _i * 8192), 16, 0, 0); } while (0)
; #define PG8_LDA(dst, b, h) do { _Pragma("unroll") for (int m = 0; m < 4; ++m) _Pragma("unroll") for (int k = 0; k < 2; ++k) dst[m][k] = *(const LAS bf16x8*)(lds + PG8_SA(b, h) + aoff + m * 2048 + k * 1024); } while (0)
; template <class Epi>
; DI void gemm_phase(LAS unsigned char* lds, const Gemm g, const StaticOrder S, const Epi E) {
;     ...
;             PG8_LDB(B0, 0, 0); PG8_SCHED; PG8_LDA(At, 0, 0); PG8_STAGE(PG8_SA(1, 1), a1 + hstep, voffA);
;             PG8_WAIT_L(8); PG8_BAR; PG8_WAIT_L(0); PG8_MMA(0, 0, At, B0); PG8_BAR; PG8_SCHED;
;             PG8_LDB(B1, 0, 1); PG8_STAGE(PG8_SB(0, 0), b2, voffB);
;             PG8_BAR; PG8_WAIT_L(0); PG8_MMA(0, 1, At, B1); PG8_BAR;
;             PG8_LDA(At, 0, 1); PG8_STAGE(PG8_SA(0, 0), a2, voffA);
;             PG8_BAR; PG8_WAIT_L(0); PG8_MMA(1, 0, At, B0); PG8_BAR; PG8_SCHED;
.LBB0_786:
	ds_read_b128 v[128:131], v187
	ds_read_b128 v[132:135], v187 offset:1024
	ds_read_b128 v[136:139], v187 offset:2048
	ds_read_b128 v[140:143], v187 offset:3072
	s_add_u32 s28, s24, 0xfffc0080
	s_addc_u32 s29, s25, -1
	s_cmp_eq_u32 s52, 12
	s_cselect_b32 s39, s6, s29
	s_cselect_b32 s38, s7, s28
	s_cselect_b32 s29, s11, s51
	s_cselect_b32 s28, s13, s50
	v_lshl_add_u64 v[200:201], s[24:25], 0, v[160:161]
	s_add_i32 m0, s19, 0xc000
	ds_read_b128 v[144:147], v188
	ds_read_b128 v[168:171], v188 offset:2048
	ds_read_b128 v[176:179], v188 offset:4096
	ds_read_b128 v[192:195], v188 offset:6144
	global_load_lds_dwordx4 v[200:201], off
	v_lshl_add_u64 v[200:201], s[24:25], 0, v[162:163]
	s_add_i32 m0, s19, 0xe000
	s_nop 0
	global_load_lds_dwordx4 v[200:201], off
	s_waitcnt lgkmcnt(4)
	s_setprio 1
	s_barrier
	ds_read_b128 v[148:151], v188 offset:1024
	ds_read_b128 v[172:175], v188 offset:3072
	ds_read_b128 v[180:183], v188 offset:5120
	ds_read_b128 v[196:199], v188 offset:7168
	s_waitcnt lgkmcnt(4)
	v_mfma_f32_16x16x32_bf16 v[124:127], v[128:131], v[144:147], v[124:127]
	v_mfma_f32_16x16x32_bf16 v[120:123], v[136:139], v[144:147], v[120:123]
	v_mfma_f32_16x16x32_bf16 v[108:111], v[128:131], v[168:171], v[108:111]
	v_mfma_f32_16x16x32_bf16 v[104:107], v[136:139], v[168:171], v[104:107]
	v_mfma_f32_16x16x32_bf16 v[92:95], v[128:131], v[176:179], v[92:95]
	v_mfma_f32_16x16x32_bf16 v[88:91], v[136:139], v[176:179], v[88:91]
	v_mfma_f32_16x16x32_bf16 v[76:79], v[128:131], v[192:195], v[76:79]
	v_mfma_f32_16x16x32_bf16 v[72:75], v[136:139], v[192:195], v[72:75]
	s_waitcnt lgkmcnt(3)
	v_mfma_f32_16x16x32_bf16 v[124:127], v[132:135], v[148:151], v[124:127]
	v_mfma_f32_16x16x32_bf16 v[120:123], v[140:143], v[148:151], v[120:123]
	s_waitcnt lgkmcnt(2)
	v_mfma_f32_16x16x32_bf16 v[108:111], v[132:135], v[172:175], v[108:111]
	v_mfma_f32_16x16x32_bf16 v[104:107], v[140:143], v[172:175], v[104:107]
	s_waitcnt lgkmcnt(1)
	v_mfma_f32_16x16x32_bf16 v[92:95], v[132:135], v[180:183], v[92:95]
	v_mfma_f32_16x16x32_bf16 v[88:91], v[140:143], v[180:183], v[88:91]
	s_waitcnt lgkmcnt(0)
	s_setprio 2
	s_barrier
	v_mfma_f32_16x16x32_bf16 v[76:79], v[132:135], v[196:199], v[76:79]
	v_mfma_f32_16x16x32_bf16 v[72:75], v[140:143], v[196:199], v[72:75]
	s_setprio 0
	s_add_i32 s53, s48, s40
	v_lshl_add_u64 v[216:217], s[28:29], 0, v[154:155]
	s_mov_b32 m0, s53
	ds_read_b128 v[200:203], v189
	ds_read_b128 v[204:207], v189 offset:1024
	ds_read_b128 v[208:211], v189 offset:2048
	ds_read_b128 v[212:215], v189 offset:3072
	global_load_lds_dwordx4 v[216:217], off
	v_lshl_add_u64 v[218:219], s[28:29], 0, v[158:159]
	s_add_i32 m0, s53, 0x2000
	s_nop 0
	global_load_lds_dwordx4 v[218:219], off
	s_setprio 1
	s_barrier
	s_waitcnt lgkmcnt(0)
	v_mfma_f32_16x16x32_bf16 v[116:119], v[200:203], v[144:147], v[116:119]
	v_mfma_f32_16x16x32_bf16 v[112:115], v[208:211], v[144:147], v[112:115]
	v_mfma_f32_16x16x32_bf16 v[100:103], v[200:203], v[168:171], v[100:103]
	v_mfma_f32_16x16x32_bf16 v[96:99], v[208:211], v[168:171], v[96:99]
	v_mfma_f32_16x16x32_bf16 v[84:87], v[200:203], v[176:179], v[84:87]
	v_mfma_f32_16x16x32_bf16 v[80:83], v[208:211], v[176:179], v[80:83]
	v_mfma_f32_16x16x32_bf16 v[68:71], v[200:203], v[192:195], v[68:71]
	v_mfma_f32_16x16x32_bf16 v[64:67], v[208:211], v[192:195], v[64:67]
	v_mfma_f32_16x16x32_bf16 v[116:119], v[204:207], v[148:151], v[116:119]
	v_mfma_f32_16x16x32_bf16 v[112:115], v[212:215], v[148:151], v[112:115]
	v_mfma_f32_16x16x32_bf16 v[100:103], v[204:207], v[172:175], v[100:103]
	v_mfma_f32_16x16x32_bf16 v[96:99], v[212:215], v[172:175], v[96:99]
	v_mfma_f32_16x16x32_bf16 v[84:87], v[204:207], v[180:183], v[84:87]
	v_mfma_f32_16x16x32_bf16 v[80:83], v[212:215], v[180:183], v[80:83]
	s_setprio 2
	s_barrier
	v_mfma_f32_16x16x32_bf16 v[68:71], v[204:207], v[196:199], v[68:71]
	v_mfma_f32_16x16x32_bf16 v[64:67], v[212:215], v[196:199], v[64:67]
	s_setprio 0
	s_mov_b32 m0, s19
	v_lshl_add_u64 v[220:221], s[38:39], 0, v[152:153]
	ds_read_b128 v[144:147], v188 offset:16384
	ds_read_b128 v[168:171], v188 offset:18432
	ds_read_b128 v[176:179], v188 offset:20480
	ds_read_b128 v[192:195], v188 offset:22528
	global_load_lds_dwordx4 v[220:221], off
	v_lshl_add_u64 v[224:225], s[38:39], 0, v[156:157]
	s_mov_b32 m0, s23
	s_nop 0
	global_load_lds_dwordx4 v[224:225], off
	s_setprio 1
	s_barrier
	ds_read_b128 v[148:151], v188 offset:17408
	ds_read_b128 v[172:175], v188 offset:19456
	ds_read_b128 v[180:183], v188 offset:21504
	ds_read_b128 v[196:199], v188 offset:23552
	s_waitcnt lgkmcnt(4)
	v_mfma_f32_16x16x32_bf16 v[60:63], v[128:131], v[144:147], v[60:63]
	v_mfma_f32_16x16x32_bf16 v[56:59], v[136:139], v[144:147], v[56:59]
	v_mfma_f32_16x16x32_bf16 v[44:47], v[128:131], v[168:171], v[44:47]
	v_mfma_f32_16x16x32_bf16 v[40:43], v[136:139], v[168:171], v[40:43]
	v_mfma_f32_16x16x32_bf16 v[28:31], v[128:131], v[176:179], v[28:31]
	v_mfma_f32_16x16x32_bf16 v[24:27], v[136:139], v[176:179], v[24:27]
	v_mfma_f32_16x16x32_bf16 v[12:15], v[128:131], v[192:195], v[12:15]
	v_mfma_f32_16x16x32_bf16 v[8:11], v[136:139], v[192:195], v[8:11]
	s_waitcnt lgkmcnt(3)
	v_mfma_f32_16x16x32_bf16 v[60:63], v[132:135], v[148:151], v[60:63]
	v_mfma_f32_16x16x32_bf16 v[56:59], v[140:143], v[148:151], v[56:59]
	s_waitcnt lgkmcnt(2)
	v_mfma_f32_16x16x32_bf16 v[44:47], v[132:135], v[172:175], v[44:47]
	v_mfma_f32_16x16x32_bf16 v[40:43], v[140:143], v[172:175], v[40:43]
	s_waitcnt lgkmcnt(1)
	v_mfma_f32_16x16x32_bf16 v[28:31], v[132:135], v[180:183], v[28:31]
	v_mfma_f32_16x16x32_bf16 v[24:27], v[140:143], v[180:183], v[24:27]
	s_waitcnt lgkmcnt(0)
	s_setprio 2
	s_barrier
; #define PG8_STAGE(bufoff, gbase, voff) do { _Pragma("unroll") for (int _i = 0; _i < 2; ++_i) \
;         __builtin_amdgcn_global_load_lds((const unsigned*)((const char*)(gbase) + (voff)[_i]), (LAS unsigned*)(lds + (bufoff) + ldsw + _i * 8192), 16, 0, 0); } while (0)
; #define PG8_LDA(dst, b, h) do { _Pragma("unroll") for (int m = 0; m < 4; ++m) _Pragma("unroll") for (int k = 0; k < 2; ++k) dst[m][k] = *(const LAS bf16x8*)(lds + PG8_SA(b, h) + aoff + m * 2048 + k * 1024); } while (0)
; #define PG8_LDB(dst, b, h) do { _Pragma("unroll") for (int n = 0; n < 2; ++n) _Pragma("unroll") for (int k = 0; k < 2; ++k) dst[n][k] = *(const LAS bf16x8*)(lds + PG8_SB(b, h) + boff + n * 2048 + k * 1024); } while (0)
; #define PG8_WAIT_V(n) asm volatile("s_waitcnt vmcnt(" #n ")" ::: "memory")
; #define PG8_WAIT_L(n) asm volatile("s_waitcnt lgkmcnt(" #n ")" ::: "memory")
; #define PG8_BAR __builtin_amdgcn_s_barrier()
; #define PG8_SCHED __builtin_amdgcn_sched_barrier(0)
; #define PG8_BAR __builtin_amdgcn_s_barrier()
; template <class Epi>
; DI void gemm_phase(LAS unsigned char* lds, const Gemm g, const StaticOrder S, const Epi E) {
;     ...
;             PG8_LDB(B0, 0, 0); PG8_SCHED; PG8_LDA(At, 0, 0); PG8_STAGE(PG8_SA(1, 1), a1 + hstep, voffA);
;             PG8_WAIT_L(8); PG8_BAR; PG8_WAIT_L(0); PG8_MMA(0, 0, At, B0); PG8_BAR; PG8_SCHED;
;             PG8_LDB(B1, 0, 1); PG8_STAGE(PG8_SB(0, 0), b2, voffB);
;             PG8_BAR; PG8_WAIT_L(0); PG8_MMA(0, 1, At, B1); PG8_BAR;
;             PG8_LDA(At, 0, 1); PG8_STAGE(PG8_SA(0, 0), a2, voffA);
;             PG8_BAR; PG8_WAIT_L(0); PG8_MMA(1, 0, At, B0); PG8_BAR; PG8_SCHED;
;             PG8_STAGE(PG8_SB(0, 1), b2 + hstep, voffB);
;             PG8_WAIT_V(6); PG8_BAR; PG8_MMA(1, 1, At, B1); PG8_BAR;
;             PG8_LDB(B0, 1, 0); PG8_SCHED; PG8_LDA(At, 1, 0); PG8_STAGE(PG8_SA(0, 1), a2 + hstep, voffA);
;             PG8_WAIT_L(8); PG8_BAR; PG8_WAIT_L(0); PG8_MMA(0, 0, At, B0); PG8_BAR; PG8_SCHED;
;             PG8_LDB(B1, 1, 1); PG8_STAGE(PG8_SB(1, 0), b3, voffB);
;             PG8_BAR; PG8_WAIT_L(0); PG8_MMA(0, 1, At, B1); PG8_BAR;
;             PG8_LDA(At, 1, 1); PG8_STAGE(PG8_SA(1, 0), a3, voffA);
;             PG8_BAR; PG8_WAIT_L(0); PG8_MMA(1, 0, At, B0); PG8_BAR; PG8_SCHED;
;             PG8_STAGE(PG8_SB(1, 1), b3 + hstep, voffB);
;             PG8_WAIT_V(6); PG8_BAR; PG8_MMA(1, 1, At, B1); PG8_BAR;
	v_mfma_f32_16x16x32_bf16 v[12:15], v[132:135], v[196:199], v[12:15]
	v_mfma_f32_16x16x32_bf16 v[8:11], v[140:143], v[196:199], v[8:11]
	s_setprio 0
	s_add_u32 s58, s28, 0x40000
	s_addc_u32 s59, s29, 0
	s_add_i32 s53, s49, s40
	v_lshl_add_u64 v[128:129], s[58:59], 0, v[154:155]
	s_mov_b32 m0, s53
	s_nop 0
	global_load_lds_dwordx4 v[128:129], off
	v_lshl_add_u64 v[128:129], s[58:59], 0, v[158:159]
	s_add_i32 m0, s53, 0x2000
	s_nop 0
	global_load_lds_dwordx4 v[128:129], off
	s_waitcnt vmcnt(6)
	s_setprio 1
	s_barrier
	v_mfma_f32_16x16x32_bf16 v[52:55], v[200:203], v[144:147], v[52:55]
	v_mfma_f32_16x16x32_bf16 v[48:51], v[208:211], v[144:147], v[48:51]
	v_mfma_f32_16x16x32_bf16 v[36:39], v[200:203], v[168:171], v[36:39]
	v_mfma_f32_16x16x32_bf16 v[32:35], v[208:211], v[168:171], v[32:35]
	v_mfma_f32_16x16x32_bf16 v[20:23], v[200:203], v[176:179], v[20:23]
	v_mfma_f32_16x16x32_bf16 v[16:19], v[208:211], v[176:179], v[16:19]
	v_mfma_f32_16x16x32_bf16 v[4:7], v[200:203], v[192:195], v[4:7]
	v_mfma_f32_16x16x32_bf16 v[0:3], v[208:211], v[192:195], v[0:3]
	v_mfma_f32_16x16x32_bf16 v[52:55], v[204:207], v[148:151], v[52:55]
	v_mfma_f32_16x16x32_bf16 v[48:51], v[212:215], v[148:151], v[48:51]
	v_mfma_f32_16x16x32_bf16 v[36:39], v[204:207], v[172:175], v[36:39]
	v_mfma_f32_16x16x32_bf16 v[32:35], v[212:215], v[172:175], v[32:35]
	v_mfma_f32_16x16x32_bf16 v[20:23], v[204:207], v[180:183], v[20:23]
	v_mfma_f32_16x16x32_bf16 v[16:19], v[212:215], v[180:183], v[16:19]
	s_setprio 2
	s_barrier
	v_mfma_f32_16x16x32_bf16 v[4:7], v[204:207], v[196:199], v[4:7]
	v_mfma_f32_16x16x32_bf16 v[0:3], v[212:215], v[196:199], v[0:3]
	s_setprio 0
	s_add_i32 s53, 0, 0x18000
	v_add_u32_e32 v140, s53, v185
	ds_read_b128 v[128:131], v140
	ds_read_b128 v[132:135], v140 offset:1024
	ds_read_b128 v[136:139], v140 offset:2048
	ds_read_b128 v[140:143], v140 offset:3072
	s_add_u32 s38, s38, 0x40000
	s_addc_u32 s39, s39, 0
	s_mov_b32 m0, s41
	v_lshl_add_u64 v[200:201], s[38:39], 0, v[152:153]
	ds_read_b128 v[144:147], v188 offset:32768
	ds_read_b128 v[168:171], v188 offset:34816
	ds_read_b128 v[176:179], v188 offset:36864
	ds_read_b128 v[192:195], v188 offset:38912
	global_load_lds_dwordx4 v[200:201], off
	v_lshl_add_u64 v[200:201], s[38:39], 0, v[156:157]
	s_mov_b32 m0, s42
	s_nop 0
	global_load_lds_dwordx4 v[200:201], off
	s_waitcnt lgkmcnt(4)
	s_setprio 1
	s_barrier
	ds_read_b128 v[148:151], v188 offset:33792
	ds_read_b128 v[172:175], v188 offset:35840
	ds_read_b128 v[180:183], v188 offset:37888
	ds_read_b128 v[196:199], v188 offset:39936
	s_waitcnt lgkmcnt(4)
	v_mfma_f32_16x16x32_bf16 v[124:127], v[128:131], v[144:147], v[124:127]
	v_mfma_f32_16x16x32_bf16 v[120:123], v[136:139], v[144:147], v[120:123]
	v_mfma_f32_16x16x32_bf16 v[108:111], v[128:131], v[168:171], v[108:111]
	v_mfma_f32_16x16x32_bf16 v[104:107], v[136:139], v[168:171], v[104:107]
	v_mfma_f32_16x16x32_bf16 v[92:95], v[128:131], v[176:179], v[92:95]
	v_mfma_f32_16x16x32_bf16 v[88:91], v[136:139], v[176:179], v[88:91]
	v_mfma_f32_16x16x32_bf16 v[76:79], v[128:131], v[192:195], v[76:79]
	v_mfma_f32_16x16x32_bf16 v[72:75], v[136:139], v[192:195], v[72:75]
	s_waitcnt lgkmcnt(3)
	v_mfma_f32_16x16x32_bf16 v[124:127], v[132:135], v[148:151], v[124:127]
	v_mfma_f32_16x16x32_bf16 v[120:123], v[140:143], v[148:151], v[120:123]
	s_waitcnt lgkmcnt(2)
	v_mfma_f32_16x16x32_bf16 v[108:111], v[132:135], v[172:175], v[108:111]
	v_mfma_f32_16x16x32_bf16 v[104:107], v[140:143], v[172:175], v[104:107]
	s_waitcnt lgkmcnt(1)
	v_mfma_f32_16x16x32_bf16 v[92:95], v[132:135], v[180:183], v[92:95]
	v_mfma_f32_16x16x32_bf16 v[88:91], v[140:143], v[180:183], v[88:91]
	s_waitcnt lgkmcnt(0)
	s_setprio 2
	s_barrier
	v_mfma_f32_16x16x32_bf16 v[76:79], v[132:135], v[196:199], v[76:79]
	v_mfma_f32_16x16x32_bf16 v[72:75], v[140:143], v[196:199], v[72:75]
	s_setprio 0
	s_add_i32 s38, 0, 0x1c000
	s_add_i32 s39, s53, s40
	v_add_u32_e32 v191, s38, v185
	v_lshl_add_u64 v[216:217], v[216:217], 0, s[8:9]
	s_mov_b32 m0, s39
	ds_read_b128 v[200:203], v191
	ds_read_b128 v[204:207], v191 offset:1024
	ds_read_b128 v[208:211], v191 offset:2048
	ds_read_b128 v[212:215], v191 offset:3072
	global_load_lds_dwordx4 v[216:217], off
	v_lshl_add_u64 v[216:217], v[218:219], 0, s[8:9]
	s_add_i32 m0, s39, 0x2000
	s_nop 0
	global_load_lds_dwordx4 v[216:217], off
	s_setprio 1
	s_barrier
	s_waitcnt lgkmcnt(0)
	v_mfma_f32_16x16x32_bf16 v[116:119], v[200:203], v[144:147], v[116:119]
	v_mfma_f32_16x16x32_bf16 v[112:115], v[208:211], v[144:147], v[112:115]
	v_mfma_f32_16x16x32_bf16 v[100:103], v[200:203], v[168:171], v[100:103]
	v_mfma_f32_16x16x32_bf16 v[96:99], v[208:211], v[168:171], v[96:99]
	v_mfma_f32_16x16x32_bf16 v[84:87], v[200:203], v[176:179], v[84:87]
	v_mfma_f32_16x16x32_bf16 v[80:83], v[208:211], v[176:179], v[80:83]
	v_mfma_f32_16x16x32_bf16 v[68:71], v[200:203], v[192:195], v[68:71]
	v_mfma_f32_16x16x32_bf16 v[64:67], v[208:211], v[192:195], v[64:67]
	v_mfma_f32_16x16x32_bf16 v[116:119], v[204:207], v[148:151], v[116:119]
	v_mfma_f32_16x16x32_bf16 v[112:115], v[212:215], v[148:151], v[112:115]
	v_mfma_f32_16x16x32_bf16 v[100:103], v[204:207], v[172:175], v[100:103]
	v_mfma_f32_16x16x32_bf16 v[96:99], v[212:215], v[172:175], v[96:99]
	v_mfma_f32_16x16x32_bf16 v[84:87], v[204:207], v[180:183], v[84:87]
	v_mfma_f32_16x16x32_bf16 v[80:83], v[212:215], v[180:183], v[80:83]
	s_setprio 2
	s_barrier
; #define PG8_STAGE(bufoff, gbase, voff) do { _Pragma("unroll") for (int _i = 0; _i < 2; ++_i) \
;         __builtin_amdgcn_global_load_lds((const unsigned*)((const char*)(gbase) + (voff)[_i]), (LAS unsigned*)(lds + (bufoff) + ldsw + _i * 8192), 16, 0, 0); } while (0)
; #define PG8_LDA(dst, b, h) do { _Pragma("unroll") for (int m = 0; m < 4; ++m) _Pragma("unroll") for (int k = 0; k < 2; ++k) dst[m][k] = *(const LAS bf16x8*)(lds + PG8_SA(b, h) + aoff + m * 2048 + k * 1024); } while (0)
; #define PG8_LDB(dst, b, h) do { _Pragma("unroll") for (int n = 0; n < 2; ++n) _Pragma("unroll") for (int k = 0; k < 2; ++k) dst[n][k] = *(const LAS bf16x8*)(lds + PG8_SB(b, h) + boff + n * 2048 + k * 1024); } while (0)
; #define PG8_WAIT_V(n) asm volatile("s_waitcnt vmcnt(" #n ")" ::: "memory")
; #define PG8_WAIT_L(n) asm volatile("s_waitcnt lgkmcnt(" #n ")" ::: "memory")
; #define PG8_BAR __builtin_amdgcn_s_barrier()
; #define PG8_SCHED __builtin_amdgcn_sched_barrier(0)
; #define PG8_BAR __builtin_amdgcn_s_barrier()
; template <class Epi>
; DI void gemm_phase(LAS unsigned char* lds, const Gemm g, const StaticOrder S, const Epi E) {
;     ...
;             PG8_LDB(B0, 0, 0); PG8_SCHED; PG8_LDA(At, 0, 0); PG8_STAGE(PG8_SA(1, 1), a1 + hstep, voffA);
;             PG8_WAIT_L(8); PG8_BAR; PG8_WAIT_L(0); PG8_MMA(0, 0, At, B0); PG8_BAR; PG8_SCHED;
;             PG8_LDB(B1, 0, 1); PG8_STAGE(PG8_SB(0, 0), b2, voffB);
;             PG8_BAR; PG8_WAIT_L(0); PG8_MMA(0, 1, At, B1); PG8_BAR;
;             PG8_LDA(At, 0, 1); PG8_STAGE(PG8_SA(0, 0), a2, voffA);
;             PG8_BAR; PG8_WAIT_L(0); PG8_MMA(1, 0, At, B0); PG8_BAR; PG8_SCHED;
;             PG8_STAGE(PG8_SB(0, 1), b2 + hstep, voffB);
;             PG8_WAIT_V(6); PG8_BAR; PG8_MMA(1, 1, At, B1); PG8_BAR;
;             PG8_LDB(B0, 1, 0); PG8_SCHED; PG8_LDA(At, 1, 0); PG8_STAGE(PG8_SA(0, 1), a2 + hstep, voffA);
;             PG8_WAIT_L(8); PG8_BAR; PG8_WAIT_L(0); PG8_MMA(0, 0, At, B0); PG8_BAR; PG8_SCHED;
;             PG8_LDB(B1, 1, 1); PG8_STAGE(PG8_SB(1, 0), b3, voffB);
;             PG8_BAR; PG8_WAIT_L(0); PG8_MMA(0, 1, At, B1); PG8_BAR;
;             PG8_LDA(At, 1, 1); PG8_STAGE(PG8_SA(1, 0), a3, voffA);
;             PG8_BAR; PG8_WAIT_L(0); PG8_MMA(1, 0, At, B0); PG8_BAR; PG8_SCHED;
;             PG8_STAGE(PG8_SB(1, 1), b3 + hstep, voffB);
;             PG8_WAIT_V(6); PG8_BAR; PG8_MMA(1, 1, At, B1); PG8_BAR;
	v_mfma_f32_16x16x32_bf16 v[68:71], v[204:207], v[196:199], v[68:71]
	v_mfma_f32_16x16x32_bf16 v[64:67], v[212:215], v[196:199], v[64:67]
	s_setprio 0
	s_mov_b32 m0, s44
	v_lshl_add_u64 v[216:217], v[220:221], 0, s[8:9]
	ds_read_b128 v[144:147], v188 offset:49152
	ds_read_b128 v[168:171], v188 offset:51200
	ds_read_b128 v[176:179], v188 offset:53248
	ds_read_b128 v[192:195], v188 offset:55296
	global_load_lds_dwordx4 v[216:217], off
	v_lshl_add_u64 v[216:217], v[224:225], 0, s[8:9]
	s_mov_b32 m0, s45
	s_nop 0
	global_load_lds_dwordx4 v[216:217], off
	s_setprio 1
	s_barrier
	ds_read_b128 v[148:151], v188 offset:50176
	ds_read_b128 v[172:175], v188 offset:52224
	ds_read_b128 v[180:183], v188 offset:54272
	ds_read_b128 v[196:199], v188 offset:56320
	s_waitcnt lgkmcnt(4)
	v_mfma_f32_16x16x32_bf16 v[60:63], v[128:131], v[144:147], v[60:63]
	v_mfma_f32_16x16x32_bf16 v[56:59], v[136:139], v[144:147], v[56:59]
	v_mfma_f32_16x16x32_bf16 v[44:47], v[128:131], v[168:171], v[44:47]
	v_mfma_f32_16x16x32_bf16 v[40:43], v[136:139], v[168:171], v[40:43]
	v_mfma_f32_16x16x32_bf16 v[28:31], v[128:131], v[176:179], v[28:31]
	v_mfma_f32_16x16x32_bf16 v[24:27], v[136:139], v[176:179], v[24:27]
	v_mfma_f32_16x16x32_bf16 v[12:15], v[128:131], v[192:195], v[12:15]
	v_mfma_f32_16x16x32_bf16 v[8:11], v[136:139], v[192:195], v[8:11]
	s_waitcnt lgkmcnt(3)
	v_mfma_f32_16x16x32_bf16 v[60:63], v[132:135], v[148:151], v[60:63]
	v_mfma_f32_16x16x32_bf16 v[56:59], v[140:143], v[148:151], v[56:59]
	s_waitcnt lgkmcnt(2)
	v_mfma_f32_16x16x32_bf16 v[44:47], v[132:135], v[172:175], v[44:47]
	v_mfma_f32_16x16x32_bf16 v[40:43], v[140:143], v[172:175], v[40:43]
	s_waitcnt lgkmcnt(1)
	v_mfma_f32_16x16x32_bf16 v[28:31], v[132:135], v[180:183], v[28:31]
	v_mfma_f32_16x16x32_bf16 v[24:27], v[140:143], v[180:183], v[24:27]
	s_waitcnt lgkmcnt(0)
	s_setprio 2
	s_barrier
	v_mfma_f32_16x16x32_bf16 v[12:15], v[132:135], v[196:199], v[12:15]
	v_mfma_f32_16x16x32_bf16 v[8:11], v[140:143], v[196:199], v[8:11]
	s_setprio 0
	s_add_u32 s28, s28, 0x40080
	s_addc_u32 s29, s29, 0
	s_add_i32 s38, s38, s40
	v_lshl_add_u64 v[128:129], s[28:29], 0, v[154:155]
	s_mov_b32 m0, s38
	s_nop 0
	global_load_lds_dwordx4 v[128:129], off
	v_lshl_add_u64 v[128:129], s[28:29], 0, v[158:159]
	s_add_i32 m0, s38, 0x2000
	s_nop 0
	global_load_lds_dwordx4 v[128:129], off
	s_waitcnt vmcnt(6)
	s_setprio 1
	s_barrier
	v_mfma_f32_16x16x32_bf16 v[52:55], v[200:203], v[144:147], v[52:55]
	v_mfma_f32_16x16x32_bf16 v[48:51], v[208:211], v[144:147], v[48:51]
	v_mfma_f32_16x16x32_bf16 v[36:39], v[200:203], v[168:171], v[36:39]
	v_mfma_f32_16x16x32_bf16 v[32:35], v[208:211], v[168:171], v[32:35]
	v_mfma_f32_16x16x32_bf16 v[20:23], v[200:203], v[176:179], v[20:23]
	v_mfma_f32_16x16x32_bf16 v[16:19], v[208:211], v[176:179], v[16:19]
	v_mfma_f32_16x16x32_bf16 v[4:7], v[200:203], v[192:195], v[4:7]
	v_mfma_f32_16x16x32_bf16 v[0:3], v[208:211], v[192:195], v[0:3]
	v_mfma_f32_16x16x32_bf16 v[52:55], v[204:207], v[148:151], v[52:55]
	v_mfma_f32_16x16x32_bf16 v[48:51], v[212:215], v[148:151], v[48:51]
	v_mfma_f32_16x16x32_bf16 v[36:39], v[204:207], v[172:175], v[36:39]
	v_mfma_f32_16x16x32_bf16 v[32:35], v[212:215], v[172:175], v[32:35]
	v_mfma_f32_16x16x32_bf16 v[20:23], v[204:207], v[180:183], v[20:23]
	v_mfma_f32_16x16x32_bf16 v[16:19], v[212:215], v[180:183], v[16:19]
	s_setprio 2
	s_barrier
	v_mfma_f32_16x16x32_bf16 v[4:7], v[204:207], v[196:199], v[4:7]
	v_mfma_f32_16x16x32_bf16 v[0:3], v[212:215], v[196:199], v[0:3]
	s_setprio 0
	s_add_i32 s52, s52, 2
	s_add_u32 s24, s24, 0x100
	s_addc_u32 s25, s25, 0
	s_add_u32 s50, s50, 0x100
	s_addc_u32 s51, s51, 0
	s_cmp_gt_u32 s52, 13
	s_cbranch_scc0 .LBB0_786
; DI unsigned pk_bf16(float lo, float hi) { f32x2 v = {lo, hi}; return __builtin_bit_cast(unsigned, __builtin_convertvector(v, bf16v2)); }
; DI f32x4 bf_lo4(u32x4 w) { f32x4 r; r[0] = bf_lo(w.x); r[1] = bf_hi(w.x); r[2] = bf_lo(w.y); r[3] = bf_hi(w.y); return r; }
; DI f32x4 bf_hi4(u32x4 w) { f32x4 r; r[0] = bf_lo(w.z); r[1] = bf_hi(w.z); r[2] = bf_lo(w.w); r[3] = bf_hi(w.w); return r; }
;     DI void operator()(AccRef acc, const Unit& u, int wr, int wc, int fr, int fq) const {
;         const float scale = HALFSTEP ? 0.5f : 1.0f;
;         const int row0 = u.pm * 256 + wr * 64 + fr, col0 = u.pn * 256 + wc * 32 + 8 * fq;
; #pragma unroll
;         for (int ai = 0; ai < 2; ++ai) {
;             f32x4 bv[4][2][2];
; #pragma unroll
;             for (int m = 0; m < 4; ++m)
; #pragma unroll
;                 for (int bj = 0; bj < 2; ++bj) {
;                     const size_t o = (size_t)(row0 + ai * 128 + m * 16) * DM + col0 + bj * 128;
;                     if (BASEF32) { bv[m][bj][0] = *(const f32x4*)(basef + o); bv[m][bj][1] = *(const f32x4*)(basef + o + 4); }
;                     else { const u32x4 h = *(const u32x4*)(xnb + o); bv[m][bj][0] = bf_lo4(h); bv[m][bj][1] = bf_hi4(h); }
;                 }
; #pragma unroll
;             for (int m = 0; m < 4; ++m) {
;                 const int row = row0 + ai * 128 + m * 16;
;                 float q = 0.f;
; #pragma unroll
;                 for (int bj = 0; bj < 2; ++bj) {
;                     const size_t o = (size_t)row * DM + col0 + bj * 128;
;                     const f32x4 r0 = bv[m][bj][0] + scale * acc[ai][bj][m][0], r1 = bv[m][bj][1] + scale * acc[ai][bj][m][1];
;                     u32x4 w; w.x = pk_bf16(r0[0], r0[1]); w.y = pk_bf16(r0[2], r0[3]); w.z = pk_bf16(r1[0], r1[1]); w.w = pk_bf16(r1[2], r1[3]);
;                     *(u32x4*)(xnb + o) = w;
;                     if (STATS) q += r0[0] * r0[0] + r0[1] * r0[1] + r0[2] * r0[2] + r0[3] * r0[3] + r1[0] * r1[0] + r1[1] * r1[1] + r1[2] * r1[2] + r1[3] * r1[3];
;                 }
;                 if (STATS) { q += __shfl_xor(q, 16); q += __shfl_xor(q, 32); if (fq == 0) atomicAdd(ss + row, q); }
;             }
	v_lshl_add_u32 v170, s18, 8, v184
	v_lshl_or_b32 v128, s22, 8, v186
	v_ashrrev_i32_e32 v129, 31, v128
	v_ashrrev_i32_e32 v171, 31, v170
	v_lshl_add_u64 v[168:169], v[128:129], 1, s[56:57]
	v_lshlrev_b64 v[128:129], 11, v[170:171]
	v_lshl_add_u64 v[202:203], v[168:169], 0, v[128:129]
	global_load_dwordx4 v[194:197], v[202:203], off
	global_load_dwordx4 v[198:201], v[202:203], off offset:256
	v_or_b32_e32 v180, 16, v170
	v_or_b32_e32 v176, 32, v170
	v_or_b32_e32 v172, 48, v170
	v_ashrrev_i32_e32 v181, 31, v180
	v_ashrrev_i32_e32 v177, 31, v176
	v_ashrrev_i32_e32 v173, 31, v172
	v_lshlrev_b64 v[128:129], 11, v[180:181]
	v_lshlrev_b64 v[130:131], 11, v[176:177]
	v_lshlrev_b64 v[132:133], 11, v[172:173]
	v_lshl_add_u64 v[182:183], v[168:169], 0, v[128:129]
	v_lshl_add_u64 v[178:179], v[168:169], 0, v[130:131]
	v_lshl_add_u64 v[174:175], v[168:169], 0, v[132:133]
	global_load_dwordx4 v[148:151], v[182:183], off
	global_load_dwordx4 v[144:147], v[182:183], off offset:256
	global_load_dwordx4 v[140:143], v[178:179], off
	global_load_dwordx4 v[136:139], v[178:179], off offset:256
	global_load_dwordx4 v[132:135], v[174:175], off
	global_load_dwordx4 v[128:131], v[174:175], off offset:256
	v_and_b32_e32 v192, 64, v190
	v_xor_b32_e32 v191, 16, v190
	v_add_u32_e32 v192, 64, v192
	v_cmp_lt_i32_e32 vcc, v191, v192
	v_xor_b32_e32 v193, 32, v190
	s_waitcnt vmcnt(0)
	v_lshlrev_b32_e32 v204, 16, v194
	v_and_b32_e32 v205, 0xffff0000, v194
	v_lshlrev_b32_e32 v208, 16, v198
	v_and_b32_e32 v209, 0xffff0000, v198
	v_lshlrev_b32_e32 v194, 16, v195
	v_and_b32_e32 v195, 0xffff0000, v195
	v_lshlrev_b32_e32 v210, 16, v200
	v_and_b32_e32 v211, 0xffff0000, v200
	v_lshlrev_b32_e32 v200, 16, v201
	v_and_b32_e32 v201, 0xffff0000, v201
	v_pk_add_f32 v[124:125], v[124:125], v[204:205]
	v_pk_add_f32 v[116:117], v[116:117], v[208:209]
	v_lshlrev_b32_e32 v198, 16, v199
	v_and_b32_e32 v199, 0xffff0000, v199
	v_pk_add_f32 v[126:127], v[126:127], v[194:195]
	v_pk_add_f32 v[194:195], v[114:115], v[200:201]
	v_mul_f32_e32 v114, v125, v125
	v_mul_f32_e32 v115, v117, v117
	v_pk_add_f32 v[118:119], v[118:119], v[198:199]
	v_fmac_f32_e32 v114, v124, v124
	v_fmac_f32_e32 v115, v116, v116
	v_lshlrev_b32_e32 v206, 16, v196
	v_and_b32_e32 v207, 0xffff0000, v196
	v_lshlrev_b32_e32 v196, 16, v197
	v_and_b32_e32 v197, 0xffff0000, v197
	v_fmac_f32_e32 v114, v126, v126
	v_fmac_f32_e32 v115, v118, v118
	v_pk_add_f32 v[122:123], v[122:123], v[196:197]
	v_pk_add_f32 v[120:121], v[120:121], v[206:207]
	v_pk_add_f32 v[196:197], v[112:113], v[210:211]
	v_fmac_f32_e32 v114, v127, v127
	v_fmac_f32_e32 v115, v119, v119
	v_fmac_f32_e32 v114, v120, v120
	v_fmac_f32_e32 v115, v196, v196
	v_fmac_f32_e32 v114, v121, v121
	v_fmac_f32_e32 v115, v197, v197
	v_fmac_f32_e32 v114, v122, v122
	v_fmac_f32_e32 v115, v194, v194
	v_cndmask_b32_e32 v191, v190, v191, vcc
	v_fmac_f32_e32 v114, v123, v123
	v_fmac_f32_e32 v115, v195, v195
	v_cmp_lt_i32_e32 vcc, v193, v192
	v_lshlrev_b32_e32 v192, 2, v191
	v_cvt_pk_bf16_f32 v112, v124, v125
	v_add_f32_e32 v124, v114, v115
	ds_bpermute_b32 v125, v192, v124
	v_cndmask_b32_e32 v193, v190, v193, vcc
	v_cvt_pk_bf16_f32 v113, v126, v127
	v_cvt_pk_bf16_f32 v114, v120, v121
	v_cvt_pk_bf16_f32 v115, v122, v123
	v_lshlrev_b32_e32 v191, 2, v193
	global_store_dwordx4 v[202:203], v[112:115], off
	s_waitcnt lgkmcnt(0)
	s_nop 0
	v_add_f32_e32 v112, v124, v125
	ds_bpermute_b32 v113, v191, v112
	v_cvt_pk_bf16_f32 v114, v116, v117
	v_cvt_pk_bf16_f32 v115, v118, v119
	v_cvt_pk_bf16_f32 v116, v196, v197
	v_cvt_pk_bf16_f32 v117, v194, v195
	global_store_dwordx4 v[202:203], v[114:117], off offset:256
	s_and_saveexec_b64 s[6:7], s[0:1]
	s_cbranch_execz .LBB0_789
	s_waitcnt lgkmcnt(0)
	v_add_f32_e32 v114, v112, v113
	v_lshl_add_u64 v[112:113], v[170:171], 2, s[20:21]
	global_atomic_add_f32 v[112:113], v114, off

; #define PG8_STAGE(bufoff, gbase, voff) do { _Pragma("unroll") for (int _i = 0; _i < 2; ++_i) \
;         __builtin_amdgcn_global_load_lds((const unsigned*)((const char*)(gbase) + (voff)[_i]), (LAS unsigned*)(lds + (bufoff) + ldsw + _i * 8192), 16, 0, 0); } while (0)
; #define PG8_LDA(dst, b, h) do { _Pragma("unroll") for (int m = 0; m < 4; ++m) _Pragma("unroll") for (int k = 0; k < 2; ++k) dst[m][k] = *(const LAS bf16x8*)(lds + PG8_SA(b, h) + aoff + m * 2048 + k * 1024); } while (0)
; #define PG8_LDB(dst, b, h) do { _Pragma("unroll") for (int n = 0; n < 2; ++n) _Pragma("unroll") for (int k = 0; k < 2; ++k) dst[n][k] = *(const LAS bf16x8*)(lds + PG8_SB(b, h) + boff + n * 2048 + k * 1024); } while (0)
; #define PG8_WAIT_V(n) asm volatile("s_waitcnt vmcnt(" #n ")" ::: "memory")
; #define PG8_WAIT_L(n) asm volatile("s_waitcnt lgkmcnt(" #n ")" ::: "memory")
; #define PG8_BAR __builtin_amdgcn_s_barrier()
; #define PG8_SCHED __builtin_amdgcn_sched_barrier(0)
; #define PG8_BAR __builtin_amdgcn_s_barrier()
; template <class Epi>
; DI void gemm_phase(LAS unsigned char* lds, const Gemm g, const StaticOrder S, const Epi E) {
;     ...
;             PG8_LDB(B0, 0, 0); PG8_SCHED; PG8_LDA(At, 0, 0); PG8_STAGE(PG8_SA(1, 1), a1 + hstep, voffA);
;             PG8_WAIT_L(8); PG8_BAR; PG8_WAIT_L(0); PG8_MMA(0, 0, At, B0); PG8_BAR; PG8_SCHED;
;             PG8_LDB(B1, 0, 1); PG8_STAGE(PG8_SB(0, 0), b2, voffB);
;             PG8_BAR; PG8_WAIT_L(0); PG8_MMA(0, 1, At, B1); PG8_BAR;
;             PG8_LDA(At, 0, 1); PG8_STAGE(PG8_SA(0, 0), a2, voffA);
;             PG8_BAR; PG8_WAIT_L(0); PG8_MMA(1, 0, At, B0); PG8_BAR; PG8_SCHED;
;             PG8_STAGE(PG8_SB(0, 1), b2 + hstep, voffB);
;             PG8_WAIT_V(6); PG8_BAR; PG8_MMA(1, 1, At, B1); PG8_BAR;
;             PG8_LDB(B0, 1, 0); PG8_SCHED; PG8_LDA(At, 1, 0); PG8_STAGE(PG8_SA(0, 1), a2 + hstep, voffA);
;             PG8_WAIT_L(8); PG8_BAR; PG8_WAIT_L(0); PG8_MMA(0, 0, At, B0); PG8_BAR; PG8_SCHED;
;             PG8_LDB(B1, 1, 1); PG8_STAGE(PG8_SB(1, 0), b3, voffB);
;             PG8_BAR; PG8_WAIT_L(0); PG8_MMA(0, 1, At, B1); PG8_BAR;
;             PG8_LDA(At, 1, 1); PG8_STAGE(PG8_SA(1, 0), a3, voffA);
;             PG8_BAR; PG8_WAIT_L(0); PG8_MMA(1, 0, At, B0); PG8_BAR; PG8_SCHED;
;             PG8_STAGE(PG8_SB(1, 1), b3 + hstep, voffB);
;             PG8_WAIT_V(6); PG8_BAR; PG8_MMA(1, 1, At, B1); PG8_BAR;
.LBB0_865:
	ds_read_b128 v[144:147], v155
	ds_read_b128 v[160:163], v155 offset:1024
	ds_read_b128 v[164:167], v155 offset:2048
	ds_read_b128 v[168:171], v155 offset:3072
	s_add_u32 s10, s8, 0xfffc0080
	s_addc_u32 s11, s9, -1
	s_cmp_eq_u32 s25, 12
	s_cselect_b32 s13, s14, s11
	s_cselect_b32 s12, s15, s10
	s_cselect_b32 s11, s16, s19
	s_cselect_b32 s10, s17, s18
	v_lshl_add_u64 v[204:205], s[8:9], 0, v[136:137]
	s_add_i32 m0, s40, 0xc000
	ds_read_b128 v[172:175], v157
	ds_read_b128 v[180:183], v157 offset:2048
	ds_read_b128 v[188:191], v157 offset:4096
	ds_read_b128 v[196:199], v157 offset:6144
	global_load_lds_dwordx4 v[204:205], off
	v_lshl_add_u64 v[204:205], s[8:9], 0, v[138:139]
	s_add_i32 m0, s40, 0xe000
	s_nop 0
	global_load_lds_dwordx4 v[204:205], off
	s_waitcnt lgkmcnt(4)
	s_setprio 1
	s_barrier
	ds_read_b128 v[176:179], v157 offset:1024
	ds_read_b128 v[184:187], v157 offset:3072
	ds_read_b128 v[192:195], v157 offset:5120
	ds_read_b128 v[200:203], v157 offset:7168
	s_waitcnt lgkmcnt(4)
	v_mfma_f32_16x16x32_bf16 v[124:127], v[144:147], v[172:175], v[124:127]
	v_mfma_f32_16x16x32_bf16 v[120:123], v[164:167], v[172:175], v[120:123]
	v_mfma_f32_16x16x32_bf16 v[108:111], v[144:147], v[180:183], v[108:111]
	v_mfma_f32_16x16x32_bf16 v[104:107], v[164:167], v[180:183], v[104:107]
	v_mfma_f32_16x16x32_bf16 v[92:95], v[144:147], v[188:191], v[92:95]
	v_mfma_f32_16x16x32_bf16 v[88:91], v[164:167], v[188:191], v[88:91]
	v_mfma_f32_16x16x32_bf16 v[76:79], v[144:147], v[196:199], v[76:79]
	v_mfma_f32_16x16x32_bf16 v[72:75], v[164:167], v[196:199], v[72:75]
	s_waitcnt lgkmcnt(3)
	v_mfma_f32_16x16x32_bf16 v[124:127], v[160:163], v[176:179], v[124:127]
	v_mfma_f32_16x16x32_bf16 v[120:123], v[168:171], v[176:179], v[120:123]
	s_waitcnt lgkmcnt(2)
	v_mfma_f32_16x16x32_bf16 v[108:111], v[160:163], v[184:187], v[108:111]
	v_mfma_f32_16x16x32_bf16 v[104:107], v[168:171], v[184:187], v[104:107]
	s_waitcnt lgkmcnt(1)
	v_mfma_f32_16x16x32_bf16 v[92:95], v[160:163], v[192:195], v[92:95]
	v_mfma_f32_16x16x32_bf16 v[88:91], v[168:171], v[192:195], v[88:91]
	s_waitcnt lgkmcnt(0)
	s_setprio 2
	s_barrier
	v_mfma_f32_16x16x32_bf16 v[76:79], v[160:163], v[200:203], v[76:79]
	v_mfma_f32_16x16x32_bf16 v[72:75], v[168:171], v[200:203], v[72:75]
	s_setprio 0
	s_add_i32 s29, s49, s34
	v_lshl_add_u64 v[220:221], s[10:11], 0, v[132:133]
	s_mov_b32 m0, s29
	ds_read_b128 v[204:207], v158
	ds_read_b128 v[208:211], v158 offset:1024
	ds_read_b128 v[212:215], v158 offset:2048
	ds_read_b128 v[216:219], v158 offset:3072
	global_load_lds_dwordx4 v[220:221], off
	v_lshl_add_u64 v[224:225], s[10:11], 0, v[128:129]
	s_add_i32 m0, s29, 0x2000
	s_nop 0
	global_load_lds_dwordx4 v[224:225], off
	s_setprio 1
	s_barrier
	s_waitcnt lgkmcnt(0)
	v_mfma_f32_16x16x32_bf16 v[116:119], v[204:207], v[172:175], v[116:119]
	v_mfma_f32_16x16x32_bf16 v[112:115], v[212:215], v[172:175], v[112:115]
	v_mfma_f32_16x16x32_bf16 v[100:103], v[204:207], v[180:183], v[100:103]
	v_mfma_f32_16x16x32_bf16 v[96:99], v[212:215], v[180:183], v[96:99]
	v_mfma_f32_16x16x32_bf16 v[84:87], v[204:207], v[188:191], v[84:87]
	v_mfma_f32_16x16x32_bf16 v[80:83], v[212:215], v[188:191], v[80:83]
	v_mfma_f32_16x16x32_bf16 v[68:71], v[204:207], v[196:199], v[68:71]
	v_mfma_f32_16x16x32_bf16 v[64:67], v[212:215], v[196:199], v[64:67]
	v_mfma_f32_16x16x32_bf16 v[116:119], v[208:211], v[176:179], v[116:119]
	v_mfma_f32_16x16x32_bf16 v[112:115], v[216:219], v[176:179], v[112:115]
	v_mfma_f32_16x16x32_bf16 v[100:103], v[208:211], v[184:187], v[100:103]
	v_mfma_f32_16x16x32_bf16 v[96:99], v[216:219], v[184:187], v[96:99]
	v_mfma_f32_16x16x32_bf16 v[84:87], v[208:211], v[192:195], v[84:87]
	v_mfma_f32_16x16x32_bf16 v[80:83], v[216:219], v[192:195], v[80:83]
	s_setprio 2
	s_barrier
	v_mfma_f32_16x16x32_bf16 v[68:71], v[208:211], v[200:203], v[68:71]
	v_mfma_f32_16x16x32_bf16 v[64:67], v[216:219], v[200:203], v[64:67]
	s_setprio 0
	s_mov_b32 m0, s40
	v_lshl_add_u64 v[226:227], s[12:13], 0, v[134:135]
	ds_read_b128 v[172:175], v157 offset:16384
	ds_read_b128 v[180:183], v157 offset:18432
	ds_read_b128 v[188:191], v157 offset:20480
	ds_read_b128 v[196:199], v157 offset:22528
	global_load_lds_dwordx4 v[226:227], off
	v_lshl_add_u64 v[228:229], s[12:13], 0, v[130:131]
	s_mov_b32 m0, s41
	s_nop 0
	global_load_lds_dwordx4 v[228:229], off
	s_setprio 1
	s_barrier
	ds_read_b128 v[176:179], v157 offset:17408
	ds_read_b128 v[184:187], v157 offset:19456
	ds_read_b128 v[192:195], v157 offset:21504
	ds_read_b128 v[200:203], v157 offset:23552
	s_waitcnt lgkmcnt(4)
	v_mfma_f32_16x16x32_bf16 v[60:63], v[144:147], v[172:175], v[60:63]
	v_mfma_f32_16x16x32_bf16 v[56:59], v[164:167], v[172:175], v[56:59]
	v_mfma_f32_16x16x32_bf16 v[44:47], v[144:147], v[180:183], v[44:47]
	v_mfma_f32_16x16x32_bf16 v[40:43], v[164:167], v[180:183], v[40:43]
	v_mfma_f32_16x16x32_bf16 v[28:31], v[144:147], v[188:191], v[28:31]
	v_mfma_f32_16x16x32_bf16 v[24:27], v[164:167], v[188:191], v[24:27]
	v_mfma_f32_16x16x32_bf16 v[12:15], v[144:147], v[196:199], v[12:15]
	v_mfma_f32_16x16x32_bf16 v[8:11], v[164:167], v[196:199], v[8:11]
	s_waitcnt lgkmcnt(3)
	v_mfma_f32_16x16x32_bf16 v[60:63], v[160:163], v[176:179], v[60:63]
	v_mfma_f32_16x16x32_bf16 v[56:59], v[168:171], v[176:179], v[56:59]
	s_waitcnt lgkmcnt(2)
	v_mfma_f32_16x16x32_bf16 v[44:47], v[160:163], v[184:187], v[44:47]
	v_mfma_f32_16x16x32_bf16 v[40:43], v[168:171], v[184:187], v[40:43]
	s_waitcnt lgkmcnt(1)
	v_mfma_f32_16x16x32_bf16 v[28:31], v[160:163], v[192:195], v[28:31]
	v_mfma_f32_16x16x32_bf16 v[24:27], v[168:171], v[192:195], v[24:27]
	s_waitcnt lgkmcnt(0)
	s_setprio 2
	s_barrier
; #define PG8_STAGE(bufoff, gbase, voff) do { _Pragma("unroll") for (int _i = 0; _i < 2; ++_i) \
;         __builtin_amdgcn_global_load_lds((const unsigned*)((const char*)(gbase) + (voff)[_i]), (LAS unsigned*)(lds + (bufoff) + ldsw + _i * 8192), 16, 0, 0); } while (0)
; #define PG8_LDA(dst, b, h) do { _Pragma("unroll") for (int m = 0; m < 4; ++m) _Pragma("unroll") for (int k = 0; k < 2; ++k) dst[m][k] = *(const LAS bf16x8*)(lds + PG8_SA(b, h) + aoff + m * 2048 + k * 1024); } while (0)
; #define PG8_LDB(dst, b, h) do { _Pragma("unroll") for (int n = 0; n < 2; ++n) _Pragma("unroll") for (int k = 0; k < 2; ++k) dst[n][k] = *(const LAS bf16x8*)(lds + PG8_SB(b, h) + boff + n * 2048 + k * 1024); } while (0)
; #define PG8_WAIT_V(n) asm volatile("s_waitcnt vmcnt(" #n ")" ::: "memory")
; #define PG8_WAIT_L(n) asm volatile("s_waitcnt lgkmcnt(" #n ")" ::: "memory")
; #define PG8_BAR __builtin_amdgcn_s_barrier()
; #define PG8_SCHED __builtin_amdgcn_sched_barrier(0)
; #define PG8_BAR __builtin_amdgcn_s_barrier()
; template <class Epi>
; DI void gemm_phase(LAS unsigned char* lds, const Gemm g, const StaticOrder S, const Epi E) {
;     ...
;             PG8_LDB(B0, 0, 0); PG8_SCHED; PG8_LDA(At, 0, 0); PG8_STAGE(PG8_SA(1, 1), a1 + hstep, voffA);
;             PG8_WAIT_L(8); PG8_BAR; PG8_WAIT_L(0); PG8_MMA(0, 0, At, B0); PG8_BAR; PG8_SCHED;
;             PG8_LDB(B1, 0, 1); PG8_STAGE(PG8_SB(0, 0), b2, voffB);
;             PG8_BAR; PG8_WAIT_L(0); PG8_MMA(0, 1, At, B1); PG8_BAR;
;             PG8_LDA(At, 0, 1); PG8_STAGE(PG8_SA(0, 0), a2, voffA);
;             PG8_BAR; PG8_WAIT_L(0); PG8_MMA(1, 0, At, B0); PG8_BAR; PG8_SCHED;
;             PG8_STAGE(PG8_SB(0, 1), b2 + hstep, voffB);
;             PG8_WAIT_V(6); PG8_BAR; PG8_MMA(1, 1, At, B1); PG8_BAR;
;             PG8_LDB(B0, 1, 0); PG8_SCHED; PG8_LDA(At, 1, 0); PG8_STAGE(PG8_SA(0, 1), a2 + hstep, voffA);
;             PG8_WAIT_L(8); PG8_BAR; PG8_WAIT_L(0); PG8_MMA(0, 0, At, B0); PG8_BAR; PG8_SCHED;
;             PG8_LDB(B1, 1, 1); PG8_STAGE(PG8_SB(1, 0), b3, voffB);
;             PG8_BAR; PG8_WAIT_L(0); PG8_MMA(0, 1, At, B1); PG8_BAR;
;             PG8_LDA(At, 1, 1); PG8_STAGE(PG8_SA(1, 0), a3, voffA);
;             PG8_BAR; PG8_WAIT_L(0); PG8_MMA(1, 0, At, B0); PG8_BAR; PG8_SCHED;
;             PG8_STAGE(PG8_SB(1, 1), b3 + hstep, voffB);
;             PG8_WAIT_V(6); PG8_BAR; PG8_MMA(1, 1, At, B1); PG8_BAR;
	v_mfma_f32_16x16x32_bf16 v[12:15], v[160:163], v[200:203], v[12:15]
	v_mfma_f32_16x16x32_bf16 v[8:11], v[168:171], v[200:203], v[8:11]
	s_setprio 0
	s_add_u32 s58, s10, 0x40000
	s_addc_u32 s59, s11, 0
	s_add_i32 s29, s50, s34
	v_lshl_add_u64 v[144:145], s[58:59], 0, v[132:133]
	s_mov_b32 m0, s29
	s_nop 0
	global_load_lds_dwordx4 v[144:145], off
	v_lshl_add_u64 v[144:145], s[58:59], 0, v[128:129]
	s_add_i32 m0, s29, 0x2000
	s_nop 0
	global_load_lds_dwordx4 v[144:145], off
	s_waitcnt vmcnt(6)
	s_setprio 1
	s_barrier
	v_mfma_f32_16x16x32_bf16 v[52:55], v[204:207], v[172:175], v[52:55]
	v_mfma_f32_16x16x32_bf16 v[48:51], v[212:215], v[172:175], v[48:51]
	v_mfma_f32_16x16x32_bf16 v[36:39], v[204:207], v[180:183], v[36:39]
	v_mfma_f32_16x16x32_bf16 v[32:35], v[212:215], v[180:183], v[32:35]
	v_mfma_f32_16x16x32_bf16 v[20:23], v[204:207], v[188:191], v[20:23]
	v_mfma_f32_16x16x32_bf16 v[16:19], v[212:215], v[188:191], v[16:19]
	v_mfma_f32_16x16x32_bf16 v[4:7], v[204:207], v[196:199], v[4:7]
	v_mfma_f32_16x16x32_bf16 v[0:3], v[212:215], v[196:199], v[0:3]
	v_mfma_f32_16x16x32_bf16 v[52:55], v[208:211], v[176:179], v[52:55]
	v_mfma_f32_16x16x32_bf16 v[48:51], v[216:219], v[176:179], v[48:51]
	v_mfma_f32_16x16x32_bf16 v[36:39], v[208:211], v[184:187], v[36:39]
	v_mfma_f32_16x16x32_bf16 v[32:35], v[216:219], v[184:187], v[32:35]
	v_mfma_f32_16x16x32_bf16 v[20:23], v[208:211], v[192:195], v[20:23]
	v_mfma_f32_16x16x32_bf16 v[16:19], v[216:219], v[192:195], v[16:19]
	s_setprio 2
	s_barrier
	v_mfma_f32_16x16x32_bf16 v[4:7], v[208:211], v[200:203], v[4:7]
	v_mfma_f32_16x16x32_bf16 v[0:3], v[216:219], v[200:203], v[0:3]
	s_setprio 0
	s_add_i32 s29, 0, 0x18000
	v_add_u32_e32 v148, s29, v151
	ds_read_b128 v[144:147], v148
	ds_read_b128 v[160:163], v148 offset:1024
	ds_read_b128 v[164:167], v148 offset:2048
	ds_read_b128 v[168:171], v148 offset:3072
	s_add_u32 s12, s12, 0x40000
	s_addc_u32 s13, s13, 0
	s_mov_b32 m0, s42
	v_lshl_add_u64 v[204:205], s[12:13], 0, v[134:135]
	ds_read_b128 v[172:175], v157 offset:32768
	ds_read_b128 v[180:183], v157 offset:34816
	ds_read_b128 v[188:191], v157 offset:36864
	ds_read_b128 v[196:199], v157 offset:38912
	global_load_lds_dwordx4 v[204:205], off
	v_lshl_add_u64 v[204:205], s[12:13], 0, v[130:131]
	s_mov_b32 m0, s43
	s_nop 0
	global_load_lds_dwordx4 v[204:205], off
	s_waitcnt lgkmcnt(4)
	s_setprio 1
	s_barrier
	ds_read_b128 v[176:179], v157 offset:33792
	ds_read_b128 v[184:187], v157 offset:35840
	ds_read_b128 v[192:195], v157 offset:37888
	ds_read_b128 v[200:203], v157 offset:39936
	s_waitcnt lgkmcnt(4)
	v_mfma_f32_16x16x32_bf16 v[124:127], v[144:147], v[172:175], v[124:127]
	v_mfma_f32_16x16x32_bf16 v[120:123], v[164:167], v[172:175], v[120:123]
	v_mfma_f32_16x16x32_bf16 v[108:111], v[144:147], v[180:183], v[108:111]
	v_mfma_f32_16x16x32_bf16 v[104:107], v[164:167], v[180:183], v[104:107]
	v_mfma_f32_16x16x32_bf16 v[92:95], v[144:147], v[188:191], v[92:95]
	v_mfma_f32_16x16x32_bf16 v[88:91], v[164:167], v[188:191], v[88:91]
	v_mfma_f32_16x16x32_bf16 v[76:79], v[144:147], v[196:199], v[76:79]
	v_mfma_f32_16x16x32_bf16 v[72:75], v[164:167], v[196:199], v[72:75]
	s_waitcnt lgkmcnt(3)
	v_mfma_f32_16x16x32_bf16 v[124:127], v[160:163], v[176:179], v[124:127]
	v_mfma_f32_16x16x32_bf16 v[120:123], v[168:171], v[176:179], v[120:123]
	s_waitcnt lgkmcnt(2)
	v_mfma_f32_16x16x32_bf16 v[108:111], v[160:163], v[184:187], v[108:111]
	v_mfma_f32_16x16x32_bf16 v[104:107], v[168:171], v[184:187], v[104:107]
	s_waitcnt lgkmcnt(1)
	v_mfma_f32_16x16x32_bf16 v[92:95], v[160:163], v[192:195], v[92:95]
	v_mfma_f32_16x16x32_bf16 v[88:91], v[168:171], v[192:195], v[88:91]
	s_waitcnt lgkmcnt(0)
	s_setprio 2
	s_barrier
	v_mfma_f32_16x16x32_bf16 v[76:79], v[160:163], v[200:203], v[76:79]
	v_mfma_f32_16x16x32_bf16 v[72:75], v[168:171], v[200:203], v[72:75]
	s_setprio 0
	s_add_i32 s12, 0, 0x1c000
	s_add_i32 s13, s29, s34
	v_add_u32_e32 v148, s12, v151
	v_lshl_add_u64 v[220:221], v[220:221], 0, s[22:23]
	s_mov_b32 m0, s13
	ds_read_b128 v[204:207], v148
	ds_read_b128 v[208:211], v148 offset:1024
	ds_read_b128 v[212:215], v148 offset:2048
	ds_read_b128 v[216:219], v148 offset:3072
	global_load_lds_dwordx4 v[220:221], off
	v_lshl_add_u64 v[220:221], v[224:225], 0, s[22:23]
	s_add_i32 m0, s13, 0x2000
	s_nop 0
	global_load_lds_dwordx4 v[220:221], off
	s_setprio 1
	s_barrier
	s_waitcnt lgkmcnt(0)
	v_mfma_f32_16x16x32_bf16 v[116:119], v[204:207], v[172:175], v[116:119]
	v_mfma_f32_16x16x32_bf16 v[112:115], v[212:215], v[172:175], v[112:115]
	v_mfma_f32_16x16x32_bf16 v[100:103], v[204:207], v[180:183], v[100:103]
	v_mfma_f32_16x16x32_bf16 v[96:99], v[212:215], v[180:183], v[96:99]
	v_mfma_f32_16x16x32_bf16 v[84:87], v[204:207], v[188:191], v[84:87]
	v_mfma_f32_16x16x32_bf16 v[80:83], v[212:215], v[188:191], v[80:83]
	v_mfma_f32_16x16x32_bf16 v[68:71], v[204:207], v[196:199], v[68:71]
	v_mfma_f32_16x16x32_bf16 v[64:67], v[212:215], v[196:199], v[64:67]
	v_mfma_f32_16x16x32_bf16 v[116:119], v[208:211], v[176:179], v[116:119]
	v_mfma_f32_16x16x32_bf16 v[112:115], v[216:219], v[176:179], v[112:115]
	v_mfma_f32_16x16x32_bf16 v[100:103], v[208:211], v[184:187], v[100:103]
	v_mfma_f32_16x16x32_bf16 v[96:99], v[216:219], v[184:187], v[96:99]
	v_mfma_f32_16x16x32_bf16 v[84:87], v[208:211], v[192:195], v[84:87]
	v_mfma_f32_16x16x32_bf16 v[80:83], v[216:219], v[192:195], v[80:83]
	s_setprio 2
	s_barrier
; #define PG8_STAGE(bufoff, gbase, voff) do { _Pragma("unroll") for (int _i = 0; _i < 2; ++_i) \
;         __builtin_amdgcn_global_load_lds((const unsigned*)((const char*)(gbase) + (voff)[_i]), (LAS unsigned*)(lds + (bufoff) + ldsw + _i * 8192), 16, 0, 0); } while (0)
; #define PG8_LDA(dst, b, h) do { _Pragma("unroll") for (int m = 0; m < 4; ++m) _Pragma("unroll") for (int k = 0; k < 2; ++k) dst[m][k] = *(const LAS bf16x8*)(lds + PG8_SA(b, h) + aoff + m * 2048 + k * 1024); } while (0)
; #define PG8_LDB(dst, b, h) do { _Pragma("unroll") for (int n = 0; n < 2; ++n) _Pragma("unroll") for (int k = 0; k < 2; ++k) dst[n][k] = *(const LAS bf16x8*)(lds + PG8_SB(b, h) + boff + n * 2048 + k * 1024); } while (0)
; #define PG8_WAIT_V(n) asm volatile("s_waitcnt vmcnt(" #n ")" ::: "memory")
; DI RowScales load_rowscales(const float* ss, int row0) {
;     RowScales t;
; #pragma unroll
;     for (int ai = 0; ai < 2; ++ai)
; #pragma unroll
;         for (int m = 0; m < 4; ++m) t.r[ai][m] = ss[row0 + ai * 128 + m * 16];
; template <class Epi>
; DI void gemm_phase(LAS unsigned char* lds, const Gemm g, const StaticOrder S, const Epi E) {
;     ...
;             PG8_LDB(B0, 0, 0); PG8_SCHED; PG8_LDA(At, 0, 0); PG8_STAGE(PG8_SA(1, 1), a1 + hstep, voffA);
;             PG8_WAIT_L(8); PG8_BAR; PG8_WAIT_L(0); PG8_MMA(0, 0, At, B0); PG8_BAR; PG8_SCHED;
;             PG8_LDB(B1, 0, 1); PG8_STAGE(PG8_SB(0, 0), b2, voffB);
;             PG8_BAR; PG8_WAIT_L(0); PG8_MMA(0, 1, At, B1); PG8_BAR;
;             PG8_LDA(At, 0, 1); PG8_STAGE(PG8_SA(0, 0), a2, voffA);
;             PG8_BAR; PG8_WAIT_L(0); PG8_MMA(1, 0, At, B0); PG8_BAR; PG8_SCHED;
;             PG8_STAGE(PG8_SB(0, 1), b2 + hstep, voffB);
;             PG8_WAIT_V(6); PG8_BAR; PG8_MMA(1, 1, At, B1); PG8_BAR;
;             PG8_LDB(B0, 1, 0); PG8_SCHED; PG8_LDA(At, 1, 0); PG8_STAGE(PG8_SA(0, 1), a2 + hstep, voffA);
;             PG8_WAIT_L(8); PG8_BAR; PG8_WAIT_L(0); PG8_MMA(0, 0, At, B0); PG8_BAR; PG8_SCHED;
;             PG8_LDB(B1, 1, 1); PG8_STAGE(PG8_SB(1, 0), b3, voffB);
;             PG8_BAR; PG8_WAIT_L(0); PG8_MMA(0, 1, At, B1); PG8_BAR;
;             PG8_LDA(At, 1, 1); PG8_STAGE(PG8_SA(1, 0), a3, voffA);
;             PG8_BAR; PG8_WAIT_L(0); PG8_MMA(1, 0, At, B0); PG8_BAR; PG8_SCHED;
;             PG8_STAGE(PG8_SB(1, 1), b3 + hstep, voffB);
;             PG8_WAIT_V(6); PG8_BAR; PG8_MMA(1, 1, At, B1); PG8_BAR;
	v_mfma_f32_16x16x32_bf16 v[68:71], v[208:211], v[200:203], v[68:71]
	v_mfma_f32_16x16x32_bf16 v[64:67], v[216:219], v[200:203], v[64:67]
	s_setprio 0
	s_mov_b32 m0, s45
	v_lshl_add_u64 v[220:221], v[226:227], 0, s[22:23]
	ds_read_b128 v[172:175], v157 offset:49152
	ds_read_b128 v[180:183], v157 offset:51200
	ds_read_b128 v[188:191], v157 offset:53248
	ds_read_b128 v[196:199], v157 offset:55296
	global_load_lds_dwordx4 v[220:221], off
	v_lshl_add_u64 v[220:221], v[228:229], 0, s[22:23]
	s_mov_b32 m0, s46
	s_nop 0
	global_load_lds_dwordx4 v[220:221], off
	s_setprio 1
	s_barrier
	ds_read_b128 v[176:179], v157 offset:50176
	ds_read_b128 v[184:187], v157 offset:52224
	ds_read_b128 v[192:195], v157 offset:54272
	ds_read_b128 v[200:203], v157 offset:56320
	s_waitcnt lgkmcnt(4)
	v_mfma_f32_16x16x32_bf16 v[60:63], v[144:147], v[172:175], v[60:63]
	v_mfma_f32_16x16x32_bf16 v[56:59], v[164:167], v[172:175], v[56:59]
	v_mfma_f32_16x16x32_bf16 v[44:47], v[144:147], v[180:183], v[44:47]
	v_mfma_f32_16x16x32_bf16 v[40:43], v[164:167], v[180:183], v[40:43]
	v_mfma_f32_16x16x32_bf16 v[28:31], v[144:147], v[188:191], v[28:31]
	v_mfma_f32_16x16x32_bf16 v[24:27], v[164:167], v[188:191], v[24:27]
	v_mfma_f32_16x16x32_bf16 v[12:15], v[144:147], v[196:199], v[12:15]
	v_mfma_f32_16x16x32_bf16 v[8:11], v[164:167], v[196:199], v[8:11]
	s_waitcnt lgkmcnt(3)
	v_mfma_f32_16x16x32_bf16 v[60:63], v[160:163], v[176:179], v[60:63]
	v_mfma_f32_16x16x32_bf16 v[56:59], v[168:171], v[176:179], v[56:59]
	s_waitcnt lgkmcnt(2)
	v_mfma_f32_16x16x32_bf16 v[44:47], v[160:163], v[184:187], v[44:47]
	v_mfma_f32_16x16x32_bf16 v[40:43], v[168:171], v[184:187], v[40:43]
	s_waitcnt lgkmcnt(1)
	v_mfma_f32_16x16x32_bf16 v[28:31], v[160:163], v[192:195], v[28:31]
	v_mfma_f32_16x16x32_bf16 v[24:27], v[168:171], v[192:195], v[24:27]
	s_waitcnt lgkmcnt(0)
	s_setprio 2
	s_barrier
	v_mfma_f32_16x16x32_bf16 v[12:15], v[160:163], v[200:203], v[12:15]
	v_mfma_f32_16x16x32_bf16 v[8:11], v[168:171], v[200:203], v[8:11]
	s_setprio 0
	s_add_u32 s10, s10, 0x40080
	s_addc_u32 s11, s11, 0
	s_add_i32 s12, s12, s34
	v_lshl_add_u64 v[144:145], s[10:11], 0, v[132:133]
	s_mov_b32 m0, s12
	s_nop 0
	global_load_lds_dwordx4 v[144:145], off
	v_lshl_add_u64 v[144:145], s[10:11], 0, v[128:129]
	s_add_i32 m0, s12, 0x2000
	s_nop 0
	global_load_lds_dwordx4 v[144:145], off
	s_waitcnt vmcnt(6)
	s_setprio 1
	s_barrier
	v_mfma_f32_16x16x32_bf16 v[52:55], v[204:207], v[172:175], v[52:55]
	v_mfma_f32_16x16x32_bf16 v[48:51], v[212:215], v[172:175], v[48:51]
	v_mfma_f32_16x16x32_bf16 v[36:39], v[204:207], v[180:183], v[36:39]
	v_mfma_f32_16x16x32_bf16 v[32:35], v[212:215], v[180:183], v[32:35]
	v_mfma_f32_16x16x32_bf16 v[20:23], v[204:207], v[188:191], v[20:23]
	v_mfma_f32_16x16x32_bf16 v[16:19], v[212:215], v[188:191], v[16:19]
	v_mfma_f32_16x16x32_bf16 v[4:7], v[204:207], v[196:199], v[4:7]
	v_mfma_f32_16x16x32_bf16 v[0:3], v[212:215], v[196:199], v[0:3]
	v_mfma_f32_16x16x32_bf16 v[52:55], v[208:211], v[176:179], v[52:55]
	v_mfma_f32_16x16x32_bf16 v[48:51], v[216:219], v[176:179], v[48:51]
	v_mfma_f32_16x16x32_bf16 v[36:39], v[208:211], v[184:187], v[36:39]
	v_mfma_f32_16x16x32_bf16 v[32:35], v[216:219], v[184:187], v[32:35]
	v_mfma_f32_16x16x32_bf16 v[20:23], v[208:211], v[192:195], v[20:23]
	v_mfma_f32_16x16x32_bf16 v[16:19], v[216:219], v[192:195], v[16:19]
	s_setprio 2
	s_barrier
	v_mfma_f32_16x16x32_bf16 v[4:7], v[208:211], v[200:203], v[4:7]
	v_mfma_f32_16x16x32_bf16 v[0:3], v[216:219], v[200:203], v[0:3]
	s_setprio 0
	s_add_i32 s25, s25, 2
	s_add_u32 s8, s8, 0x100
	s_addc_u32 s9, s9, 0
	s_add_u32 s18, s18, 0x100
	s_addc_u32 s19, s19, 0
	s_cmp_gt_u32 s25, 13
	s_cbranch_scc0 .LBB0_865
	v_lshl_add_u32 v146, s4, 8, v149
	v_ashrrev_i32_e32 v147, 31, v146
	v_lshl_add_u64 v[144:145], v[146:147], 2, s[20:21]
	global_load_dword v147, v[144:145], off
	global_load_dword v148, v[144:145], off offset:64
	global_load_dword v150, v[144:145], off offset:128
	global_load_dword v152, v[144:145], off offset:192
	global_load_dword v154, v[144:145], off offset:512
	global_load_dword v156, v[144:145], off offset:576
	global_load_dword v160, v[144:145], off offset:640
	global_load_dword v161, v[144:145], off offset:704
	v_lshl_or_b32 v144, s5, 7, v153
	v_ashrrev_i32_e32 v145, 31, v144
	v_lshl_add_u64 v[144:145], v[144:145], 1, s[54:55]
	s_waitcnt vmcnt(0)
; DI unsigned pk_bf16(float lo, float hi) { f32x2 v = {lo, hi}; return __builtin_bit_cast(unsigned, __builtin_convertvector(v, bf16v2)); }
; DI float fast_silu(float x) { return x * fast_sigmoid(x); }
; DI RowScales load_rowscales(const float* ss, int row0) {
;     RowScales t;
; #pragma unroll
;     for (int ai = 0; ai < 2; ++ai)
; #pragma unroll
;         for (int m = 0; m < 4; ++m) t.r[ai][m] = ss[row0 + ai * 128 + m * 16];
; #pragma unroll
;     for (int ai = 0; ai < 2; ++ai)
; #pragma unroll
;         for (int m = 0; m < 4; ++m) t.r[ai][m] = rsqrtf(t.r[ai][m] * (1.0f / 1024.0f) + 1e-6f);
;     return t;
; }
;     DI void operator()(AccRef acc, const Unit& u, int wr, int wc, int fr, int fq) const {
;         const int row0 = u.pm * 256 + wr * 64 + fr, col = u.pn * 128 + wc * 32 + 8 * fq;
;         RowScales rsc; if (RS) rsc = load_rowscales(ss, row0);
; #pragma unroll
;         for (int ai = 0; ai < 2; ++ai)
; #pragma unroll
;             for (int m = 0; m < 4; ++m) {
;                 const int row = row0 + ai * 128 + m * 16;
;                 const float r = RS ? rsc.r[ai][m] : 1.0f;
;                 const f32x4 a0 = acc[ai][0][m][0] * r, a1 = acc[ai][0][m][1] * r, b0 = acc[ai][1][m][0] * r, b1 = acc[ai][1][m][1] * r;
;                 u32x4 w;
;                 w.x = pk_bf16(fast_silu(a0[0]) * b0[0], fast_silu(a0[1]) * b0[1]); w.y = pk_bf16(fast_silu(a0[2]) * b0[2], fast_silu(a0[3]) * b0[3]);
;                 w.z = pk_bf16(fast_silu(a1[0]) * b1[0], fast_silu(a1[1]) * b1[1]); w.w = pk_bf16(fast_silu(a1[2]) * b1[2], fast_silu(a1[3]) * b1[3]);
;                 *(u32x4*)(G + (size_t)row * DFF + col) = w;
;             }
	v_fmamk_f32 v147, v147, 0x3a800000, v159
	v_mul_f32_e32 v162, 0x4b800000, v147
	v_cmp_gt_f32_e32 vcc, s51, v147
	v_fmamk_f32 v152, v152, 0x3a800000, v159
	v_fmamk_f32 v154, v154, 0x3a800000, v159
	v_cndmask_b32_e32 v147, v147, v162, vcc
	v_mul_f32_e32 v165, 0x4b800000, v152
	v_fmamk_f32 v161, v161, 0x3a800000, v159
	v_mul_f32_e32 v166, 0x4b800000, v154
	v_mul_f32_e32 v169, 0x4b800000, v161
	v_cmp_gt_f32_e64 s[10:11], s51, v152
	v_cmp_gt_f32_e64 s[12:13], s51, v154
	v_cmp_gt_f32_e64 s[18:19], s51, v161
	v_rsq_f32_e32 v147, v147
	v_fmamk_f32 v156, v156, 0x3a800000, v159
	v_cndmask_b32_e64 v152, v152, v165, s[10:11]
	v_cndmask_b32_e64 v154, v154, v166, s[12:13]
	v_cndmask_b32_e64 v161, v161, v169, s[18:19]
	v_fmamk_f32 v148, v148, 0x3a800000, v159
	v_fmamk_f32 v160, v160, 0x3a800000, v159
	v_mul_f32_e32 v167, 0x4b800000, v156
	v_cmp_gt_f32_e64 s[14:15], s51, v156
	v_rsq_f32_e32 v152, v152
	v_rsq_f32_e32 v154, v154
	v_rsq_f32_e32 v161, v161
	v_mul_f32_e32 v163, 0x4b800000, v148
	v_mul_f32_e32 v168, 0x4b800000, v160
	v_cmp_gt_f32_e64 s[4:5], s51, v148
	v_cndmask_b32_e64 v156, v156, v167, s[14:15]
	v_cmp_gt_f32_e64 s[16:17], s51, v160
	v_fmamk_f32 v150, v150, 0x3a800000, v159
	v_cndmask_b32_e64 v148, v148, v163, s[4:5]
	v_cndmask_b32_e64 v160, v160, v168, s[16:17]
	v_rsq_f32_e32 v163, v156
	v_mul_f32_e32 v156, 0x45800000, v147
	v_mul_f32_e32 v164, 0x4b800000, v150
	v_cmp_gt_f32_e64 s[8:9], s51, v150
	v_rsq_f32_e32 v165, v160
	v_cndmask_b32_e32 v160, v147, v156, vcc
	v_cndmask_b32_e64 v150, v150, v164, s[8:9]
	v_rsq_f32_e32 v148, v148
	v_mul_f32_e32 v166, 0x45800000, v152
	v_mul_f32_e32 v167, 0x45800000, v154
	v_pk_mul_f32 v[126:127], v[126:127], v[160:161] op_sel_hi:[1,0]
	v_pk_mul_f32 v[124:125], v[124:125], v[160:161] op_sel_hi:[1,0]
	v_rsq_f32_e32 v150, v150
	v_cndmask_b32_e64 v156, v152, v166, s[10:11]
	v_cndmask_b32_e64 v154, v154, v167, s[12:13]
	v_pk_mul_f32 v[122:123], v[122:123], v[160:161] op_sel_hi:[1,0]
	v_pk_mul_f32 v[120:121], v[120:121], v[160:161] op_sel_hi:[1,0]
	v_pk_mul_f32 v[118:119], v[118:119], v[160:161] op_sel_hi:[1,0]
	v_pk_mul_f32 v[116:117], v[116:117], v[160:161] op_sel_hi:[1,0]
	v_pk_mul_f32 v[166:167], v[114:115], v[160:161] op_sel_hi:[1,0]
	v_pk_mul_f32 v[114:115], v[112:113], v[160:161] op_sel_hi:[1,0]
	v_mul_f32_e32 v112, 0xbfb8aa3b, v124
	v_mul_f32_e32 v113, 0xbfb8aa3b, v125
	v_mul_f32_e32 v147, 0xbfb8aa3b, v126
	v_mul_f32_e32 v160, 0xbfb8aa3b, v127
	v_exp_f32_e32 v112, v112
	v_exp_f32_e32 v113, v113
	v_exp_f32_e32 v147, v147
	v_exp_f32_e32 v160, v160
	v_mul_f32_e32 v162, 0x45800000, v148
	v_mul_f32_e32 v170, 0x45800000, v161
	v_mul_f32_e32 v164, 0x45800000, v150
	v_mul_f32_e32 v169, 0x45800000, v165
	v_cndmask_b32_e64 v162, v148, v162, s[4:5]
	v_cndmask_b32_e64 v148, v161, v170, s[18:19]
	v_mul_f32_e32 v161, 0xbfb8aa3b, v120
	v_cndmask_b32_e64 v164, v150, v164, s[8:9]
	v_cndmask_b32_e64 v150, v165, v169, s[16:17]
	v_exp_f32_e32 v165, v161
	v_add_f32_e32 v112, 1.0, v112
	v_add_f32_e32 v113, 1.0, v113
	v_add_f32_e32 v147, 1.0, v147
	v_add_f32_e32 v161, 1.0, v160
	v_rcp_f32_e32 v112, v112
	v_rcp_f32_e32 v113, v113
	v_rcp_f32_e32 v160, v147
	v_rcp_f32_e32 v161, v161
	v_mul_f32_e32 v168, 0x45800000, v163
	v_pk_mul_f32 v[112:113], v[124:125], v[112:113]
	v_cndmask_b32_e64 v152, v163, v168, s[14:15]
	v_pk_mul_f32 v[124:125], v[126:127], v[160:161]
	v_mul_f32_e32 v163, 0xbfb8aa3b, v121
	v_pk_mul_f32 v[112:113], v[116:117], v[112:113]
	v_pk_mul_f32 v[116:117], v[118:119], v[124:125]
	v_exp_f32_e32 v163, v163
	v_cvt_pk_bf16_f32 v112, v112, v113
	v_cvt_pk_bf16_f32 v113, v116, v117
	v_mul_f32_e32 v117, 0xbfb8aa3b, v122
	v_mul_f32_e32 v118, 0xbfb8aa3b, v123
	v_exp_f32_e32 v117, v117
	v_exp_f32_e32 v118, v118
	v_add_f32_e32 v116, 1.0, v163
	v_add_f32_e32 v147, 1.0, v165
	v_rcp_f32_e32 v169, v116
	v_add_f32_e32 v116, 1.0, v117
	v_add_f32_e32 v117, 1.0, v118
	v_rcp_f32_e32 v168, v147
	v_rcp_f32_e32 v116, v116
	v_rcp_f32_e32 v117, v117
	v_pk_mul_f32 v[108:109], v[108:109], v[162:163] op_sel_hi:[1,0]
	v_pk_mul_f32 v[118:119], v[120:121], v[168:169]
	v_pk_mul_f32 v[110:111], v[110:111], v[162:163] op_sel_hi:[1,0]
	v_pk_mul_f32 v[116:117], v[122:123], v[116:117]
	v_pk_mul_f32 v[114:115], v[114:115], v[118:119]
	v_pk_mul_f32 v[116:117], v[166:167], v[116:117]
	v_cvt_pk_bf16_f32 v114, v114, v115
	v_cvt_pk_bf16_f32 v115, v116, v117
	v_mad_i64_i32 v[116:117], s[4:5], v146, s52, v[144:145]
	global_store_dwordx4 v[116:117], v[112:115], off
	v_pk_mul_f32 v[100:101], v[100:101], v[162:163] op_sel_hi:[1,0]
	v_pk_mul_f32 v[104:105], v[104:105], v[162:163] op_sel_hi:[1,0]
	v_pk_mul_f32 v[112:113], v[98:99], v[162:163] op_sel_hi:[1,0]
	v_mul_f32_e32 v98, 0xbfb8aa3b, v108
	v_exp_f32_e32 v114, v98
	v_mul_f32_e32 v98, 0xbfb8aa3b, v109
	v_exp_f32_e32 v115, v98
	v_pk_mul_f32 v[98:99], v[96:97], v[162:163] op_sel_hi:[1,0]
	v_add_f32_e32 v96, 1.0, v114
	v_mul_f32_e32 v114, 0xbfb8aa3b, v110
	v_add_f32_e32 v97, 1.0, v115
	v_mul_f32_e32 v115, 0xbfb8aa3b, v111
	v_exp_f32_e32 v114, v114
	v_exp_f32_e32 v115, v115
	v_rcp_f32_e32 v96, v96
	v_rcp_f32_e32 v97, v97
	v_add_f32_e32 v114, 1.0, v114
	v_add_f32_e32 v115, 1.0, v115
	v_rcp_f32_e32 v114, v114
	v_rcp_f32_e32 v115, v115
	v_pk_mul_f32 v[96:97], v[108:109], v[96:97]
	v_pk_mul_f32 v[102:103], v[102:103], v[162:163] op_sel_hi:[1,0]
	v_pk_mul_f32 v[96:97], v[100:101], v[96:97]
	v_pk_mul_f32 v[100:101], v[110:111], v[114:115]
	v_cvt_pk_bf16_f32 v96, v96, v97
	v_mul_f32_e32 v97, 0xbfb8aa3b, v104
	v_pk_mul_f32 v[100:101], v[102:103], v[100:101]
	v_exp_f32_e32 v102, v97
	v_mul_f32_e32 v97, 0xbfb8aa3b, v105
	v_exp_f32_e32 v103, v97
	v_pk_mul_f32 v[106:107], v[106:107], v[162:163] op_sel_hi:[1,0]
; DI unsigned pk_bf16(float lo, float hi) { f32x2 v = {lo, hi}; return __builtin_bit_cast(unsigned, __builtin_convertvector(v, bf16v2)); }
; DI float fast_silu(float x) { return x * fast_sigmoid(x); }
;     DI void operator()(AccRef acc, const Unit& u, int wr, int wc, int fr, int fq) const {
;         const int row0 = u.pm * 256 + wr * 64 + fr, col = u.pn * 128 + wc * 32 + 8 * fq;
;         RowScales rsc; if (RS) rsc = load_rowscales(ss, row0);
; #pragma unroll
;         for (int ai = 0; ai < 2; ++ai)
; #pragma unroll
;             for (int m = 0; m < 4; ++m) {
;                 const int row = row0 + ai * 128 + m * 16;
;                 const float r = RS ? rsc.r[ai][m] : 1.0f;
;                 const f32x4 a0 = acc[ai][0][m][0] * r, a1 = acc[ai][0][m][1] * r, b0 = acc[ai][1][m][0] * r, b1 = acc[ai][1][m][1] * r;
;                 u32x4 w;
;                 w.x = pk_bf16(fast_silu(a0[0]) * b0[0], fast_silu(a0[1]) * b0[1]); w.y = pk_bf16(fast_silu(a0[2]) * b0[2], fast_silu(a0[3]) * b0[3]);
;                 w.z = pk_bf16(fast_silu(a1[0]) * b1[0], fast_silu(a1[1]) * b1[1]); w.w = pk_bf16(fast_silu(a1[2]) * b1[2], fast_silu(a1[3]) * b1[3]);
;                 *(u32x4*)(G + (size_t)row * DFF + col) = w;
;             }
	v_cvt_pk_bf16_f32 v97, v100, v101
	v_add_f32_e32 v100, 1.0, v102
	v_add_f32_e32 v101, 1.0, v103
	v_mul_f32_e32 v102, 0xbfb8aa3b, v106
	v_mul_f32_e32 v103, 0xbfb8aa3b, v107
	v_exp_f32_e32 v102, v102
	v_exp_f32_e32 v103, v103
	v_rcp_f32_e32 v100, v100
	v_rcp_f32_e32 v101, v101
	v_add_f32_e32 v102, 1.0, v102
	v_add_f32_e32 v103, 1.0, v103
	v_rcp_f32_e32 v102, v102
	v_rcp_f32_e32 v103, v103
	v_pk_mul_f32 v[100:101], v[104:105], v[100:101]
	v_or_b32_e32 v116, 16, v146
	v_pk_mul_f32 v[98:99], v[98:99], v[100:101]
	v_pk_mul_f32 v[100:101], v[106:107], v[102:103]
	v_cvt_pk_bf16_f32 v98, v98, v99
	v_pk_mul_f32 v[100:101], v[112:113], v[100:101]
	v_pk_mul_f32 v[92:93], v[92:93], v[164:165] op_sel_hi:[1,0]
	v_cvt_pk_bf16_f32 v99, v100, v101
	v_mad_i64_i32 v[100:101], s[4:5], v116, s52, v[144:145]
	global_store_dwordx4 v[100:101], v[96:99], off
	v_pk_mul_f32 v[94:95], v[94:95], v[164:165] op_sel_hi:[1,0]
	v_pk_mul_f32 v[84:85], v[84:85], v[164:165] op_sel_hi:[1,0]
	v_pk_mul_f32 v[96:97], v[82:83], v[164:165] op_sel_hi:[1,0]
	v_mul_f32_e32 v82, 0xbfb8aa3b, v92
	v_exp_f32_e32 v98, v82
	v_mul_f32_e32 v82, 0xbfb8aa3b, v93
	v_exp_f32_e32 v99, v82
	v_pk_mul_f32 v[82:83], v[80:81], v[164:165] op_sel_hi:[1,0]
	v_add_f32_e32 v80, 1.0, v98
	v_mul_f32_e32 v98, 0xbfb8aa3b, v94
	v_add_f32_e32 v81, 1.0, v99
	v_mul_f32_e32 v99, 0xbfb8aa3b, v95
	v_exp_f32_e32 v98, v98
	v_exp_f32_e32 v99, v99
	v_rcp_f32_e32 v80, v80
	v_rcp_f32_e32 v81, v81
	v_add_f32_e32 v98, 1.0, v98
	v_add_f32_e32 v99, 1.0, v99
	v_rcp_f32_e32 v98, v98
	v_rcp_f32_e32 v99, v99
	v_pk_mul_f32 v[80:81], v[92:93], v[80:81]
	v_pk_mul_f32 v[88:89], v[88:89], v[164:165] op_sel_hi:[1,0]
	v_pk_mul_f32 v[80:81], v[84:85], v[80:81]
	v_pk_mul_f32 v[86:87], v[86:87], v[164:165] op_sel_hi:[1,0]
	v_cvt_pk_bf16_f32 v80, v80, v81
	v_pk_mul_f32 v[84:85], v[94:95], v[98:99]
	v_mul_f32_e32 v81, 0xbfb8aa3b, v88
	v_pk_mul_f32 v[84:85], v[86:87], v[84:85]
	v_exp_f32_e32 v86, v81
	v_mul_f32_e32 v81, 0xbfb8aa3b, v89
	v_exp_f32_e32 v87, v81
	v_pk_mul_f32 v[90:91], v[90:91], v[164:165] op_sel_hi:[1,0]
	v_cvt_pk_bf16_f32 v81, v84, v85
	v_add_f32_e32 v84, 1.0, v86
	v_add_f32_e32 v85, 1.0, v87
	v_mul_f32_e32 v86, 0xbfb8aa3b, v90
	v_mul_f32_e32 v87, 0xbfb8aa3b, v91
	v_exp_f32_e32 v86, v86
	v_exp_f32_e32 v87, v87
	v_rcp_f32_e32 v84, v84
	v_rcp_f32_e32 v85, v85
	v_add_f32_e32 v86, 1.0, v86
	v_add_f32_e32 v87, 1.0, v87
	v_rcp_f32_e32 v86, v86
	v_rcp_f32_e32 v87, v87
	v_pk_mul_f32 v[84:85], v[88:89], v[84:85]
	v_or_b32_e32 v100, 32, v146
	v_pk_mul_f32 v[82:83], v[82:83], v[84:85]
	v_pk_mul_f32 v[84:85], v[90:91], v[86:87]
	v_cvt_pk_bf16_f32 v82, v82, v83
	v_pk_mul_f32 v[84:85], v[96:97], v[84:85]
	v_pk_mul_f32 v[76:77], v[76:77], v[156:157] op_sel_hi:[1,0]
	v_cvt_pk_bf16_f32 v83, v84, v85
	v_mad_i64_i32 v[84:85], s[4:5], v100, s52, v[144:145]
	global_store_dwordx4 v[84:85], v[80:83], off
	v_pk_mul_f32 v[78:79], v[78:79], v[156:157] op_sel_hi:[1,0]
	v_pk_mul_f32 v[68:69], v[68:69], v[156:157] op_sel_hi:[1,0]
	v_pk_mul_f32 v[80:81], v[66:67], v[156:157] op_sel_hi:[1,0]
	v_mul_f32_e32 v66, 0xbfb8aa3b, v76
	v_exp_f32_e32 v82, v66
	v_mul_f32_e32 v66, 0xbfb8aa3b, v77
	v_exp_f32_e32 v83, v66
	v_pk_mul_f32 v[66:67], v[64:65], v[156:157] op_sel_hi:[1,0]
	v_add_f32_e32 v64, 1.0, v82
	v_mul_f32_e32 v82, 0xbfb8aa3b, v78
	v_add_f32_e32 v65, 1.0, v83
	v_mul_f32_e32 v83, 0xbfb8aa3b, v79
	v_exp_f32_e32 v82, v82
	v_exp_f32_e32 v83, v83
	v_rcp_f32_e32 v64, v64
	v_rcp_f32_e32 v65, v65
	v_add_f32_e32 v82, 1.0, v82
	v_add_f32_e32 v83, 1.0, v83
	v_rcp_f32_e32 v82, v82
	v_rcp_f32_e32 v83, v83
	v_pk_mul_f32 v[64:65], v[76:77], v[64:65]
	v_pk_mul_f32 v[72:73], v[72:73], v[156:157] op_sel_hi:[1,0]
	v_pk_mul_f32 v[64:65], v[68:69], v[64:65]
	v_pk_mul_f32 v[70:71], v[70:71], v[156:157] op_sel_hi:[1,0]
	v_cvt_pk_bf16_f32 v64, v64, v65
	v_pk_mul_f32 v[68:69], v[78:79], v[82:83]
	v_mul_f32_e32 v65, 0xbfb8aa3b, v72
	v_pk_mul_f32 v[68:69], v[70:71], v[68:69]
	v_exp_f32_e32 v70, v65
	v_mul_f32_e32 v65, 0xbfb8aa3b, v73
	v_exp_f32_e32 v71, v65
	v_pk_mul_f32 v[74:75], v[74:75], v[156:157] op_sel_hi:[1,0]
	v_cvt_pk_bf16_f32 v65, v68, v69
	v_add_f32_e32 v68, 1.0, v70
	v_add_f32_e32 v69, 1.0, v71
	v_mul_f32_e32 v70, 0xbfb8aa3b, v74
	v_mul_f32_e32 v71, 0xbfb8aa3b, v75
	v_exp_f32_e32 v70, v70
	v_exp_f32_e32 v71, v71
	v_rcp_f32_e32 v68, v68
	v_rcp_f32_e32 v69, v69
	v_add_f32_e32 v70, 1.0, v70
	v_add_f32_e32 v71, 1.0, v71
	v_rcp_f32_e32 v70, v70
	v_rcp_f32_e32 v71, v71
	v_pk_mul_f32 v[68:69], v[72:73], v[68:69]
	v_or_b32_e32 v84, 48, v146
	v_pk_mul_f32 v[66:67], v[66:67], v[68:69]
	v_pk_mul_f32 v[68:69], v[74:75], v[70:71]
	v_cvt_pk_bf16_f32 v66, v66, v67
	v_pk_mul_f32 v[68:69], v[80:81], v[68:69]
	v_pk_mul_f32 v[60:61], v[60:61], v[154:155] op_sel_hi:[1,0]
	v_cvt_pk_bf16_f32 v67, v68, v69
	v_mad_i64_i32 v[68:69], s[4:5], v84, s52, v[144:145]
	global_store_dwordx4 v[68:69], v[64:67], off
	v_pk_mul_f32 v[62:63], v[62:63], v[154:155] op_sel_hi:[1,0]
	v_pk_mul_f32 v[52:53], v[52:53], v[154:155] op_sel_hi:[1,0]
	v_pk_mul_f32 v[64:65], v[50:51], v[154:155] op_sel_hi:[1,0]
	v_mul_f32_e32 v50, 0xbfb8aa3b, v60
	v_exp_f32_e32 v66, v50
	v_mul_f32_e32 v50, 0xbfb8aa3b, v61
	v_exp_f32_e32 v67, v50
	v_pk_mul_f32 v[50:51], v[48:49], v[154:155] op_sel_hi:[1,0]
	v_add_f32_e32 v48, 1.0, v66
	v_mul_f32_e32 v66, 0xbfb8aa3b, v62
	v_add_f32_e32 v49, 1.0, v67
	v_mul_f32_e32 v67, 0xbfb8aa3b, v63
	v_exp_f32_e32 v66, v66
	v_exp_f32_e32 v67, v67
	v_rcp_f32_e32 v48, v48
	v_rcp_f32_e32 v49, v49
	v_add_f32_e32 v66, 1.0, v66
	v_add_f32_e32 v67, 1.0, v67
	v_rcp_f32_e32 v66, v66
	v_rcp_f32_e32 v67, v67
	v_pk_mul_f32 v[48:49], v[60:61], v[48:49]
	v_pk_mul_f32 v[56:57], v[56:57], v[154:155] op_sel_hi:[1,0]
; DI unsigned pk_bf16(float lo, float hi) { f32x2 v = {lo, hi}; return __builtin_bit_cast(unsigned, __builtin_convertvector(v, bf16v2)); }
; DI float fast_silu(float x) { return x * fast_sigmoid(x); }
;     DI void operator()(AccRef acc, const Unit& u, int wr, int wc, int fr, int fq) const {
;         const int row0 = u.pm * 256 + wr * 64 + fr, col = u.pn * 128 + wc * 32 + 8 * fq;
;         RowScales rsc; if (RS) rsc = load_rowscales(ss, row0);
; #pragma unroll
;         for (int ai = 0; ai < 2; ++ai)
; #pragma unroll
;             for (int m = 0; m < 4; ++m) {
;                 const int row = row0 + ai * 128 + m * 16;
;                 const float r = RS ? rsc.r[ai][m] : 1.0f;
;                 const f32x4 a0 = acc[ai][0][m][0] * r, a1 = acc[ai][0][m][1] * r, b0 = acc[ai][1][m][0] * r, b1 = acc[ai][1][m][1] * r;
;                 u32x4 w;
;                 w.x = pk_bf16(fast_silu(a0[0]) * b0[0], fast_silu(a0[1]) * b0[1]); w.y = pk_bf16(fast_silu(a0[2]) * b0[2], fast_silu(a0[3]) * b0[3]);
;                 w.z = pk_bf16(fast_silu(a1[0]) * b1[0], fast_silu(a1[1]) * b1[1]); w.w = pk_bf16(fast_silu(a1[2]) * b1[2], fast_silu(a1[3]) * b1[3]);
;                 *(u32x4*)(G + (size_t)row * DFF + col) = w;
;             }
	v_pk_mul_f32 v[48:49], v[52:53], v[48:49]
	v_pk_mul_f32 v[54:55], v[54:55], v[154:155] op_sel_hi:[1,0]
	v_cvt_pk_bf16_f32 v48, v48, v49
	v_pk_mul_f32 v[52:53], v[62:63], v[66:67]
	v_mul_f32_e32 v49, 0xbfb8aa3b, v56
	v_pk_mul_f32 v[52:53], v[54:55], v[52:53]
	v_exp_f32_e32 v54, v49
	v_mul_f32_e32 v49, 0xbfb8aa3b, v57
	v_exp_f32_e32 v55, v49
	v_pk_mul_f32 v[58:59], v[58:59], v[154:155] op_sel_hi:[1,0]
	v_cvt_pk_bf16_f32 v49, v52, v53
	v_add_f32_e32 v52, 1.0, v54
	v_add_f32_e32 v53, 1.0, v55
	v_mul_f32_e32 v54, 0xbfb8aa3b, v58
	v_mul_f32_e32 v55, 0xbfb8aa3b, v59
	v_exp_f32_e32 v54, v54
	v_exp_f32_e32 v55, v55
	v_rcp_f32_e32 v52, v52
	v_rcp_f32_e32 v53, v53
	v_add_f32_e32 v54, 1.0, v54
	v_add_f32_e32 v55, 1.0, v55
	v_rcp_f32_e32 v54, v54
	v_rcp_f32_e32 v55, v55
	v_pk_mul_f32 v[52:53], v[56:57], v[52:53]
	v_add_u32_e32 v68, 0x80, v146
	v_pk_mul_f32 v[50:51], v[50:51], v[52:53]
	v_pk_mul_f32 v[52:53], v[58:59], v[54:55]
	v_cvt_pk_bf16_f32 v50, v50, v51
	v_pk_mul_f32 v[52:53], v[64:65], v[52:53]
	v_pk_mul_f32 v[44:45], v[44:45], v[152:153] op_sel_hi:[1,0]
	v_cvt_pk_bf16_f32 v51, v52, v53
	v_mad_i64_i32 v[52:53], s[4:5], v68, s52, v[144:145]
	global_store_dwordx4 v[52:53], v[48:51], off
	v_pk_mul_f32 v[46:47], v[46:47], v[152:153] op_sel_hi:[1,0]
	v_pk_mul_f32 v[36:37], v[36:37], v[152:153] op_sel_hi:[1,0]
	v_pk_mul_f32 v[48:49], v[34:35], v[152:153] op_sel_hi:[1,0]
	v_mul_f32_e32 v34, 0xbfb8aa3b, v44
	v_exp_f32_e32 v50, v34
	v_mul_f32_e32 v34, 0xbfb8aa3b, v45
	v_exp_f32_e32 v51, v34
	v_pk_mul_f32 v[34:35], v[32:33], v[152:153] op_sel_hi:[1,0]
	v_add_f32_e32 v32, 1.0, v50
	v_mul_f32_e32 v50, 0xbfb8aa3b, v46
	v_add_f32_e32 v33, 1.0, v51
	v_mul_f32_e32 v51, 0xbfb8aa3b, v47
	v_exp_f32_e32 v50, v50
	v_exp_f32_e32 v51, v51
	v_rcp_f32_e32 v32, v32
	v_rcp_f32_e32 v33, v33
	v_add_f32_e32 v50, 1.0, v50
	v_add_f32_e32 v51, 1.0, v51
	v_rcp_f32_e32 v50, v50
	v_rcp_f32_e32 v51, v51
	v_pk_mul_f32 v[32:33], v[44:45], v[32:33]
	v_pk_mul_f32 v[40:41], v[40:41], v[152:153] op_sel_hi:[1,0]
	v_pk_mul_f32 v[32:33], v[36:37], v[32:33]
	v_pk_mul_f32 v[38:39], v[38:39], v[152:153] op_sel_hi:[1,0]
	v_cvt_pk_bf16_f32 v32, v32, v33
	v_pk_mul_f32 v[36:37], v[46:47], v[50:51]
	v_mul_f32_e32 v33, 0xbfb8aa3b, v40
	v_pk_mul_f32 v[36:37], v[38:39], v[36:37]
	v_exp_f32_e32 v38, v33
	v_mul_f32_e32 v33, 0xbfb8aa3b, v41
	v_exp_f32_e32 v39, v33
	v_pk_mul_f32 v[42:43], v[42:43], v[152:153] op_sel_hi:[1,0]
	v_cvt_pk_bf16_f32 v33, v36, v37
	v_add_f32_e32 v36, 1.0, v38
	v_add_f32_e32 v37, 1.0, v39
	v_mul_f32_e32 v38, 0xbfb8aa3b, v42
	v_mul_f32_e32 v39, 0xbfb8aa3b, v43
	v_exp_f32_e32 v38, v38
	v_exp_f32_e32 v39, v39
	v_rcp_f32_e32 v36, v36
	v_rcp_f32_e32 v37, v37
	v_add_f32_e32 v38, 1.0, v38
	v_add_f32_e32 v39, 1.0, v39
	v_rcp_f32_e32 v38, v38
	v_rcp_f32_e32 v39, v39
	v_pk_mul_f32 v[36:37], v[40:41], v[36:37]
	v_add_u32_e32 v52, 0x90, v146
	v_pk_mul_f32 v[34:35], v[34:35], v[36:37]
	v_pk_mul_f32 v[36:37], v[42:43], v[38:39]
	v_cvt_pk_bf16_f32 v34, v34, v35
	v_pk_mul_f32 v[36:37], v[48:49], v[36:37]
	v_pk_mul_f32 v[28:29], v[28:29], v[150:151] op_sel_hi:[1,0]
	v_cvt_pk_bf16_f32 v35, v36, v37
	v_mad_i64_i32 v[36:37], s[4:5], v52, s52, v[144:145]
	global_store_dwordx4 v[36:37], v[32:35], off
	v_pk_mul_f32 v[30:31], v[30:31], v[150:151] op_sel_hi:[1,0]
	v_pk_mul_f32 v[20:21], v[20:21], v[150:151] op_sel_hi:[1,0]
	v_pk_mul_f32 v[32:33], v[18:19], v[150:151] op_sel_hi:[1,0]
	v_mul_f32_e32 v18, 0xbfb8aa3b, v28
	v_exp_f32_e32 v34, v18
	v_mul_f32_e32 v18, 0xbfb8aa3b, v29
	v_exp_f32_e32 v35, v18
	v_pk_mul_f32 v[18:19], v[16:17], v[150:151] op_sel_hi:[1,0]
	v_add_f32_e32 v16, 1.0, v34
	v_mul_f32_e32 v34, 0xbfb8aa3b, v30
; DI unsigned pk_bf16(float lo, float hi) { f32x2 v = {lo, hi}; return __builtin_bit_cast(unsigned, __builtin_convertvector(v, bf16v2)); }
; DI float fast_silu(float x) { return x * fast_sigmoid(x); }
; #define PG8_WAIT_V(n) asm volatile("s_waitcnt vmcnt(" #n ")" ::: "memory")
; #define PG8_BAR __builtin_amdgcn_s_barrier()
; #define PG8_WAIT_V(n) asm volatile("s_waitcnt vmcnt(" #n ")" ::: "memory")
; #define PG8_BAR __builtin_amdgcn_s_barrier()
; template <class Epi>
; DI void gemm_phase(LAS unsigned char* lds, const Gemm g, const StaticOrder S, const Epi E) {
;     ...
;         if (!has_next) break;
; #pragma unroll
;         for (int a = 0; a < 2; ++a)
; #pragma unroll
;             for (int b = 0; b < 2; ++b)
; #pragma unroll
;                 for (int m = 0; m < 4; ++m)
; #pragma unroll
;                     for (int n = 0; n < 2; ++n) acc[a][b][m][n] = (f32x4){0.f, 0.f, 0.f, 0.f};
;         cur = nxt; cA = nA; cB = nB; ++ui;
;     }
;     PG8_WAIT_V(0);
;     if (wr == 0) PG8_BAR;
;     PG8_BAR;
;     DI void operator()(AccRef acc, const Unit& u, int wr, int wc, int fr, int fq) const {
;         const int row0 = u.pm * 256 + wr * 64 + fr, col = u.pn * 128 + wc * 32 + 8 * fq;
;         RowScales rsc; if (RS) rsc = load_rowscales(ss, row0);
; #pragma unroll
;         for (int ai = 0; ai < 2; ++ai)
; #pragma unroll
;             for (int m = 0; m < 4; ++m) {
;                 const int row = row0 + ai * 128 + m * 16;
;                 const float r = RS ? rsc.r[ai][m] : 1.0f;
;                 const f32x4 a0 = acc[ai][0][m][0] * r, a1 = acc[ai][0][m][1] * r, b0 = acc[ai][1][m][0] * r, b1 = acc[ai][1][m][1] * r;
;                 u32x4 w;
;                 w.x = pk_bf16(fast_silu(a0[0]) * b0[0], fast_silu(a0[1]) * b0[1]); w.y = pk_bf16(fast_silu(a0[2]) * b0[2], fast_silu(a0[3]) * b0[3]);
;                 w.z = pk_bf16(fast_silu(a1[0]) * b1[0], fast_silu(a1[1]) * b1[1]); w.w = pk_bf16(fast_silu(a1[2]) * b1[2], fast_silu(a1[3]) * b1[3]);
;                 *(u32x4*)(G + (size_t)row * DFF + col) = w;
;             }
	v_add_f32_e32 v17, 1.0, v35
	v_mul_f32_e32 v35, 0xbfb8aa3b, v31
	v_exp_f32_e32 v34, v34
	v_exp_f32_e32 v35, v35
	v_rcp_f32_e32 v16, v16
	v_rcp_f32_e32 v17, v17
	v_add_f32_e32 v34, 1.0, v34
	v_add_f32_e32 v35, 1.0, v35
	v_rcp_f32_e32 v34, v34
	v_rcp_f32_e32 v35, v35
	v_pk_mul_f32 v[16:17], v[28:29], v[16:17]
	v_pk_mul_f32 v[24:25], v[24:25], v[150:151] op_sel_hi:[1,0]
	v_pk_mul_f32 v[16:17], v[20:21], v[16:17]
	v_pk_mul_f32 v[22:23], v[22:23], v[150:151] op_sel_hi:[1,0]
	v_cvt_pk_bf16_f32 v16, v16, v17
	v_pk_mul_f32 v[20:21], v[30:31], v[34:35]
	v_mul_f32_e32 v17, 0xbfb8aa3b, v24
	v_pk_mul_f32 v[20:21], v[22:23], v[20:21]
	v_exp_f32_e32 v22, v17
	v_mul_f32_e32 v17, 0xbfb8aa3b, v25
	v_exp_f32_e32 v23, v17
	v_pk_mul_f32 v[26:27], v[26:27], v[150:151] op_sel_hi:[1,0]
	v_cvt_pk_bf16_f32 v17, v20, v21
	v_add_f32_e32 v20, 1.0, v22
	v_add_f32_e32 v21, 1.0, v23
	v_mul_f32_e32 v22, 0xbfb8aa3b, v26
	v_mul_f32_e32 v23, 0xbfb8aa3b, v27
	v_exp_f32_e32 v22, v22
	v_exp_f32_e32 v23, v23
	v_rcp_f32_e32 v20, v20
	v_rcp_f32_e32 v21, v21
	v_add_f32_e32 v22, 1.0, v22
	v_add_f32_e32 v23, 1.0, v23
	v_rcp_f32_e32 v22, v22
	v_rcp_f32_e32 v23, v23
	v_pk_mul_f32 v[20:21], v[24:25], v[20:21]
	v_add_u32_e32 v36, 0xa0, v146
	v_pk_mul_f32 v[18:19], v[18:19], v[20:21]
	v_pk_mul_f32 v[20:21], v[26:27], v[22:23]
	v_cvt_pk_bf16_f32 v18, v18, v19
	v_pk_mul_f32 v[20:21], v[32:33], v[20:21]
	v_pk_mul_f32 v[12:13], v[12:13], v[148:149] op_sel_hi:[1,0]
	v_cvt_pk_bf16_f32 v19, v20, v21
	v_mad_i64_i32 v[20:21], s[4:5], v36, s52, v[144:145]
	global_store_dwordx4 v[20:21], v[16:19], off
	v_pk_mul_f32 v[14:15], v[14:15], v[148:149] op_sel_hi:[1,0]
	v_pk_mul_f32 v[4:5], v[4:5], v[148:149] op_sel_hi:[1,0]
	v_pk_mul_f32 v[16:17], v[2:3], v[148:149] op_sel_hi:[1,0]
	v_mul_f32_e32 v2, 0xbfb8aa3b, v12
	v_exp_f32_e32 v18, v2
	v_mul_f32_e32 v2, 0xbfb8aa3b, v13
	v_exp_f32_e32 v19, v2
	v_pk_mul_f32 v[2:3], v[0:1], v[148:149] op_sel_hi:[1,0]
	v_add_f32_e32 v0, 1.0, v18
	v_mul_f32_e32 v18, 0xbfb8aa3b, v14
	v_add_f32_e32 v1, 1.0, v19
	v_mul_f32_e32 v19, 0xbfb8aa3b, v15
	v_exp_f32_e32 v18, v18
	v_exp_f32_e32 v19, v19
	v_rcp_f32_e32 v0, v0
	v_rcp_f32_e32 v1, v1
	v_add_f32_e32 v18, 1.0, v18
	v_add_f32_e32 v19, 1.0, v19
	v_rcp_f32_e32 v18, v18
	v_rcp_f32_e32 v19, v19
	v_pk_mul_f32 v[0:1], v[12:13], v[0:1]
	v_pk_mul_f32 v[8:9], v[8:9], v[148:149] op_sel_hi:[1,0]
	v_pk_mul_f32 v[0:1], v[4:5], v[0:1]
	v_pk_mul_f32 v[6:7], v[6:7], v[148:149] op_sel_hi:[1,0]
	v_cvt_pk_bf16_f32 v0, v0, v1
	v_pk_mul_f32 v[4:5], v[14:15], v[18:19]
	v_mul_f32_e32 v1, 0xbfb8aa3b, v8
	v_pk_mul_f32 v[4:5], v[6:7], v[4:5]
	v_exp_f32_e32 v6, v1
	v_mul_f32_e32 v1, 0xbfb8aa3b, v9
	v_exp_f32_e32 v7, v1
	v_pk_mul_f32 v[10:11], v[10:11], v[148:149] op_sel_hi:[1,0]
	v_cvt_pk_bf16_f32 v1, v4, v5
	v_add_f32_e32 v4, 1.0, v6
	v_add_f32_e32 v5, 1.0, v7
	v_mul_f32_e32 v6, 0xbfb8aa3b, v10
	v_mul_f32_e32 v7, 0xbfb8aa3b, v11
	v_exp_f32_e32 v6, v6
	v_exp_f32_e32 v7, v7
	v_rcp_f32_e32 v4, v4
	v_rcp_f32_e32 v5, v5
	v_add_f32_e32 v6, 1.0, v6
	v_add_f32_e32 v7, 1.0, v7
	v_rcp_f32_e32 v6, v6
	v_rcp_f32_e32 v7, v7
	v_pk_mul_f32 v[4:5], v[8:9], v[4:5]
	v_add_u32_e32 v20, 0xb0, v146
	v_pk_mul_f32 v[2:3], v[2:3], v[4:5]
	v_pk_mul_f32 v[4:5], v[10:11], v[6:7]
	v_cvt_pk_bf16_f32 v2, v2, v3
	v_pk_mul_f32 v[4:5], v[16:17], v[4:5]
	s_and_b64 vcc, exec, s[0:1]
	v_cvt_pk_bf16_f32 v3, v4, v5
	v_mad_i64_i32 v[4:5], s[4:5], v20, s52, v[144:145]
	s_mov_b32 s5, s24
	s_mov_b32 s4, s28
	s_mov_b64 s[10:11], s[38:39]
	s_mov_b64 s[8:9], s[36:37]
	global_store_dwordx4 v[4:5], v[0:3], off
	s_cbranch_vccz .LBB0_862
	s_waitcnt vmcnt(0)
	s_cmpk_gt_u32 s6, 0xff
	s_cbranch_scc1 .LBB0_869
	s_barrier

; #define PG8_STAGE(bufoff, gbase, voff) do { _Pragma("unroll") for (int _i = 0; _i < 2; ++_i) \
;         __builtin_amdgcn_global_load_lds((const unsigned*)((const char*)(gbase) + (voff)[_i]), (LAS unsigned*)(lds + (bufoff) + ldsw + _i * 8192), 16, 0, 0); } while (0)
; #define PG8_LDA(dst, b, h) do { _Pragma("unroll") for (int m = 0; m < 4; ++m) _Pragma("unroll") for (int k = 0; k < 2; ++k) dst[m][k] = *(const LAS bf16x8*)(lds + PG8_SA(b, h) + aoff + m * 2048 + k * 1024); } while (0)
; #define PG8_LDB(dst, b, h) do { _Pragma("unroll") for (int n = 0; n < 2; ++n) _Pragma("unroll") for (int k = 0; k < 2; ++k) dst[n][k] = *(const LAS bf16x8*)(lds + PG8_SB(b, h) + boff + n * 2048 + k * 1024); } while (0)
; #define PG8_WAIT_V(n) asm volatile("s_waitcnt vmcnt(" #n ")" ::: "memory")
; #define PG8_WAIT_L(n) asm volatile("s_waitcnt lgkmcnt(" #n ")" ::: "memory")
; #define PG8_BAR __builtin_amdgcn_s_barrier()
; #define PG8_SCHED __builtin_amdgcn_sched_barrier(0)
; #define PG8_BAR __builtin_amdgcn_s_barrier()
; template <class Epi>
; DI void gemm_phase(LAS unsigned char* lds, const Gemm g, const StaticOrder S, const Epi E) {
;     ...
;             PG8_LDB(B0, 0, 0); PG8_SCHED; PG8_LDA(At, 0, 0); PG8_STAGE(PG8_SA(1, 1), a1 + hstep, voffA);
;             PG8_WAIT_L(8); PG8_BAR; PG8_WAIT_L(0); PG8_MMA(0, 0, At, B0); PG8_BAR; PG8_SCHED;
;             PG8_LDB(B1, 0, 1); PG8_STAGE(PG8_SB(0, 0), b2, voffB);
;             PG8_BAR; PG8_WAIT_L(0); PG8_MMA(0, 1, At, B1); PG8_BAR;
;             PG8_LDA(At, 0, 1); PG8_STAGE(PG8_SA(0, 0), a2, voffA);
;             PG8_BAR; PG8_WAIT_L(0); PG8_MMA(1, 0, At, B0); PG8_BAR; PG8_SCHED;
;             PG8_STAGE(PG8_SB(0, 1), b2 + hstep, voffB);
;             PG8_WAIT_V(6); PG8_BAR; PG8_MMA(1, 1, At, B1); PG8_BAR;
;             PG8_LDB(B0, 1, 0); PG8_SCHED; PG8_LDA(At, 1, 0); PG8_STAGE(PG8_SA(0, 1), a2 + hstep, voffA);
;             PG8_WAIT_L(8); PG8_BAR; PG8_WAIT_L(0); PG8_MMA(0, 0, At, B0); PG8_BAR; PG8_SCHED;
;             PG8_LDB(B1, 1, 1); PG8_STAGE(PG8_SB(1, 0), b3, voffB);
;             PG8_BAR; PG8_WAIT_L(0); PG8_MMA(0, 1, At, B1); PG8_BAR;
;             PG8_LDA(At, 1, 1); PG8_STAGE(PG8_SA(1, 0), a3, voffA);
;             PG8_BAR; PG8_WAIT_L(0); PG8_MMA(1, 0, At, B0); PG8_BAR; PG8_SCHED;
;             PG8_STAGE(PG8_SB(1, 1), b3 + hstep, voffB);
;             PG8_WAIT_V(6); PG8_BAR; PG8_MMA(1, 1, At, B1); PG8_BAR;
.LBB0_941:
	ds_read_b128 v[144:147], v199
	ds_read_b128 v[148:151], v199 offset:1024
	ds_read_b128 v[152:155], v199 offset:2048
	ds_read_b128 v[156:159], v199 offset:3072
	s_add_u32 s22, s20, 0x100
	s_addc_u32 s23, s21, 0
	s_cmp_eq_u32 s58, 40
	s_cselect_b32 s27, s9, s23
	s_cselect_b32 s26, s8, s22
	s_cselect_b32 s25, s5, s53
	s_cselect_b32 s24, s4, s52
	v_lshl_add_u64 v[192:193], s[20:21], 0, v[136:137]
	s_add_i32 m0, s33, 0xc000
	ds_read_b128 v[160:163], v200
	ds_read_b128 v[168:171], v200 offset:2048
	ds_read_b128 v[176:179], v200 offset:4096
	ds_read_b128 v[184:187], v200 offset:6144
	global_load_lds_dwordx4 v[192:193], off
	v_lshl_add_u64 v[192:193], s[20:21], 0, v[138:139]
	s_add_i32 m0, s33, 0xe000
	s_nop 0
	global_load_lds_dwordx4 v[192:193], off
	s_waitcnt lgkmcnt(4)
	s_setprio 1
	s_barrier
	ds_read_b128 v[164:167], v200 offset:1024
	ds_read_b128 v[172:175], v200 offset:3072
	ds_read_b128 v[180:183], v200 offset:5120
	ds_read_b128 v[188:191], v200 offset:7168
	s_waitcnt lgkmcnt(4)
	v_mfma_f32_16x16x32_bf16 v[124:127], v[144:147], v[160:163], v[124:127]
	v_mfma_f32_16x16x32_bf16 v[120:123], v[152:155], v[160:163], v[120:123]
	v_mfma_f32_16x16x32_bf16 v[108:111], v[144:147], v[168:171], v[108:111]
	v_mfma_f32_16x16x32_bf16 v[104:107], v[152:155], v[168:171], v[104:107]
	v_mfma_f32_16x16x32_bf16 v[92:95], v[144:147], v[176:179], v[92:95]
	v_mfma_f32_16x16x32_bf16 v[88:91], v[152:155], v[176:179], v[88:91]
	v_mfma_f32_16x16x32_bf16 v[84:87], v[144:147], v[184:187], v[84:87]
	v_mfma_f32_16x16x32_bf16 v[76:79], v[152:155], v[184:187], v[76:79]
	s_waitcnt lgkmcnt(3)
	v_mfma_f32_16x16x32_bf16 v[124:127], v[148:151], v[164:167], v[124:127]
	v_mfma_f32_16x16x32_bf16 v[120:123], v[156:159], v[164:167], v[120:123]
	s_waitcnt lgkmcnt(2)
	v_mfma_f32_16x16x32_bf16 v[108:111], v[148:151], v[172:175], v[108:111]
	v_mfma_f32_16x16x32_bf16 v[104:107], v[156:159], v[172:175], v[104:107]
	s_waitcnt lgkmcnt(1)
	v_mfma_f32_16x16x32_bf16 v[92:95], v[148:151], v[180:183], v[92:95]
	v_mfma_f32_16x16x32_bf16 v[88:91], v[156:159], v[180:183], v[88:91]
	s_waitcnt lgkmcnt(0)
	s_setprio 2
	s_barrier
	v_mfma_f32_16x16x32_bf16 v[84:87], v[148:151], v[188:191], v[84:87]
	v_mfma_f32_16x16x32_bf16 v[76:79], v[156:159], v[188:191], v[76:79]
	s_setprio 0
	s_add_i32 s20, s42, s29
	v_lshl_add_u64 v[214:215], s[24:25], 0, v[130:131]
	s_mov_b32 m0, s20
	ds_read_b128 v[192:195], v201
	ds_read_b128 v[202:205], v201 offset:1024
	ds_read_b128 v[206:209], v201 offset:2048
	ds_read_b128 v[210:213], v201 offset:3072
	global_load_lds_dwordx4 v[214:215], off
	v_lshl_add_u64 v[216:217], s[24:25], 0, v[134:135]
	s_add_i32 m0, s20, 0x2000
	s_nop 0
	global_load_lds_dwordx4 v[216:217], off
	s_setprio 1
	s_barrier
	s_waitcnt lgkmcnt(0)
	v_mfma_f32_16x16x32_bf16 v[116:119], v[192:195], v[160:163], v[116:119]
	v_mfma_f32_16x16x32_bf16 v[112:115], v[206:209], v[160:163], v[112:115]
	v_mfma_f32_16x16x32_bf16 v[100:103], v[192:195], v[168:171], v[100:103]
	v_mfma_f32_16x16x32_bf16 v[96:99], v[206:209], v[168:171], v[96:99]
	v_mfma_f32_16x16x32_bf16 v[80:83], v[192:195], v[176:179], v[80:83]
	v_mfma_f32_16x16x32_bf16 v[72:75], v[206:209], v[176:179], v[72:75]
	v_mfma_f32_16x16x32_bf16 v[68:71], v[192:195], v[184:187], v[68:71]
	v_mfma_f32_16x16x32_bf16 v[64:67], v[206:209], v[184:187], v[64:67]
	v_mfma_f32_16x16x32_bf16 v[116:119], v[202:205], v[164:167], v[116:119]
	v_mfma_f32_16x16x32_bf16 v[112:115], v[210:213], v[164:167], v[112:115]
	v_mfma_f32_16x16x32_bf16 v[100:103], v[202:205], v[172:175], v[100:103]
	v_mfma_f32_16x16x32_bf16 v[96:99], v[210:213], v[172:175], v[96:99]
	v_mfma_f32_16x16x32_bf16 v[80:83], v[202:205], v[180:183], v[80:83]
	v_mfma_f32_16x16x32_bf16 v[72:75], v[210:213], v[180:183], v[72:75]
	s_setprio 2
	s_barrier
	v_mfma_f32_16x16x32_bf16 v[68:71], v[202:205], v[188:191], v[68:71]
	v_mfma_f32_16x16x32_bf16 v[64:67], v[210:213], v[188:191], v[64:67]
	s_setprio 0
	s_mov_b32 m0, s33
	v_lshl_add_u64 v[218:219], s[26:27], 0, v[128:129]
	ds_read_b128 v[160:163], v200 offset:16384
	ds_read_b128 v[168:171], v200 offset:18432
	ds_read_b128 v[176:179], v200 offset:20480
	ds_read_b128 v[184:187], v200 offset:22528
	global_load_lds_dwordx4 v[218:219], off
	v_lshl_add_u64 v[220:221], s[26:27], 0, v[132:133]
	s_mov_b32 m0, s34
	s_nop 0
	global_load_lds_dwordx4 v[220:221], off
	s_setprio 1
	s_barrier
	ds_read_b128 v[164:167], v200 offset:17408
	ds_read_b128 v[172:175], v200 offset:19456
	ds_read_b128 v[180:183], v200 offset:21504
	ds_read_b128 v[188:191], v200 offset:23552
	s_waitcnt lgkmcnt(4)
	v_mfma_f32_16x16x32_bf16 v[60:63], v[144:147], v[160:163], v[60:63]
	v_mfma_f32_16x16x32_bf16 v[56:59], v[152:155], v[160:163], v[56:59]
	v_mfma_f32_16x16x32_bf16 v[48:51], v[144:147], v[168:171], v[48:51]
	v_mfma_f32_16x16x32_bf16 v[40:43], v[152:155], v[168:171], v[40:43]
	v_mfma_f32_16x16x32_bf16 v[32:35], v[144:147], v[176:179], v[32:35]
	v_mfma_f32_16x16x32_bf16 v[24:27], v[152:155], v[176:179], v[24:27]
	v_mfma_f32_16x16x32_bf16 v[16:19], v[144:147], v[184:187], v[16:19]
	v_mfma_f32_16x16x32_bf16 v[8:11], v[152:155], v[184:187], v[8:11]
	s_waitcnt lgkmcnt(3)
	v_mfma_f32_16x16x32_bf16 v[60:63], v[148:151], v[164:167], v[60:63]
	v_mfma_f32_16x16x32_bf16 v[56:59], v[156:159], v[164:167], v[56:59]
	s_waitcnt lgkmcnt(2)
	v_mfma_f32_16x16x32_bf16 v[48:51], v[148:151], v[172:175], v[48:51]
	v_mfma_f32_16x16x32_bf16 v[40:43], v[156:159], v[172:175], v[40:43]
	s_waitcnt lgkmcnt(1)
	v_mfma_f32_16x16x32_bf16 v[32:35], v[148:151], v[180:183], v[32:35]
	v_mfma_f32_16x16x32_bf16 v[24:27], v[156:159], v[180:183], v[24:27]
	s_waitcnt lgkmcnt(0)
	s_setprio 2
	s_barrier
; #define PG8_STAGE(bufoff, gbase, voff) do { _Pragma("unroll") for (int _i = 0; _i < 2; ++_i) \
;         __builtin_amdgcn_global_load_lds((const unsigned*)((const char*)(gbase) + (voff)[_i]), (LAS unsigned*)(lds + (bufoff) + ldsw + _i * 8192), 16, 0, 0); } while (0)
; #define PG8_LDA(dst, b, h) do { _Pragma("unroll") for (int m = 0; m < 4; ++m) _Pragma("unroll") for (int k = 0; k < 2; ++k) dst[m][k] = *(const LAS bf16x8*)(lds + PG8_SA(b, h) + aoff + m * 2048 + k * 1024); } while (0)
; #define PG8_LDB(dst, b, h) do { _Pragma("unroll") for (int n = 0; n < 2; ++n) _Pragma("unroll") for (int k = 0; k < 2; ++k) dst[n][k] = *(const LAS bf16x8*)(lds + PG8_SB(b, h) + boff + n * 2048 + k * 1024); } while (0)
; #define PG8_WAIT_V(n) asm volatile("s_waitcnt vmcnt(" #n ")" ::: "memory")
; #define PG8_WAIT_L(n) asm volatile("s_waitcnt lgkmcnt(" #n ")" ::: "memory")
; #define PG8_BAR __builtin_amdgcn_s_barrier()
; #define PG8_SCHED __builtin_amdgcn_sched_barrier(0)
; #define PG8_BAR __builtin_amdgcn_s_barrier()
; template <class Epi>
; DI void gemm_phase(LAS unsigned char* lds, const Gemm g, const StaticOrder S, const Epi E) {
;     ...
;             PG8_LDB(B0, 0, 0); PG8_SCHED; PG8_LDA(At, 0, 0); PG8_STAGE(PG8_SA(1, 1), a1 + hstep, voffA);
;             PG8_WAIT_L(8); PG8_BAR; PG8_WAIT_L(0); PG8_MMA(0, 0, At, B0); PG8_BAR; PG8_SCHED;
;             PG8_LDB(B1, 0, 1); PG8_STAGE(PG8_SB(0, 0), b2, voffB);
;             PG8_BAR; PG8_WAIT_L(0); PG8_MMA(0, 1, At, B1); PG8_BAR;
;             PG8_LDA(At, 0, 1); PG8_STAGE(PG8_SA(0, 0), a2, voffA);
;             PG8_BAR; PG8_WAIT_L(0); PG8_MMA(1, 0, At, B0); PG8_BAR; PG8_SCHED;
;             PG8_STAGE(PG8_SB(0, 1), b2 + hstep, voffB);
;             PG8_WAIT_V(6); PG8_BAR; PG8_MMA(1, 1, At, B1); PG8_BAR;
;             PG8_LDB(B0, 1, 0); PG8_SCHED; PG8_LDA(At, 1, 0); PG8_STAGE(PG8_SA(0, 1), a2 + hstep, voffA);
;             PG8_WAIT_L(8); PG8_BAR; PG8_WAIT_L(0); PG8_MMA(0, 0, At, B0); PG8_BAR; PG8_SCHED;
;             PG8_LDB(B1, 1, 1); PG8_STAGE(PG8_SB(1, 0), b3, voffB);
;             PG8_BAR; PG8_WAIT_L(0); PG8_MMA(0, 1, At, B1); PG8_BAR;
;             PG8_LDA(At, 1, 1); PG8_STAGE(PG8_SA(1, 0), a3, voffA);
;             PG8_BAR; PG8_WAIT_L(0); PG8_MMA(1, 0, At, B0); PG8_BAR; PG8_SCHED;
;             PG8_STAGE(PG8_SB(1, 1), b3 + hstep, voffB);
;             PG8_WAIT_V(6); PG8_BAR; PG8_MMA(1, 1, At, B1); PG8_BAR;
	v_mfma_f32_16x16x32_bf16 v[16:19], v[148:151], v[188:191], v[16:19]
	v_mfma_f32_16x16x32_bf16 v[8:11], v[156:159], v[188:191], v[8:11]
	s_setprio 0
	s_add_u32 s20, s24, 0xb0000
	s_addc_u32 s21, s25, 0
	s_add_i32 s59, s43, s29
	v_lshl_add_u64 v[144:145], s[20:21], 0, v[130:131]
	s_mov_b32 m0, s59
	s_nop 0
	global_load_lds_dwordx4 v[144:145], off
	v_lshl_add_u64 v[144:145], s[20:21], 0, v[134:135]
	s_add_i32 m0, s59, 0x2000
	s_nop 0
	global_load_lds_dwordx4 v[144:145], off
	s_waitcnt vmcnt(6)
	s_setprio 1
	s_barrier
	v_mfma_f32_16x16x32_bf16 v[52:55], v[192:195], v[160:163], v[52:55]
	v_mfma_f32_16x16x32_bf16 v[44:47], v[206:209], v[160:163], v[44:47]
	v_mfma_f32_16x16x32_bf16 v[36:39], v[192:195], v[168:171], v[36:39]
	v_mfma_f32_16x16x32_bf16 v[28:31], v[206:209], v[168:171], v[28:31]
	v_mfma_f32_16x16x32_bf16 v[20:23], v[192:195], v[176:179], v[20:23]
	v_mfma_f32_16x16x32_bf16 v[12:15], v[206:209], v[176:179], v[12:15]
	v_mfma_f32_16x16x32_bf16 v[4:7], v[192:195], v[184:187], v[4:7]
	v_mfma_f32_16x16x32_bf16 v[0:3], v[206:209], v[184:187], v[0:3]
	v_mfma_f32_16x16x32_bf16 v[52:55], v[202:205], v[164:167], v[52:55]
	v_mfma_f32_16x16x32_bf16 v[44:47], v[210:213], v[164:167], v[44:47]
	v_mfma_f32_16x16x32_bf16 v[36:39], v[202:205], v[172:175], v[36:39]
	v_mfma_f32_16x16x32_bf16 v[28:31], v[210:213], v[172:175], v[28:31]
	v_mfma_f32_16x16x32_bf16 v[20:23], v[202:205], v[180:183], v[20:23]
	v_mfma_f32_16x16x32_bf16 v[12:15], v[210:213], v[180:183], v[12:15]
	s_setprio 2
	s_barrier
	v_mfma_f32_16x16x32_bf16 v[4:7], v[202:205], v[188:191], v[4:7]
	v_mfma_f32_16x16x32_bf16 v[0:3], v[210:213], v[188:191], v[0:3]
	s_setprio 0
	s_add_i32 s59, 0, 0x18000
	v_add_u32_e32 v156, s59, v197
	ds_read_b128 v[144:147], v156
	ds_read_b128 v[148:151], v156 offset:1024
	ds_read_b128 v[152:155], v156 offset:2048
	ds_read_b128 v[156:159], v156 offset:3072
	s_add_u32 s20, s26, 0xb0000
	s_addc_u32 s21, s27, 0
	s_mov_b32 m0, s35
	v_lshl_add_u64 v[192:193], s[20:21], 0, v[128:129]
	ds_read_b128 v[160:163], v200 offset:32768
	ds_read_b128 v[168:171], v200 offset:34816
	ds_read_b128 v[176:179], v200 offset:36864
	ds_read_b128 v[184:187], v200 offset:38912
	global_load_lds_dwordx4 v[192:193], off
	v_lshl_add_u64 v[192:193], s[20:21], 0, v[132:133]
	s_mov_b32 m0, s36
	s_nop 0
	global_load_lds_dwordx4 v[192:193], off
	s_waitcnt lgkmcnt(4)
	s_setprio 1
	s_barrier
	ds_read_b128 v[164:167], v200 offset:33792
	ds_read_b128 v[172:175], v200 offset:35840
	ds_read_b128 v[180:183], v200 offset:37888
	ds_read_b128 v[188:191], v200 offset:39936
	s_waitcnt lgkmcnt(4)
	v_mfma_f32_16x16x32_bf16 v[124:127], v[144:147], v[160:163], v[124:127]
	v_mfma_f32_16x16x32_bf16 v[120:123], v[152:155], v[160:163], v[120:123]
	v_mfma_f32_16x16x32_bf16 v[108:111], v[144:147], v[168:171], v[108:111]
	v_mfma_f32_16x16x32_bf16 v[104:107], v[152:155], v[168:171], v[104:107]
	v_mfma_f32_16x16x32_bf16 v[92:95], v[144:147], v[176:179], v[92:95]
	v_mfma_f32_16x16x32_bf16 v[88:91], v[152:155], v[176:179], v[88:91]
	v_mfma_f32_16x16x32_bf16 v[84:87], v[144:147], v[184:187], v[84:87]
	v_mfma_f32_16x16x32_bf16 v[76:79], v[152:155], v[184:187], v[76:79]
	s_waitcnt lgkmcnt(3)
	v_mfma_f32_16x16x32_bf16 v[124:127], v[148:151], v[164:167], v[124:127]
	v_mfma_f32_16x16x32_bf16 v[120:123], v[156:159], v[164:167], v[120:123]
	s_waitcnt lgkmcnt(2)
	v_mfma_f32_16x16x32_bf16 v[108:111], v[148:151], v[172:175], v[108:111]
	v_mfma_f32_16x16x32_bf16 v[104:107], v[156:159], v[172:175], v[104:107]
	s_waitcnt lgkmcnt(1)
	v_mfma_f32_16x16x32_bf16 v[92:95], v[148:151], v[180:183], v[92:95]
	v_mfma_f32_16x16x32_bf16 v[88:91], v[156:159], v[180:183], v[88:91]
	s_waitcnt lgkmcnt(0)
	s_setprio 2
	s_barrier
	v_mfma_f32_16x16x32_bf16 v[84:87], v[148:151], v[188:191], v[84:87]
	v_mfma_f32_16x16x32_bf16 v[76:79], v[156:159], v[188:191], v[76:79]
	s_setprio 0
	s_add_i32 s26, 0, 0x1c000
	s_add_i32 s20, s59, s29
	v_add_u32_e32 v210, s26, v197
	v_lshl_add_u64 v[214:215], v[214:215], 0, s[10:11]
	s_mov_b32 m0, s20
	ds_read_b128 v[192:195], v210
	ds_read_b128 v[202:205], v210 offset:1024
	ds_read_b128 v[206:209], v210 offset:2048
	ds_read_b128 v[210:213], v210 offset:3072
	global_load_lds_dwordx4 v[214:215], off
	v_lshl_add_u64 v[214:215], v[216:217], 0, s[10:11]
	s_add_i32 m0, s20, 0x2000
	s_nop 0
	global_load_lds_dwordx4 v[214:215], off
	s_setprio 1
	s_barrier
	s_waitcnt lgkmcnt(0)
	v_mfma_f32_16x16x32_bf16 v[116:119], v[192:195], v[160:163], v[116:119]
	v_mfma_f32_16x16x32_bf16 v[112:115], v[206:209], v[160:163], v[112:115]
	v_mfma_f32_16x16x32_bf16 v[100:103], v[192:195], v[168:171], v[100:103]
	v_mfma_f32_16x16x32_bf16 v[96:99], v[206:209], v[168:171], v[96:99]
	v_mfma_f32_16x16x32_bf16 v[80:83], v[192:195], v[176:179], v[80:83]
	v_mfma_f32_16x16x32_bf16 v[72:75], v[206:209], v[176:179], v[72:75]
	v_mfma_f32_16x16x32_bf16 v[68:71], v[192:195], v[184:187], v[68:71]
	v_mfma_f32_16x16x32_bf16 v[64:67], v[206:209], v[184:187], v[64:67]
	v_mfma_f32_16x16x32_bf16 v[116:119], v[202:205], v[164:167], v[116:119]
	v_mfma_f32_16x16x32_bf16 v[112:115], v[210:213], v[164:167], v[112:115]
	v_mfma_f32_16x16x32_bf16 v[100:103], v[202:205], v[172:175], v[100:103]
	v_mfma_f32_16x16x32_bf16 v[96:99], v[210:213], v[172:175], v[96:99]
	v_mfma_f32_16x16x32_bf16 v[80:83], v[202:205], v[180:183], v[80:83]
	v_mfma_f32_16x16x32_bf16 v[72:75], v[210:213], v[180:183], v[72:75]
	s_setprio 2
	s_barrier
; DI f32x4 bf_lo4(u32x4 w) { f32x4 r; r[0] = bf_lo(w.x); r[1] = bf_hi(w.x); r[2] = bf_lo(w.y); r[3] = bf_hi(w.y); return r; }
; DI f32x4 bf_hi4(u32x4 w) { f32x4 r; r[0] = bf_lo(w.z); r[1] = bf_hi(w.z); r[2] = bf_lo(w.w); r[3] = bf_hi(w.w); return r; }
; #define PG8_WAIT_V(n) asm volatile("s_waitcnt vmcnt(" #n ")" ::: "memory")
; template <class Epi>
; DI void gemm_phase(LAS unsigned char* lds, const Gemm g, const StaticOrder S, const Epi E) {
;     ...
;             PG8_LDB(B0, 0, 0); PG8_SCHED; PG8_LDA(At, 0, 0); PG8_STAGE(PG8_SA(1, 1), a1 + hstep, voffA);
;             PG8_WAIT_L(8); PG8_BAR; PG8_WAIT_L(0); PG8_MMA(0, 0, At, B0); PG8_BAR; PG8_SCHED;
;             PG8_LDB(B1, 0, 1); PG8_STAGE(PG8_SB(0, 0), b2, voffB);
;             PG8_BAR; PG8_WAIT_L(0); PG8_MMA(0, 1, At, B1); PG8_BAR;
;             PG8_LDA(At, 0, 1); PG8_STAGE(PG8_SA(0, 0), a2, voffA);
;             PG8_BAR; PG8_WAIT_L(0); PG8_MMA(1, 0, At, B0); PG8_BAR; PG8_SCHED;
;             PG8_STAGE(PG8_SB(0, 1), b2 + hstep, voffB);
;             PG8_WAIT_V(6); PG8_BAR; PG8_MMA(1, 1, At, B1); PG8_BAR;
;             PG8_LDB(B0, 1, 0); PG8_SCHED; PG8_LDA(At, 1, 0); PG8_STAGE(PG8_SA(0, 1), a2 + hstep, voffA);
;             PG8_WAIT_L(8); PG8_BAR; PG8_WAIT_L(0); PG8_MMA(0, 0, At, B0); PG8_BAR; PG8_SCHED;
;             PG8_LDB(B1, 1, 1); PG8_STAGE(PG8_SB(1, 0), b3, voffB);
;             PG8_BAR; PG8_WAIT_L(0); PG8_MMA(0, 1, At, B1); PG8_BAR;
;             PG8_LDA(At, 1, 1); PG8_STAGE(PG8_SA(1, 0), a3, voffA);
;             PG8_BAR; PG8_WAIT_L(0); PG8_MMA(1, 0, At, B0); PG8_BAR; PG8_SCHED;
;             PG8_STAGE(PG8_SB(1, 1), b3 + hstep, voffB);
;             PG8_WAIT_V(6); PG8_BAR; PG8_MMA(1, 1, At, B1); PG8_BAR;
;     DI void operator()(AccRef acc, const Unit& u, int wr, int wc, int fr, int fq) const {
;     ...
; #pragma unroll
;         for (int ai = 0; ai < 2; ++ai) {
;             f32x4 bv[4][2][2];
; #pragma unroll
;             for (int m = 0; m < 4; ++m)
; #pragma unroll
;                 for (int bj = 0; bj < 2; ++bj) {
;                     const size_t o = (size_t)(row0 + ai * 128 + m * 16) * DM + col0 + bj * 128;
;                     if (BASEF32) { bv[m][bj][0] = *(const f32x4*)(basef + o); bv[m][bj][1] = *(const f32x4*)(basef + o + 4); }
;                     else { const u32x4 h = *(const u32x4*)(xnb + o); bv[m][bj][0] = bf_lo4(h); bv[m][bj][1] = bf_hi4(h); }
;                 }
	v_mfma_f32_16x16x32_bf16 v[68:71], v[202:205], v[188:191], v[68:71]
	v_mfma_f32_16x16x32_bf16 v[64:67], v[210:213], v[188:191], v[64:67]
	s_setprio 0
	s_mov_b32 m0, s38
	v_lshl_add_u64 v[214:215], v[218:219], 0, s[10:11]
	ds_read_b128 v[160:163], v200 offset:49152
	ds_read_b128 v[168:171], v200 offset:51200
	ds_read_b128 v[176:179], v200 offset:53248
	ds_read_b128 v[184:187], v200 offset:55296
	global_load_lds_dwordx4 v[214:215], off
	v_lshl_add_u64 v[214:215], v[220:221], 0, s[10:11]
	s_mov_b32 m0, s39
	s_nop 0
	global_load_lds_dwordx4 v[214:215], off
	s_setprio 1
	s_barrier
	ds_read_b128 v[164:167], v200 offset:50176
	ds_read_b128 v[172:175], v200 offset:52224
	ds_read_b128 v[180:183], v200 offset:54272
	ds_read_b128 v[188:191], v200 offset:56320
	s_waitcnt lgkmcnt(4)
	v_mfma_f32_16x16x32_bf16 v[60:63], v[144:147], v[160:163], v[60:63]
	v_mfma_f32_16x16x32_bf16 v[56:59], v[152:155], v[160:163], v[56:59]
	v_mfma_f32_16x16x32_bf16 v[48:51], v[144:147], v[168:171], v[48:51]
	v_mfma_f32_16x16x32_bf16 v[40:43], v[152:155], v[168:171], v[40:43]
	v_mfma_f32_16x16x32_bf16 v[32:35], v[144:147], v[176:179], v[32:35]
	v_mfma_f32_16x16x32_bf16 v[24:27], v[152:155], v[176:179], v[24:27]
	v_mfma_f32_16x16x32_bf16 v[16:19], v[144:147], v[184:187], v[16:19]
	v_mfma_f32_16x16x32_bf16 v[8:11], v[152:155], v[184:187], v[8:11]
	s_waitcnt lgkmcnt(3)
	v_mfma_f32_16x16x32_bf16 v[60:63], v[148:151], v[164:167], v[60:63]
	v_mfma_f32_16x16x32_bf16 v[56:59], v[156:159], v[164:167], v[56:59]
	s_waitcnt lgkmcnt(2)
	v_mfma_f32_16x16x32_bf16 v[48:51], v[148:151], v[172:175], v[48:51]
	v_mfma_f32_16x16x32_bf16 v[40:43], v[156:159], v[172:175], v[40:43]
	s_waitcnt lgkmcnt(1)
	v_mfma_f32_16x16x32_bf16 v[32:35], v[148:151], v[180:183], v[32:35]
	v_mfma_f32_16x16x32_bf16 v[24:27], v[156:159], v[180:183], v[24:27]
	s_waitcnt lgkmcnt(0)
	s_setprio 2
	s_barrier
	v_mfma_f32_16x16x32_bf16 v[16:19], v[148:151], v[188:191], v[16:19]
	v_mfma_f32_16x16x32_bf16 v[8:11], v[156:159], v[188:191], v[8:11]
	s_setprio 0
	s_add_u32 s20, s24, 0xb0080
	s_addc_u32 s21, s25, 0
	s_add_i32 s24, s26, s29
	v_lshl_add_u64 v[144:145], s[20:21], 0, v[130:131]
	s_mov_b32 m0, s24
	s_nop 0
	global_load_lds_dwordx4 v[144:145], off
	v_lshl_add_u64 v[144:145], s[20:21], 0, v[134:135]
	s_add_i32 m0, s24, 0x2000
	s_nop 0
	global_load_lds_dwordx4 v[144:145], off
	s_waitcnt vmcnt(6)
	s_setprio 1
	s_barrier
	v_mfma_f32_16x16x32_bf16 v[52:55], v[192:195], v[160:163], v[52:55]
	v_mfma_f32_16x16x32_bf16 v[44:47], v[206:209], v[160:163], v[44:47]
	v_mfma_f32_16x16x32_bf16 v[36:39], v[192:195], v[168:171], v[36:39]
	v_mfma_f32_16x16x32_bf16 v[28:31], v[206:209], v[168:171], v[28:31]
	v_mfma_f32_16x16x32_bf16 v[20:23], v[192:195], v[176:179], v[20:23]
	v_mfma_f32_16x16x32_bf16 v[12:15], v[206:209], v[176:179], v[12:15]
	v_mfma_f32_16x16x32_bf16 v[4:7], v[192:195], v[184:187], v[4:7]
	v_mfma_f32_16x16x32_bf16 v[0:3], v[206:209], v[184:187], v[0:3]
	v_mfma_f32_16x16x32_bf16 v[52:55], v[202:205], v[164:167], v[52:55]
	v_mfma_f32_16x16x32_bf16 v[44:47], v[210:213], v[164:167], v[44:47]
	v_mfma_f32_16x16x32_bf16 v[36:39], v[202:205], v[172:175], v[36:39]
	v_mfma_f32_16x16x32_bf16 v[28:31], v[210:213], v[172:175], v[28:31]
	v_mfma_f32_16x16x32_bf16 v[20:23], v[202:205], v[180:183], v[20:23]
	v_mfma_f32_16x16x32_bf16 v[12:15], v[210:213], v[180:183], v[12:15]
	s_setprio 2
	s_barrier
	v_mfma_f32_16x16x32_bf16 v[4:7], v[202:205], v[188:191], v[4:7]
	v_mfma_f32_16x16x32_bf16 v[0:3], v[210:213], v[188:191], v[0:3]
	s_setprio 0
	s_add_i32 s58, s58, 2
	s_add_u32 s52, s52, 0x100
	s_addc_u32 s53, s53, 0
	s_cmp_gt_u32 s58, 41
	s_mov_b64 s[20:21], s[22:23]
	s_cbranch_scc0 .LBB0_941
	v_lshl_add_u32 v148, s50, 8, v196
	v_lshl_or_b32 v144, s51, 8, v198
	v_or_b32_e32 v146, 16, v148
	v_ashrrev_i32_e32 v145, 31, v144
	v_ashrrev_i32_e32 v147, 31, v146
	v_lshl_add_u64 v[176:177], v[144:145], 1, s[56:57]
	v_ashrrev_i32_e32 v149, 31, v148
	v_lshlrev_b64 v[146:147], 11, v[146:147]
	v_lshlrev_b64 v[144:145], 11, v[148:149]
	v_lshl_add_u64 v[150:151], v[176:177], 0, v[146:147]
	v_or_b32_e32 v146, 32, v148
	v_or_b32_e32 v148, 48, v148
	v_ashrrev_i32_e32 v147, 31, v146
	v_ashrrev_i32_e32 v149, 31, v148
	v_lshl_add_u64 v[144:145], v[176:177], 0, v[144:145]
	v_lshlrev_b64 v[146:147], 11, v[146:147]
	v_lshlrev_b64 v[148:149], 11, v[148:149]
	global_load_dwordx4 v[152:155], v[144:145], off
	global_load_dwordx4 v[156:159], v[144:145], off offset:256
	v_lshl_add_u64 v[146:147], v[176:177], 0, v[146:147]
	v_lshl_add_u64 v[148:149], v[176:177], 0, v[148:149]
	global_load_dwordx4 v[160:163], v[150:151], off
	global_load_dwordx4 v[164:167], v[150:151], off offset:256
	global_load_dwordx4 v[168:171], v[146:147], off
	global_load_dwordx4 v[172:175], v[146:147], off offset:256
	global_load_dwordx4 v[202:205], v[148:149], off
	global_load_dwordx4 v[206:209], v[148:149], off offset:256
	s_mov_b32 s51, s48
	s_mov_b32 s50, s49
	s_mov_b64 s[22:23], s[4:5]
	s_mov_b64 s[20:21], s[8:9]
	s_waitcnt vmcnt(0)
; DI unsigned pk_bf16(float lo, float hi) { f32x2 v = {lo, hi}; return __builtin_bit_cast(unsigned, __builtin_convertvector(v, bf16v2)); }
;     DI void operator()(AccRef acc, const Unit& u, int wr, int wc, int fr, int fq) const {
;     ...
;             for (int m = 0; m < 4; ++m) {
;                 const int row = row0 + ai * 128 + m * 16;
;                 float q = 0.f;
; #pragma unroll
;                 for (int bj = 0; bj < 2; ++bj) {
;                     const size_t o = (size_t)row * DM + col0 + bj * 128;
;                     const f32x4 r0 = bv[m][bj][0] + scale * acc[ai][bj][m][0], r1 = bv[m][bj][1] + scale * acc[ai][bj][m][1];
;                     u32x4 w; w.x = pk_bf16(r0[0], r0[1]); w.y = pk_bf16(r0[2], r0[3]); w.z = pk_bf16(r1[0], r1[1]); w.w = pk_bf16(r1[2], r1[3]);
;                     *(u32x4*)(xnb + o) = w;
;                     if (STATS) q += r0[0] * r0[0] + r0[1] * r0[1] + r0[2] * r0[2] + r0[3] * r0[3] + r1[0] * r1[0] + r1[1] * r1[1] + r1[2] * r1[2] + r1[3] * r1[3];
;                 }
;                 if (STATS) { q += __shfl_xor(q, 16); q += __shfl_xor(q, 32); if (fq == 0) atomicAdd(ss + row, q); }
;             }
	v_lshlrev_b32_e32 v214, 16, v154
	v_and_b32_e32 v215, 0xffff0000, v154
	v_lshlrev_b32_e32 v216, 16, v155
	v_and_b32_e32 v217, 0xffff0000, v155
	v_lshlrev_b32_e32 v210, 16, v152
	v_and_b32_e32 v211, 0xffff0000, v152
	v_lshlrev_b32_e32 v212, 16, v153
	v_and_b32_e32 v213, 0xffff0000, v153
	v_lshlrev_b32_e32 v194, 16, v162
	v_and_b32_e32 v195, 0xffff0000, v162
	v_lshlrev_b32_e32 v230, 16, v163
	v_and_b32_e32 v231, 0xffff0000, v163
	v_lshlrev_b32_e32 v154, 16, v202
	v_and_b32_e32 v155, 0xffff0000, v202
	v_lshlrev_b32_e32 v162, 16, v203
	v_and_b32_e32 v163, 0xffff0000, v203
	v_pk_fma_f32 v[202:203], v[122:123], 0.5, v[216:217] op_sel_hi:[1,0,1]
	v_pk_fma_f32 v[122:123], v[120:121], 0.5, v[214:215] op_sel_hi:[1,0,1]
	v_lshlrev_b32_e32 v218, 16, v156
	v_and_b32_e32 v219, 0xffff0000, v156
	v_lshlrev_b32_e32 v220, 16, v157
	v_and_b32_e32 v221, 0xffff0000, v157
	v_pk_fma_f32 v[126:127], v[126:127], 0.5, v[212:213] op_sel_hi:[1,0,1]
	v_pk_fma_f32 v[124:125], v[124:125], 0.5, v[210:211] op_sel_hi:[1,0,1]
	v_cvt_pk_bf16_f32 v122, v122, v123
	v_cvt_pk_bf16_f32 v123, v202, v203
	v_add_co_u32_e32 v202, vcc, s44, v144
	v_lshlrev_b32_e32 v224, 16, v158
	v_and_b32_e32 v225, 0xffff0000, v158
	v_lshlrev_b32_e32 v226, 16, v159
	v_and_b32_e32 v227, 0xffff0000, v159
	v_cvt_pk_bf16_f32 v120, v124, v125
	v_cvt_pk_bf16_f32 v121, v126, v127
	v_pk_fma_f32 v[118:119], v[118:119], 0.5, v[220:221] op_sel_hi:[1,0,1]
	v_pk_fma_f32 v[116:117], v[116:117], 0.5, v[218:219] op_sel_hi:[1,0,1]
	v_addc_co_u32_e32 v203, vcc, 0, v145, vcc
	v_lshlrev_b32_e32 v192, 16, v160
	v_and_b32_e32 v193, 0xffff0000, v160
	global_store_dwordx4 v[144:145], v[120:123], off
	v_pk_fma_f32 v[108:109], v[108:109], 0.5, v[192:193] op_sel_hi:[1,0,1]
	v_lshl_add_u64 v[192:193], v[144:145], 0, s[12:13]
	v_pk_fma_f32 v[120:121], v[114:115], 0.5, v[226:227] op_sel_hi:[1,0,1]
	v_pk_fma_f32 v[114:115], v[112:113], 0.5, v[224:225] op_sel_hi:[1,0,1]
	v_cvt_pk_bf16_f32 v112, v116, v117
	v_cvt_pk_bf16_f32 v113, v118, v119
	global_load_dwordx4 v[116:119], v[202:203], off
	v_cvt_pk_bf16_f32 v114, v114, v115
	v_cvt_pk_bf16_f32 v115, v120, v121
	v_lshlrev_b32_e32 v228, 16, v161
	v_and_b32_e32 v229, 0xffff0000, v161
	global_store_dwordx4 v[144:145], v[112:115], off offset:256
	v_pk_fma_f32 v[120:121], v[106:107], 0.5, v[230:231] op_sel_hi:[1,0,1]
	v_pk_fma_f32 v[110:111], v[110:111], 0.5, v[228:229] op_sel_hi:[1,0,1]
	v_pk_fma_f32 v[112:113], v[104:105], 0.5, v[194:195] op_sel_hi:[1,0,1]
	global_load_dwordx4 v[104:107], v[192:193], off offset:256
	v_add_co_u32_e32 v194, vcc, s45, v144
	v_lshlrev_b32_e32 v184, 16, v164
	s_nop 0
	v_addc_co_u32_e32 v195, vcc, 0, v145, vcc
	v_and_b32_e32 v185, 0xffff0000, v164
	v_lshlrev_b32_e32 v188, 16, v165
	v_and_b32_e32 v189, 0xffff0000, v165
	v_lshlrev_b32_e32 v186, 16, v166
	v_and_b32_e32 v187, 0xffff0000, v166
	v_lshlrev_b32_e32 v190, 16, v167
	v_and_b32_e32 v191, 0xffff0000, v167
	v_cvt_pk_bf16_f32 v108, v108, v109
	v_cvt_pk_bf16_f32 v109, v110, v111
	v_cvt_pk_bf16_f32 v110, v112, v113
	global_load_dwordx4 v[112:115], v[194:195], off
	v_cvt_pk_bf16_f32 v111, v120, v121
	global_store_dwordx4 v[150:151], v[108:111], off
	v_pk_fma_f32 v[124:125], v[98:99], 0.5, v[190:191] op_sel_hi:[1,0,1]
	v_pk_fma_f32 v[96:97], v[96:97], 0.5, v[186:187] op_sel_hi:[1,0,1]
	v_pk_fma_f32 v[110:111], v[102:103], 0.5, v[188:189] op_sel_hi:[1,0,1]
	v_pk_fma_f32 v[108:109], v[100:101], 0.5, v[184:185] op_sel_hi:[1,0,1]
	v_lshl_add_u64 v[98:99], v[144:145], 0, s[14:15]
	global_load_dwordx4 v[100:103], v[98:99], off offset:256
	v_cvt_pk_bf16_f32 v108, v108, v109
	v_cvt_pk_bf16_f32 v109, v110, v111
	v_cvt_pk_bf16_f32 v110, v96, v97
	v_add_co_u32_e32 v96, vcc, s46, v144
	v_lshlrev_b32_e32 v176, 16, v168
	s_nop 0
	v_addc_co_u32_e32 v97, vcc, 0, v145, vcc
	v_and_b32_e32 v177, 0xffff0000, v168
	v_lshlrev_b32_e32 v180, 16, v169
	v_and_b32_e32 v181, 0xffff0000, v169
	v_lshlrev_b32_e32 v178, 16, v170
	v_and_b32_e32 v179, 0xffff0000, v170
	v_lshlrev_b32_e32 v182, 16, v171
	v_and_b32_e32 v183, 0xffff0000, v171
	global_load_dwordx4 v[120:123], v[96:97], off
	v_cvt_pk_bf16_f32 v111, v124, v125
	global_store_dwordx4 v[150:151], v[108:111], off offset:256
	v_pk_fma_f32 v[150:151], v[90:91], 0.5, v[182:183] op_sel_hi:[1,0,1]
	v_pk_fma_f32 v[88:89], v[88:89], 0.5, v[178:179] op_sel_hi:[1,0,1]
	v_pk_fma_f32 v[110:111], v[94:95], 0.5, v[180:181] op_sel_hi:[1,0,1]
	v_pk_fma_f32 v[108:109], v[92:93], 0.5, v[176:177] op_sel_hi:[1,0,1]
	v_lshl_add_u64 v[90:91], v[144:145], 0, s[16:17]
	global_load_dwordx4 v[92:95], v[90:91], off offset:256
	v_cvt_pk_bf16_f32 v108, v108, v109
	v_cvt_pk_bf16_f32 v109, v110, v111
	v_cvt_pk_bf16_f32 v110, v88, v89
	v_add_co_u32_e32 v88, vcc, s47, v144
	v_lshlrev_b32_e32 v170, 16, v174
	s_nop 0
	v_addc_co_u32_e32 v89, vcc, 0, v145, vcc
	v_and_b32_e32 v171, 0xffff0000, v174
	global_load_dwordx4 v[124:127], v[88:89], off
	v_lshlrev_b32_e32 v168, 16, v172
	v_and_b32_e32 v169, 0xffff0000, v172
	v_lshlrev_b32_e32 v172, 16, v173
	v_and_b32_e32 v173, 0xffff0000, v173
	v_cvt_pk_bf16_f32 v111, v150, v151
	v_pk_fma_f32 v[150:151], v[72:73], 0.5, v[170:171] op_sel_hi:[1,0,1]
	v_lshl_add_u64 v[72:73], v[144:145], 0, s[18:19]
	global_store_dwordx4 v[146:147], v[108:111], off
	v_lshlrev_b32_e32 v174, 16, v175
	v_and_b32_e32 v175, 0xffff0000, v175
	v_pk_fma_f32 v[110:111], v[82:83], 0.5, v[172:173] op_sel_hi:[1,0,1]
	v_pk_fma_f32 v[108:109], v[80:81], 0.5, v[168:169] op_sel_hi:[1,0,1]
	global_load_dwordx4 v[80:83], v[72:73], off offset:256
	v_lshlrev_b32_e32 v160, 16, v204
	v_and_b32_e32 v161, 0xffff0000, v204
	v_lshlrev_b32_e32 v166, 16, v205
	v_and_b32_e32 v167, 0xffff0000, v205
	v_pk_fma_f32 v[74:75], v[74:75], 0.5, v[174:175] op_sel_hi:[1,0,1]
	v_cvt_pk_bf16_f32 v108, v108, v109
	v_cvt_pk_bf16_f32 v109, v110, v111
	v_cvt_pk_bf16_f32 v111, v74, v75
	v_pk_fma_f32 v[86:87], v[86:87], 0.5, v[162:163] op_sel_hi:[1,0,1]
	v_pk_fma_f32 v[74:75], v[84:85], 0.5, v[154:155] op_sel_hi:[1,0,1]
	v_pk_fma_f32 v[78:79], v[78:79], 0.5, v[166:167] op_sel_hi:[1,0,1]
	v_pk_fma_f32 v[76:77], v[76:77], 0.5, v[160:161] op_sel_hi:[1,0,1]
	v_lshlrev_b32_e32 v152, 16, v206
	v_and_b32_e32 v153, 0xffff0000, v206
	v_lshlrev_b32_e32 v158, 16, v207
	v_and_b32_e32 v159, 0xffff0000, v207
	v_lshlrev_b32_e32 v156, 16, v208
	v_and_b32_e32 v157, 0xffff0000, v208
	v_lshlrev_b32_e32 v164, 16, v209
	v_and_b32_e32 v165, 0xffff0000, v209
	v_cvt_pk_bf16_f32 v74, v74, v75
	v_cvt_pk_bf16_f32 v75, v86, v87
	v_cvt_pk_bf16_f32 v76, v76, v77
	v_cvt_pk_bf16_f32 v77, v78, v79
	global_store_dwordx4 v[148:149], v[74:77], off
	v_pk_fma_f32 v[70:71], v[70:71], 0.5, v[158:159] op_sel_hi:[1,0,1]
	v_pk_fma_f32 v[68:69], v[68:69], 0.5, v[152:153] op_sel_hi:[1,0,1]
	v_pk_fma_f32 v[74:75], v[66:67], 0.5, v[164:165] op_sel_hi:[1,0,1]
	v_pk_fma_f32 v[66:67], v[64:65], 0.5, v[156:157] op_sel_hi:[1,0,1]
	v_cvt_pk_bf16_f32 v64, v68, v69
	v_cvt_pk_bf16_f32 v65, v70, v71
	v_cvt_pk_bf16_f32 v66, v66, v67
	v_cvt_pk_bf16_f32 v67, v74, v75
	global_store_dwordx4 v[148:149], v[64:67], off offset:256
	s_waitcnt vmcnt(0)
; DI unsigned pk_bf16(float lo, float hi) { f32x2 v = {lo, hi}; return __builtin_bit_cast(unsigned, __builtin_convertvector(v, bf16v2)); }
; #define PG8_WAIT_V(n) asm volatile("s_waitcnt vmcnt(" #n ")" ::: "memory")
; #define PG8_BAR __builtin_amdgcn_s_barrier()
; #define PG8_WAIT_V(n) asm volatile("s_waitcnt vmcnt(" #n ")" ::: "memory")
; #define PG8_BAR __builtin_amdgcn_s_barrier()
; template <class Epi>
; DI void gemm_phase(LAS unsigned char* lds, const Gemm g, const StaticOrder S, const Epi E) {
;     ...
;         if (!has_next) break;
; #pragma unroll
;         for (int a = 0; a < 2; ++a)
; #pragma unroll
;             for (int b = 0; b < 2; ++b)
; #pragma unroll
;                 for (int m = 0; m < 4; ++m)
; #pragma unroll
;                     for (int n = 0; n < 2; ++n) acc[a][b][m][n] = (f32x4){0.f, 0.f, 0.f, 0.f};
;         cur = nxt; cA = nA; cB = nB; ++ui;
;     }
;     PG8_WAIT_V(0);
;     if (wr == 0) PG8_BAR;
;     PG8_BAR;
;     DI void operator()(AccRef acc, const Unit& u, int wr, int wc, int fr, int fq) const {
;     ...
;             for (int m = 0; m < 4; ++m) {
;                 const int row = row0 + ai * 128 + m * 16;
;                 float q = 0.f;
; #pragma unroll
;                 for (int bj = 0; bj < 2; ++bj) {
;                     const size_t o = (size_t)row * DM + col0 + bj * 128;
;                     const f32x4 r0 = bv[m][bj][0] + scale * acc[ai][bj][m][0], r1 = bv[m][bj][1] + scale * acc[ai][bj][m][1];
;                     u32x4 w; w.x = pk_bf16(r0[0], r0[1]); w.y = pk_bf16(r0[2], r0[3]); w.z = pk_bf16(r1[0], r1[1]); w.w = pk_bf16(r1[2], r1[3]);
;                     *(u32x4*)(xnb + o) = w;
;                     if (STATS) q += r0[0] * r0[0] + r0[1] * r0[1] + r0[2] * r0[2] + r0[3] * r0[3] + r1[0] * r1[0] + r1[1] * r1[1] + r1[2] * r1[2] + r1[3] * r1[3];
;                 }
;                 if (STATS) { q += __shfl_xor(q, 16); q += __shfl_xor(q, 32); if (fq == 0) atomicAdd(ss + row, q); }
;             }
	v_lshlrev_b32_e32 v68, 16, v118
	v_and_b32_e32 v69, 0xffff0000, v118
	v_lshlrev_b32_e32 v64, 16, v116
	v_and_b32_e32 v65, 0xffff0000, v116
	v_lshlrev_b32_e32 v66, 16, v117
	v_and_b32_e32 v67, 0xffff0000, v117
	v_lshlrev_b32_e32 v70, 16, v119
	v_and_b32_e32 v71, 0xffff0000, v119
	v_pk_fma_f32 v[62:63], v[62:63], 0.5, v[66:67] op_sel_hi:[1,0,1]
	v_pk_fma_f32 v[60:61], v[60:61], 0.5, v[64:65] op_sel_hi:[1,0,1]
	v_pk_fma_f32 v[64:65], v[58:59], 0.5, v[70:71] op_sel_hi:[1,0,1]
	v_pk_fma_f32 v[58:59], v[56:57], 0.5, v[68:69] op_sel_hi:[1,0,1]
	v_lshlrev_b32_e32 v74, 16, v104
	v_and_b32_e32 v75, 0xffff0000, v104
	v_lshlrev_b32_e32 v76, 16, v105
	v_and_b32_e32 v77, 0xffff0000, v105
	v_lshlrev_b32_e32 v78, 16, v106
	v_and_b32_e32 v79, 0xffff0000, v106
	v_lshlrev_b32_e32 v84, 16, v107
	v_and_b32_e32 v85, 0xffff0000, v107
	v_cvt_pk_bf16_f32 v56, v60, v61
	v_cvt_pk_bf16_f32 v57, v62, v63
	v_cvt_pk_bf16_f32 v58, v58, v59
	v_cvt_pk_bf16_f32 v59, v64, v65
	v_cvt_pk_bf16_f32 v110, v150, v151
	global_store_dwordx4 v[202:203], v[56:59], off
	v_pk_fma_f32 v[54:55], v[54:55], 0.5, v[76:77] op_sel_hi:[1,0,1]
	v_pk_fma_f32 v[52:53], v[52:53], 0.5, v[74:75] op_sel_hi:[1,0,1]
	v_pk_fma_f32 v[56:57], v[46:47], 0.5, v[84:85] op_sel_hi:[1,0,1]
	v_pk_fma_f32 v[46:47], v[44:45], 0.5, v[78:79] op_sel_hi:[1,0,1]
	global_store_dwordx4 v[146:147], v[108:111], off offset:256
	v_lshlrev_b32_e32 v86, 16, v112
	v_and_b32_e32 v87, 0xffff0000, v112
	v_lshlrev_b32_e32 v104, 16, v113
	v_and_b32_e32 v105, 0xffff0000, v113
	v_lshlrev_b32_e32 v106, 16, v114
	v_and_b32_e32 v107, 0xffff0000, v114
	v_lshlrev_b32_e32 v108, 16, v115
	v_and_b32_e32 v109, 0xffff0000, v115
	v_cvt_pk_bf16_f32 v44, v52, v53
	v_cvt_pk_bf16_f32 v45, v54, v55
	v_cvt_pk_bf16_f32 v46, v46, v47
	v_cvt_pk_bf16_f32 v47, v56, v57
	global_store_dwordx4 v[192:193], v[44:47], off offset:256
	v_lshlrev_b32_e32 v110, 16, v100
	v_and_b32_e32 v111, 0xffff0000, v100
	v_pk_fma_f32 v[44:45], v[50:51], 0.5, v[104:105] op_sel_hi:[1,0,1]
	v_pk_fma_f32 v[46:47], v[48:49], 0.5, v[86:87] op_sel_hi:[1,0,1]
	v_pk_fma_f32 v[48:49], v[42:43], 0.5, v[108:109] op_sel_hi:[1,0,1]
	v_pk_fma_f32 v[42:43], v[40:41], 0.5, v[106:107] op_sel_hi:[1,0,1]
	v_lshlrev_b32_e32 v100, 16, v101
	v_and_b32_e32 v101, 0xffff0000, v101
	v_lshlrev_b32_e32 v112, 16, v102
	v_and_b32_e32 v113, 0xffff0000, v102
	v_lshlrev_b32_e32 v102, 16, v103
	v_and_b32_e32 v103, 0xffff0000, v103
	v_cvt_pk_bf16_f32 v40, v46, v47
	v_cvt_pk_bf16_f32 v41, v44, v45
	v_cvt_pk_bf16_f32 v42, v42, v43
	v_cvt_pk_bf16_f32 v43, v48, v49
	global_store_dwordx4 v[194:195], v[40:43], off
	v_pk_fma_f32 v[38:39], v[38:39], 0.5, v[100:101] op_sel_hi:[1,0,1]
	v_pk_fma_f32 v[36:37], v[36:37], 0.5, v[110:111] op_sel_hi:[1,0,1]
	v_pk_fma_f32 v[40:41], v[30:31], 0.5, v[102:103] op_sel_hi:[1,0,1]
	v_pk_fma_f32 v[30:31], v[28:29], 0.5, v[112:113] op_sel_hi:[1,0,1]
	v_lshlrev_b32_e32 v114, 16, v120
	v_and_b32_e32 v115, 0xffff0000, v120
	v_lshlrev_b32_e32 v116, 16, v121
	v_and_b32_e32 v117, 0xffff0000, v121
	v_lshlrev_b32_e32 v118, 16, v122
	v_and_b32_e32 v119, 0xffff0000, v122
	v_lshlrev_b32_e32 v120, 16, v123
	v_and_b32_e32 v121, 0xffff0000, v123
	v_cvt_pk_bf16_f32 v28, v36, v37
	v_cvt_pk_bf16_f32 v29, v38, v39
	v_cvt_pk_bf16_f32 v30, v30, v31
	v_cvt_pk_bf16_f32 v31, v40, v41
	global_store_dwordx4 v[98:99], v[28:31], off offset:256
	v_lshlrev_b32_e32 v122, 16, v92
	v_and_b32_e32 v123, 0xffff0000, v92
	v_pk_fma_f32 v[28:29], v[34:35], 0.5, v[116:117] op_sel_hi:[1,0,1]
	v_pk_fma_f32 v[30:31], v[32:33], 0.5, v[114:115] op_sel_hi:[1,0,1]
	v_pk_fma_f32 v[32:33], v[26:27], 0.5, v[120:121] op_sel_hi:[1,0,1]
	v_pk_fma_f32 v[26:27], v[24:25], 0.5, v[118:119] op_sel_hi:[1,0,1]
	v_lshlrev_b32_e32 v92, 16, v93
	v_and_b32_e32 v93, 0xffff0000, v93
	v_lshlrev_b32_e32 v144, 16, v94
	v_and_b32_e32 v145, 0xffff0000, v94
	v_lshlrev_b32_e32 v94, 16, v95
	v_and_b32_e32 v95, 0xffff0000, v95
	v_cvt_pk_bf16_f32 v24, v30, v31
	v_cvt_pk_bf16_f32 v25, v28, v29
	v_cvt_pk_bf16_f32 v26, v26, v27
	v_cvt_pk_bf16_f32 v27, v32, v33
	global_store_dwordx4 v[96:97], v[24:27], off
	v_pk_fma_f32 v[22:23], v[22:23], 0.5, v[92:93] op_sel_hi:[1,0,1]
	v_pk_fma_f32 v[20:21], v[20:21], 0.5, v[122:123] op_sel_hi:[1,0,1]
	v_pk_fma_f32 v[24:25], v[14:15], 0.5, v[94:95] op_sel_hi:[1,0,1]
	v_pk_fma_f32 v[14:15], v[12:13], 0.5, v[144:145] op_sel_hi:[1,0,1]
	v_lshlrev_b32_e32 v146, 16, v124
	v_and_b32_e32 v147, 0xffff0000, v124
	v_lshlrev_b32_e32 v124, 16, v125
	v_and_b32_e32 v125, 0xffff0000, v125
	v_lshlrev_b32_e32 v148, 16, v126
	v_and_b32_e32 v149, 0xffff0000, v126
	v_lshlrev_b32_e32 v126, 16, v127
	v_and_b32_e32 v127, 0xffff0000, v127
	v_cvt_pk_bf16_f32 v12, v20, v21
	v_cvt_pk_bf16_f32 v13, v22, v23
	v_cvt_pk_bf16_f32 v14, v14, v15
	v_cvt_pk_bf16_f32 v15, v24, v25
	global_store_dwordx4 v[90:91], v[12:15], off offset:256
	v_lshlrev_b32_e32 v150, 16, v80
	v_and_b32_e32 v151, 0xffff0000, v80
	v_pk_fma_f32 v[12:13], v[18:19], 0.5, v[124:125] op_sel_hi:[1,0,1]
	v_pk_fma_f32 v[14:15], v[16:17], 0.5, v[146:147] op_sel_hi:[1,0,1]
	v_pk_fma_f32 v[16:17], v[10:11], 0.5, v[126:127] op_sel_hi:[1,0,1]
	v_pk_fma_f32 v[10:11], v[8:9], 0.5, v[148:149] op_sel_hi:[1,0,1]
	v_lshlrev_b32_e32 v80, 16, v81
	v_and_b32_e32 v81, 0xffff0000, v81
	v_lshlrev_b32_e32 v152, 16, v82
	v_and_b32_e32 v153, 0xffff0000, v82
	v_lshlrev_b32_e32 v82, 16, v83
	v_and_b32_e32 v83, 0xffff0000, v83
	v_cvt_pk_bf16_f32 v8, v14, v15
	v_cvt_pk_bf16_f32 v9, v12, v13
	v_cvt_pk_bf16_f32 v10, v10, v11
	v_cvt_pk_bf16_f32 v11, v16, v17
	global_store_dwordx4 v[88:89], v[8:11], off
	v_pk_fma_f32 v[6:7], v[6:7], 0.5, v[80:81] op_sel_hi:[1,0,1]
	v_pk_fma_f32 v[4:5], v[4:5], 0.5, v[150:151] op_sel_hi:[1,0,1]
	v_pk_fma_f32 v[8:9], v[2:3], 0.5, v[82:83] op_sel_hi:[1,0,1]
	v_pk_fma_f32 v[2:3], v[0:1], 0.5, v[152:153] op_sel_hi:[1,0,1]
	v_cvt_pk_bf16_f32 v0, v4, v5
	v_cvt_pk_bf16_f32 v1, v6, v7
	v_cvt_pk_bf16_f32 v2, v2, v3
	v_cvt_pk_bf16_f32 v3, v8, v9
	s_and_b64 vcc, exec, s[0:1]
	global_store_dwordx4 v[72:73], v[0:3], off offset:256
	s_cbranch_vccz .LBB0_930
	s_waitcnt vmcnt(0)
	s_cmpk_gt_u32 s6, 0xff
	s_cbranch_scc1 .LBB0_945
	s_barrier
